# c24 + write-through (sc1) on the dwordx2/x4 global stores of phase 0 and the GEMM epilogues, so little dirty L2 data is left for the release write-back at each grid barrier
# speedup vs baseline: 1.0289x; 1.0119x over previous
.LBB0_25:
	s_cmpk_gt_i32 s79, 0x15f
	s_mov_b64 s[4:5], -1
	s_cbranch_scc0 .LBB0_107
	s_cmpk_gt_u32 s79, 0x27f
	s_cbranch_scc0 .LBB0_80
	s_cmpk_gt_u32 s79, 0x37f
	s_cbranch_scc0 .LBB0_53
	s_cmpk_gt_u32 s79, 0x57f
	s_cbranch_scc0 .LBB0_50
	s_cmpk_gt_u32 s79, 0xb7f
	s_cbranch_scc0 .LBB0_47
	s_cmpk_gt_u32 s79, 0xd7f
	s_cbranch_scc0 .LBB0_44
	s_cmpk_gt_u32 s79, 0x187f
	s_cbranch_scc0 .LBB0_41
	s_cmpk_gt_u32 s79, 0x237f
	s_cbranch_scc0 .LBB0_38
	s_load_dwordx2 s[4:5], s[16:17], 0x88
	s_cmpk_gt_u32 s79, 0x28ff
	s_mov_b64 s[34:35], -1
	s_cbranch_scc0 .LBB0_35
	s_and_b32 s34, s1, 0x3e0
	s_and_b32 s6, s11, 0x1ffc0
	s_lshl_b32 s35, s34, 2
	v_add_u32_e32 v26, s6, v5
	s_waitcnt lgkmcnt(0)
	s_add_u32 s80, s4, s35
	s_addc_u32 s81, s5, 0
	v_ashrrev_i32_e32 v27, 31, v26
	v_lshl_add_u64 v[28:29], s[80:81], 0, v[0:1]
	v_lshlrev_b64 v[26:27], 12, v[26:27]
	v_lshl_add_u64 v[26:27], v[28:29], 0, v[26:27]
	s_mov_b32 s35, 0xb00000
	v_add_co_u32_e32 v28, vcc, s35, v26
	s_mov_b32 s35, 0xb02000
	s_nop 0
	v_addc_co_u32_e32 v29, vcc, 0, v27, vcc
	v_add_co_u32_e32 v30, vcc, s35, v26
	s_mov_b32 s35, 0xb04000
	s_nop 0
	v_addc_co_u32_e32 v31, vcc, 0, v27, vcc
	v_add_co_u32_e32 v32, vcc, s35, v26
	s_mov_b32 s35, 0xb06000
	s_nop 0
	v_addc_co_u32_e32 v33, vcc, 0, v27, vcc
	v_add_co_u32_e32 v34, vcc, s35, v26
	s_mov_b32 s35, 0xb08000
	s_nop 0
	v_addc_co_u32_e32 v35, vcc, 0, v27, vcc
	v_add_co_u32_e32 v36, vcc, s35, v26
	s_mov_b32 s35, 0xb0a000
	s_nop 0
	v_addc_co_u32_e32 v37, vcc, 0, v27, vcc
	v_add_co_u32_e32 v38, vcc, s35, v26
	s_mov_b32 s35, 0xb0c000
	s_nop 0
	v_addc_co_u32_e32 v39, vcc, 0, v27, vcc
	v_add_co_u32_e32 v40, vcc, s35, v26
	s_mov_b32 s35, 0xb0e000
	s_nop 0
	v_addc_co_u32_e32 v41, vcc, 0, v27, vcc
	v_add_co_u32_e32 v42, vcc, s35, v26
	s_mov_b32 s35, 0xb10000
	s_nop 0
	v_addc_co_u32_e32 v43, vcc, 0, v27, vcc
	global_load_dword v44, v[28:29], off nt
	global_load_dword v45, v[30:31], off nt
	global_load_dword v76, v[32:33], off nt
	global_load_dword v77, v[34:35], off nt
	global_load_dword v78, v[36:37], off nt
	global_load_dword v79, v[38:39], off nt
	global_load_dword v80, v[40:41], off nt
	global_load_dword v81, v[42:43], off nt
	v_add_co_u32_e32 v28, vcc, s35, v26
	s_mov_b32 s35, 0xb12000
	s_nop 0
	v_addc_co_u32_e32 v29, vcc, 0, v27, vcc
	v_add_co_u32_e32 v30, vcc, s35, v26
	s_mov_b32 s35, 0xb14000
	s_nop 0
	v_addc_co_u32_e32 v31, vcc, 0, v27, vcc
	v_add_co_u32_e32 v32, vcc, s35, v26
	s_mov_b32 s35, 0xb16000
	s_nop 0
	v_addc_co_u32_e32 v33, vcc, 0, v27, vcc
	v_add_co_u32_e32 v34, vcc, s35, v26
	s_mov_b32 s35, 0xb18000
	s_nop 0
	v_addc_co_u32_e32 v35, vcc, 0, v27, vcc
	v_add_co_u32_e32 v36, vcc, s35, v26
	s_mov_b32 s35, 0xb1a000
	s_nop 0
	v_addc_co_u32_e32 v37, vcc, 0, v27, vcc
	v_add_co_u32_e32 v38, vcc, s35, v26
	s_mov_b32 s35, 0xb1c000
	s_nop 0
	v_addc_co_u32_e32 v39, vcc, 0, v27, vcc
	v_add_co_u32_e32 v40, vcc, s35, v26
	s_mov_b32 s35, 0xb1e000
	s_nop 0
	v_addc_co_u32_e32 v41, vcc, 0, v27, vcc
	v_add_co_u32_e32 v42, vcc, s35, v26
	s_mov_b32 s35, 0xb20000
	s_nop 0
	v_addc_co_u32_e32 v43, vcc, 0, v27, vcc
	global_load_dword v82, v[28:29], off nt
	global_load_dword v83, v[30:31], off nt
	global_load_dword v84, v[32:33], off nt
	global_load_dword v85, v[34:35], off nt
	global_load_dword v86, v[36:37], off nt
	global_load_dword v87, v[38:39], off nt
	global_load_dword v88, v[40:41], off nt
	global_load_dword v89, v[42:43], off nt
	v_add_co_u32_e32 v28, vcc, s35, v26
	s_mov_b32 s35, 0xb22000
	s_nop 0
	v_addc_co_u32_e32 v29, vcc, 0, v27, vcc
	v_add_co_u32_e32 v30, vcc, s35, v26
	s_mov_b32 s35, 0xb24000
	s_nop 0
	v_addc_co_u32_e32 v31, vcc, 0, v27, vcc
	v_add_co_u32_e32 v32, vcc, s35, v26
	s_mov_b32 s35, 0xb26000
	s_nop 0
	v_addc_co_u32_e32 v33, vcc, 0, v27, vcc
	v_add_co_u32_e32 v34, vcc, s35, v26
	s_mov_b32 s35, 0xb28000
	s_nop 0
	v_addc_co_u32_e32 v35, vcc, 0, v27, vcc
	v_add_co_u32_e32 v36, vcc, s35, v26
	s_mov_b32 s35, 0xb2a000
	s_nop 0
	v_addc_co_u32_e32 v37, vcc, 0, v27, vcc
	v_add_co_u32_e32 v38, vcc, s35, v26
	s_mov_b32 s35, 0xb2c000
	s_nop 0
	v_addc_co_u32_e32 v39, vcc, 0, v27, vcc
	v_add_co_u32_e32 v40, vcc, s35, v26
	s_mov_b32 s35, 0xb2e000
	s_nop 0
	v_addc_co_u32_e32 v41, vcc, 0, v27, vcc
	v_add_co_u32_e32 v42, vcc, s35, v26
	s_mov_b32 s35, 0xb30000
	s_nop 0
	v_addc_co_u32_e32 v43, vcc, 0, v27, vcc
	global_load_dword v90, v[28:29], off nt
	global_load_dword v91, v[30:31], off nt
	global_load_dword v92, v[32:33], off nt
	global_load_dword v93, v[34:35], off nt
	global_load_dword v94, v[36:37], off nt
	global_load_dword v95, v[38:39], off nt
	global_load_dword v96, v[40:41], off nt
	s_nop 0
	global_load_dword v42, v[42:43], off nt
	v_add_co_u32_e32 v28, vcc, s35, v26
	s_mov_b32 s35, 0xb32000
	s_nop 0
	v_addc_co_u32_e32 v29, vcc, 0, v27, vcc
	v_add_co_u32_e32 v30, vcc, s35, v26
	s_mov_b32 s35, 0xb34000
	s_nop 0
	v_addc_co_u32_e32 v31, vcc, 0, v27, vcc
	v_add_co_u32_e32 v32, vcc, s35, v26
	s_mov_b32 s35, 0xb36000
	s_nop 0
	v_addc_co_u32_e32 v33, vcc, 0, v27, vcc
	v_add_co_u32_e32 v34, vcc, s35, v26
	s_mov_b32 s35, 0xb38000
	s_nop 0
	v_addc_co_u32_e32 v35, vcc, 0, v27, vcc
	v_add_co_u32_e32 v36, vcc, s35, v26
	s_mov_b32 s35, 0xb3a000
	s_nop 0
	v_addc_co_u32_e32 v37, vcc, 0, v27, vcc
	v_add_co_u32_e32 v38, vcc, s35, v26
	s_mov_b32 s35, 0xb3c000
	s_nop 0
	v_addc_co_u32_e32 v39, vcc, 0, v27, vcc
	v_add_co_u32_e32 v40, vcc, s35, v26
	s_mov_b32 s35, 0xb3e000
	s_nop 0
	v_addc_co_u32_e32 v41, vcc, 0, v27, vcc
	v_add_co_u32_e32 v26, vcc, s35, v26
	s_lshl_b32 s6, s6, 1
	s_nop 0
	v_addc_co_u32_e32 v27, vcc, 0, v27, vcc
	global_load_dword v28, v[28:29], off nt
	s_nop 0
	global_load_dword v29, v[30:31], off nt
	s_nop 0
	global_load_dword v30, v[32:33], off nt
	global_load_dword v31, v[34:35], off nt
	s_nop 0
	global_load_dword v32, v[36:37], off nt
	global_load_dword v33, v[38:39], off nt
	global_load_dword v34, v[40:41], off nt
	s_nop 0
	global_load_dword v26, v[26:27], off nt
	s_waitcnt vmcnt(30)
	ds_write2_b32 v46, v44, v45 offset1:66
	s_waitcnt vmcnt(28)
	ds_write2_b32 v46, v76, v77 offset0:132 offset1:198
	s_waitcnt vmcnt(26)
	ds_write2_b32 v64, v78, v79 offset0:8 offset1:74
	s_waitcnt vmcnt(24)
	ds_write2_b32 v64, v80, v81 offset0:140 offset1:206
	s_waitcnt vmcnt(22)
	ds_write2_b32 v65, v82, v83 offset0:16 offset1:82
	s_waitcnt vmcnt(20)
	ds_write2_b32 v65, v84, v85 offset0:148 offset1:214
	s_waitcnt vmcnt(18)
	ds_write2_b32 v66, v86, v87 offset0:24 offset1:90
	s_waitcnt vmcnt(16)
	ds_write2_b32 v66, v88, v89 offset0:156 offset1:222
	s_waitcnt vmcnt(14)
	ds_write2_b32 v67, v90, v91 offset0:32 offset1:98
	s_waitcnt vmcnt(12)
	ds_write2_b32 v67, v92, v93 offset0:164 offset1:230
	s_waitcnt vmcnt(10)
	ds_write2_b32 v68, v94, v95 offset0:40 offset1:106
	s_waitcnt vmcnt(8)
	ds_write2_b32 v68, v96, v42 offset0:172 offset1:238
	s_waitcnt vmcnt(6)
	ds_write2_b32 v69, v28, v29 offset0:48 offset1:114
	s_waitcnt vmcnt(4)
	ds_write2_b32 v69, v30, v31 offset0:180 offset1:246
	s_waitcnt vmcnt(2)
	ds_write2_b32 v70, v32, v33 offset0:56 offset1:122
	s_waitcnt vmcnt(0)
	ds_write2_b32 v70, v34, v26 offset0:188 offset1:254
	s_waitcnt lgkmcnt(0)
	ds_read2_b32 v[30:31], v48 offset0:33 offset1:41
	ds_read2_b32 v[32:33], v48 offset1:8
	ds_read2_b32 v[34:35], v48 offset0:66 offset1:74
	ds_read2_b32 v[36:37], v48 offset0:99 offset1:107
	ds_read2_b32 v[38:39], v48 offset0:132 offset1:140
	ds_read2_b32 v[40:41], v48 offset0:165 offset1:173
	ds_read2_b32 v[42:43], v48 offset0:198 offset1:206
	ds_read2_b32 v[44:45], v48 offset0:231 offset1:239
	v_lshl_add_u64 v[76:77], v[2:3], 0, s[6:7]
	s_waitcnt lgkmcnt(6)
	v_cvt_pk_bf16_f32 v26, v32, v30
	v_add_u32_e32 v30, s34, v47
	v_mad_i64_i32 v[78:79], s[80:81], v30, s22, v[76:77]
	s_waitcnt lgkmcnt(4)
	v_cvt_pk_bf16_f32 v27, v34, v36
	s_waitcnt lgkmcnt(2)
	v_cvt_pk_bf16_f32 v28, v38, v40
	s_waitcnt lgkmcnt(0)
	v_cvt_pk_bf16_f32 v29, v42, v44
	global_store_dwordx4 v[78:79], v[26:29], off sc1
	v_add_u32_e32 v30, s34, v49
	s_nop 0
	v_cvt_pk_bf16_f32 v26, v33, v31
	v_cvt_pk_bf16_f32 v27, v35, v37
	v_cvt_pk_bf16_f32 v28, v39, v41
	v_cvt_pk_bf16_f32 v29, v43, v45
	ds_read2_b32 v[32:33], v48 offset0:16 offset1:24
	ds_read2_b32 v[34:35], v48 offset0:49 offset1:57
	ds_read2_b32 v[36:37], v48 offset0:82 offset1:90
	ds_read2_b32 v[38:39], v48 offset0:115 offset1:123
	ds_read2_b32 v[40:41], v48 offset0:148 offset1:156
	ds_read2_b32 v[42:43], v48 offset0:181 offset1:189
	ds_read2_b32 v[44:45], v48 offset0:214 offset1:222
	ds_read2_b32 v[78:79], v48 offset0:247 offset1:255
	v_mad_i64_i32 v[30:31], s[80:81], v30, s22, v[76:77]
	global_store_dwordx4 v[30:31], v[26:29], off sc1
	v_add_u32_e32 v30, s34, v50
	v_mad_i64_i32 v[30:31], s[80:81], v30, s22, v[76:77]
	s_waitcnt lgkmcnt(6)
	v_cvt_pk_bf16_f32 v26, v32, v34
	s_waitcnt lgkmcnt(4)
	v_cvt_pk_bf16_f32 v27, v36, v38
	s_waitcnt lgkmcnt(2)
	v_cvt_pk_bf16_f32 v28, v40, v42
	s_waitcnt lgkmcnt(0)
	v_cvt_pk_bf16_f32 v29, v44, v78
	global_store_dwordx4 v[30:31], v[26:29], off sc1
	v_add_u32_e32 v30, s34, v51
	v_mad_i64_i32 v[30:31], s[34:35], v30, s22, v[76:77]
	v_cvt_pk_bf16_f32 v26, v33, v35
	v_cvt_pk_bf16_f32 v27, v37, v39
	v_cvt_pk_bf16_f32 v28, v41, v43
	v_cvt_pk_bf16_f32 v29, v45, v79
	global_store_dwordx4 v[30:31], v[26:29], off sc1
	s_waitcnt lgkmcnt(0)
	s_mov_b64 s[34:35], 0
.LBB0_35:
	s_andn2_b64 vcc, exec, s[34:35]
	s_cbranch_vccnz .LBB0_37
	s_add_i32 s6, s11, 0xb00
	s_and_b32 s34, s1, 0x3e0
	s_and_b32 s6, s6, 0x1ffc0
	s_lshl_b32 s35, s34, 2
	v_add_u32_e32 v26, s6, v5
	s_waitcnt lgkmcnt(0)
	s_add_u32 s4, s4, s35
	s_addc_u32 s5, s5, 0
	v_ashrrev_i32_e32 v27, 31, v26
	v_lshl_add_u64 v[28:29], s[4:5], 0, v[0:1]
	v_lshlrev_b64 v[26:27], 12, v[26:27]
	v_lshl_add_u64 v[26:27], v[28:29], 0, v[26:27]
	v_add_co_u32_e32 v28, vcc, s24, v26
	s_lshl_b32 s6, s6, 1
	s_nop 0
	v_addc_co_u32_e32 v29, vcc, 0, v27, vcc
	v_add_co_u32_e32 v30, vcc, s25, v26
	s_nop 1
	v_addc_co_u32_e32 v31, vcc, 0, v27, vcc
	v_add_co_u32_e32 v32, vcc, s26, v26
	s_nop 1
	v_addc_co_u32_e32 v33, vcc, 0, v27, vcc
	v_add_co_u32_e32 v34, vcc, s27, v26
	s_nop 1
	v_addc_co_u32_e32 v35, vcc, 0, v27, vcc
	v_add_co_u32_e32 v36, vcc, s28, v26
	s_nop 1
	v_addc_co_u32_e32 v37, vcc, 0, v27, vcc
	v_add_co_u32_e32 v38, vcc, s29, v26
	s_nop 1
	v_addc_co_u32_e32 v39, vcc, 0, v27, vcc
	v_add_co_u32_e32 v40, vcc, s30, v26
	s_nop 1
	v_addc_co_u32_e32 v41, vcc, 0, v27, vcc
	global_load_dword v44, v[26:27], off nt
	global_load_dword v45, v[28:29], off nt
	global_load_dword v76, v[30:31], off nt
	global_load_dword v77, v[32:33], off nt
	global_load_dword v78, v[34:35], off nt
	global_load_dword v79, v[36:37], off nt
	global_load_dword v80, v[38:39], off nt
	global_load_dword v81, v[40:41], off nt
	v_add_co_u32_e32 v28, vcc, s31, v26
	s_nop 1
	v_addc_co_u32_e32 v29, vcc, 0, v27, vcc
	v_add_co_u32_e32 v30, vcc, s33, v26
	s_nop 1
	v_addc_co_u32_e32 v31, vcc, 0, v27, vcc
	v_add_co_u32_e32 v32, vcc, s36, v26
	s_nop 1
	v_addc_co_u32_e32 v33, vcc, 0, v27, vcc
	v_add_co_u32_e32 v34, vcc, s37, v26
	s_nop 1
	v_addc_co_u32_e32 v35, vcc, 0, v27, vcc
	v_add_co_u32_e32 v36, vcc, s38, v26
	s_nop 1
	v_addc_co_u32_e32 v37, vcc, 0, v27, vcc
	v_add_co_u32_e32 v38, vcc, s39, v26
	s_nop 1
	v_addc_co_u32_e32 v39, vcc, 0, v27, vcc
	v_add_co_u32_e32 v40, vcc, s40, v26
	s_nop 1
	v_addc_co_u32_e32 v41, vcc, 0, v27, vcc
	v_add_co_u32_e32 v42, vcc, s41, v26
	s_nop 1
	v_addc_co_u32_e32 v43, vcc, 0, v27, vcc
	global_load_dword v82, v[28:29], off nt
	global_load_dword v83, v[30:31], off nt
	global_load_dword v84, v[32:33], off nt
	global_load_dword v85, v[34:35], off nt
	global_load_dword v86, v[36:37], off nt
	global_load_dword v87, v[38:39], off nt
	global_load_dword v88, v[40:41], off nt
	global_load_dword v89, v[42:43], off nt
	v_add_co_u32_e32 v28, vcc, s42, v26
	s_nop 1
	v_addc_co_u32_e32 v29, vcc, 0, v27, vcc
	v_add_co_u32_e32 v30, vcc, s43, v26
	s_nop 1
	v_addc_co_u32_e32 v31, vcc, 0, v27, vcc
	v_add_co_u32_e32 v32, vcc, s44, v26
	s_nop 1
	v_addc_co_u32_e32 v33, vcc, 0, v27, vcc
	v_add_co_u32_e32 v34, vcc, s45, v26
	s_nop 1
	v_addc_co_u32_e32 v35, vcc, 0, v27, vcc
	v_add_co_u32_e32 v36, vcc, s46, v26
	s_nop 1
	v_addc_co_u32_e32 v37, vcc, 0, v27, vcc
	v_add_co_u32_e32 v38, vcc, s47, v26
	s_nop 1
	v_addc_co_u32_e32 v39, vcc, 0, v27, vcc
	v_add_co_u32_e32 v40, vcc, s48, v26
	s_nop 1
	v_addc_co_u32_e32 v41, vcc, 0, v27, vcc
	v_add_co_u32_e32 v42, vcc, s49, v26
	s_nop 1
	v_addc_co_u32_e32 v43, vcc, 0, v27, vcc
	global_load_dword v90, v[28:29], off nt
	global_load_dword v91, v[30:31], off nt
	global_load_dword v92, v[32:33], off nt
	global_load_dword v93, v[34:35], off nt
	global_load_dword v94, v[36:37], off nt
	global_load_dword v95, v[38:39], off nt
	global_load_dword v96, v[40:41], off nt
	s_nop 0
	global_load_dword v42, v[42:43], off nt
	v_add_co_u32_e32 v28, vcc, s50, v26
	s_nop 1
	v_addc_co_u32_e32 v29, vcc, 0, v27, vcc
	v_add_co_u32_e32 v30, vcc, s51, v26
	s_nop 1
	v_addc_co_u32_e32 v31, vcc, 0, v27, vcc
	v_add_co_u32_e32 v32, vcc, s52, v26
	s_nop 1
	v_addc_co_u32_e32 v33, vcc, 0, v27, vcc
	v_add_co_u32_e32 v34, vcc, s53, v26
	s_nop 1
	v_addc_co_u32_e32 v35, vcc, 0, v27, vcc
	v_add_co_u32_e32 v36, vcc, s54, v26
	s_nop 1
	v_addc_co_u32_e32 v37, vcc, 0, v27, vcc
	v_add_co_u32_e32 v38, vcc, s55, v26
	s_nop 1
	v_addc_co_u32_e32 v39, vcc, 0, v27, vcc
	v_add_co_u32_e32 v40, vcc, s56, v26
	s_nop 1
	v_addc_co_u32_e32 v41, vcc, 0, v27, vcc
	v_add_co_u32_e32 v26, vcc, s57, v26
	s_nop 1
	v_addc_co_u32_e32 v27, vcc, 0, v27, vcc
	global_load_dword v28, v[28:29], off nt
	s_nop 0
	global_load_dword v29, v[30:31], off nt
	s_nop 0
	global_load_dword v30, v[32:33], off nt
	global_load_dword v31, v[34:35], off nt
	s_nop 0
	global_load_dword v32, v[36:37], off nt
	global_load_dword v33, v[38:39], off nt
	global_load_dword v34, v[40:41], off nt
	s_nop 0
	global_load_dword v26, v[26:27], off nt
	s_waitcnt vmcnt(30)
	ds_write2_b32 v46, v44, v45 offset1:66
	s_waitcnt vmcnt(28)
	ds_write2_b32 v46, v76, v77 offset0:132 offset1:198
	s_waitcnt vmcnt(26)
	ds_write2_b32 v64, v78, v79 offset0:8 offset1:74
	s_waitcnt vmcnt(24)
	ds_write2_b32 v64, v80, v81 offset0:140 offset1:206
	s_waitcnt vmcnt(22)
	ds_write2_b32 v65, v82, v83 offset0:16 offset1:82
	s_waitcnt vmcnt(20)
	ds_write2_b32 v65, v84, v85 offset0:148 offset1:214
	s_waitcnt vmcnt(18)
	ds_write2_b32 v66, v86, v87 offset0:24 offset1:90
	s_waitcnt vmcnt(16)
	ds_write2_b32 v66, v88, v89 offset0:156 offset1:222
	s_waitcnt vmcnt(14)
	ds_write2_b32 v67, v90, v91 offset0:32 offset1:98
	s_waitcnt vmcnt(12)
	ds_write2_b32 v67, v92, v93 offset0:164 offset1:230
	s_waitcnt vmcnt(10)
	ds_write2_b32 v68, v94, v95 offset0:40 offset1:106
	s_waitcnt vmcnt(8)
	ds_write2_b32 v68, v96, v42 offset0:172 offset1:238
	s_waitcnt vmcnt(6)
	ds_write2_b32 v69, v28, v29 offset0:48 offset1:114
	s_waitcnt vmcnt(4)
	ds_write2_b32 v69, v30, v31 offset0:180 offset1:246
	s_waitcnt vmcnt(2)
	ds_write2_b32 v70, v32, v33 offset0:56 offset1:122
	s_waitcnt vmcnt(0)
	ds_write2_b32 v70, v34, v26 offset0:188 offset1:254
	s_waitcnt lgkmcnt(0)
	ds_read2_b32 v[30:31], v48 offset0:33 offset1:41
	ds_read2_b32 v[32:33], v48 offset1:8
	ds_read2_b32 v[34:35], v48 offset0:66 offset1:74
	ds_read2_b32 v[36:37], v48 offset0:99 offset1:107
	ds_read2_b32 v[38:39], v48 offset0:132 offset1:140
	ds_read2_b32 v[40:41], v48 offset0:165 offset1:173
	ds_read2_b32 v[42:43], v48 offset0:198 offset1:206
	ds_read2_b32 v[44:45], v48 offset0:231 offset1:239
	v_lshl_add_u64 v[76:77], v[8:9], 0, s[6:7]
	s_waitcnt lgkmcnt(6)
	v_cvt_pk_bf16_f32 v26, v32, v30
	v_add_u32_e32 v30, s34, v47
	v_mad_i64_i32 v[78:79], s[4:5], v30, s22, v[76:77]
	s_waitcnt lgkmcnt(4)
	v_cvt_pk_bf16_f32 v27, v34, v36
	s_waitcnt lgkmcnt(2)
	v_cvt_pk_bf16_f32 v28, v38, v40
	s_waitcnt lgkmcnt(0)
	v_cvt_pk_bf16_f32 v29, v42, v44
	global_store_dwordx4 v[78:79], v[26:29], off sc1
	v_add_u32_e32 v30, s34, v49
	s_nop 0
	v_cvt_pk_bf16_f32 v26, v33, v31
	v_cvt_pk_bf16_f32 v27, v35, v37
	v_cvt_pk_bf16_f32 v28, v39, v41
	v_cvt_pk_bf16_f32 v29, v43, v45
	ds_read2_b32 v[32:33], v48 offset0:16 offset1:24
	ds_read2_b32 v[34:35], v48 offset0:49 offset1:57
	ds_read2_b32 v[36:37], v48 offset0:82 offset1:90
	ds_read2_b32 v[38:39], v48 offset0:115 offset1:123
	ds_read2_b32 v[40:41], v48 offset0:148 offset1:156
	ds_read2_b32 v[42:43], v48 offset0:181 offset1:189
	ds_read2_b32 v[44:45], v48 offset0:214 offset1:222
	ds_read2_b32 v[78:79], v48 offset0:247 offset1:255
	v_mad_i64_i32 v[30:31], s[4:5], v30, s22, v[76:77]
	global_store_dwordx4 v[30:31], v[26:29], off sc1
	v_add_u32_e32 v30, s34, v50
	v_mad_i64_i32 v[30:31], s[4:5], v30, s22, v[76:77]
	s_waitcnt lgkmcnt(6)
	v_cvt_pk_bf16_f32 v26, v32, v34
	s_waitcnt lgkmcnt(4)
	v_cvt_pk_bf16_f32 v27, v36, v38
	s_waitcnt lgkmcnt(2)
	v_cvt_pk_bf16_f32 v28, v40, v42
	s_waitcnt lgkmcnt(0)
	v_cvt_pk_bf16_f32 v29, v44, v78
	global_store_dwordx4 v[30:31], v[26:29], off sc1
	v_add_u32_e32 v30, s34, v51
	v_mad_i64_i32 v[30:31], s[4:5], v30, s22, v[76:77]
	v_cvt_pk_bf16_f32 v26, v33, v35
	v_cvt_pk_bf16_f32 v27, v37, v39
	v_cvt_pk_bf16_f32 v28, v41, v43
	v_cvt_pk_bf16_f32 v29, v45, v79
	global_store_dwordx4 v[30:31], v[26:29], off sc1
	s_waitcnt lgkmcnt(0)

.LBB0_38:
	s_andn2_b64 vcc, exec, s[4:5]
	s_cbranch_vccnz .LBB0_40
	s_add_i32 s4, s79, 0xe780
	s_and_b32 s5, s4, 0xffff
	s_mul_i32 s5, s5, 0xba2f
	s_lshr_b32 s5, s5, 23
	s_load_dwordx2 s[34:35], s[16:17], 0x80
	s_mul_i32 s6, s5, 0xb0
	s_sub_i32 s4, s4, s6
	s_lshl_b32 s4, s4, 5
	s_and_b32 s4, s4, 0xffe0
	s_lshl_b32 s6, s4, 2
	s_waitcnt lgkmcnt(0)
	s_add_u32 s34, s34, s6
	s_addc_u32 s35, s35, 0
	v_lshl_add_u32 v44, s5, 6, v5
	v_lshl_add_u64 v[26:27], s[34:35], 0, v[0:1]
	v_lshl_add_u64 v[26:27], v[26:27], 0, s[18:19]
	v_add_u32_e32 v30, 2, v44
	v_add_u32_e32 v32, 4, v44
	v_add_u32_e32 v34, 6, v44
	v_add_u32_e32 v36, 8, v44
	v_add_u32_e32 v38, 10, v44
	v_add_u32_e32 v40, 12, v44
	v_add_u32_e32 v42, 14, v44
	v_mad_i64_i32 v[28:29], s[34:35], v44, s58, v[26:27]
	v_mad_i64_i32 v[30:31], s[34:35], v30, s58, v[26:27]
	v_mad_i64_i32 v[32:33], s[34:35], v32, s58, v[26:27]
	v_mad_i64_i32 v[34:35], s[34:35], v34, s58, v[26:27]
	v_mad_i64_i32 v[36:37], s[34:35], v36, s58, v[26:27]
	v_mad_i64_i32 v[38:39], s[34:35], v38, s58, v[26:27]
	v_mad_i64_i32 v[40:41], s[34:35], v40, s58, v[26:27]
	v_mad_i64_i32 v[42:43], s[34:35], v42, s58, v[26:27]
	global_load_dword v45, v[28:29], off nt
	global_load_dword v76, v[30:31], off nt
	global_load_dword v77, v[32:33], off nt
	global_load_dword v78, v[34:35], off nt
	global_load_dword v79, v[36:37], off nt
	global_load_dword v80, v[38:39], off nt
	global_load_dword v81, v[40:41], off nt
	global_load_dword v82, v[42:43], off nt
	v_add_u32_e32 v28, 16, v44
	v_add_u32_e32 v30, 18, v44
	v_add_u32_e32 v32, 20, v44
	v_add_u32_e32 v34, 22, v44
	v_add_u32_e32 v36, 24, v44
	v_add_u32_e32 v38, 26, v44
	v_add_u32_e32 v40, 28, v44
	v_add_u32_e32 v42, 30, v44
	v_mad_i64_i32 v[28:29], s[34:35], v28, s58, v[26:27]
	v_mad_i64_i32 v[30:31], s[34:35], v30, s58, v[26:27]
	v_mad_i64_i32 v[32:33], s[34:35], v32, s58, v[26:27]
	v_mad_i64_i32 v[34:35], s[34:35], v34, s58, v[26:27]
	v_mad_i64_i32 v[36:37], s[34:35], v36, s58, v[26:27]
	v_mad_i64_i32 v[38:39], s[34:35], v38, s58, v[26:27]
	v_mad_i64_i32 v[40:41], s[34:35], v40, s58, v[26:27]
	v_mad_i64_i32 v[42:43], s[34:35], v42, s58, v[26:27]
	global_load_dword v83, v[28:29], off nt
	global_load_dword v84, v[30:31], off nt
	global_load_dword v85, v[32:33], off nt
	global_load_dword v86, v[34:35], off nt
	global_load_dword v87, v[36:37], off nt
	global_load_dword v88, v[38:39], off nt
	global_load_dword v89, v[40:41], off nt
	global_load_dword v90, v[42:43], off nt
	v_add_u32_e32 v28, 32, v44
	v_add_u32_e32 v30, 34, v44
	v_add_u32_e32 v32, 36, v44
	v_add_u32_e32 v34, 38, v44
	v_add_u32_e32 v36, 40, v44
	v_add_u32_e32 v38, 42, v44
	v_add_u32_e32 v40, 44, v44
	v_add_u32_e32 v42, 46, v44
	v_mad_i64_i32 v[28:29], s[34:35], v28, s58, v[26:27]
	v_mad_i64_i32 v[30:31], s[34:35], v30, s58, v[26:27]
	v_mad_i64_i32 v[32:33], s[34:35], v32, s58, v[26:27]
	v_mad_i64_i32 v[34:35], s[34:35], v34, s58, v[26:27]
	v_mad_i64_i32 v[36:37], s[34:35], v36, s58, v[26:27]
	v_mad_i64_i32 v[38:39], s[34:35], v38, s58, v[26:27]
	v_mad_i64_i32 v[40:41], s[34:35], v40, s58, v[26:27]
	v_mad_i64_i32 v[42:43], s[34:35], v42, s58, v[26:27]
	global_load_dword v91, v[28:29], off nt
	global_load_dword v92, v[30:31], off nt
	global_load_dword v93, v[32:33], off nt
	global_load_dword v94, v[34:35], off nt
	global_load_dword v95, v[36:37], off nt
	global_load_dword v96, v[38:39], off nt
	global_load_dword v97, v[40:41], off nt
	s_nop 0
	global_load_dword v42, v[42:43], off nt
	v_add_u32_e32 v28, 48, v44
	v_add_u32_e32 v30, 50, v44
	v_add_u32_e32 v32, 52, v44
	v_add_u32_e32 v34, 54, v44
	v_add_u32_e32 v36, 56, v44
	v_add_u32_e32 v38, 58, v44
	v_add_u32_e32 v40, 60, v44
	v_add_u32_e32 v43, 62, v44
	v_mad_i64_i32 v[28:29], s[34:35], v28, s58, v[26:27]
	v_mad_i64_i32 v[30:31], s[34:35], v30, s58, v[26:27]
	v_mad_i64_i32 v[32:33], s[34:35], v32, s58, v[26:27]
	v_mad_i64_i32 v[34:35], s[34:35], v34, s58, v[26:27]
	v_mad_i64_i32 v[36:37], s[34:35], v36, s58, v[26:27]
	v_mad_i64_i32 v[38:39], s[34:35], v38, s58, v[26:27]
	v_mad_i64_i32 v[40:41], s[34:35], v40, s58, v[26:27]
	v_mad_i64_i32 v[26:27], s[34:35], v43, s58, v[26:27]
	global_load_dword v28, v[28:29], off nt
	s_nop 0
	global_load_dword v29, v[30:31], off nt
	s_nop 0
	global_load_dword v30, v[32:33], off nt
	global_load_dword v31, v[34:35], off nt
	s_nop 0
	global_load_dword v32, v[36:37], off nt
	global_load_dword v33, v[38:39], off nt
	global_load_dword v34, v[40:41], off nt
	s_nop 0
	global_load_dword v26, v[26:27], off nt
	s_waitcnt vmcnt(30)
	ds_write2_b32 v46, v45, v76 offset1:66
	s_waitcnt vmcnt(28)
	ds_write2_b32 v46, v77, v78 offset0:132 offset1:198
	s_waitcnt vmcnt(26)
	ds_write2_b32 v64, v79, v80 offset0:8 offset1:74
	s_waitcnt vmcnt(24)
	ds_write2_b32 v64, v81, v82 offset0:140 offset1:206
	s_waitcnt vmcnt(22)
	ds_write2_b32 v65, v83, v84 offset0:16 offset1:82
	s_waitcnt vmcnt(20)
	ds_write2_b32 v65, v85, v86 offset0:148 offset1:214
	s_waitcnt vmcnt(18)
	ds_write2_b32 v66, v87, v88 offset0:24 offset1:90
	s_waitcnt vmcnt(16)
	ds_write2_b32 v66, v89, v90 offset0:156 offset1:222
	s_waitcnt vmcnt(14)
	ds_write2_b32 v67, v91, v92 offset0:32 offset1:98
	s_waitcnt vmcnt(12)
	ds_write2_b32 v67, v93, v94 offset0:164 offset1:230
	s_waitcnt vmcnt(10)
	ds_write2_b32 v68, v95, v96 offset0:40 offset1:106
	s_waitcnt vmcnt(8)
	ds_write2_b32 v68, v97, v42 offset0:172 offset1:238
	s_waitcnt vmcnt(6)
	ds_write2_b32 v69, v28, v29 offset0:48 offset1:114
	s_waitcnt vmcnt(4)
	ds_write2_b32 v69, v30, v31 offset0:180 offset1:246
	s_waitcnt vmcnt(2)
	ds_write2_b32 v70, v32, v33 offset0:56 offset1:122
	s_waitcnt vmcnt(0)
	ds_write2_b32 v70, v34, v26 offset0:188 offset1:254
	s_waitcnt lgkmcnt(0)
	ds_read2_b32 v[30:31], v48 offset0:33 offset1:41
	ds_read2_b32 v[32:33], v48 offset1:8
	ds_read2_b32 v[34:35], v48 offset0:66 offset1:74
	ds_read2_b32 v[36:37], v48 offset0:99 offset1:107
	ds_read2_b32 v[38:39], v48 offset0:132 offset1:140
	ds_read2_b32 v[40:41], v48 offset0:165 offset1:173
	ds_read2_b32 v[42:43], v48 offset0:198 offset1:206
	ds_read2_b32 v[44:45], v48 offset0:231 offset1:239
	s_waitcnt lgkmcnt(6)
	v_cvt_pk_bf16_f32 v26, v32, v30
	v_add_u32_e32 v30, s4, v47
	v_cmp_lt_i32_e32 vcc, s59, v30
	s_waitcnt lgkmcnt(4)
	v_cvt_pk_bf16_f32 v27, v34, v36
	s_lshl_b32 s6, s5, 7
	v_lshl_add_u64 v[76:77], v[10:11], 0, s[6:7]
	v_cndmask_b32_e32 v32, 0, v71, vcc
	v_add_lshl_u32 v32, v32, v30, 1
	v_and_b32_e32 v32, 0xffffff00, v32
	v_cndmask_b32_e32 v34, 0, v72, vcc
	v_and_b32_e32 v30, 0x7f, v30
	v_or3_b32 v78, v34, v30, v32
	v_ashrrev_i32_e32 v79, 31, v78
	v_lshlrev_b64 v[78:79], 11, v[78:79]
	v_add_u32_e32 v30, s4, v49
	v_lshl_add_u64 v[78:79], v[76:77], 0, v[78:79]
	v_cmp_lt_i32_e32 vcc, s59, v30
	s_waitcnt lgkmcnt(2)
	v_cvt_pk_bf16_f32 v28, v38, v40
	s_waitcnt lgkmcnt(0)
	v_cvt_pk_bf16_f32 v29, v42, v44
	global_store_dwordx4 v[78:79], v[26:29], off sc1
	v_cndmask_b32_e32 v32, 0, v72, vcc
	s_nop 0
	v_cvt_pk_bf16_f32 v26, v33, v31
	v_cndmask_b32_e32 v31, 0, v71, vcc
	v_add_lshl_u32 v31, v31, v30, 1
	v_and_b32_e32 v31, 0xffffff00, v31
	v_and_b32_e32 v30, 0x7f, v30
	v_or3_b32 v30, v32, v30, v31
	v_ashrrev_i32_e32 v31, 31, v30
	v_lshlrev_b64 v[30:31], 11, v[30:31]
	v_lshl_add_u64 v[30:31], v[76:77], 0, v[30:31]
	v_cvt_pk_bf16_f32 v27, v35, v37
	v_cvt_pk_bf16_f32 v28, v39, v41
	v_cvt_pk_bf16_f32 v29, v43, v45
	ds_read2_b32 v[32:33], v48 offset0:16 offset1:24
	ds_read2_b32 v[34:35], v48 offset0:49 offset1:57
	ds_read2_b32 v[36:37], v48 offset0:82 offset1:90
	ds_read2_b32 v[38:39], v48 offset0:115 offset1:123
	ds_read2_b32 v[40:41], v48 offset0:148 offset1:156
	ds_read2_b32 v[42:43], v48 offset0:181 offset1:189
	ds_read2_b32 v[44:45], v48 offset0:214 offset1:222
	ds_read2_b32 v[78:79], v48 offset0:247 offset1:255
	global_store_dwordx4 v[30:31], v[26:29], off sc1
	v_add_u32_e32 v30, s4, v50
	v_cmp_lt_i32_e32 vcc, s59, v30
	s_waitcnt lgkmcnt(6)
	v_cvt_pk_bf16_f32 v26, v32, v34
	s_waitcnt lgkmcnt(4)
	v_cvt_pk_bf16_f32 v27, v36, v38
	s_waitcnt lgkmcnt(2)
	v_cvt_pk_bf16_f32 v28, v40, v42
	s_waitcnt lgkmcnt(0)
	v_cvt_pk_bf16_f32 v29, v44, v78
	v_cndmask_b32_e32 v31, 0, v71, vcc
	v_add_lshl_u32 v31, v31, v30, 1
	v_and_b32_e32 v31, 0xffffff00, v31
	v_cndmask_b32_e32 v32, 0, v72, vcc
	v_and_b32_e32 v30, 0x7f, v30
	v_or3_b32 v30, v32, v30, v31
	v_ashrrev_i32_e32 v31, 31, v30
	v_lshlrev_b64 v[30:31], 11, v[30:31]
	v_lshl_add_u64 v[30:31], v[76:77], 0, v[30:31]
	global_store_dwordx4 v[30:31], v[26:29], off sc1
	v_add_u32_e32 v30, s4, v51
	v_cmp_lt_i32_e32 vcc, s59, v30
	v_cvt_pk_bf16_f32 v26, v33, v35
	v_cvt_pk_bf16_f32 v27, v37, v39
	v_cvt_pk_bf16_f32 v28, v41, v43
	v_cvt_pk_bf16_f32 v29, v45, v79
	s_nop 1
	v_cndmask_b32_e32 v31, 0, v71, vcc
	v_add_lshl_u32 v31, v31, v30, 1
	v_and_b32_e32 v31, 0xffffff00, v31
	v_cndmask_b32_e32 v32, 0, v72, vcc
	v_and_b32_e32 v30, 0x7f, v30
	v_or3_b32 v30, v32, v30, v31
	v_ashrrev_i32_e32 v31, 31, v30
	v_lshlrev_b64 v[30:31], 11, v[30:31]
	v_lshl_add_u64 v[30:31], v[76:77], 0, v[30:31]
	global_store_dwordx4 v[30:31], v[26:29], off sc1
	s_waitcnt lgkmcnt(0)

.LBB0_41:
	s_andn2_b64 vcc, exec, s[4:5]
	s_cbranch_vccnz .LBB0_43
	s_add_i32 s4, s79, 0xf280
	s_and_b32 s5, s4, 0xffff
	s_mul_i32 s5, s5, 0xba2f
	s_lshr_b32 s5, s5, 23
	s_load_dwordx2 s[34:35], s[16:17], 0x80
	s_mul_i32 s6, s5, 0xb0
	s_sub_i32 s4, s4, s6
	s_lshl_b32 s4, s4, 5
	s_and_b32 s4, s4, 0xffe0
	s_lshl_b32 s6, s4, 2
	s_waitcnt lgkmcnt(0)
	s_add_u32 s34, s34, s6
	v_lshl_add_u32 v44, s5, 6, v5
	s_addc_u32 s35, s35, 0
	v_lshl_add_u64 v[26:27], s[34:35], 0, v[0:1]
	v_add_u32_e32 v30, 2, v44
	v_add_u32_e32 v32, 4, v44
	v_add_u32_e32 v34, 6, v44
	v_add_u32_e32 v36, 8, v44
	v_add_u32_e32 v38, 10, v44
	v_add_u32_e32 v40, 12, v44
	v_add_u32_e32 v42, 14, v44
	v_mad_i64_i32 v[28:29], s[34:35], v44, s58, v[26:27]
	v_mad_i64_i32 v[30:31], s[34:35], v30, s58, v[26:27]
	v_mad_i64_i32 v[32:33], s[34:35], v32, s58, v[26:27]
	v_mad_i64_i32 v[34:35], s[34:35], v34, s58, v[26:27]
	v_mad_i64_i32 v[36:37], s[34:35], v36, s58, v[26:27]
	v_mad_i64_i32 v[38:39], s[34:35], v38, s58, v[26:27]
	v_mad_i64_i32 v[40:41], s[34:35], v40, s58, v[26:27]
	v_mad_i64_i32 v[42:43], s[34:35], v42, s58, v[26:27]
	global_load_dword v45, v[28:29], off nt
	global_load_dword v76, v[30:31], off nt
	global_load_dword v77, v[32:33], off nt
	global_load_dword v78, v[34:35], off nt
	global_load_dword v79, v[36:37], off nt
	global_load_dword v80, v[38:39], off nt
	global_load_dword v81, v[40:41], off nt
	global_load_dword v82, v[42:43], off nt
	v_add_u32_e32 v28, 16, v44
	v_add_u32_e32 v30, 18, v44
	v_add_u32_e32 v32, 20, v44
	v_add_u32_e32 v34, 22, v44
	v_add_u32_e32 v36, 24, v44
	v_add_u32_e32 v38, 26, v44
	v_add_u32_e32 v40, 28, v44
	v_add_u32_e32 v42, 30, v44
	v_mad_i64_i32 v[28:29], s[34:35], v28, s58, v[26:27]
	v_mad_i64_i32 v[30:31], s[34:35], v30, s58, v[26:27]
	v_mad_i64_i32 v[32:33], s[34:35], v32, s58, v[26:27]
	v_mad_i64_i32 v[34:35], s[34:35], v34, s58, v[26:27]
	v_mad_i64_i32 v[36:37], s[34:35], v36, s58, v[26:27]
	v_mad_i64_i32 v[38:39], s[34:35], v38, s58, v[26:27]
	v_mad_i64_i32 v[40:41], s[34:35], v40, s58, v[26:27]
	v_mad_i64_i32 v[42:43], s[34:35], v42, s58, v[26:27]
	global_load_dword v83, v[28:29], off nt
	global_load_dword v84, v[30:31], off nt
	global_load_dword v85, v[32:33], off nt
	global_load_dword v86, v[34:35], off nt
	global_load_dword v87, v[36:37], off nt
	global_load_dword v88, v[38:39], off nt
	global_load_dword v89, v[40:41], off nt
	global_load_dword v90, v[42:43], off nt
	v_add_u32_e32 v28, 32, v44
	v_add_u32_e32 v30, 34, v44
	v_add_u32_e32 v32, 36, v44
	v_add_u32_e32 v34, 38, v44
	v_add_u32_e32 v36, 40, v44
	v_add_u32_e32 v38, 42, v44
	v_add_u32_e32 v40, 44, v44
	v_add_u32_e32 v42, 46, v44
	v_mad_i64_i32 v[28:29], s[34:35], v28, s58, v[26:27]
	v_mad_i64_i32 v[30:31], s[34:35], v30, s58, v[26:27]
	v_mad_i64_i32 v[32:33], s[34:35], v32, s58, v[26:27]
	v_mad_i64_i32 v[34:35], s[34:35], v34, s58, v[26:27]
	v_mad_i64_i32 v[36:37], s[34:35], v36, s58, v[26:27]
	v_mad_i64_i32 v[38:39], s[34:35], v38, s58, v[26:27]
	v_mad_i64_i32 v[40:41], s[34:35], v40, s58, v[26:27]
	v_mad_i64_i32 v[42:43], s[34:35], v42, s58, v[26:27]
	global_load_dword v91, v[28:29], off nt
	global_load_dword v92, v[30:31], off nt
	global_load_dword v93, v[32:33], off nt
	global_load_dword v94, v[34:35], off nt
	global_load_dword v95, v[36:37], off nt
	global_load_dword v96, v[38:39], off nt
	global_load_dword v97, v[40:41], off nt
	s_nop 0
	global_load_dword v42, v[42:43], off nt
	v_add_u32_e32 v28, 48, v44
	v_add_u32_e32 v30, 50, v44
	v_add_u32_e32 v32, 52, v44
	v_add_u32_e32 v34, 54, v44
	v_add_u32_e32 v36, 56, v44
	v_add_u32_e32 v38, 58, v44
	v_add_u32_e32 v40, 60, v44
	v_add_u32_e32 v43, 62, v44
	v_mad_i64_i32 v[28:29], s[34:35], v28, s58, v[26:27]
	v_mad_i64_i32 v[30:31], s[34:35], v30, s58, v[26:27]
	v_mad_i64_i32 v[32:33], s[34:35], v32, s58, v[26:27]
	v_mad_i64_i32 v[34:35], s[34:35], v34, s58, v[26:27]
	v_mad_i64_i32 v[36:37], s[34:35], v36, s58, v[26:27]
	v_mad_i64_i32 v[38:39], s[34:35], v38, s58, v[26:27]
	v_mad_i64_i32 v[40:41], s[34:35], v40, s58, v[26:27]
	v_mad_i64_i32 v[26:27], s[34:35], v43, s58, v[26:27]
	global_load_dword v28, v[28:29], off nt
	s_nop 0
	global_load_dword v29, v[30:31], off nt
	s_nop 0
	global_load_dword v30, v[32:33], off nt
	global_load_dword v31, v[34:35], off nt
	s_nop 0
	global_load_dword v32, v[36:37], off nt
	global_load_dword v33, v[38:39], off nt
	global_load_dword v34, v[40:41], off nt
	s_nop 0
	global_load_dword v26, v[26:27], off nt
	s_waitcnt vmcnt(30)
	ds_write2_b32 v46, v45, v76 offset1:66
	s_waitcnt vmcnt(28)
	ds_write2_b32 v46, v77, v78 offset0:132 offset1:198
	s_waitcnt vmcnt(26)
	ds_write2_b32 v64, v79, v80 offset0:8 offset1:74
	s_waitcnt vmcnt(24)
	ds_write2_b32 v64, v81, v82 offset0:140 offset1:206
	s_waitcnt vmcnt(22)
	ds_write2_b32 v65, v83, v84 offset0:16 offset1:82
	s_waitcnt vmcnt(20)
	ds_write2_b32 v65, v85, v86 offset0:148 offset1:214
	s_waitcnt vmcnt(18)
	ds_write2_b32 v66, v87, v88 offset0:24 offset1:90
	s_waitcnt vmcnt(16)
	ds_write2_b32 v66, v89, v90 offset0:156 offset1:222
	s_waitcnt vmcnt(14)
	ds_write2_b32 v67, v91, v92 offset0:32 offset1:98
	s_waitcnt vmcnt(12)
	ds_write2_b32 v67, v93, v94 offset0:164 offset1:230
	s_waitcnt vmcnt(10)
	ds_write2_b32 v68, v95, v96 offset0:40 offset1:106
	s_waitcnt vmcnt(8)
	ds_write2_b32 v68, v97, v42 offset0:172 offset1:238
	s_waitcnt vmcnt(6)
	ds_write2_b32 v69, v28, v29 offset0:48 offset1:114
	s_waitcnt vmcnt(4)
	ds_write2_b32 v69, v30, v31 offset0:180 offset1:246
	s_waitcnt vmcnt(2)
	ds_write2_b32 v70, v32, v33 offset0:56 offset1:122
	s_waitcnt vmcnt(0)
	ds_write2_b32 v70, v34, v26 offset0:188 offset1:254
	s_waitcnt lgkmcnt(0)
	ds_read2_b32 v[30:31], v48 offset0:33 offset1:41
	ds_read2_b32 v[32:33], v48 offset1:8
	ds_read2_b32 v[34:35], v48 offset0:66 offset1:74
	ds_read2_b32 v[36:37], v48 offset0:99 offset1:107
	ds_read2_b32 v[38:39], v48 offset0:132 offset1:140
	ds_read2_b32 v[40:41], v48 offset0:165 offset1:173
	ds_read2_b32 v[42:43], v48 offset0:198 offset1:206
	ds_read2_b32 v[44:45], v48 offset0:231 offset1:239
	s_waitcnt lgkmcnt(6)
	v_cvt_pk_bf16_f32 v26, v32, v30
	v_add_u32_e32 v30, s4, v47
	v_cmp_lt_i32_e32 vcc, s59, v30
	s_waitcnt lgkmcnt(4)
	v_cvt_pk_bf16_f32 v27, v34, v36
	s_lshl_b32 s6, s5, 7
	v_lshl_add_u64 v[76:77], v[12:13], 0, s[6:7]
	v_cndmask_b32_e32 v32, 0, v71, vcc
	v_add_lshl_u32 v32, v32, v30, 1
	v_and_b32_e32 v32, 0xffffff00, v32
	v_cndmask_b32_e32 v34, 0, v72, vcc
	v_and_b32_e32 v30, 0x7f, v30
	v_or3_b32 v78, v34, v30, v32
	v_ashrrev_i32_e32 v79, 31, v78
	v_lshlrev_b64 v[78:79], 11, v[78:79]
	v_add_u32_e32 v30, s4, v49
	v_lshl_add_u64 v[78:79], v[76:77], 0, v[78:79]
	v_cmp_lt_i32_e32 vcc, s59, v30
	s_waitcnt lgkmcnt(2)
	v_cvt_pk_bf16_f32 v28, v38, v40
	s_waitcnt lgkmcnt(0)
	v_cvt_pk_bf16_f32 v29, v42, v44
	global_store_dwordx4 v[78:79], v[26:29], off sc1
	v_cndmask_b32_e32 v32, 0, v72, vcc
	s_nop 0
	v_cvt_pk_bf16_f32 v26, v33, v31
	v_cndmask_b32_e32 v31, 0, v71, vcc
	v_add_lshl_u32 v31, v31, v30, 1
	v_and_b32_e32 v31, 0xffffff00, v31
	v_and_b32_e32 v30, 0x7f, v30
	v_or3_b32 v30, v32, v30, v31
	v_ashrrev_i32_e32 v31, 31, v30
	v_lshlrev_b64 v[30:31], 11, v[30:31]
	v_lshl_add_u64 v[30:31], v[76:77], 0, v[30:31]
	v_cvt_pk_bf16_f32 v27, v35, v37
	v_cvt_pk_bf16_f32 v28, v39, v41
	v_cvt_pk_bf16_f32 v29, v43, v45
	ds_read2_b32 v[32:33], v48 offset0:16 offset1:24
	ds_read2_b32 v[34:35], v48 offset0:49 offset1:57
	ds_read2_b32 v[36:37], v48 offset0:82 offset1:90
	ds_read2_b32 v[38:39], v48 offset0:115 offset1:123
	ds_read2_b32 v[40:41], v48 offset0:148 offset1:156
	ds_read2_b32 v[42:43], v48 offset0:181 offset1:189
	ds_read2_b32 v[44:45], v48 offset0:214 offset1:222
	ds_read2_b32 v[78:79], v48 offset0:247 offset1:255
	global_store_dwordx4 v[30:31], v[26:29], off sc1
	v_add_u32_e32 v30, s4, v50
	v_cmp_lt_i32_e32 vcc, s59, v30
	s_waitcnt lgkmcnt(6)
	v_cvt_pk_bf16_f32 v26, v32, v34
	s_waitcnt lgkmcnt(4)
	v_cvt_pk_bf16_f32 v27, v36, v38
	s_waitcnt lgkmcnt(2)
	v_cvt_pk_bf16_f32 v28, v40, v42
	s_waitcnt lgkmcnt(0)
	v_cvt_pk_bf16_f32 v29, v44, v78
	v_cndmask_b32_e32 v31, 0, v71, vcc
	v_add_lshl_u32 v31, v31, v30, 1
	v_and_b32_e32 v31, 0xffffff00, v31
	v_cndmask_b32_e32 v32, 0, v72, vcc
	v_and_b32_e32 v30, 0x7f, v30
	v_or3_b32 v30, v32, v30, v31
	v_ashrrev_i32_e32 v31, 31, v30
	v_lshlrev_b64 v[30:31], 11, v[30:31]
	v_lshl_add_u64 v[30:31], v[76:77], 0, v[30:31]
	global_store_dwordx4 v[30:31], v[26:29], off sc1
	v_add_u32_e32 v30, s4, v51
	v_cmp_lt_i32_e32 vcc, s59, v30
	v_cvt_pk_bf16_f32 v26, v33, v35
	v_cvt_pk_bf16_f32 v27, v37, v39
	v_cvt_pk_bf16_f32 v28, v41, v43
	v_cvt_pk_bf16_f32 v29, v45, v79
	s_nop 1
	v_cndmask_b32_e32 v31, 0, v71, vcc
	v_add_lshl_u32 v31, v31, v30, 1
	v_and_b32_e32 v31, 0xffffff00, v31
	v_cndmask_b32_e32 v32, 0, v72, vcc
	v_and_b32_e32 v30, 0x7f, v30
	v_or3_b32 v30, v32, v30, v31
	v_ashrrev_i32_e32 v31, 31, v30
	v_lshlrev_b64 v[30:31], 11, v[30:31]
	v_lshl_add_u64 v[30:31], v[76:77], 0, v[30:31]
	global_store_dwordx4 v[30:31], v[26:29], off sc1
	s_waitcnt lgkmcnt(0)

.LBB0_44:
	s_andn2_b64 vcc, exec, s[4:5]
	s_cbranch_vccnz .LBB0_46
	s_load_dwordx2 s[34:35], s[16:17], 0x68
	s_add_i32 s4, s11, 0x3b00
	s_and_b32 s5, s4, 0x1ffc0
	s_and_b32 s4, s1, 0x3e0
	s_lshl_b32 s6, s4, 2
	v_add_u32_e32 v26, s5, v5
	s_waitcnt lgkmcnt(0)
	s_add_u32 s34, s34, s6
	s_addc_u32 s35, s35, 0
	v_ashrrev_i32_e32 v27, 31, v26
	v_lshl_add_u64 v[28:29], s[34:35], 0, v[0:1]
	v_lshlrev_b64 v[26:27], 12, v[26:27]
	v_lshl_add_u64 v[26:27], v[28:29], 0, v[26:27]
	v_add_co_u32_e32 v28, vcc, s24, v26
	s_lshl_b32 s6, s5, 1
	s_nop 0
	v_addc_co_u32_e32 v29, vcc, 0, v27, vcc
	v_add_co_u32_e32 v30, vcc, s25, v26
	s_nop 1
	v_addc_co_u32_e32 v31, vcc, 0, v27, vcc
	v_add_co_u32_e32 v32, vcc, s26, v26
	s_nop 1
	v_addc_co_u32_e32 v33, vcc, 0, v27, vcc
	v_add_co_u32_e32 v34, vcc, s27, v26
	s_nop 1
	v_addc_co_u32_e32 v35, vcc, 0, v27, vcc
	v_add_co_u32_e32 v36, vcc, s28, v26
	s_nop 1
	v_addc_co_u32_e32 v37, vcc, 0, v27, vcc
	v_add_co_u32_e32 v38, vcc, s29, v26
	s_nop 1
	v_addc_co_u32_e32 v39, vcc, 0, v27, vcc
	v_add_co_u32_e32 v40, vcc, s30, v26
	s_nop 1
	v_addc_co_u32_e32 v41, vcc, 0, v27, vcc
	global_load_dword v44, v[26:27], off nt
	global_load_dword v45, v[28:29], off nt
	global_load_dword v76, v[30:31], off nt
	global_load_dword v77, v[32:33], off nt
	global_load_dword v78, v[34:35], off nt
	global_load_dword v79, v[36:37], off nt
	global_load_dword v80, v[38:39], off nt
	global_load_dword v81, v[40:41], off nt
	v_add_co_u32_e32 v28, vcc, s31, v26
	s_nop 1
	v_addc_co_u32_e32 v29, vcc, 0, v27, vcc
	v_add_co_u32_e32 v30, vcc, s33, v26
	s_nop 1
	v_addc_co_u32_e32 v31, vcc, 0, v27, vcc
	v_add_co_u32_e32 v32, vcc, s36, v26
	s_nop 1
	v_addc_co_u32_e32 v33, vcc, 0, v27, vcc
	v_add_co_u32_e32 v34, vcc, s37, v26
	s_nop 1
	v_addc_co_u32_e32 v35, vcc, 0, v27, vcc
	v_add_co_u32_e32 v36, vcc, s38, v26
	s_nop 1
	v_addc_co_u32_e32 v37, vcc, 0, v27, vcc
	v_add_co_u32_e32 v38, vcc, s39, v26
	s_nop 1
	v_addc_co_u32_e32 v39, vcc, 0, v27, vcc
	v_add_co_u32_e32 v40, vcc, s40, v26
	s_nop 1
	v_addc_co_u32_e32 v41, vcc, 0, v27, vcc
	v_add_co_u32_e32 v42, vcc, s41, v26
	s_nop 1
	v_addc_co_u32_e32 v43, vcc, 0, v27, vcc
	global_load_dword v82, v[28:29], off nt
	global_load_dword v83, v[30:31], off nt
	global_load_dword v84, v[32:33], off nt
	global_load_dword v85, v[34:35], off nt
	global_load_dword v86, v[36:37], off nt
	global_load_dword v87, v[38:39], off nt
	global_load_dword v88, v[40:41], off nt
	global_load_dword v89, v[42:43], off nt
	v_add_co_u32_e32 v28, vcc, s42, v26
	s_nop 1
	v_addc_co_u32_e32 v29, vcc, 0, v27, vcc
	v_add_co_u32_e32 v30, vcc, s43, v26
	s_nop 1
	v_addc_co_u32_e32 v31, vcc, 0, v27, vcc
	v_add_co_u32_e32 v32, vcc, s44, v26
	s_nop 1
	v_addc_co_u32_e32 v33, vcc, 0, v27, vcc
	v_add_co_u32_e32 v34, vcc, s45, v26
	s_nop 1
	v_addc_co_u32_e32 v35, vcc, 0, v27, vcc
	v_add_co_u32_e32 v36, vcc, s46, v26
	s_nop 1
	v_addc_co_u32_e32 v37, vcc, 0, v27, vcc
	v_add_co_u32_e32 v38, vcc, s47, v26
	s_nop 1
	v_addc_co_u32_e32 v39, vcc, 0, v27, vcc
	v_add_co_u32_e32 v40, vcc, s48, v26
	s_nop 1
	v_addc_co_u32_e32 v41, vcc, 0, v27, vcc
	v_add_co_u32_e32 v42, vcc, s49, v26
	s_nop 1
	v_addc_co_u32_e32 v43, vcc, 0, v27, vcc
	global_load_dword v90, v[28:29], off nt
	global_load_dword v91, v[30:31], off nt
	global_load_dword v92, v[32:33], off nt
	global_load_dword v93, v[34:35], off nt
	global_load_dword v94, v[36:37], off nt
	global_load_dword v95, v[38:39], off nt
	global_load_dword v96, v[40:41], off nt
	s_nop 0
	global_load_dword v42, v[42:43], off nt
	v_add_co_u32_e32 v28, vcc, s50, v26
	s_nop 1
	v_addc_co_u32_e32 v29, vcc, 0, v27, vcc
	v_add_co_u32_e32 v30, vcc, s51, v26
	s_nop 1
	v_addc_co_u32_e32 v31, vcc, 0, v27, vcc
	v_add_co_u32_e32 v32, vcc, s52, v26
	s_nop 1
	v_addc_co_u32_e32 v33, vcc, 0, v27, vcc
	v_add_co_u32_e32 v34, vcc, s53, v26
	s_nop 1
	v_addc_co_u32_e32 v35, vcc, 0, v27, vcc
	v_add_co_u32_e32 v36, vcc, s54, v26
	s_nop 1
	v_addc_co_u32_e32 v37, vcc, 0, v27, vcc
	v_add_co_u32_e32 v38, vcc, s55, v26
	s_nop 1
	v_addc_co_u32_e32 v39, vcc, 0, v27, vcc
	v_add_co_u32_e32 v40, vcc, s56, v26
	s_nop 1
	v_addc_co_u32_e32 v41, vcc, 0, v27, vcc
	v_add_co_u32_e32 v26, vcc, s57, v26
	s_nop 1
	v_addc_co_u32_e32 v27, vcc, 0, v27, vcc
	global_load_dword v28, v[28:29], off nt
	s_nop 0
	global_load_dword v29, v[30:31], off nt
	s_nop 0
	global_load_dword v30, v[32:33], off nt
	global_load_dword v31, v[34:35], off nt
	s_nop 0
	global_load_dword v32, v[36:37], off nt
	global_load_dword v33, v[38:39], off nt
	global_load_dword v34, v[40:41], off nt
	s_nop 0
	global_load_dword v26, v[26:27], off nt
	s_waitcnt vmcnt(30)
	ds_write2_b32 v46, v44, v45 offset1:66
	s_waitcnt vmcnt(28)
	ds_write2_b32 v46, v76, v77 offset0:132 offset1:198
	s_waitcnt vmcnt(26)
	ds_write2_b32 v64, v78, v79 offset0:8 offset1:74
	s_waitcnt vmcnt(24)
	ds_write2_b32 v64, v80, v81 offset0:140 offset1:206
	s_waitcnt vmcnt(22)
	ds_write2_b32 v65, v82, v83 offset0:16 offset1:82
	s_waitcnt vmcnt(20)
	ds_write2_b32 v65, v84, v85 offset0:148 offset1:214
	s_waitcnt vmcnt(18)
	ds_write2_b32 v66, v86, v87 offset0:24 offset1:90
	s_waitcnt vmcnt(16)
	ds_write2_b32 v66, v88, v89 offset0:156 offset1:222
	s_waitcnt vmcnt(14)
	ds_write2_b32 v67, v90, v91 offset0:32 offset1:98
	s_waitcnt vmcnt(12)
	ds_write2_b32 v67, v92, v93 offset0:164 offset1:230
	s_waitcnt vmcnt(10)
	ds_write2_b32 v68, v94, v95 offset0:40 offset1:106
	s_waitcnt vmcnt(8)
	ds_write2_b32 v68, v96, v42 offset0:172 offset1:238
	s_waitcnt vmcnt(6)
	ds_write2_b32 v69, v28, v29 offset0:48 offset1:114
	s_waitcnt vmcnt(4)
	ds_write2_b32 v69, v30, v31 offset0:180 offset1:246
	s_waitcnt vmcnt(2)
	ds_write2_b32 v70, v32, v33 offset0:56 offset1:122
	s_waitcnt vmcnt(0)
	ds_write2_b32 v70, v34, v26 offset0:188 offset1:254
	s_waitcnt lgkmcnt(0)
	ds_read2_b32 v[30:31], v48 offset0:33 offset1:41
	ds_read2_b32 v[32:33], v48 offset1:8
	ds_read2_b32 v[34:35], v48 offset0:66 offset1:74
	ds_read2_b32 v[36:37], v48 offset0:99 offset1:107
	ds_read2_b32 v[38:39], v48 offset0:132 offset1:140
	ds_read2_b32 v[40:41], v48 offset0:165 offset1:173
	ds_read2_b32 v[42:43], v48 offset0:198 offset1:206
	ds_read2_b32 v[44:45], v48 offset0:231 offset1:239
	v_add_u32_e32 v78, s4, v47
	v_ashrrev_i32_e32 v79, 31, v78
	v_lshl_add_u64 v[76:77], v[14:15], 0, s[6:7]
	v_lshlrev_b64 v[78:79], 11, v[78:79]
	s_waitcnt lgkmcnt(6)
	v_cvt_pk_bf16_f32 v26, v32, v30
	v_lshl_add_u64 v[78:79], v[76:77], 0, v[78:79]
	v_add_u32_e32 v30, s4, v49
	s_waitcnt lgkmcnt(4)
	v_cvt_pk_bf16_f32 v27, v34, v36
	s_waitcnt lgkmcnt(2)
	v_cvt_pk_bf16_f32 v28, v38, v40
	s_waitcnt lgkmcnt(0)
	v_cvt_pk_bf16_f32 v29, v42, v44
	global_store_dwordx4 v[78:79], v[26:29], off sc1
	s_nop 1
	v_cvt_pk_bf16_f32 v26, v33, v31
	v_ashrrev_i32_e32 v31, 31, v30
	v_lshlrev_b64 v[30:31], 11, v[30:31]
	v_cvt_pk_bf16_f32 v27, v35, v37
	v_cvt_pk_bf16_f32 v28, v39, v41
	v_cvt_pk_bf16_f32 v29, v43, v45
	v_lshl_add_u64 v[30:31], v[76:77], 0, v[30:31]
	ds_read2_b32 v[32:33], v48 offset0:16 offset1:24
	ds_read2_b32 v[34:35], v48 offset0:49 offset1:57
	ds_read2_b32 v[36:37], v48 offset0:82 offset1:90
	ds_read2_b32 v[38:39], v48 offset0:115 offset1:123
	ds_read2_b32 v[40:41], v48 offset0:148 offset1:156
	ds_read2_b32 v[42:43], v48 offset0:181 offset1:189
	ds_read2_b32 v[44:45], v48 offset0:214 offset1:222
	ds_read2_b32 v[78:79], v48 offset0:247 offset1:255
	global_store_dwordx4 v[30:31], v[26:29], off sc1
	v_add_u32_e32 v30, s4, v50
	v_ashrrev_i32_e32 v31, 31, v30
	v_lshlrev_b64 v[30:31], 11, v[30:31]
	v_lshl_add_u64 v[30:31], v[76:77], 0, v[30:31]
	s_waitcnt lgkmcnt(6)
	v_cvt_pk_bf16_f32 v26, v32, v34
	s_waitcnt lgkmcnt(4)
	v_cvt_pk_bf16_f32 v27, v36, v38
	s_waitcnt lgkmcnt(2)
	v_cvt_pk_bf16_f32 v28, v40, v42
	s_waitcnt lgkmcnt(0)
	v_cvt_pk_bf16_f32 v29, v44, v78
	global_store_dwordx4 v[30:31], v[26:29], off sc1
	v_add_u32_e32 v30, s4, v51
	v_ashrrev_i32_e32 v31, 31, v30
	v_lshlrev_b64 v[30:31], 11, v[30:31]
	v_lshl_add_u64 v[30:31], v[76:77], 0, v[30:31]
	v_cvt_pk_bf16_f32 v26, v33, v35
	v_cvt_pk_bf16_f32 v27, v37, v39
	v_cvt_pk_bf16_f32 v28, v41, v43
	v_cvt_pk_bf16_f32 v29, v45, v79
	global_store_dwordx4 v[30:31], v[26:29], off sc1
	s_waitcnt lgkmcnt(0)

.LBB0_47:
	s_andn2_b64 vcc, exec, s[4:5]
	s_cbranch_vccnz .LBB0_49
	s_add_i32 s4, s79, 0xfa80
	s_and_b32 s5, s4, 0xffff
	s_mul_i32 s5, s5, 0xaaab
	s_lshr_b32 s6, s5, 16
	s_lshr_b32 s5, s5, 22
	s_load_dwordx2 s[34:35], s[16:17], 0x38
	s_mulk_i32 s5, 0x60
	s_sub_i32 s4, s4, s5
	s_lshl_b32 s4, s4, 5
	s_and_b32 s4, s4, 0xffe0
	s_and_b32 s5, s6, 0xffc0
	s_lshl_b32 s6, s4, 2
	s_waitcnt lgkmcnt(0)
	s_add_u32 s34, s34, s6
	v_add_u32_e32 v44, s5, v5
	s_addc_u32 s35, s35, 0
	v_lshl_add_u64 v[26:27], s[34:35], 0, v[0:1]
	v_add_u32_e32 v30, 2, v44
	v_add_u32_e32 v32, 4, v44
	v_add_u32_e32 v34, 6, v44
	v_add_u32_e32 v36, 8, v44
	v_add_u32_e32 v38, 10, v44
	v_add_u32_e32 v40, 12, v44
	v_add_u32_e32 v42, 14, v44
	v_mad_i64_i32 v[28:29], s[34:35], v44, s61, v[26:27]
	v_mad_i64_i32 v[30:31], s[34:35], v30, s61, v[26:27]
	v_mad_i64_i32 v[32:33], s[34:35], v32, s61, v[26:27]
	v_mad_i64_i32 v[34:35], s[34:35], v34, s61, v[26:27]
	v_mad_i64_i32 v[36:37], s[34:35], v36, s61, v[26:27]
	v_mad_i64_i32 v[38:39], s[34:35], v38, s61, v[26:27]
	v_mad_i64_i32 v[40:41], s[34:35], v40, s61, v[26:27]
	v_mad_i64_i32 v[42:43], s[34:35], v42, s61, v[26:27]
	global_load_dword v45, v[28:29], off nt
	global_load_dword v76, v[30:31], off nt
	global_load_dword v77, v[32:33], off nt
	global_load_dword v78, v[34:35], off nt
	global_load_dword v79, v[36:37], off nt
	global_load_dword v80, v[38:39], off nt
	global_load_dword v81, v[40:41], off nt
	global_load_dword v82, v[42:43], off nt
	v_add_u32_e32 v28, 16, v44
	v_add_u32_e32 v30, 18, v44
	v_add_u32_e32 v32, 20, v44
	v_add_u32_e32 v34, 22, v44
	v_add_u32_e32 v36, 24, v44
	v_add_u32_e32 v38, 26, v44
	v_add_u32_e32 v40, 28, v44
	v_add_u32_e32 v42, 30, v44
	v_mad_i64_i32 v[28:29], s[34:35], v28, s61, v[26:27]
	v_mad_i64_i32 v[30:31], s[34:35], v30, s61, v[26:27]
	v_mad_i64_i32 v[32:33], s[34:35], v32, s61, v[26:27]
	v_mad_i64_i32 v[34:35], s[34:35], v34, s61, v[26:27]
	v_mad_i64_i32 v[36:37], s[34:35], v36, s61, v[26:27]
	v_mad_i64_i32 v[38:39], s[34:35], v38, s61, v[26:27]
	v_mad_i64_i32 v[40:41], s[34:35], v40, s61, v[26:27]
	v_mad_i64_i32 v[42:43], s[34:35], v42, s61, v[26:27]
	global_load_dword v83, v[28:29], off nt
	global_load_dword v84, v[30:31], off nt
	global_load_dword v85, v[32:33], off nt
	global_load_dword v86, v[34:35], off nt
	global_load_dword v87, v[36:37], off nt
	global_load_dword v88, v[38:39], off nt
	global_load_dword v89, v[40:41], off nt
	global_load_dword v90, v[42:43], off nt
	v_add_u32_e32 v28, 32, v44
	v_add_u32_e32 v30, 34, v44
	v_add_u32_e32 v32, 36, v44
	v_add_u32_e32 v34, 38, v44
	v_add_u32_e32 v36, 40, v44
	v_add_u32_e32 v38, 42, v44
	v_add_u32_e32 v40, 44, v44
	v_add_u32_e32 v42, 46, v44
	v_mad_i64_i32 v[28:29], s[34:35], v28, s61, v[26:27]
	v_mad_i64_i32 v[30:31], s[34:35], v30, s61, v[26:27]
	v_mad_i64_i32 v[32:33], s[34:35], v32, s61, v[26:27]
	v_mad_i64_i32 v[34:35], s[34:35], v34, s61, v[26:27]
	v_mad_i64_i32 v[36:37], s[34:35], v36, s61, v[26:27]
	v_mad_i64_i32 v[38:39], s[34:35], v38, s61, v[26:27]
	v_mad_i64_i32 v[40:41], s[34:35], v40, s61, v[26:27]
	v_mad_i64_i32 v[42:43], s[34:35], v42, s61, v[26:27]
	global_load_dword v91, v[28:29], off nt
	global_load_dword v92, v[30:31], off nt
	global_load_dword v93, v[32:33], off nt
	global_load_dword v94, v[34:35], off nt
	global_load_dword v95, v[36:37], off nt
	global_load_dword v96, v[38:39], off nt
	global_load_dword v97, v[40:41], off nt
	s_nop 0
	global_load_dword v42, v[42:43], off nt
	v_add_u32_e32 v28, 48, v44
	v_add_u32_e32 v30, 50, v44
	v_add_u32_e32 v32, 52, v44
	v_add_u32_e32 v34, 54, v44
	v_add_u32_e32 v36, 56, v44
	v_add_u32_e32 v38, 58, v44
	v_add_u32_e32 v40, 60, v44
	v_add_u32_e32 v43, 62, v44
	v_mad_i64_i32 v[28:29], s[34:35], v28, s61, v[26:27]
	v_mad_i64_i32 v[30:31], s[34:35], v30, s61, v[26:27]
	v_mad_i64_i32 v[32:33], s[34:35], v32, s61, v[26:27]
	v_mad_i64_i32 v[34:35], s[34:35], v34, s61, v[26:27]
	v_mad_i64_i32 v[36:37], s[34:35], v36, s61, v[26:27]
	v_mad_i64_i32 v[38:39], s[34:35], v38, s61, v[26:27]
	v_mad_i64_i32 v[40:41], s[34:35], v40, s61, v[26:27]
	v_mad_i64_i32 v[26:27], s[34:35], v43, s61, v[26:27]
	global_load_dword v28, v[28:29], off nt
	s_nop 0
	global_load_dword v29, v[30:31], off nt
	s_nop 0
	global_load_dword v30, v[32:33], off nt
	global_load_dword v31, v[34:35], off nt
	s_nop 0
	global_load_dword v32, v[36:37], off nt
	global_load_dword v33, v[38:39], off nt
	global_load_dword v34, v[40:41], off nt
	s_nop 0
	global_load_dword v26, v[26:27], off nt
	s_waitcnt vmcnt(30)
	ds_write2_b32 v46, v45, v76 offset1:66
	s_waitcnt vmcnt(28)
	ds_write2_b32 v46, v77, v78 offset0:132 offset1:198
	s_waitcnt vmcnt(26)
	ds_write2_b32 v64, v79, v80 offset0:8 offset1:74
	s_waitcnt vmcnt(24)
	ds_write2_b32 v64, v81, v82 offset0:140 offset1:206
	s_waitcnt vmcnt(22)
	ds_write2_b32 v65, v83, v84 offset0:16 offset1:82
	s_waitcnt vmcnt(20)
	ds_write2_b32 v65, v85, v86 offset0:148 offset1:214
	s_waitcnt vmcnt(18)
	ds_write2_b32 v66, v87, v88 offset0:24 offset1:90
	s_waitcnt vmcnt(16)
	ds_write2_b32 v66, v89, v90 offset0:156 offset1:222
	s_waitcnt vmcnt(14)
	ds_write2_b32 v67, v91, v92 offset0:32 offset1:98
	s_waitcnt vmcnt(12)
	ds_write2_b32 v67, v93, v94 offset0:164 offset1:230
	s_waitcnt vmcnt(10)
	ds_write2_b32 v68, v95, v96 offset0:40 offset1:106
	s_waitcnt vmcnt(8)
	ds_write2_b32 v68, v97, v42 offset0:172 offset1:238
	s_waitcnt vmcnt(6)
	ds_write2_b32 v69, v28, v29 offset0:48 offset1:114
	s_waitcnt vmcnt(4)
	ds_write2_b32 v69, v30, v31 offset0:180 offset1:246
	s_waitcnt vmcnt(2)
	ds_write2_b32 v70, v32, v33 offset0:56 offset1:122
	s_waitcnt vmcnt(0)
	ds_write2_b32 v70, v34, v26 offset0:188 offset1:254
	s_waitcnt lgkmcnt(0)
	ds_read2_b32 v[30:31], v48 offset0:33 offset1:41
	ds_read2_b32 v[32:33], v48 offset1:8
	ds_read2_b32 v[34:35], v48 offset0:66 offset1:74
	ds_read2_b32 v[36:37], v48 offset0:99 offset1:107
	ds_read2_b32 v[38:39], v48 offset0:132 offset1:140
	ds_read2_b32 v[40:41], v48 offset0:165 offset1:173
	ds_read2_b32 v[42:43], v48 offset0:198 offset1:206
	ds_read2_b32 v[44:45], v48 offset0:231 offset1:239
	v_add_u32_e32 v78, s4, v47
	s_lshl_b32 s6, s5, 1
	v_ashrrev_i32_e32 v79, 31, v78
	v_lshl_add_u64 v[76:77], v[16:17], 0, s[6:7]
	v_lshlrev_b64 v[78:79], 11, v[78:79]
	s_waitcnt lgkmcnt(6)
	v_cvt_pk_bf16_f32 v26, v32, v30
	v_lshl_add_u64 v[78:79], v[76:77], 0, v[78:79]
	v_add_u32_e32 v30, s4, v49
	s_waitcnt lgkmcnt(4)
	v_cvt_pk_bf16_f32 v27, v34, v36
	s_waitcnt lgkmcnt(2)
	v_cvt_pk_bf16_f32 v28, v38, v40
	s_waitcnt lgkmcnt(0)
	v_cvt_pk_bf16_f32 v29, v42, v44
	global_store_dwordx4 v[78:79], v[26:29], off sc1
	s_nop 1
	v_cvt_pk_bf16_f32 v26, v33, v31
	v_ashrrev_i32_e32 v31, 31, v30
	v_lshlrev_b64 v[30:31], 11, v[30:31]
	v_cvt_pk_bf16_f32 v27, v35, v37
	v_cvt_pk_bf16_f32 v28, v39, v41
	v_cvt_pk_bf16_f32 v29, v43, v45
	v_lshl_add_u64 v[30:31], v[76:77], 0, v[30:31]
	ds_read2_b32 v[32:33], v48 offset0:16 offset1:24
	ds_read2_b32 v[34:35], v48 offset0:49 offset1:57
	ds_read2_b32 v[36:37], v48 offset0:82 offset1:90
	ds_read2_b32 v[38:39], v48 offset0:115 offset1:123
	ds_read2_b32 v[40:41], v48 offset0:148 offset1:156
	ds_read2_b32 v[42:43], v48 offset0:181 offset1:189
	ds_read2_b32 v[44:45], v48 offset0:214 offset1:222
	ds_read2_b32 v[78:79], v48 offset0:247 offset1:255
	global_store_dwordx4 v[30:31], v[26:29], off sc1
	v_add_u32_e32 v30, s4, v50
	v_ashrrev_i32_e32 v31, 31, v30
	v_lshlrev_b64 v[30:31], 11, v[30:31]
	v_lshl_add_u64 v[30:31], v[76:77], 0, v[30:31]
	s_waitcnt lgkmcnt(6)
	v_cvt_pk_bf16_f32 v26, v32, v34
	s_waitcnt lgkmcnt(4)
	v_cvt_pk_bf16_f32 v27, v36, v38
	s_waitcnt lgkmcnt(2)
	v_cvt_pk_bf16_f32 v28, v40, v42
	s_waitcnt lgkmcnt(0)
	v_cvt_pk_bf16_f32 v29, v44, v78
	global_store_dwordx4 v[30:31], v[26:29], off sc1
	v_add_u32_e32 v30, s4, v51
	v_ashrrev_i32_e32 v31, 31, v30
	v_lshlrev_b64 v[30:31], 11, v[30:31]
	v_lshl_add_u64 v[30:31], v[76:77], 0, v[30:31]
	v_cvt_pk_bf16_f32 v26, v33, v35
	v_cvt_pk_bf16_f32 v27, v37, v39
	v_cvt_pk_bf16_f32 v28, v41, v43
	v_cvt_pk_bf16_f32 v29, v45, v79
	global_store_dwordx4 v[30:31], v[26:29], off sc1
	s_waitcnt lgkmcnt(0)

.LBB0_50:
	s_andn2_b64 vcc, exec, s[4:5]
	s_cbranch_vccnz .LBB0_52
	s_load_dwordx2 s[34:35], s[16:17], 0x30
	s_add_i32 s4, s11, 0x4b00
	s_and_b32 s5, s4, 0x1ffc0
	s_and_b32 s4, s1, 0x3e0
	s_lshl_b32 s6, s4, 2
	v_add_u32_e32 v26, s5, v5
	s_waitcnt lgkmcnt(0)
	s_add_u32 s34, s34, s6
	s_addc_u32 s35, s35, 0
	v_ashrrev_i32_e32 v27, 31, v26
	v_lshl_add_u64 v[28:29], s[34:35], 0, v[0:1]
	v_lshlrev_b64 v[26:27], 12, v[26:27]
	v_lshl_add_u64 v[26:27], v[28:29], 0, v[26:27]
	v_add_co_u32_e32 v28, vcc, s24, v26
	s_lshl_b32 s6, s5, 1
	s_nop 0
	v_addc_co_u32_e32 v29, vcc, 0, v27, vcc
	v_add_co_u32_e32 v30, vcc, s25, v26
	s_nop 1
	v_addc_co_u32_e32 v31, vcc, 0, v27, vcc
	v_add_co_u32_e32 v32, vcc, s26, v26
	s_nop 1
	v_addc_co_u32_e32 v33, vcc, 0, v27, vcc
	v_add_co_u32_e32 v34, vcc, s27, v26
	s_nop 1
	v_addc_co_u32_e32 v35, vcc, 0, v27, vcc
	v_add_co_u32_e32 v36, vcc, s28, v26
	s_nop 1
	v_addc_co_u32_e32 v37, vcc, 0, v27, vcc
	v_add_co_u32_e32 v38, vcc, s29, v26
	s_nop 1
	v_addc_co_u32_e32 v39, vcc, 0, v27, vcc
	v_add_co_u32_e32 v40, vcc, s30, v26
	s_nop 1
	v_addc_co_u32_e32 v41, vcc, 0, v27, vcc
	global_load_dword v44, v[26:27], off nt
	global_load_dword v45, v[28:29], off nt
	global_load_dword v76, v[30:31], off nt
	global_load_dword v77, v[32:33], off nt
	global_load_dword v78, v[34:35], off nt
	global_load_dword v79, v[36:37], off nt
	global_load_dword v80, v[38:39], off nt
	global_load_dword v81, v[40:41], off nt
	v_add_co_u32_e32 v28, vcc, s31, v26
	s_nop 1
	v_addc_co_u32_e32 v29, vcc, 0, v27, vcc
	v_add_co_u32_e32 v30, vcc, s33, v26
	s_nop 1
	v_addc_co_u32_e32 v31, vcc, 0, v27, vcc
	v_add_co_u32_e32 v32, vcc, s36, v26
	s_nop 1
	v_addc_co_u32_e32 v33, vcc, 0, v27, vcc
	v_add_co_u32_e32 v34, vcc, s37, v26
	s_nop 1
	v_addc_co_u32_e32 v35, vcc, 0, v27, vcc
	v_add_co_u32_e32 v36, vcc, s38, v26
	s_nop 1
	v_addc_co_u32_e32 v37, vcc, 0, v27, vcc
	v_add_co_u32_e32 v38, vcc, s39, v26
	s_nop 1
	v_addc_co_u32_e32 v39, vcc, 0, v27, vcc
	v_add_co_u32_e32 v40, vcc, s40, v26
	s_nop 1
	v_addc_co_u32_e32 v41, vcc, 0, v27, vcc
	v_add_co_u32_e32 v42, vcc, s41, v26
	s_nop 1
	v_addc_co_u32_e32 v43, vcc, 0, v27, vcc
	global_load_dword v82, v[28:29], off nt
	global_load_dword v83, v[30:31], off nt
	global_load_dword v84, v[32:33], off nt
	global_load_dword v85, v[34:35], off nt
	global_load_dword v86, v[36:37], off nt
	global_load_dword v87, v[38:39], off nt
	global_load_dword v88, v[40:41], off nt
	global_load_dword v89, v[42:43], off nt
	v_add_co_u32_e32 v28, vcc, s42, v26
	s_nop 1
	v_addc_co_u32_e32 v29, vcc, 0, v27, vcc
	v_add_co_u32_e32 v30, vcc, s43, v26
	s_nop 1
	v_addc_co_u32_e32 v31, vcc, 0, v27, vcc
	v_add_co_u32_e32 v32, vcc, s44, v26
	s_nop 1
	v_addc_co_u32_e32 v33, vcc, 0, v27, vcc
	v_add_co_u32_e32 v34, vcc, s45, v26
	s_nop 1
	v_addc_co_u32_e32 v35, vcc, 0, v27, vcc
	v_add_co_u32_e32 v36, vcc, s46, v26
	s_nop 1
	v_addc_co_u32_e32 v37, vcc, 0, v27, vcc
	v_add_co_u32_e32 v38, vcc, s47, v26
	s_nop 1
	v_addc_co_u32_e32 v39, vcc, 0, v27, vcc
	v_add_co_u32_e32 v40, vcc, s48, v26
	s_nop 1
	v_addc_co_u32_e32 v41, vcc, 0, v27, vcc
	v_add_co_u32_e32 v42, vcc, s49, v26
	s_nop 1
	v_addc_co_u32_e32 v43, vcc, 0, v27, vcc
	global_load_dword v90, v[28:29], off nt
	global_load_dword v91, v[30:31], off nt
	global_load_dword v92, v[32:33], off nt
	global_load_dword v93, v[34:35], off nt
	global_load_dword v94, v[36:37], off nt
	global_load_dword v95, v[38:39], off nt
	global_load_dword v96, v[40:41], off nt
	s_nop 0
	global_load_dword v42, v[42:43], off nt
	v_add_co_u32_e32 v28, vcc, s50, v26
	s_nop 1
	v_addc_co_u32_e32 v29, vcc, 0, v27, vcc
	v_add_co_u32_e32 v30, vcc, s51, v26
	s_nop 1
	v_addc_co_u32_e32 v31, vcc, 0, v27, vcc
	v_add_co_u32_e32 v32, vcc, s52, v26
	s_nop 1
	v_addc_co_u32_e32 v33, vcc, 0, v27, vcc
	v_add_co_u32_e32 v34, vcc, s53, v26
	s_nop 1
	v_addc_co_u32_e32 v35, vcc, 0, v27, vcc
	v_add_co_u32_e32 v36, vcc, s54, v26
	s_nop 1
	v_addc_co_u32_e32 v37, vcc, 0, v27, vcc
	v_add_co_u32_e32 v38, vcc, s55, v26
	s_nop 1
	v_addc_co_u32_e32 v39, vcc, 0, v27, vcc
	v_add_co_u32_e32 v40, vcc, s56, v26
	s_nop 1
	v_addc_co_u32_e32 v41, vcc, 0, v27, vcc
	v_add_co_u32_e32 v26, vcc, s57, v26
	s_nop 1
	v_addc_co_u32_e32 v27, vcc, 0, v27, vcc
	global_load_dword v28, v[28:29], off nt
	s_nop 0
	global_load_dword v29, v[30:31], off nt
	s_nop 0
	global_load_dword v30, v[32:33], off nt
	global_load_dword v31, v[34:35], off nt
	s_nop 0
	global_load_dword v32, v[36:37], off nt
	global_load_dword v33, v[38:39], off nt
	global_load_dword v34, v[40:41], off nt
	s_nop 0
	global_load_dword v26, v[26:27], off nt
	s_waitcnt vmcnt(30)
	ds_write2_b32 v46, v44, v45 offset1:66
	s_waitcnt vmcnt(28)
	ds_write2_b32 v46, v76, v77 offset0:132 offset1:198
	s_waitcnt vmcnt(26)
	ds_write2_b32 v64, v78, v79 offset0:8 offset1:74
	s_waitcnt vmcnt(24)
	ds_write2_b32 v64, v80, v81 offset0:140 offset1:206
	s_waitcnt vmcnt(22)
	ds_write2_b32 v65, v82, v83 offset0:16 offset1:82
	s_waitcnt vmcnt(20)
	ds_write2_b32 v65, v84, v85 offset0:148 offset1:214
	s_waitcnt vmcnt(18)
	ds_write2_b32 v66, v86, v87 offset0:24 offset1:90
	s_waitcnt vmcnt(16)
	ds_write2_b32 v66, v88, v89 offset0:156 offset1:222
	s_waitcnt vmcnt(14)
	ds_write2_b32 v67, v90, v91 offset0:32 offset1:98
	s_waitcnt vmcnt(12)
	ds_write2_b32 v67, v92, v93 offset0:164 offset1:230
	s_waitcnt vmcnt(10)
	ds_write2_b32 v68, v94, v95 offset0:40 offset1:106
	s_waitcnt vmcnt(8)
	ds_write2_b32 v68, v96, v42 offset0:172 offset1:238
	s_waitcnt vmcnt(6)
	ds_write2_b32 v69, v28, v29 offset0:48 offset1:114
	s_waitcnt vmcnt(4)
	ds_write2_b32 v69, v30, v31 offset0:180 offset1:246
	s_waitcnt vmcnt(2)
	ds_write2_b32 v70, v32, v33 offset0:56 offset1:122
	s_waitcnt vmcnt(0)
	ds_write2_b32 v70, v34, v26 offset0:188 offset1:254
	s_waitcnt lgkmcnt(0)
	ds_read2_b32 v[30:31], v48 offset0:33 offset1:41
	ds_read2_b32 v[32:33], v48 offset1:8
	ds_read2_b32 v[34:35], v48 offset0:66 offset1:74
	ds_read2_b32 v[36:37], v48 offset0:99 offset1:107
	ds_read2_b32 v[38:39], v48 offset0:132 offset1:140
	ds_read2_b32 v[40:41], v48 offset0:165 offset1:173
	ds_read2_b32 v[42:43], v48 offset0:198 offset1:206
	ds_read2_b32 v[44:45], v48 offset0:231 offset1:239
	v_add_u32_e32 v78, s4, v47
	v_ashrrev_i32_e32 v79, 31, v78
	v_lshl_add_u64 v[76:77], v[18:19], 0, s[6:7]
	v_lshlrev_b64 v[78:79], 11, v[78:79]
	s_waitcnt lgkmcnt(6)
	v_cvt_pk_bf16_f32 v26, v32, v30
	v_lshl_add_u64 v[78:79], v[76:77], 0, v[78:79]
	v_add_u32_e32 v30, s4, v49
	s_waitcnt lgkmcnt(4)
	v_cvt_pk_bf16_f32 v27, v34, v36
	s_waitcnt lgkmcnt(2)
	v_cvt_pk_bf16_f32 v28, v38, v40
	s_waitcnt lgkmcnt(0)
	v_cvt_pk_bf16_f32 v29, v42, v44
	global_store_dwordx4 v[78:79], v[26:29], off sc1
	s_nop 1
	v_cvt_pk_bf16_f32 v26, v33, v31
	v_ashrrev_i32_e32 v31, 31, v30
	v_lshlrev_b64 v[30:31], 11, v[30:31]
	v_cvt_pk_bf16_f32 v27, v35, v37
	v_cvt_pk_bf16_f32 v28, v39, v41
	v_cvt_pk_bf16_f32 v29, v43, v45
	v_lshl_add_u64 v[30:31], v[76:77], 0, v[30:31]
	ds_read2_b32 v[32:33], v48 offset0:16 offset1:24
	ds_read2_b32 v[34:35], v48 offset0:49 offset1:57
	ds_read2_b32 v[36:37], v48 offset0:82 offset1:90
	ds_read2_b32 v[38:39], v48 offset0:115 offset1:123
	ds_read2_b32 v[40:41], v48 offset0:148 offset1:156
	ds_read2_b32 v[42:43], v48 offset0:181 offset1:189
	ds_read2_b32 v[44:45], v48 offset0:214 offset1:222
	ds_read2_b32 v[78:79], v48 offset0:247 offset1:255
	global_store_dwordx4 v[30:31], v[26:29], off sc1
	v_add_u32_e32 v30, s4, v50
	v_ashrrev_i32_e32 v31, 31, v30
	v_lshlrev_b64 v[30:31], 11, v[30:31]
	v_lshl_add_u64 v[30:31], v[76:77], 0, v[30:31]
	s_waitcnt lgkmcnt(6)
	v_cvt_pk_bf16_f32 v26, v32, v34
	s_waitcnt lgkmcnt(4)
	v_cvt_pk_bf16_f32 v27, v36, v38
	s_waitcnt lgkmcnt(2)
	v_cvt_pk_bf16_f32 v28, v40, v42
	s_waitcnt lgkmcnt(0)
	v_cvt_pk_bf16_f32 v29, v44, v78
	global_store_dwordx4 v[30:31], v[26:29], off sc1
	v_add_u32_e32 v30, s4, v51
	v_ashrrev_i32_e32 v31, 31, v30
	v_lshlrev_b64 v[30:31], 11, v[30:31]
	v_lshl_add_u64 v[30:31], v[76:77], 0, v[30:31]
	v_cvt_pk_bf16_f32 v26, v33, v35
	v_cvt_pk_bf16_f32 v27, v37, v39
	v_cvt_pk_bf16_f32 v28, v41, v43
	v_cvt_pk_bf16_f32 v29, v45, v79
	global_store_dwordx4 v[30:31], v[26:29], off sc1
	s_waitcnt lgkmcnt(0)

.LBB0_78:
	s_waitcnt vmcnt(4)
	ds_write2_b32 v30, v28, v29 offset0:148 offset1:214
	s_waitcnt lgkmcnt(0)
	ds_read2_b32 v[30:31], v48 offset0:33 offset1:41
	ds_read2_b32 v[32:33], v48 offset1:8
	ds_read2_b32 v[34:35], v48 offset0:66 offset1:74
	ds_read2_b32 v[36:37], v48 offset0:99 offset1:107
	ds_read2_b32 v[38:39], v48 offset0:132 offset1:140
	ds_read2_b32 v[40:41], v48 offset0:165 offset1:173
	ds_read2_b32 v[42:43], v48 offset0:198 offset1:206
	ds_read2_b32 v[44:45], v48 offset0:231 offset1:239
	v_add_u32_e32 v78, s80, v47
	s_lshl_b32 s6, s6, 1
	v_ashrrev_i32_e32 v79, 31, v78
	s_waitcnt vmcnt(2)
	v_lshl_add_u64 v[76:77], v[20:21], 0, s[6:7]
	v_lshlrev_b64 v[78:79], 9, v[78:79]
	s_waitcnt vmcnt(1) lgkmcnt(6)
	v_cvt_pk_bf16_f32 v26, v32, v30
	v_lshl_add_u64 v[78:79], v[76:77], 0, v[78:79]
	v_add_u32_e32 v30, s80, v49
	s_waitcnt vmcnt(0) lgkmcnt(4)
	v_cvt_pk_bf16_f32 v27, v34, v36
	s_waitcnt lgkmcnt(2)
	v_cvt_pk_bf16_f32 v28, v38, v40
	s_waitcnt lgkmcnt(0)
	v_cvt_pk_bf16_f32 v29, v42, v44
	global_store_dwordx4 v[78:79], v[26:29], off sc1
	s_nop 1
	v_cvt_pk_bf16_f32 v26, v33, v31
	v_ashrrev_i32_e32 v31, 31, v30
	v_lshlrev_b64 v[30:31], 9, v[30:31]
	v_cvt_pk_bf16_f32 v27, v35, v37
	v_cvt_pk_bf16_f32 v28, v39, v41
	v_cvt_pk_bf16_f32 v29, v43, v45
	v_lshl_add_u64 v[30:31], v[76:77], 0, v[30:31]
	ds_read2_b32 v[32:33], v48 offset0:16 offset1:24
	ds_read2_b32 v[34:35], v48 offset0:49 offset1:57
	ds_read2_b32 v[36:37], v48 offset0:82 offset1:90
	ds_read2_b32 v[38:39], v48 offset0:115 offset1:123
	ds_read2_b32 v[40:41], v48 offset0:148 offset1:156
	ds_read2_b32 v[42:43], v48 offset0:181 offset1:189
	ds_read2_b32 v[44:45], v48 offset0:214 offset1:222
	ds_read2_b32 v[78:79], v48 offset0:247 offset1:255
	global_store_dwordx4 v[30:31], v[26:29], off sc1
	v_add_u32_e32 v30, s80, v50
	v_ashrrev_i32_e32 v31, 31, v30
	v_lshlrev_b64 v[30:31], 9, v[30:31]
	v_lshl_add_u64 v[30:31], v[76:77], 0, v[30:31]
	s_waitcnt lgkmcnt(6)
	v_cvt_pk_bf16_f32 v26, v32, v34
	s_waitcnt lgkmcnt(4)
	v_cvt_pk_bf16_f32 v27, v36, v38
	s_waitcnt lgkmcnt(2)
	v_cvt_pk_bf16_f32 v28, v40, v42
	s_waitcnt lgkmcnt(0)
	v_cvt_pk_bf16_f32 v29, v44, v78
	global_store_dwordx4 v[30:31], v[26:29], off sc1
	v_add_u32_e32 v30, s80, v51
	v_ashrrev_i32_e32 v31, 31, v30
	v_lshlrev_b64 v[30:31], 9, v[30:31]
	v_lshl_add_u64 v[30:31], v[76:77], 0, v[30:31]
	v_cvt_pk_bf16_f32 v26, v33, v35
	v_cvt_pk_bf16_f32 v27, v37, v39
	v_cvt_pk_bf16_f32 v28, v41, v43
	v_cvt_pk_bf16_f32 v29, v45, v79
	global_store_dwordx4 v[30:31], v[26:29], off sc1
	s_waitcnt lgkmcnt(0)

.LBB0_105:
	s_waitcnt vmcnt(4)
	ds_write2_b32 v30, v28, v29 offset0:148 offset1:214
	s_waitcnt lgkmcnt(0)
	s_lshl_b32 s4, s80, 5
	s_and_b32 s34, 0xffff, s4
	ds_read2_b32 v[30:31], v48 offset0:33 offset1:41
	ds_read2_b32 v[32:33], v48 offset1:8
	ds_read2_b32 v[34:35], v48 offset0:66 offset1:74
	ds_read2_b32 v[36:37], v48 offset0:99 offset1:107
	ds_read2_b32 v[38:39], v48 offset0:132 offset1:140
	ds_read2_b32 v[40:41], v48 offset0:165 offset1:173
	ds_read2_b32 v[42:43], v48 offset0:198 offset1:206
	ds_read2_b32 v[44:45], v48 offset0:231 offset1:239
	s_waitcnt vmcnt(1) lgkmcnt(6)
	v_cvt_pk_bf16_f32 v26, v32, v30
	v_add_u32_e32 v30, s34, v47
	v_mul_hi_i32 v32, v30, s76
	s_waitcnt vmcnt(0) lgkmcnt(4)
	v_cvt_pk_bf16_f32 v27, v34, v36
	v_lshrrev_b32_e32 v34, 31, v32
	v_lshrrev_b32_e32 v32, 5, v32
	v_add_u32_e32 v32, v32, v34
	v_mul_lo_u32 v32, v32, s62
	v_sub_u32_e32 v30, v30, v32
	v_add_u32_e32 v34, 0xffffff80, v30
	v_lshlrev_b32_e32 v36, 1, v34
	s_waitcnt lgkmcnt(2)
	v_cvt_pk_bf16_f32 v28, v38, v40
	v_subrev_u32_e32 v38, 63, v36
	v_cmp_gt_u32_e32 vcc, 32, v34
	s_lshl_b32 s6, s6, 1
	v_lshl_add_u64 v[76:77], v[22:23], 0, s[6:7]
	v_cndmask_b32_e32 v34, v38, v36, vcc
	v_add_u32_e32 v34, 0x80, v34
	v_cmp_lt_i32_e32 vcc, s60, v30
	s_waitcnt lgkmcnt(0)
	v_cvt_pk_bf16_f32 v29, v42, v44
	s_nop 0
	v_cndmask_b32_e32 v30, v30, v34, vcc
	v_add_u32_e32 v30, v32, v30
	v_mad_i64_i32 v[78:79], s[4:5], v30, s77, v[76:77]
	v_add_u32_e32 v30, s34, v49
	global_store_dwordx4 v[78:79], v[26:29], off sc1
	s_nop 1
	v_cvt_pk_bf16_f32 v26, v33, v31
	v_mul_hi_i32 v31, v30, s76
	v_lshrrev_b32_e32 v32, 31, v31
	v_lshrrev_b32_e32 v31, 5, v31
	v_add_u32_e32 v31, v31, v32
	v_mul_lo_u32 v31, v31, s62
	v_sub_u32_e32 v30, v30, v31
	v_add_u32_e32 v32, 0xffffff80, v30
	v_lshlrev_b32_e32 v33, 1, v32
	v_subrev_u32_e32 v34, 63, v33
	v_cmp_gt_u32_e32 vcc, 32, v32
	v_cvt_pk_bf16_f32 v27, v35, v37
	v_cvt_pk_bf16_f32 v28, v39, v41
	v_cvt_pk_bf16_f32 v29, v43, v45
	s_nop 1
	v_cndmask_b32_e32 v32, v34, v33, vcc
	v_add_u32_e32 v32, 0x80, v32
	v_cmp_lt_i32_e32 vcc, s60, v30
	s_nop 1
	v_cndmask_b32_e32 v30, v30, v32, vcc
	v_add_u32_e32 v30, v31, v30
	v_mad_i64_i32 v[30:31], s[4:5], v30, s77, v[76:77]
	ds_read2_b32 v[32:33], v48 offset0:16 offset1:24
	ds_read2_b32 v[34:35], v48 offset0:49 offset1:57
	ds_read2_b32 v[36:37], v48 offset0:82 offset1:90
	ds_read2_b32 v[38:39], v48 offset0:115 offset1:123
	ds_read2_b32 v[40:41], v48 offset0:148 offset1:156
	ds_read2_b32 v[42:43], v48 offset0:181 offset1:189
	ds_read2_b32 v[44:45], v48 offset0:214 offset1:222
	ds_read2_b32 v[78:79], v48 offset0:247 offset1:255
	global_store_dwordx4 v[30:31], v[26:29], off sc1
	v_add_u32_e32 v30, s34, v50
	v_mul_hi_i32 v31, v30, s76
	s_waitcnt lgkmcnt(6)
	v_cvt_pk_bf16_f32 v26, v32, v34
	v_lshrrev_b32_e32 v32, 31, v31
	v_lshrrev_b32_e32 v31, 5, v31
	v_add_u32_e32 v31, v31, v32
	v_mul_lo_u32 v31, v31, s62
	v_sub_u32_e32 v30, v30, v31
	v_add_u32_e32 v32, 0xffffff80, v30
	v_lshlrev_b32_e32 v34, 1, v32
	s_waitcnt lgkmcnt(4)
	v_cvt_pk_bf16_f32 v27, v36, v38
	v_subrev_u32_e32 v36, 63, v34
	v_cmp_gt_u32_e32 vcc, 32, v32
	s_waitcnt lgkmcnt(2)
	v_cvt_pk_bf16_f32 v28, v40, v42
	s_waitcnt lgkmcnt(0)
	v_cvt_pk_bf16_f32 v29, v44, v78
	v_cndmask_b32_e32 v32, v36, v34, vcc
	v_add_u32_e32 v32, 0x80, v32
	v_cmp_lt_i32_e32 vcc, s60, v30
	s_nop 1
	v_cndmask_b32_e32 v30, v30, v32, vcc
	v_add_u32_e32 v30, v31, v30
	v_mad_i64_i32 v[30:31], s[4:5], v30, s77, v[76:77]
	global_store_dwordx4 v[30:31], v[26:29], off sc1
	v_add_u32_e32 v30, s34, v51
	v_mul_hi_i32 v31, v30, s76
	v_lshrrev_b32_e32 v32, 31, v31
	v_lshrrev_b32_e32 v31, 5, v31
	v_add_u32_e32 v31, v31, v32
	v_mul_lo_u32 v31, v31, s62
	v_sub_u32_e32 v30, v30, v31
	v_add_u32_e32 v32, 0xffffff80, v30
	v_cvt_pk_bf16_f32 v26, v33, v35
	v_lshlrev_b32_e32 v33, 1, v32
	v_subrev_u32_e32 v34, 63, v33
	v_cmp_gt_u32_e32 vcc, 32, v32
	v_cvt_pk_bf16_f32 v27, v37, v39
	v_cvt_pk_bf16_f32 v28, v41, v43
	v_cvt_pk_bf16_f32 v29, v45, v79
	s_nop 1
	v_cndmask_b32_e32 v32, v34, v33, vcc
	v_add_u32_e32 v32, 0x80, v32
	v_cmp_lt_i32_e32 vcc, s60, v30
	s_nop 1
	v_cndmask_b32_e32 v30, v30, v32, vcc
	v_add_u32_e32 v30, v31, v30
	v_mad_i64_i32 v[30:31], s[4:5], v30, s77, v[76:77]
	global_store_dwordx4 v[30:31], v[26:29], off sc1
	s_waitcnt lgkmcnt(0)

.LBB0_107:
	s_andn2_b64 vcc, exec, s[4:5]
	s_cbranch_vccnz .LBB0_24
	s_mul_hi_i32 s4, s79, 0x2e8ba2e9
	s_lshr_b32 s5, s4, 31
	s_ashr_i32 s6, s4, 2
	s_load_dwordx2 s[80:81], s[16:17], 0x8
	s_add_i32 s6, s6, s5
	s_mul_i32 s4, s6, 0xfffffd40
	s_add_i32 s4, s1, s4
	s_ashr_i32 s5, s4, 31
	s_lshl_b32 s34, s6, 6
	s_lshl_b64 s[82:83], s[4:5], 2
	s_waitcnt lgkmcnt(0)
	s_add_u32 s80, s80, s82
	v_add_u32_e32 v44, s34, v5
	s_addc_u32 s81, s81, s83
	v_lshl_add_u64 v[26:27], s[80:81], 0, v[0:1]
	v_add_u32_e32 v30, 2, v44
	v_add_u32_e32 v32, 4, v44
	v_add_u32_e32 v34, 6, v44
	v_add_u32_e32 v36, 8, v44
	v_add_u32_e32 v38, 10, v44
	v_add_u32_e32 v40, 12, v44
	v_add_u32_e32 v42, 14, v44
	v_mad_i64_i32 v[28:29], s[80:81], v44, s23, v[26:27]
	v_mad_i64_i32 v[30:31], s[80:81], v30, s23, v[26:27]
	v_mad_i64_i32 v[32:33], s[80:81], v32, s23, v[26:27]
	v_mad_i64_i32 v[34:35], s[80:81], v34, s23, v[26:27]
	v_mad_i64_i32 v[36:37], s[80:81], v36, s23, v[26:27]
	v_mad_i64_i32 v[38:39], s[80:81], v38, s23, v[26:27]
	v_mad_i64_i32 v[40:41], s[80:81], v40, s23, v[26:27]
	v_mad_i64_i32 v[42:43], s[80:81], v42, s23, v[26:27]
	global_load_dword v45, v[28:29], off nt
	global_load_dword v76, v[30:31], off nt
	global_load_dword v77, v[32:33], off nt
	global_load_dword v78, v[34:35], off nt
	global_load_dword v79, v[36:37], off nt
	global_load_dword v80, v[38:39], off nt
	global_load_dword v81, v[40:41], off nt
	global_load_dword v82, v[42:43], off nt
	v_add_u32_e32 v28, 16, v44
	v_add_u32_e32 v30, 18, v44
	v_add_u32_e32 v32, 20, v44
	v_add_u32_e32 v34, 22, v44
	v_add_u32_e32 v36, 24, v44
	v_add_u32_e32 v38, 26, v44
	v_add_u32_e32 v40, 28, v44
	v_add_u32_e32 v42, 30, v44
	v_mad_i64_i32 v[28:29], s[80:81], v28, s23, v[26:27]
	v_mad_i64_i32 v[30:31], s[80:81], v30, s23, v[26:27]
	v_mad_i64_i32 v[32:33], s[80:81], v32, s23, v[26:27]
	v_mad_i64_i32 v[34:35], s[80:81], v34, s23, v[26:27]
	v_mad_i64_i32 v[36:37], s[80:81], v36, s23, v[26:27]
	v_mad_i64_i32 v[38:39], s[80:81], v38, s23, v[26:27]
	v_mad_i64_i32 v[40:41], s[80:81], v40, s23, v[26:27]
	v_mad_i64_i32 v[42:43], s[80:81], v42, s23, v[26:27]
	global_load_dword v83, v[28:29], off nt
	global_load_dword v84, v[30:31], off nt
	global_load_dword v85, v[32:33], off nt
	global_load_dword v86, v[34:35], off nt
	global_load_dword v87, v[36:37], off nt
	global_load_dword v88, v[38:39], off nt
	global_load_dword v89, v[40:41], off nt
	global_load_dword v90, v[42:43], off nt
	v_add_u32_e32 v28, 32, v44
	v_add_u32_e32 v30, 34, v44
	v_add_u32_e32 v32, 36, v44
	v_add_u32_e32 v34, 38, v44
	v_add_u32_e32 v36, 40, v44
	v_add_u32_e32 v38, 42, v44
	v_add_u32_e32 v40, 44, v44
	v_add_u32_e32 v42, 46, v44
	v_mad_i64_i32 v[28:29], s[80:81], v28, s23, v[26:27]
	v_mad_i64_i32 v[30:31], s[80:81], v30, s23, v[26:27]
	v_mad_i64_i32 v[32:33], s[80:81], v32, s23, v[26:27]
	v_mad_i64_i32 v[34:35], s[80:81], v34, s23, v[26:27]
	v_mad_i64_i32 v[36:37], s[80:81], v36, s23, v[26:27]
	v_mad_i64_i32 v[38:39], s[80:81], v38, s23, v[26:27]
	v_mad_i64_i32 v[40:41], s[80:81], v40, s23, v[26:27]
	v_mad_i64_i32 v[42:43], s[80:81], v42, s23, v[26:27]
	global_load_dword v91, v[28:29], off nt
	global_load_dword v92, v[30:31], off nt
	global_load_dword v93, v[32:33], off nt
	global_load_dword v94, v[34:35], off nt
	global_load_dword v95, v[36:37], off nt
	global_load_dword v96, v[38:39], off nt
	global_load_dword v97, v[40:41], off nt
	s_nop 0
	global_load_dword v42, v[42:43], off nt
	v_add_u32_e32 v28, 48, v44
	v_add_u32_e32 v30, 50, v44
	v_add_u32_e32 v32, 52, v44
	v_add_u32_e32 v34, 54, v44
	v_add_u32_e32 v36, 56, v44
	v_add_u32_e32 v38, 58, v44
	v_add_u32_e32 v40, 60, v44
	v_add_u32_e32 v43, 62, v44
	v_mad_i64_i32 v[28:29], s[80:81], v28, s23, v[26:27]
	v_mad_i64_i32 v[30:31], s[80:81], v30, s23, v[26:27]
	v_mad_i64_i32 v[32:33], s[80:81], v32, s23, v[26:27]
	v_mad_i64_i32 v[34:35], s[80:81], v34, s23, v[26:27]
	v_mad_i64_i32 v[36:37], s[80:81], v36, s23, v[26:27]
	v_mad_i64_i32 v[38:39], s[80:81], v38, s23, v[26:27]
	v_mad_i64_i32 v[40:41], s[80:81], v40, s23, v[26:27]
	v_mad_i64_i32 v[26:27], s[80:81], v43, s23, v[26:27]
	global_load_dword v28, v[28:29], off nt
	s_nop 0
	global_load_dword v29, v[30:31], off nt
	s_nop 0
	global_load_dword v30, v[32:33], off nt
	global_load_dword v31, v[34:35], off nt
	s_nop 0
	global_load_dword v32, v[36:37], off nt
	global_load_dword v33, v[38:39], off nt
	global_load_dword v34, v[40:41], off nt
	s_nop 0
	global_load_dword v26, v[26:27], off nt
	s_waitcnt vmcnt(30)
	ds_write2_b32 v46, v45, v76 offset1:66
	s_waitcnt vmcnt(28)
	ds_write2_b32 v46, v77, v78 offset0:132 offset1:198
	s_waitcnt vmcnt(26)
	ds_write2_b32 v64, v79, v80 offset0:8 offset1:74
	s_waitcnt vmcnt(24)
	ds_write2_b32 v64, v81, v82 offset0:140 offset1:206
	s_waitcnt vmcnt(22)
	ds_write2_b32 v65, v83, v84 offset0:16 offset1:82
	s_waitcnt vmcnt(20)
	ds_write2_b32 v65, v85, v86 offset0:148 offset1:214
	s_waitcnt vmcnt(18)
	ds_write2_b32 v66, v87, v88 offset0:24 offset1:90
	s_waitcnt vmcnt(16)
	ds_write2_b32 v66, v89, v90 offset0:156 offset1:222
	s_waitcnt vmcnt(14)
	ds_write2_b32 v67, v91, v92 offset0:32 offset1:98
	s_waitcnt vmcnt(12)
	ds_write2_b32 v67, v93, v94 offset0:164 offset1:230
	s_waitcnt vmcnt(10)
	ds_write2_b32 v68, v95, v96 offset0:40 offset1:106
	s_waitcnt vmcnt(8)
	ds_write2_b32 v68, v97, v42 offset0:172 offset1:238
	s_waitcnt vmcnt(6)
	ds_write2_b32 v69, v28, v29 offset0:48 offset1:114
	s_waitcnt vmcnt(4)
	ds_write2_b32 v69, v30, v31 offset0:180 offset1:246
	s_waitcnt vmcnt(2)
	ds_write2_b32 v70, v32, v33 offset0:56 offset1:122
	s_waitcnt vmcnt(0)
	ds_write2_b32 v70, v34, v26 offset0:188 offset1:254
	s_waitcnt lgkmcnt(0)
	ds_read2_b32 v[30:31], v48 offset0:33 offset1:41
	ds_read2_b32 v[32:33], v48 offset1:8
	ds_read2_b32 v[34:35], v48 offset0:66 offset1:74
	ds_read2_b32 v[36:37], v48 offset0:99 offset1:107
	ds_read2_b32 v[38:39], v48 offset0:132 offset1:140
	ds_read2_b32 v[40:41], v48 offset0:165 offset1:173
	ds_read2_b32 v[42:43], v48 offset0:198 offset1:206
	ds_read2_b32 v[44:45], v48 offset0:231 offset1:239
	v_add_u32_e32 v80, s4, v47
	s_mulk_i32 s6, 0xfa80
	s_waitcnt lgkmcnt(6)
	v_cvt_pk_bf16_f32 v26, v32, v30
	v_add_u32_e32 v30, 0xfffffd80, v80
	v_add_u32_e32 v81, s6, v63
	v_add_u32_e32 v32, 63, v81
	v_cmp_gt_u32_e32 vcc, 32, v30
	s_ashr_i32 s35, s34, 31
	v_lshl_add_u64 v[76:77], s[34:35], 1, v[24:25]
	v_cndmask_b32_e32 v30, v81, v32, vcc
	v_add_u32_e32 v30, 0x280, v30
	v_cmp_lt_i32_e32 vcc, s21, v80
	s_waitcnt lgkmcnt(4)
	v_cvt_pk_bf16_f32 v27, v34, v36
	s_waitcnt lgkmcnt(2)
	v_cvt_pk_bf16_f32 v28, v38, v40
	s_waitcnt lgkmcnt(0)
	v_cvt_pk_bf16_f32 v29, v42, v44
	v_cndmask_b32_e32 v78, v80, v30, vcc
	v_ashrrev_i32_e32 v79, 31, v78
	v_lshlrev_b64 v[78:79], 11, v[78:79]
	v_lshl_add_u64 v[78:79], v[76:77], 0, v[78:79]
	global_store_dwordx4 v[78:79], v[26:29], off sc1
	v_add_u32_e32 v30, 8, v80
	s_nop 0
	v_cvt_pk_bf16_f32 v26, v33, v31
	v_add_u32_e32 v31, 0xfffffd88, v80
	v_cmp_gt_u32_e32 vcc, 32, v31
	v_cvt_pk_bf16_f32 v27, v35, v37
	v_cvt_pk_bf16_f32 v28, v39, v41
	v_cvt_pk_bf16_f32 v29, v43, v45
	ds_read2_b32 v[32:33], v48 offset0:16 offset1:24
	ds_read2_b32 v[34:35], v48 offset0:49 offset1:57
	ds_read2_b32 v[36:37], v48 offset0:82 offset1:90
	ds_read2_b32 v[38:39], v48 offset0:115 offset1:123
	ds_read2_b32 v[40:41], v48 offset0:148 offset1:156
	ds_read2_b32 v[42:43], v48 offset0:181 offset1:189
	ds_read2_b32 v[44:45], v48 offset0:214 offset1:222
	ds_read2_b32 v[78:79], v48 offset0:247 offset1:255
	v_cndmask_b32_e32 v31, 16, v73, vcc
	v_add3_u32 v31, v81, v31, s78
	v_cmp_lt_i32_e32 vcc, s21, v30
	s_nop 1
	v_cndmask_b32_e32 v30, v30, v31, vcc
	v_ashrrev_i32_e32 v31, 31, v30
	v_lshlrev_b64 v[30:31], 11, v[30:31]
	v_lshl_add_u64 v[30:31], v[76:77], 0, v[30:31]
	global_store_dwordx4 v[30:31], v[26:29], off sc1
	v_add_u32_e32 v31, 0xfffffd90, v80
	v_cmp_gt_u32_e32 vcc, 32, v31
	v_add_u32_e32 v30, 16, v80
	s_waitcnt lgkmcnt(6)
	v_cvt_pk_bf16_f32 v26, v32, v34
	s_waitcnt lgkmcnt(4)
	v_cvt_pk_bf16_f32 v27, v36, v38
	s_waitcnt lgkmcnt(2)
	v_cvt_pk_bf16_f32 v28, v40, v42
	s_waitcnt lgkmcnt(0)
	v_cvt_pk_bf16_f32 v29, v44, v78
	v_cndmask_b32_e32 v31, 32, v74, vcc
	v_add3_u32 v31, v81, v31, s78
	v_cmp_lt_i32_e32 vcc, s21, v30
	s_nop 1
	v_cndmask_b32_e32 v30, v30, v31, vcc
	v_ashrrev_i32_e32 v31, 31, v30
	v_lshlrev_b64 v[30:31], 11, v[30:31]
	v_lshl_add_u64 v[30:31], v[76:77], 0, v[30:31]
	global_store_dwordx4 v[30:31], v[26:29], off sc1
	v_add_u32_e32 v31, 0xfffffd98, v80
	v_cmp_gt_u32_e32 vcc, 32, v31
	v_add_u32_e32 v30, 24, v80
	v_cvt_pk_bf16_f32 v26, v33, v35
	v_cvt_pk_bf16_f32 v27, v37, v39
	v_cvt_pk_bf16_f32 v28, v41, v43
	v_cvt_pk_bf16_f32 v29, v45, v79
	s_nop 0
	v_cndmask_b32_e32 v31, 48, v75, vcc
	v_add3_u32 v31, v81, v31, s78
	v_cmp_lt_i32_e32 vcc, s21, v30
	s_nop 1
	v_cndmask_b32_e32 v30, v30, v31, vcc
	v_ashrrev_i32_e32 v31, 31, v30
	v_lshlrev_b64 v[30:31], 11, v[30:31]
	v_lshl_add_u64 v[30:31], v[76:77], 0, v[30:31]
	global_store_dwordx4 v[30:31], v[26:29], off sc1
	s_waitcnt lgkmcnt(0)
	s_branch .LBB0_24

.LBB0_127:
	v_add_u32_e32 v5, s6, v5
	v_cmp_lt_i32_e32 vcc, s1, v5
	global_store_dwordx4 v[10:11], v[0:3], off sc1
	s_or_b64 s[18:19], vcc, s[18:19]
	v_lshl_add_u64 v[10:11], v[10:11], 0, s[16:17]
	s_andn2_b64 exec, exec, s[18:19]
	s_cbranch_execnz .LBB0_127

.LBB0_137:
	s_ashr_i32 s11, s10, 31
	s_add_i32 s12, s0, s10
	s_lshl_b64 s[4:5], s[10:11], 12
	s_ashr_i32 s13, s12, 31
	s_add_i32 s6, s2, s10
	v_lshl_add_u64 v[20:21], v[0:1], 0, s[4:5]
	s_lshl_b64 s[4:5], s[12:13], 12
	s_ashr_i32 s7, s6, 31
	v_lshl_add_u64 v[32:33], v[0:1], 0, s[4:5]
	s_lshl_b64 s[4:5], s[6:7], 12
	v_lshl_add_u64 v[48:49], v[0:1], 0, s[4:5]
	s_add_i32 s4, s3, s10
	s_ashr_i32 s5, s4, 31
	s_lshl_b64 s[14:15], s[4:5], 12
	global_load_dwordx4 v[4:7], v[20:21], off nt
	global_load_dwordx4 v[8:11], v[20:21], off offset:1024 nt
	global_load_dwordx4 v[12:15], v[20:21], off offset:2048 nt
	global_load_dwordx4 v[16:19], v[20:21], off offset:3072 nt
	v_lshl_add_u64 v[68:69], v[0:1], 0, s[14:15]
	global_load_dwordx4 v[20:23], v[32:33], off nt
	global_load_dwordx4 v[24:27], v[32:33], off offset:1024 nt
	global_load_dwordx4 v[28:31], v[32:33], off offset:2048 nt
	global_load_dwordx4 v[36:39], v[48:49], off nt
	global_load_dwordx4 v[40:43], v[48:49], off offset:1024 nt
	global_load_dwordx4 v[44:47], v[48:49], off offset:2048 nt
	s_lshl_b64 s[14:15], s[10:11], 11
	global_load_dwordx4 v[32:35], v[32:33], off offset:3072 nt
	s_lshl_b64 s[12:13], s[12:13], 11
	global_load_dwordx4 v[48:51], v[48:49], off offset:3072 nt
	s_nop 0
	global_load_dwordx4 v[52:55], v[68:69], off nt
	global_load_dwordx4 v[56:59], v[68:69], off offset:1024 nt
	global_load_dwordx4 v[60:63], v[68:69], off offset:2048 nt
	global_load_dwordx4 v[64:67], v[68:69], off offset:3072 nt
	v_lshl_add_u64 v[68:69], v[2:3], 0, s[14:15]
	s_lshl_b64 s[6:7], s[6:7], 11
	s_lshl_b64 s[4:5], s[4:5], 11
	s_add_i32 s10, s10, s1
	v_lshl_add_u64 v[70:71], v[2:3], 0, s[12:13]
	v_lshl_add_u64 v[74:75], v[2:3], 0, s[4:5]
	s_cmpk_lt_i32 s10, 0x4000
	v_lshl_add_u64 v[72:73], v[2:3], 0, s[6:7]
	s_waitcnt vmcnt(15)
	v_cvt_pk_bf16_f32 v4, v4, v5
	v_cvt_pk_bf16_f32 v5, v6, v7
	s_waitcnt vmcnt(14)
	v_cvt_pk_bf16_f32 v6, v8, v9
	v_cvt_pk_bf16_f32 v7, v10, v11
	s_waitcnt vmcnt(13)
	v_cvt_pk_bf16_f32 v8, v12, v13
	v_cvt_pk_bf16_f32 v9, v14, v15
	s_waitcnt vmcnt(12)
	v_cvt_pk_bf16_f32 v10, v16, v17
	v_cvt_pk_bf16_f32 v11, v18, v19
	global_store_dwordx2 v[68:69], v[4:5], off sc1
	global_store_dwordx2 v[68:69], v[6:7], off offset:512 sc1
	global_store_dwordx2 v[68:69], v[8:9], off offset:1024 sc1
	global_store_dwordx2 v[68:69], v[10:11], off offset:1536 sc1
	s_waitcnt vmcnt(15)
	v_cvt_pk_bf16_f32 v4, v20, v21
	v_cvt_pk_bf16_f32 v5, v22, v23
	s_waitcnt vmcnt(14)
	v_cvt_pk_bf16_f32 v6, v24, v25
	v_cvt_pk_bf16_f32 v7, v26, v27
	s_waitcnt vmcnt(13)
	v_cvt_pk_bf16_f32 v8, v28, v29
	v_cvt_pk_bf16_f32 v9, v30, v31
	s_waitcnt vmcnt(9)
	v_cvt_pk_bf16_f32 v10, v32, v33
	v_cvt_pk_bf16_f32 v11, v34, v35
	v_cvt_pk_bf16_f32 v12, v36, v37
	v_cvt_pk_bf16_f32 v13, v38, v39
	v_cvt_pk_bf16_f32 v14, v40, v41
	v_cvt_pk_bf16_f32 v15, v42, v43
	v_cvt_pk_bf16_f32 v16, v44, v45
	v_cvt_pk_bf16_f32 v17, v46, v47
	s_waitcnt vmcnt(8)
	v_cvt_pk_bf16_f32 v18, v48, v49
	v_cvt_pk_bf16_f32 v19, v50, v51
	s_waitcnt vmcnt(7)
	v_cvt_pk_bf16_f32 v20, v52, v53
	v_cvt_pk_bf16_f32 v21, v54, v55
	s_waitcnt vmcnt(6)
	v_cvt_pk_bf16_f32 v22, v56, v57
	v_cvt_pk_bf16_f32 v23, v58, v59
	s_waitcnt vmcnt(5)
	v_cvt_pk_bf16_f32 v24, v60, v61
	v_cvt_pk_bf16_f32 v25, v62, v63
	s_waitcnt vmcnt(4)
	v_cvt_pk_bf16_f32 v26, v64, v65
	v_cvt_pk_bf16_f32 v27, v66, v67
	global_store_dwordx2 v[70:71], v[4:5], off sc1
	global_store_dwordx2 v[70:71], v[6:7], off offset:512 sc1
	global_store_dwordx2 v[70:71], v[8:9], off offset:1024 sc1
	global_store_dwordx2 v[70:71], v[10:11], off offset:1536 sc1
	global_store_dwordx2 v[72:73], v[12:13], off sc1
	global_store_dwordx2 v[72:73], v[14:15], off offset:512 sc1
	global_store_dwordx2 v[72:73], v[16:17], off offset:1024 sc1
	global_store_dwordx2 v[72:73], v[18:19], off offset:1536 sc1
	global_store_dwordx2 v[74:75], v[20:21], off sc1
	global_store_dwordx2 v[74:75], v[22:23], off offset:512 sc1
	global_store_dwordx2 v[74:75], v[24:25], off offset:1024 sc1
	global_store_dwordx2 v[74:75], v[26:27], off offset:1536 sc1
	s_cbranch_scc1 .LBB0_137

.LBB0_217:
	s_andn2_b64 vcc, exec, s[14:15]
	v_ashrrev_i32_e32 v143, 31, v142
	s_cbranch_vccnz .LBB0_219
	v_lshl_add_u64 v[124:125], v[142:143], 1, v[152:153]
	v_mov_b32_e32 v165, v132
	global_store_dwordx2 v[124:125], v[154:155], off sc1

.LBB0_230:
	s_andn2_b64 vcc, exec, s[14:15]
	s_cbranch_vccnz .LBB0_232
	v_lshl_add_u64 v[120:121], v[142:143], 1, v[124:125]
	global_store_dwordx2 v[120:121], v[126:127], off offset:32 sc1

.LBB0_246:
	v_lshl_add_u64 v[116:117], v[142:143], 1, v[120:121]
	global_store_dwordx2 v[116:117], v[122:123], off sc1
	v_cndmask_b32_e64 v116, 0, 1, s[16:17]
	v_cmp_ne_u32_e64 s[14:15], 1, v116
	s_andn2_b64 vcc, exec, s[16:17]
	s_cbranch_vccz .LBB0_239

.LBB0_255:
	s_andn2_b64 vcc, exec, s[18:19]
	s_cbranch_vccnz .LBB0_257
	v_lshl_add_u64 v[112:113], v[142:143], 1, v[116:117]
	global_store_dwordx2 v[112:113], v[118:119], off offset:32 sc1

.LBB0_279:
	v_lshl_add_u64 v[108:109], v[142:143], 1, v[120:121]
	v_mov_b32_e32 v125, v127
	global_store_dwordx2 v[108:109], v[122:123], off sc1
	s_and_b64 vcc, exec, s[12:13]
	s_cbranch_vccz .LBB0_272

.LBB0_291:
	v_lshl_add_u64 v[104:105], v[142:143], 1, v[108:109]
	global_store_dwordx2 v[104:105], v[110:111], off offset:32 sc1
	s_and_b64 vcc, exec, s[14:15]
	s_cbranch_vccz .LBB0_284

.LBB0_303:
	v_lshl_add_u64 v[100:101], v[142:143], 1, v[104:105]
	global_store_dwordx2 v[100:101], v[106:107], off sc1
	s_and_b64 vcc, exec, s[14:15]
	s_cbranch_vccz .LBB0_296

.LBB0_314:
	v_lshl_add_u64 v[96:97], v[142:143], 1, v[100:101]
	global_store_dwordx2 v[96:97], v[102:103], off offset:32 sc1
	s_and_b64 vcc, exec, s[16:17]
	s_cbranch_vccnz .LBB0_308

.LBB0_335:
	v_lshl_add_u64 v[92:93], v[142:143], 1, v[104:105]
	v_mov_b32_e32 v109, v111
	global_store_dwordx2 v[92:93], v[106:107], off sc1
	s_and_b64 vcc, exec, s[12:13]
	s_cbranch_vccz .LBB0_328

.LBB0_347:
	v_lshl_add_u64 v[88:89], v[142:143], 1, v[92:93]
	global_store_dwordx2 v[88:89], v[94:95], off offset:32 sc1
	s_and_b64 vcc, exec, s[14:15]
	s_cbranch_vccz .LBB0_340

.LBB0_359:
	v_lshl_add_u64 v[84:85], v[142:143], 1, v[88:89]
	global_store_dwordx2 v[84:85], v[90:91], off sc1
	s_and_b64 vcc, exec, s[14:15]
	s_cbranch_vccz .LBB0_352

.LBB0_370:
	v_lshl_add_u64 v[80:81], v[142:143], 1, v[84:85]
	global_store_dwordx2 v[80:81], v[86:87], off offset:32 sc1
	s_and_b64 vcc, exec, s[16:17]
	s_cbranch_vccnz .LBB0_364

.LBB0_391:
	v_lshl_add_u64 v[76:77], v[142:143], 1, v[88:89]
	v_mov_b32_e32 v93, v95
	global_store_dwordx2 v[76:77], v[90:91], off sc1
	s_and_b64 vcc, exec, s[12:13]
	s_cbranch_vccz .LBB0_384

.LBB0_403:
	v_lshl_add_u64 v[72:73], v[142:143], 1, v[76:77]
	global_store_dwordx2 v[72:73], v[78:79], off offset:32 sc1
	s_and_b64 vcc, exec, s[14:15]
	s_cbranch_vccz .LBB0_396

.LBB0_415:
	v_lshl_add_u64 v[68:69], v[142:143], 1, v[72:73]
	global_store_dwordx2 v[68:69], v[74:75], off sc1
	s_and_b64 vcc, exec, s[14:15]
	s_cbranch_vccz .LBB0_408

.LBB0_426:
	v_lshl_add_u64 v[64:65], v[142:143], 1, v[68:69]
	global_store_dwordx2 v[64:65], v[70:71], off offset:32 sc1
	s_and_b64 vcc, exec, s[16:17]
	s_cbranch_vccnz .LBB0_420

.LBB0_447:
	v_lshl_add_u64 v[60:61], v[142:143], 1, v[72:73]
	v_mov_b32_e32 v77, v79
	global_store_dwordx2 v[60:61], v[74:75], off sc1
	s_and_b64 vcc, exec, s[12:13]
	s_cbranch_vccz .LBB0_440

.LBB0_459:
	v_lshl_add_u64 v[56:57], v[142:143], 1, v[60:61]
	global_store_dwordx2 v[56:57], v[62:63], off offset:32 sc1
	s_and_b64 vcc, exec, s[14:15]
	s_cbranch_vccz .LBB0_452

.LBB0_471:
	v_lshl_add_u64 v[52:53], v[142:143], 1, v[56:57]
	global_store_dwordx2 v[52:53], v[58:59], off sc1
	s_and_b64 vcc, exec, s[14:15]
	s_cbranch_vccz .LBB0_464

.LBB0_482:
	v_lshl_add_u64 v[48:49], v[142:143], 1, v[52:53]
	global_store_dwordx2 v[48:49], v[54:55], off offset:32 sc1
	s_and_b64 vcc, exec, s[16:17]
	s_cbranch_vccnz .LBB0_476

.LBB0_503:
	v_lshl_add_u64 v[44:45], v[142:143], 1, v[56:57]
	v_mov_b32_e32 v61, v63
	global_store_dwordx2 v[44:45], v[58:59], off sc1
	s_and_b64 vcc, exec, s[12:13]
	s_cbranch_vccz .LBB0_496

.LBB0_515:
	v_lshl_add_u64 v[40:41], v[142:143], 1, v[44:45]
	global_store_dwordx2 v[40:41], v[46:47], off offset:32 sc1
	s_and_b64 vcc, exec, s[14:15]
	s_cbranch_vccz .LBB0_508

.LBB0_527:
	v_lshl_add_u64 v[36:37], v[142:143], 1, v[40:41]
	global_store_dwordx2 v[36:37], v[42:43], off sc1
	s_and_b64 vcc, exec, s[14:15]
	s_cbranch_vccz .LBB0_520

.LBB0_538:
	v_lshl_add_u64 v[32:33], v[142:143], 1, v[36:37]
	global_store_dwordx2 v[32:33], v[38:39], off offset:32 sc1
	s_and_b64 vcc, exec, s[16:17]
	s_cbranch_vccnz .LBB0_532

.LBB0_559:
	v_lshl_add_u64 v[28:29], v[142:143], 1, v[40:41]
	v_mov_b32_e32 v45, v47
	global_store_dwordx2 v[28:29], v[42:43], off sc1
	s_and_b64 vcc, exec, s[12:13]
	s_cbranch_vccz .LBB0_552

.LBB0_571:
	v_lshl_add_u64 v[24:25], v[142:143], 1, v[28:29]
	global_store_dwordx2 v[24:25], v[30:31], off offset:32 sc1
	s_and_b64 vcc, exec, s[14:15]
	s_cbranch_vccz .LBB0_564

.LBB0_583:
	v_lshl_add_u64 v[20:21], v[142:143], 1, v[24:25]
	global_store_dwordx2 v[20:21], v[26:27], off sc1
	s_and_b64 vcc, exec, s[14:15]
	s_cbranch_vccz .LBB0_576

.LBB0_594:
	v_lshl_add_u64 v[16:17], v[142:143], 1, v[20:21]
	global_store_dwordx2 v[16:17], v[22:23], off offset:32 sc1
	s_and_b64 vcc, exec, s[16:17]
	s_cbranch_vccnz .LBB0_588

.LBB0_615:
	v_lshl_add_u64 v[12:13], v[142:143], 1, v[24:25]
	v_mov_b32_e32 v29, v31
	global_store_dwordx2 v[12:13], v[26:27], off sc1
	s_and_b64 vcc, exec, s[12:13]
	s_cbranch_vccz .LBB0_608

.LBB0_627:
	v_lshl_add_u64 v[8:9], v[142:143], 1, v[12:13]
	global_store_dwordx2 v[8:9], v[14:15], off offset:32 sc1
	s_and_b64 vcc, exec, s[14:15]
	s_cbranch_vccz .LBB0_620

.LBB0_639:
	v_lshl_add_u64 v[4:5], v[142:143], 1, v[8:9]
	global_store_dwordx2 v[4:5], v[10:11], off sc1
	s_and_b64 vcc, exec, s[14:15]
	s_cbranch_vccz .LBB0_632

.LBB0_650:
	v_lshl_add_u64 v[0:1], v[142:143], 1, v[4:5]
	global_store_dwordx2 v[0:1], v[6:7], off offset:32 sc1
	s_and_b64 vcc, exec, s[16:17]
	s_cbranch_vccnz .LBB0_644

.LBB0_738:
	s_or_b64 exec, exec, s[8:9]
	s_waitcnt vmcnt(0)
	v_mov_b32_e32 v168, v132
	v_mov_b32_e32 v169, v128
	v_mov_b32_e32 v128, v133
	v_mov_b32_e32 v132, v134
	v_mov_b32_e32 v133, v130
	v_mov_b32_e32 v130, v135
	v_pk_add_f32 v[128:129], v[168:169], v[128:129]
	v_pk_add_f32 v[130:131], v[132:133], v[130:131]
	v_ashrrev_i32_e32 v157, 31, v156
	v_pk_add_f32 v[128:129], v[128:129], v[130:131]
	s_nop 0
	v_add_f32_e32 v128, v128, v129
	v_fmamk_f32 v128, v128, 0x3b2aaaab, v165
	v_mul_f32_e32 v129, 0x4f800000, v128
	v_cmp_gt_f32_e32 vcc, s55, v128
	s_nop 1
	v_cndmask_b32_e32 v128, v128, v129, vcc
	v_sqrt_f32_e32 v129, v128
	s_nop 0
	v_add_u32_e32 v130, -1, v129
	v_fma_f32 v131, -v130, v129, v128
	v_cmp_ge_f32_e64 s[8:9], 0, v131
	v_add_u32_e32 v131, 1, v129
	s_nop 0
	v_cndmask_b32_e64 v130, v129, v130, s[8:9]
	v_fma_f32 v129, -v131, v129, v128
	v_cmp_lt_f32_e64 s[8:9], 0, v129
	s_nop 1
	v_cndmask_b32_e64 v129, v130, v131, s[8:9]
	v_mul_f32_e32 v130, 0x37800000, v129
	v_cndmask_b32_e32 v129, v129, v130, vcc
	v_cmp_class_f32_e32 vcc, v128, v166
	s_nop 1
	v_cndmask_b32_e32 v128, v129, v128, vcc
	v_div_scale_f32 v129, s[8:9], v128, v128, 1.0
	v_rcp_f32_e32 v130, v129
	s_nop 0
	v_fma_f32 v131, -v129, v130, 1.0
	v_fmac_f32_e32 v130, v131, v130
	v_div_scale_f32 v131, vcc, 1.0, v128, 1.0
	v_mul_f32_e32 v132, v131, v130
	v_fma_f32 v133, -v129, v132, v131
	v_fmac_f32_e32 v132, v133, v130
	v_fma_f32 v129, -v129, v132, v131
	v_div_fmas_f32 v129, v129, v130, v132
	v_div_fixup_f32 v128, v129, v128, 1.0
	v_mul_f32_e32 v128, 0x3dd53b95, v128
	v_pk_mul_f32 v[124:125], v[128:129], v[124:125] op_sel_hi:[0,1]
	v_pk_mul_f32 v[120:121], v[128:129], v[120:121] op_sel_hi:[0,1]
	v_pk_mul_f32 v[126:127], v[128:129], v[126:127] op_sel_hi:[0,1]
	v_pk_mul_f32 v[130:131], v[128:129], v[122:123] op_sel_hi:[0,1]
	v_cvt_pk_bf16_f32 v122, v124, v125
	v_cvt_pk_bf16_f32 v123, v126, v127
	v_cvt_pk_bf16_f32 v124, v120, v121
	v_mov_b64_e32 v[120:121], s[36:37]
	v_mad_i64_i32 v[120:121], s[8:9], v158, s56, v[120:121]
	v_lshl_add_u64 v[120:121], v[156:157], 1, v[120:121]
	v_cvt_pk_bf16_f32 v125, v130, v131
	global_store_dwordx4 v[120:121], v[122:125], off sc1
	s_nop 1
	v_add_u32_e32 v122, 0x80, v156
	v_ashrrev_i32_e32 v122, 6, v122
	v_mul_hi_i32 v123, v122, s54
	v_lshrrev_b32_e32 v124, 31, v123
	v_add_u32_e32 v123, v123, v124
	v_lshl_add_u32 v123, v123, 1, v123
	v_sub_u32_e32 v122, v122, v123
	v_cmp_eq_u32_e64 s[8:9], 2, v122
	s_and_saveexec_b64 s[10:11], s[8:9]
	s_cbranch_execz .LBB0_740
	v_lshl_add_u64 v[122:123], s[18:19], 0, v[144:145]
	v_mov_b32_e32 v155, v145
	v_lshl_add_u64 v[126:127], v[122:123], 0, v[154:155]
	v_lshl_add_u64 v[122:123], s[34:35], 0, v[144:145]
	v_lshl_add_u64 v[122:123], v[122:123], 0, v[154:155]
	global_load_dwordx4 v[122:125], v[122:123], off
	s_nop 0
	global_load_dwordx4 v[130:133], v[126:127], off
	s_waitcnt vmcnt(1)
	v_pk_mul_f32 v[126:127], v[116:117], v[122:123] op_sel:[1,0] op_sel_hi:[0,0]
	v_pk_mul_f32 v[174:175], v[112:113], v[124:125] op_sel:[1,0] op_sel_hi:[0,0]
	s_waitcnt vmcnt(0)
	v_mov_b32_e32 v122, v131
	v_mul_f32_e32 v134, v119, v123
	v_mul_f32_e32 v144, v119, v131
	v_mov_b32_e32 v124, v133
	v_mul_f32_e32 v176, v115, v125
	v_mul_f32_e32 v178, v115, v133
	v_pk_fma_f32 v[168:169], v[116:117], v[130:131], v[126:127] op_sel_hi:[1,0,1] neg_lo:[0,0,1] neg_hi:[0,0,1]
	v_pk_fma_f32 v[116:117], v[116:117], v[130:131], v[126:127] op_sel_hi:[1,0,1]
	v_mov_b32_e32 v130, v123
	v_pk_fma_f32 v[172:173], v[112:113], v[132:133], v[174:175] op_sel_hi:[1,0,1] neg_lo:[0,0,1] neg_hi:[0,0,1]
	v_pk_fma_f32 v[112:113], v[112:113], v[132:133], v[174:175] op_sel_hi:[1,0,1]
	v_mov_b32_e32 v132, v125
	v_pk_fma_f32 v[170:171], v[118:119], v[122:123], v[134:135] op_sel_hi:[1,1,0] neg_lo:[0,0,1] neg_hi:[0,0,1]
	v_pk_fma_f32 v[174:175], v[114:115], v[124:125], v[176:177] op_sel_hi:[1,1,0] neg_lo:[0,0,1] neg_hi:[0,0,1]
	v_pk_fma_f32 v[118:119], v[118:119], v[130:131], v[144:145] op_sel_hi:[1,1,0]
	v_mov_b32_e32 v169, v117
	v_pk_fma_f32 v[114:115], v[114:115], v[132:133], v[178:179] op_sel_hi:[1,1,0]
	v_mov_b32_e32 v173, v113
	v_mov_b32_e32 v171, v118
	v_mov_b32_e32 v175, v114
	v_mov_b64_e32 v[116:117], v[168:169]
	v_mov_b64_e32 v[112:113], v[172:173]
	v_mov_b64_e32 v[118:119], v[170:171]
	v_mov_b64_e32 v[114:115], v[174:175]
.LBB0_740:
	s_or_b64 exec, exec, s[10:11]
	v_mov_b32_e32 v129, v128
	v_mov_b32_e32 v122, v128
	v_mov_b32_e32 v123, v128
	v_pk_mul_f32 v[118:119], v[122:123], v[118:119]
	v_pk_mul_f32 v[122:123], v[122:123], v[114:115]
	v_pk_mul_f32 v[114:115], v[128:129], v[112:113]
	v_pk_mul_f32 v[116:117], v[128:129], v[116:117]
	s_nop 0
	v_cvt_pk_bf16_f32 v112, v116, v117
	v_cvt_pk_bf16_f32 v113, v118, v119
	v_cvt_pk_bf16_f32 v114, v114, v115
	v_cvt_pk_bf16_f32 v115, v122, v123
	global_store_dwordx4 v[120:121], v[112:115], off offset:256 sc1
	v_or_b32_e32 v120, 16, v158
	v_ashrrev_i32_e32 v121, 31, v120
	v_lshlrev_b64 v[112:113], 6, v[120:121]
	v_lshl_add_u64 v[116:117], s[38:39], 0, v[112:113]
	global_load_dwordx4 v[112:115], v[116:117], off offset:16
	s_nop 0
	global_load_dwordx4 v[116:119], v[116:117], off
	v_lshlrev_b32_e32 v121, 5, v120
	v_and_b32_e32 v121, 0x3fbe0, v121
	v_lshlrev_b32_e32 v144, 2, v121
	s_and_saveexec_b64 s[10:11], s[6:7]
	s_cbranch_execz .LBB0_742
	v_lshl_add_u64 v[122:123], s[18:19], 0, v[144:145]
	v_mov_b32_e32 v155, v145
	v_lshl_add_u64 v[126:127], v[122:123], 0, v[154:155]
	v_lshl_add_u64 v[122:123], s[34:35], 0, v[144:145]
	v_lshl_add_u64 v[122:123], v[122:123], 0, v[154:155]
	global_load_dwordx4 v[122:125], v[122:123], off
	s_nop 0
	global_load_dwordx4 v[126:129], v[126:127], off
	s_waitcnt vmcnt(1)
	v_pk_mul_f32 v[132:133], v[108:109], v[122:123] op_sel:[1,0] op_sel_hi:[0,0]
	v_pk_mul_f32 v[170:171], v[104:105], v[124:125] op_sel:[1,0] op_sel_hi:[0,0]
	s_waitcnt vmcnt(0)
	v_mov_b32_e32 v122, v127
	v_mul_f32_e32 v134, v111, v123
	v_mul_f32_e32 v172, v111, v127
	v_mov_b32_e32 v124, v129
	v_mul_f32_e32 v174, v107, v125
	v_mul_f32_e32 v176, v107, v129
	v_pk_fma_f32 v[130:131], v[108:109], v[126:127], v[132:133] op_sel_hi:[1,0,1] neg_lo:[0,0,1] neg_hi:[0,0,1]
	v_pk_fma_f32 v[108:109], v[108:109], v[126:127], v[132:133] op_sel_hi:[1,0,1]
	v_mov_b32_e32 v126, v123
	v_pk_fma_f32 v[168:169], v[104:105], v[128:129], v[170:171] op_sel_hi:[1,0,1] neg_lo:[0,0,1] neg_hi:[0,0,1]
	v_pk_fma_f32 v[104:105], v[104:105], v[128:129], v[170:171] op_sel_hi:[1,0,1]
	v_mov_b32_e32 v128, v125
	v_pk_fma_f32 v[132:133], v[110:111], v[122:123], v[134:135] op_sel_hi:[1,1,0] neg_lo:[0,0,1] neg_hi:[0,0,1]
	v_pk_fma_f32 v[170:171], v[106:107], v[124:125], v[174:175] op_sel_hi:[1,1,0] neg_lo:[0,0,1] neg_hi:[0,0,1]
	v_pk_fma_f32 v[110:111], v[110:111], v[126:127], v[172:173] op_sel_hi:[1,1,0]
	v_mov_b32_e32 v131, v109
	v_pk_fma_f32 v[106:107], v[106:107], v[128:129], v[176:177] op_sel_hi:[1,1,0]
	v_mov_b32_e32 v169, v105
	v_mov_b32_e32 v133, v110
	v_mov_b32_e32 v171, v106
	v_mov_b64_e32 v[108:109], v[130:131]
	v_mov_b64_e32 v[104:105], v[168:169]
	v_mov_b64_e32 v[110:111], v[132:133]
	v_mov_b64_e32 v[106:107], v[170:171]
.LBB0_742:
	s_or_b64 exec, exec, s[10:11]
	s_waitcnt vmcnt(0)
	v_mov_b32_e32 v122, v116
	v_mov_b32_e32 v123, v112
	v_mov_b32_e32 v112, v117
	v_mov_b32_e32 v116, v118
	v_mov_b32_e32 v117, v114
	v_mov_b32_e32 v114, v119
	v_pk_add_f32 v[112:113], v[122:123], v[112:113]
	v_pk_add_f32 v[114:115], v[116:117], v[114:115]
	s_nop 0
	v_pk_add_f32 v[112:113], v[112:113], v[114:115]
	s_nop 0
	v_add_f32_e32 v112, v112, v113
	v_fmamk_f32 v112, v112, 0x3b2aaaab, v165
	v_mul_f32_e32 v113, 0x4f800000, v112
	v_cmp_gt_f32_e32 vcc, s55, v112
	s_nop 1
	v_cndmask_b32_e32 v112, v112, v113, vcc
	v_sqrt_f32_e32 v113, v112
	s_nop 0
	v_add_u32_e32 v114, -1, v113
	v_fma_f32 v115, -v114, v113, v112
	v_cmp_ge_f32_e64 s[10:11], 0, v115
	v_add_u32_e32 v115, 1, v113
	s_nop 0
	v_cndmask_b32_e64 v114, v113, v114, s[10:11]
	v_fma_f32 v113, -v115, v113, v112
	v_cmp_lt_f32_e64 s[10:11], 0, v113
	s_nop 1
	v_cndmask_b32_e64 v113, v114, v115, s[10:11]
	v_mul_f32_e32 v114, 0x37800000, v113
	v_cndmask_b32_e32 v113, v113, v114, vcc
	v_cmp_class_f32_e32 vcc, v112, v166
	s_nop 1
	v_cndmask_b32_e32 v112, v113, v112, vcc
	v_div_scale_f32 v113, s[10:11], v112, v112, 1.0
	v_rcp_f32_e32 v114, v113
	s_nop 0
	v_fma_f32 v115, -v113, v114, 1.0
	v_fmac_f32_e32 v114, v115, v114
	v_div_scale_f32 v115, vcc, 1.0, v112, 1.0
	v_mul_f32_e32 v116, v115, v114
	v_fma_f32 v117, -v113, v116, v115
	v_fmac_f32_e32 v116, v117, v114
	v_fma_f32 v113, -v113, v116, v115
	v_div_fmas_f32 v113, v113, v114, v116
	v_div_fixup_f32 v112, v113, v112, 1.0
	v_mul_f32_e32 v112, 0x3dd53b95, v112
	v_pk_mul_f32 v[108:109], v[112:113], v[108:109] op_sel_hi:[0,1]
	v_pk_mul_f32 v[104:105], v[112:113], v[104:105] op_sel_hi:[0,1]
	v_pk_mul_f32 v[110:111], v[112:113], v[110:111] op_sel_hi:[0,1]
	v_pk_mul_f32 v[114:115], v[112:113], v[106:107] op_sel_hi:[0,1]
	v_cvt_pk_bf16_f32 v106, v108, v109
	v_cvt_pk_bf16_f32 v107, v110, v111
	v_cvt_pk_bf16_f32 v108, v104, v105
	v_mov_b64_e32 v[104:105], s[36:37]
	v_mad_i64_i32 v[104:105], s[10:11], v120, s56, v[104:105]
	v_lshl_add_u64 v[104:105], v[156:157], 1, v[104:105]
	v_cvt_pk_bf16_f32 v109, v114, v115
	global_store_dwordx4 v[104:105], v[106:109], off sc1
	s_and_saveexec_b64 s[10:11], s[8:9]
	s_cbranch_execz .LBB0_744
	v_lshl_add_u64 v[106:107], s[18:19], 0, v[144:145]
	v_mov_b32_e32 v155, v145
	v_lshl_add_u64 v[110:111], v[106:107], 0, v[154:155]
	v_lshl_add_u64 v[106:107], s[34:35], 0, v[144:145]
	v_lshl_add_u64 v[106:107], v[106:107], 0, v[154:155]
	global_load_dwordx4 v[106:109], v[106:107], off
	s_nop 0
	global_load_dwordx4 v[114:117], v[110:111], off
	s_waitcnt vmcnt(1)
	v_pk_mul_f32 v[110:111], v[100:101], v[106:107] op_sel:[1,0] op_sel_hi:[0,0]
	v_pk_mul_f32 v[124:125], v[96:97], v[108:109] op_sel:[1,0] op_sel_hi:[0,0]
	s_waitcnt vmcnt(0)
	v_mov_b32_e32 v106, v115
	v_mul_f32_e32 v120, v103, v107
	v_mul_f32_e32 v126, v103, v115
	v_mov_b32_e32 v108, v117
	v_mul_f32_e32 v128, v99, v109
	v_mul_f32_e32 v130, v99, v117
	v_pk_fma_f32 v[118:119], v[100:101], v[114:115], v[110:111] op_sel_hi:[1,0,1] neg_lo:[0,0,1] neg_hi:[0,0,1]
	v_pk_fma_f32 v[100:101], v[100:101], v[114:115], v[110:111] op_sel_hi:[1,0,1]
	v_mov_b32_e32 v114, v107
	v_pk_fma_f32 v[122:123], v[96:97], v[116:117], v[124:125] op_sel_hi:[1,0,1] neg_lo:[0,0,1] neg_hi:[0,0,1]
	v_pk_fma_f32 v[96:97], v[96:97], v[116:117], v[124:125] op_sel_hi:[1,0,1]
	v_mov_b32_e32 v116, v109
	v_pk_fma_f32 v[120:121], v[102:103], v[106:107], v[120:121] op_sel_hi:[1,1,0] neg_lo:[0,0,1] neg_hi:[0,0,1]
	v_pk_fma_f32 v[124:125], v[98:99], v[108:109], v[128:129] op_sel_hi:[1,1,0] neg_lo:[0,0,1] neg_hi:[0,0,1]
	v_pk_fma_f32 v[102:103], v[102:103], v[114:115], v[126:127] op_sel_hi:[1,1,0]
	v_mov_b32_e32 v119, v101
	v_pk_fma_f32 v[98:99], v[98:99], v[116:117], v[130:131] op_sel_hi:[1,1,0]
	v_mov_b32_e32 v123, v97
	v_mov_b32_e32 v121, v102
	v_mov_b32_e32 v125, v98
	v_mov_b64_e32 v[100:101], v[118:119]
	v_mov_b64_e32 v[96:97], v[122:123]
	v_mov_b64_e32 v[102:103], v[120:121]
	v_mov_b64_e32 v[98:99], v[124:125]
.LBB0_744:
	s_or_b64 exec, exec, s[10:11]
	v_mov_b32_e32 v113, v112
	v_mov_b32_e32 v106, v112
	v_mov_b32_e32 v107, v112
	v_pk_mul_f32 v[102:103], v[106:107], v[102:103]
	v_pk_mul_f32 v[106:107], v[106:107], v[98:99]
	v_pk_mul_f32 v[98:99], v[112:113], v[96:97]
	v_pk_mul_f32 v[100:101], v[112:113], v[100:101]
	s_nop 0
	v_cvt_pk_bf16_f32 v96, v100, v101
	v_cvt_pk_bf16_f32 v97, v102, v103
	v_cvt_pk_bf16_f32 v98, v98, v99
	v_cvt_pk_bf16_f32 v99, v106, v107
	global_store_dwordx4 v[104:105], v[96:99], off offset:256 sc1
	v_or_b32_e32 v104, 32, v158
	v_ashrrev_i32_e32 v105, 31, v104
	v_lshlrev_b64 v[96:97], 6, v[104:105]
	v_lshl_add_u64 v[100:101], s[38:39], 0, v[96:97]
	global_load_dwordx4 v[96:99], v[100:101], off offset:16
	s_nop 0
	global_load_dwordx4 v[100:103], v[100:101], off
	v_lshlrev_b32_e32 v105, 5, v104
	v_and_b32_e32 v105, 0x3fde0, v105
	v_lshlrev_b32_e32 v144, 2, v105
	s_and_saveexec_b64 s[10:11], s[6:7]
	s_cbranch_execz .LBB0_746
	v_lshl_add_u64 v[106:107], s[18:19], 0, v[144:145]
	v_mov_b32_e32 v155, v145
	v_lshl_add_u64 v[110:111], v[106:107], 0, v[154:155]
	v_lshl_add_u64 v[106:107], s[34:35], 0, v[144:145]
	v_lshl_add_u64 v[106:107], v[106:107], 0, v[154:155]
	global_load_dwordx4 v[106:109], v[106:107], off
	s_nop 0
	global_load_dwordx4 v[110:113], v[110:111], off
	s_waitcnt vmcnt(1)
	v_pk_mul_f32 v[116:117], v[92:93], v[106:107] op_sel:[1,0] op_sel_hi:[0,0]
	s_waitcnt vmcnt(0)
	v_mov_b32_e32 v106, v111
	v_mul_f32_e32 v118, v95, v107
	v_pk_mul_f32 v[120:121], v[88:89], v[108:109] op_sel:[1,0] op_sel_hi:[0,0]
	v_mul_f32_e32 v122, v95, v111
	v_mov_b32_e32 v108, v113
	v_mul_f32_e32 v124, v91, v109
	v_mul_f32_e32 v126, v91, v113
	v_pk_fma_f32 v[114:115], v[92:93], v[110:111], v[116:117] op_sel_hi:[1,0,1] neg_lo:[0,0,1] neg_hi:[0,0,1]
	v_pk_fma_f32 v[92:93], v[92:93], v[110:111], v[116:117] op_sel_hi:[1,0,1]
	v_pk_fma_f32 v[116:117], v[94:95], v[106:107], v[118:119] op_sel_hi:[1,1,0] neg_lo:[0,0,1] neg_hi:[0,0,1]
	v_mov_b32_e32 v110, v107
	v_pk_fma_f32 v[118:119], v[88:89], v[112:113], v[120:121] op_sel_hi:[1,0,1] neg_lo:[0,0,1] neg_hi:[0,0,1]
	v_pk_fma_f32 v[88:89], v[88:89], v[112:113], v[120:121] op_sel_hi:[1,0,1]
	v_mov_b32_e32 v112, v109
	v_pk_fma_f32 v[120:121], v[90:91], v[108:109], v[124:125] op_sel_hi:[1,1,0] neg_lo:[0,0,1] neg_hi:[0,0,1]
	v_pk_fma_f32 v[94:95], v[94:95], v[110:111], v[122:123] op_sel_hi:[1,1,0]
	v_mov_b32_e32 v115, v93
	v_pk_fma_f32 v[90:91], v[90:91], v[112:113], v[126:127] op_sel_hi:[1,1,0]
	v_mov_b32_e32 v119, v89
	v_mov_b32_e32 v117, v94
	v_mov_b32_e32 v121, v90
	v_mov_b64_e32 v[92:93], v[114:115]
	v_mov_b64_e32 v[88:89], v[118:119]
	v_mov_b64_e32 v[94:95], v[116:117]
	v_mov_b64_e32 v[90:91], v[120:121]
.LBB0_746:
	s_or_b64 exec, exec, s[10:11]
	s_waitcnt vmcnt(0)
	v_mov_b32_e32 v106, v100
	v_mov_b32_e32 v107, v96
	v_mov_b32_e32 v96, v101
	v_mov_b32_e32 v100, v102
	v_mov_b32_e32 v101, v98
	v_mov_b32_e32 v98, v103
	v_pk_add_f32 v[96:97], v[106:107], v[96:97]
	v_pk_add_f32 v[98:99], v[100:101], v[98:99]
	s_nop 0
	v_pk_add_f32 v[96:97], v[96:97], v[98:99]
	s_nop 0
	v_add_f32_e32 v96, v96, v97
	v_fmamk_f32 v96, v96, 0x3b2aaaab, v165
	v_mul_f32_e32 v97, 0x4f800000, v96
	v_cmp_gt_f32_e32 vcc, s55, v96
	s_nop 1
	v_cndmask_b32_e32 v96, v96, v97, vcc
	v_sqrt_f32_e32 v97, v96
	s_nop 0
	v_add_u32_e32 v98, -1, v97
	v_fma_f32 v99, -v98, v97, v96
	v_cmp_ge_f32_e64 s[10:11], 0, v99
	v_add_u32_e32 v99, 1, v97
	s_nop 0
	v_cndmask_b32_e64 v98, v97, v98, s[10:11]
	v_fma_f32 v97, -v99, v97, v96
	v_cmp_lt_f32_e64 s[10:11], 0, v97
	s_nop 1
	v_cndmask_b32_e64 v97, v98, v99, s[10:11]
	v_mul_f32_e32 v98, 0x37800000, v97
	v_cndmask_b32_e32 v97, v97, v98, vcc
	v_cmp_class_f32_e32 vcc, v96, v166
	s_nop 1
	v_cndmask_b32_e32 v96, v97, v96, vcc
	v_div_scale_f32 v97, s[10:11], v96, v96, 1.0
	v_rcp_f32_e32 v98, v97
	s_nop 0
	v_fma_f32 v99, -v97, v98, 1.0
	v_fmac_f32_e32 v98, v99, v98
	v_div_scale_f32 v99, vcc, 1.0, v96, 1.0
	v_mul_f32_e32 v100, v99, v98
	v_fma_f32 v101, -v97, v100, v99
	v_fmac_f32_e32 v100, v101, v98
	v_fma_f32 v97, -v97, v100, v99
	v_div_fmas_f32 v97, v97, v98, v100
	v_div_fixup_f32 v96, v97, v96, 1.0
	v_mul_f32_e32 v96, 0x3dd53b95, v96
	v_pk_mul_f32 v[92:93], v[96:97], v[92:93] op_sel_hi:[0,1]
	v_pk_mul_f32 v[88:89], v[96:97], v[88:89] op_sel_hi:[0,1]
	v_pk_mul_f32 v[94:95], v[96:97], v[94:95] op_sel_hi:[0,1]
	v_pk_mul_f32 v[98:99], v[96:97], v[90:91] op_sel_hi:[0,1]
	v_cvt_pk_bf16_f32 v90, v92, v93
	v_cvt_pk_bf16_f32 v91, v94, v95
	v_cvt_pk_bf16_f32 v92, v88, v89
	v_mov_b64_e32 v[88:89], s[36:37]
	v_mad_i64_i32 v[88:89], s[10:11], v104, s56, v[88:89]
	v_lshl_add_u64 v[88:89], v[156:157], 1, v[88:89]
	v_cvt_pk_bf16_f32 v93, v98, v99
	global_store_dwordx4 v[88:89], v[90:93], off sc1
	s_and_saveexec_b64 s[10:11], s[8:9]
	s_cbranch_execz .LBB0_748
	v_lshl_add_u64 v[90:91], s[18:19], 0, v[144:145]
	v_mov_b32_e32 v155, v145
	v_lshl_add_u64 v[94:95], v[90:91], 0, v[154:155]
	v_lshl_add_u64 v[90:91], s[34:35], 0, v[144:145]
	v_lshl_add_u64 v[90:91], v[90:91], 0, v[154:155]
	global_load_dwordx4 v[90:93], v[90:91], off
	s_nop 0
	global_load_dwordx4 v[98:101], v[94:95], off
	s_waitcnt vmcnt(1)
	v_pk_mul_f32 v[94:95], v[84:85], v[90:91] op_sel:[1,0] op_sel_hi:[0,0]
	v_pk_mul_f32 v[108:109], v[80:81], v[92:93] op_sel:[1,0] op_sel_hi:[0,0]
	s_waitcnt vmcnt(0)
	v_mov_b32_e32 v90, v99
	v_mul_f32_e32 v104, v87, v91
	v_mul_f32_e32 v110, v87, v99
	v_mov_b32_e32 v92, v101
	v_mul_f32_e32 v112, v83, v93
	v_mul_f32_e32 v114, v83, v101
	v_pk_fma_f32 v[102:103], v[84:85], v[98:99], v[94:95] op_sel_hi:[1,0,1] neg_lo:[0,0,1] neg_hi:[0,0,1]
	v_pk_fma_f32 v[84:85], v[84:85], v[98:99], v[94:95] op_sel_hi:[1,0,1]
	v_mov_b32_e32 v98, v91
	v_pk_fma_f32 v[106:107], v[80:81], v[100:101], v[108:109] op_sel_hi:[1,0,1] neg_lo:[0,0,1] neg_hi:[0,0,1]
	v_pk_fma_f32 v[80:81], v[80:81], v[100:101], v[108:109] op_sel_hi:[1,0,1]
	v_mov_b32_e32 v100, v93
	v_pk_fma_f32 v[104:105], v[86:87], v[90:91], v[104:105] op_sel_hi:[1,1,0] neg_lo:[0,0,1] neg_hi:[0,0,1]
	v_pk_fma_f32 v[108:109], v[82:83], v[92:93], v[112:113] op_sel_hi:[1,1,0] neg_lo:[0,0,1] neg_hi:[0,0,1]
	v_pk_fma_f32 v[86:87], v[86:87], v[98:99], v[110:111] op_sel_hi:[1,1,0]
	v_mov_b32_e32 v103, v85
	v_pk_fma_f32 v[82:83], v[82:83], v[100:101], v[114:115] op_sel_hi:[1,1,0]
	v_mov_b32_e32 v107, v81
	v_mov_b32_e32 v105, v86
	v_mov_b32_e32 v109, v82
	v_mov_b64_e32 v[84:85], v[102:103]
	v_mov_b64_e32 v[80:81], v[106:107]
	v_mov_b64_e32 v[86:87], v[104:105]
	v_mov_b64_e32 v[82:83], v[108:109]
.LBB0_748:
	s_or_b64 exec, exec, s[10:11]
	v_mov_b32_e32 v97, v96
	v_mov_b32_e32 v90, v96
	v_mov_b32_e32 v91, v96
	v_pk_mul_f32 v[86:87], v[90:91], v[86:87]
	v_pk_mul_f32 v[90:91], v[90:91], v[82:83]
	v_pk_mul_f32 v[82:83], v[96:97], v[80:81]
	v_pk_mul_f32 v[84:85], v[96:97], v[84:85]
	s_nop 0
	v_cvt_pk_bf16_f32 v80, v84, v85
	v_cvt_pk_bf16_f32 v81, v86, v87
	v_cvt_pk_bf16_f32 v82, v82, v83
	v_cvt_pk_bf16_f32 v83, v90, v91
	global_store_dwordx4 v[88:89], v[80:83], off offset:256 sc1
	v_or_b32_e32 v88, 48, v158
	v_ashrrev_i32_e32 v89, 31, v88
	v_lshlrev_b64 v[80:81], 6, v[88:89]
	v_lshl_add_u64 v[84:85], s[38:39], 0, v[80:81]
	global_load_dwordx4 v[80:83], v[84:85], off offset:16
	s_nop 0
	global_load_dwordx4 v[84:87], v[84:85], off
	v_lshlrev_b32_e32 v89, 5, v88
	v_and_b32_e32 v89, 0x3ffe0, v89
	v_lshlrev_b32_e32 v144, 2, v89
	s_and_saveexec_b64 s[10:11], s[6:7]
	s_cbranch_execz .LBB0_750
	v_lshl_add_u64 v[90:91], s[18:19], 0, v[144:145]
	v_mov_b32_e32 v155, v145
	v_lshl_add_u64 v[94:95], v[90:91], 0, v[154:155]
	v_lshl_add_u64 v[90:91], s[34:35], 0, v[144:145]
	v_lshl_add_u64 v[90:91], v[90:91], 0, v[154:155]
	global_load_dwordx4 v[90:93], v[90:91], off
	s_nop 0
	global_load_dwordx4 v[94:97], v[94:95], off
	s_waitcnt vmcnt(1)
	v_pk_mul_f32 v[100:101], v[76:77], v[90:91] op_sel:[1,0] op_sel_hi:[0,0]
	s_waitcnt vmcnt(0)
	v_mov_b32_e32 v90, v95
	v_mul_f32_e32 v102, v79, v91
	v_pk_mul_f32 v[104:105], v[72:73], v[92:93] op_sel:[1,0] op_sel_hi:[0,0]
	v_mul_f32_e32 v106, v79, v95
	v_mov_b32_e32 v92, v97
	v_mul_f32_e32 v108, v75, v93
	v_mul_f32_e32 v110, v75, v97
	v_pk_fma_f32 v[98:99], v[76:77], v[94:95], v[100:101] op_sel_hi:[1,0,1] neg_lo:[0,0,1] neg_hi:[0,0,1]
	v_pk_fma_f32 v[76:77], v[76:77], v[94:95], v[100:101] op_sel_hi:[1,0,1]
	v_pk_fma_f32 v[100:101], v[78:79], v[90:91], v[102:103] op_sel_hi:[1,1,0] neg_lo:[0,0,1] neg_hi:[0,0,1]
	v_mov_b32_e32 v94, v91
	v_pk_fma_f32 v[102:103], v[72:73], v[96:97], v[104:105] op_sel_hi:[1,0,1] neg_lo:[0,0,1] neg_hi:[0,0,1]
	v_pk_fma_f32 v[72:73], v[72:73], v[96:97], v[104:105] op_sel_hi:[1,0,1]
	v_mov_b32_e32 v96, v93
	v_pk_fma_f32 v[104:105], v[74:75], v[92:93], v[108:109] op_sel_hi:[1,1,0] neg_lo:[0,0,1] neg_hi:[0,0,1]
	v_pk_fma_f32 v[78:79], v[78:79], v[94:95], v[106:107] op_sel_hi:[1,1,0]
	v_mov_b32_e32 v99, v77
	v_pk_fma_f32 v[74:75], v[74:75], v[96:97], v[110:111] op_sel_hi:[1,1,0]
	v_mov_b32_e32 v103, v73
	v_mov_b32_e32 v101, v78
	v_mov_b32_e32 v105, v74
	v_mov_b64_e32 v[76:77], v[98:99]
	v_mov_b64_e32 v[72:73], v[102:103]
	v_mov_b64_e32 v[78:79], v[100:101]
	v_mov_b64_e32 v[74:75], v[104:105]
.LBB0_750:
	s_or_b64 exec, exec, s[10:11]
	s_waitcnt vmcnt(0)
	v_mov_b32_e32 v90, v84
	v_mov_b32_e32 v91, v80
	v_mov_b32_e32 v80, v85
	v_mov_b32_e32 v84, v86
	v_mov_b32_e32 v85, v82
	v_mov_b32_e32 v82, v87
	v_pk_add_f32 v[80:81], v[90:91], v[80:81]
	v_pk_add_f32 v[82:83], v[84:85], v[82:83]
	s_nop 0
	v_pk_add_f32 v[80:81], v[80:81], v[82:83]
	s_nop 0
	v_add_f32_e32 v80, v80, v81
	v_fmamk_f32 v80, v80, 0x3b2aaaab, v165
	v_mul_f32_e32 v81, 0x4f800000, v80
	v_cmp_gt_f32_e32 vcc, s55, v80
	s_nop 1
	v_cndmask_b32_e32 v80, v80, v81, vcc
	v_sqrt_f32_e32 v81, v80
	s_nop 0
	v_add_u32_e32 v82, -1, v81
	v_fma_f32 v83, -v82, v81, v80
	v_cmp_ge_f32_e64 s[10:11], 0, v83
	v_add_u32_e32 v83, 1, v81
	s_nop 0
	v_cndmask_b32_e64 v82, v81, v82, s[10:11]
	v_fma_f32 v81, -v83, v81, v80
	v_cmp_lt_f32_e64 s[10:11], 0, v81
	s_nop 1
	v_cndmask_b32_e64 v81, v82, v83, s[10:11]
	v_mul_f32_e32 v82, 0x37800000, v81
	v_cndmask_b32_e32 v81, v81, v82, vcc
	v_cmp_class_f32_e32 vcc, v80, v166
	s_nop 1
	v_cndmask_b32_e32 v80, v81, v80, vcc
	v_div_scale_f32 v81, s[10:11], v80, v80, 1.0
	v_rcp_f32_e32 v82, v81
	s_nop 0
	v_fma_f32 v83, -v81, v82, 1.0
	v_fmac_f32_e32 v82, v83, v82
	v_div_scale_f32 v83, vcc, 1.0, v80, 1.0
	v_mul_f32_e32 v84, v83, v82
	v_fma_f32 v85, -v81, v84, v83
	v_fmac_f32_e32 v84, v85, v82
	v_fma_f32 v81, -v81, v84, v83
	v_div_fmas_f32 v81, v81, v82, v84
	v_div_fixup_f32 v80, v81, v80, 1.0
	v_mul_f32_e32 v80, 0x3dd53b95, v80
	v_pk_mul_f32 v[76:77], v[80:81], v[76:77] op_sel_hi:[0,1]
	v_pk_mul_f32 v[72:73], v[80:81], v[72:73] op_sel_hi:[0,1]
	v_pk_mul_f32 v[78:79], v[80:81], v[78:79] op_sel_hi:[0,1]
	v_pk_mul_f32 v[82:83], v[80:81], v[74:75] op_sel_hi:[0,1]
	v_cvt_pk_bf16_f32 v74, v76, v77
	v_cvt_pk_bf16_f32 v75, v78, v79
	v_cvt_pk_bf16_f32 v76, v72, v73
	v_mov_b64_e32 v[72:73], s[36:37]
	v_mad_i64_i32 v[72:73], s[10:11], v88, s56, v[72:73]
	v_lshl_add_u64 v[72:73], v[156:157], 1, v[72:73]
	v_cvt_pk_bf16_f32 v77, v82, v83
	global_store_dwordx4 v[72:73], v[74:77], off sc1
	s_and_saveexec_b64 s[10:11], s[8:9]
	s_cbranch_execz .LBB0_752
	v_lshl_add_u64 v[74:75], s[18:19], 0, v[144:145]
	v_mov_b32_e32 v155, v145
	v_lshl_add_u64 v[78:79], v[74:75], 0, v[154:155]
	v_lshl_add_u64 v[74:75], s[34:35], 0, v[144:145]
	v_lshl_add_u64 v[74:75], v[74:75], 0, v[154:155]
	global_load_dwordx4 v[74:77], v[74:75], off
	s_nop 0
	global_load_dwordx4 v[82:85], v[78:79], off
	s_waitcnt vmcnt(1)
	v_pk_mul_f32 v[78:79], v[68:69], v[74:75] op_sel:[1,0] op_sel_hi:[0,0]
	v_pk_mul_f32 v[92:93], v[64:65], v[76:77] op_sel:[1,0] op_sel_hi:[0,0]
	s_waitcnt vmcnt(0)
	v_mov_b32_e32 v74, v83
	v_mul_f32_e32 v88, v71, v75
	v_mul_f32_e32 v94, v71, v83
	v_mov_b32_e32 v76, v85
	v_mul_f32_e32 v96, v67, v77
	v_mul_f32_e32 v98, v67, v85
	v_pk_fma_f32 v[86:87], v[68:69], v[82:83], v[78:79] op_sel_hi:[1,0,1] neg_lo:[0,0,1] neg_hi:[0,0,1]
	v_pk_fma_f32 v[68:69], v[68:69], v[82:83], v[78:79] op_sel_hi:[1,0,1]
	v_mov_b32_e32 v82, v75
	v_pk_fma_f32 v[90:91], v[64:65], v[84:85], v[92:93] op_sel_hi:[1,0,1] neg_lo:[0,0,1] neg_hi:[0,0,1]
	v_pk_fma_f32 v[64:65], v[64:65], v[84:85], v[92:93] op_sel_hi:[1,0,1]
	v_mov_b32_e32 v84, v77
	v_pk_fma_f32 v[88:89], v[70:71], v[74:75], v[88:89] op_sel_hi:[1,1,0] neg_lo:[0,0,1] neg_hi:[0,0,1]
	v_pk_fma_f32 v[92:93], v[66:67], v[76:77], v[96:97] op_sel_hi:[1,1,0] neg_lo:[0,0,1] neg_hi:[0,0,1]
	v_pk_fma_f32 v[70:71], v[70:71], v[82:83], v[94:95] op_sel_hi:[1,1,0]
	v_mov_b32_e32 v87, v69
	v_pk_fma_f32 v[66:67], v[66:67], v[84:85], v[98:99] op_sel_hi:[1,1,0]
	v_mov_b32_e32 v91, v65
	v_mov_b32_e32 v89, v70
	v_mov_b32_e32 v93, v66
	v_mov_b64_e32 v[68:69], v[86:87]
	v_mov_b64_e32 v[64:65], v[90:91]
	v_mov_b64_e32 v[70:71], v[88:89]
	v_mov_b64_e32 v[66:67], v[92:93]
.LBB0_752:
	s_or_b64 exec, exec, s[10:11]
	v_mov_b32_e32 v81, v80
	v_mov_b32_e32 v74, v80
	v_mov_b32_e32 v75, v80
	v_pk_mul_f32 v[70:71], v[74:75], v[70:71]
	v_pk_mul_f32 v[74:75], v[74:75], v[66:67]
	v_pk_mul_f32 v[66:67], v[80:81], v[64:65]
	v_pk_mul_f32 v[68:69], v[80:81], v[68:69]
	s_nop 0
	v_cvt_pk_bf16_f32 v64, v68, v69
	v_cvt_pk_bf16_f32 v65, v70, v71
	v_cvt_pk_bf16_f32 v66, v66, v67
	v_cvt_pk_bf16_f32 v67, v74, v75
	global_store_dwordx4 v[72:73], v[64:67], off offset:256 sc1
	v_add_u32_e32 v72, 0x80, v158
	v_ashrrev_i32_e32 v73, 31, v72
	v_lshlrev_b64 v[64:65], 6, v[72:73]
	v_lshl_add_u64 v[68:69], s[38:39], 0, v[64:65]
	global_load_dwordx4 v[64:67], v[68:69], off offset:16
	s_nop 0
	global_load_dwordx4 v[68:71], v[68:69], off
	v_lshlrev_b32_e32 v73, 5, v72
	v_and_b32_e32 v73, 0x3f9e0, v73
	v_lshlrev_b32_e32 v144, 2, v73
	s_and_saveexec_b64 s[10:11], s[6:7]
	s_cbranch_execz .LBB0_754
	v_lshl_add_u64 v[74:75], s[18:19], 0, v[144:145]
	v_mov_b32_e32 v155, v145
	v_lshl_add_u64 v[78:79], v[74:75], 0, v[154:155]
	v_lshl_add_u64 v[74:75], s[34:35], 0, v[144:145]
	v_lshl_add_u64 v[74:75], v[74:75], 0, v[154:155]
	global_load_dwordx4 v[74:77], v[74:75], off
	s_nop 0
	global_load_dwordx4 v[78:81], v[78:79], off
	s_waitcnt vmcnt(1)
	v_pk_mul_f32 v[84:85], v[60:61], v[74:75] op_sel:[1,0] op_sel_hi:[0,0]
	s_waitcnt vmcnt(0)
	v_mov_b32_e32 v74, v79
	v_mul_f32_e32 v86, v63, v75
	v_pk_mul_f32 v[88:89], v[56:57], v[76:77] op_sel:[1,0] op_sel_hi:[0,0]
	v_mul_f32_e32 v90, v63, v79
	v_mov_b32_e32 v76, v81
	v_mul_f32_e32 v92, v59, v77
	v_mul_f32_e32 v94, v59, v81
	v_pk_fma_f32 v[82:83], v[60:61], v[78:79], v[84:85] op_sel_hi:[1,0,1] neg_lo:[0,0,1] neg_hi:[0,0,1]
	v_pk_fma_f32 v[60:61], v[60:61], v[78:79], v[84:85] op_sel_hi:[1,0,1]
	v_pk_fma_f32 v[84:85], v[62:63], v[74:75], v[86:87] op_sel_hi:[1,1,0] neg_lo:[0,0,1] neg_hi:[0,0,1]
	v_mov_b32_e32 v78, v75
	v_pk_fma_f32 v[86:87], v[56:57], v[80:81], v[88:89] op_sel_hi:[1,0,1] neg_lo:[0,0,1] neg_hi:[0,0,1]
	v_pk_fma_f32 v[56:57], v[56:57], v[80:81], v[88:89] op_sel_hi:[1,0,1]
	v_mov_b32_e32 v80, v77
	v_pk_fma_f32 v[88:89], v[58:59], v[76:77], v[92:93] op_sel_hi:[1,1,0] neg_lo:[0,0,1] neg_hi:[0,0,1]
	v_pk_fma_f32 v[62:63], v[62:63], v[78:79], v[90:91] op_sel_hi:[1,1,0]
	v_mov_b32_e32 v83, v61
	v_pk_fma_f32 v[58:59], v[58:59], v[80:81], v[94:95] op_sel_hi:[1,1,0]
	v_mov_b32_e32 v87, v57
	v_mov_b32_e32 v85, v62
	v_mov_b32_e32 v89, v58
	v_mov_b64_e32 v[60:61], v[82:83]
	v_mov_b64_e32 v[56:57], v[86:87]
	v_mov_b64_e32 v[62:63], v[84:85]
	v_mov_b64_e32 v[58:59], v[88:89]
.LBB0_754:
	s_or_b64 exec, exec, s[10:11]
	s_waitcnt vmcnt(0)
	v_mov_b32_e32 v74, v68
	v_mov_b32_e32 v75, v64
	v_mov_b32_e32 v64, v69
	v_mov_b32_e32 v68, v70
	v_mov_b32_e32 v69, v66
	v_mov_b32_e32 v66, v71
	v_pk_add_f32 v[64:65], v[74:75], v[64:65]
	v_pk_add_f32 v[66:67], v[68:69], v[66:67]
	s_nop 0
	v_pk_add_f32 v[64:65], v[64:65], v[66:67]
	s_nop 0
	v_add_f32_e32 v64, v64, v65
	v_fmamk_f32 v64, v64, 0x3b2aaaab, v165
	v_mul_f32_e32 v65, 0x4f800000, v64
	v_cmp_gt_f32_e32 vcc, s55, v64
	s_nop 1
	v_cndmask_b32_e32 v64, v64, v65, vcc
	v_sqrt_f32_e32 v65, v64
	s_nop 0
	v_add_u32_e32 v66, -1, v65
	v_fma_f32 v67, -v66, v65, v64
	v_cmp_ge_f32_e64 s[10:11], 0, v67
	v_add_u32_e32 v67, 1, v65
	s_nop 0
	v_cndmask_b32_e64 v66, v65, v66, s[10:11]
	v_fma_f32 v65, -v67, v65, v64
	v_cmp_lt_f32_e64 s[10:11], 0, v65
	s_nop 1
	v_cndmask_b32_e64 v65, v66, v67, s[10:11]
	v_mul_f32_e32 v66, 0x37800000, v65
	v_cndmask_b32_e32 v65, v65, v66, vcc
	v_cmp_class_f32_e32 vcc, v64, v166
	s_nop 1
	v_cndmask_b32_e32 v64, v65, v64, vcc
	v_div_scale_f32 v65, s[10:11], v64, v64, 1.0
	v_rcp_f32_e32 v66, v65
	s_nop 0
	v_fma_f32 v67, -v65, v66, 1.0
	v_fmac_f32_e32 v66, v67, v66
	v_div_scale_f32 v67, vcc, 1.0, v64, 1.0
	v_mul_f32_e32 v68, v67, v66
	v_fma_f32 v69, -v65, v68, v67
	v_fmac_f32_e32 v68, v69, v66
	v_fma_f32 v65, -v65, v68, v67
	v_div_fmas_f32 v65, v65, v66, v68
	v_div_fixup_f32 v64, v65, v64, 1.0
	v_mul_f32_e32 v64, 0x3dd53b95, v64
	v_pk_mul_f32 v[60:61], v[64:65], v[60:61] op_sel_hi:[0,1]
	v_pk_mul_f32 v[56:57], v[64:65], v[56:57] op_sel_hi:[0,1]
	v_pk_mul_f32 v[62:63], v[64:65], v[62:63] op_sel_hi:[0,1]
	v_pk_mul_f32 v[66:67], v[64:65], v[58:59] op_sel_hi:[0,1]
	v_cvt_pk_bf16_f32 v58, v60, v61
	v_cvt_pk_bf16_f32 v59, v62, v63
	v_cvt_pk_bf16_f32 v60, v56, v57
	v_mov_b64_e32 v[56:57], s[36:37]
	v_mad_i64_i32 v[56:57], s[10:11], v72, s56, v[56:57]
	v_lshl_add_u64 v[56:57], v[156:157], 1, v[56:57]
	v_cvt_pk_bf16_f32 v61, v66, v67
	global_store_dwordx4 v[56:57], v[58:61], off sc1
	s_and_saveexec_b64 s[10:11], s[8:9]
	s_cbranch_execz .LBB0_756
	v_lshl_add_u64 v[58:59], s[18:19], 0, v[144:145]
	v_mov_b32_e32 v155, v145
	v_lshl_add_u64 v[62:63], v[58:59], 0, v[154:155]
	v_lshl_add_u64 v[58:59], s[34:35], 0, v[144:145]
	v_lshl_add_u64 v[58:59], v[58:59], 0, v[154:155]
	global_load_dwordx4 v[58:61], v[58:59], off
	s_nop 0
	global_load_dwordx4 v[66:69], v[62:63], off
	s_waitcnt vmcnt(1)
	v_pk_mul_f32 v[62:63], v[52:53], v[58:59] op_sel:[1,0] op_sel_hi:[0,0]
	v_pk_mul_f32 v[76:77], v[48:49], v[60:61] op_sel:[1,0] op_sel_hi:[0,0]
	s_waitcnt vmcnt(0)
	v_mov_b32_e32 v58, v67
	v_mul_f32_e32 v72, v55, v59
	v_mul_f32_e32 v78, v55, v67
	v_mov_b32_e32 v60, v69
	v_mul_f32_e32 v80, v51, v61
	v_mul_f32_e32 v82, v51, v69
	v_pk_fma_f32 v[70:71], v[52:53], v[66:67], v[62:63] op_sel_hi:[1,0,1] neg_lo:[0,0,1] neg_hi:[0,0,1]
	v_pk_fma_f32 v[52:53], v[52:53], v[66:67], v[62:63] op_sel_hi:[1,0,1]
	v_mov_b32_e32 v66, v59
	v_pk_fma_f32 v[74:75], v[48:49], v[68:69], v[76:77] op_sel_hi:[1,0,1] neg_lo:[0,0,1] neg_hi:[0,0,1]
	v_pk_fma_f32 v[48:49], v[48:49], v[68:69], v[76:77] op_sel_hi:[1,0,1]
	v_mov_b32_e32 v68, v61
	v_pk_fma_f32 v[72:73], v[54:55], v[58:59], v[72:73] op_sel_hi:[1,1,0] neg_lo:[0,0,1] neg_hi:[0,0,1]
	v_pk_fma_f32 v[76:77], v[50:51], v[60:61], v[80:81] op_sel_hi:[1,1,0] neg_lo:[0,0,1] neg_hi:[0,0,1]
	v_pk_fma_f32 v[54:55], v[54:55], v[66:67], v[78:79] op_sel_hi:[1,1,0]
	v_mov_b32_e32 v71, v53
	v_pk_fma_f32 v[50:51], v[50:51], v[68:69], v[82:83] op_sel_hi:[1,1,0]
	v_mov_b32_e32 v75, v49
	v_mov_b32_e32 v73, v54
	v_mov_b32_e32 v77, v50
	v_mov_b64_e32 v[52:53], v[70:71]
	v_mov_b64_e32 v[48:49], v[74:75]
	v_mov_b64_e32 v[54:55], v[72:73]
	v_mov_b64_e32 v[50:51], v[76:77]
.LBB0_756:
	s_or_b64 exec, exec, s[10:11]
	v_mov_b32_e32 v65, v64
	v_mov_b32_e32 v58, v64
	v_mov_b32_e32 v59, v64
	v_pk_mul_f32 v[54:55], v[58:59], v[54:55]
	v_pk_mul_f32 v[58:59], v[58:59], v[50:51]
	v_pk_mul_f32 v[50:51], v[64:65], v[48:49]
	v_pk_mul_f32 v[52:53], v[64:65], v[52:53]
	s_nop 0
	v_cvt_pk_bf16_f32 v48, v52, v53
	v_cvt_pk_bf16_f32 v49, v54, v55
	v_cvt_pk_bf16_f32 v50, v50, v51
	v_cvt_pk_bf16_f32 v51, v58, v59
	global_store_dwordx4 v[56:57], v[48:51], off offset:256 sc1
	v_add_u32_e32 v56, 0x90, v158
	v_ashrrev_i32_e32 v57, 31, v56
	v_lshlrev_b64 v[48:49], 6, v[56:57]
	v_lshl_add_u64 v[52:53], s[38:39], 0, v[48:49]
	global_load_dwordx4 v[48:51], v[52:53], off offset:16
	s_nop 0
	global_load_dwordx4 v[52:55], v[52:53], off
	v_lshlrev_b32_e32 v57, 5, v56
	v_and_b32_e32 v57, 0x3fbe0, v57
	v_lshlrev_b32_e32 v144, 2, v57
	s_and_saveexec_b64 s[10:11], s[6:7]
	s_cbranch_execz .LBB0_758
	v_lshl_add_u64 v[58:59], s[18:19], 0, v[144:145]
	v_mov_b32_e32 v155, v145
	v_lshl_add_u64 v[62:63], v[58:59], 0, v[154:155]
	v_lshl_add_u64 v[58:59], s[34:35], 0, v[144:145]
	v_lshl_add_u64 v[58:59], v[58:59], 0, v[154:155]
	global_load_dwordx4 v[58:61], v[58:59], off
	s_nop 0
	global_load_dwordx4 v[62:65], v[62:63], off
	s_waitcnt vmcnt(1)
	v_pk_mul_f32 v[68:69], v[44:45], v[58:59] op_sel:[1,0] op_sel_hi:[0,0]
	s_waitcnt vmcnt(0)
	v_mov_b32_e32 v58, v63
	v_mul_f32_e32 v70, v47, v59
	v_pk_mul_f32 v[72:73], v[40:41], v[60:61] op_sel:[1,0] op_sel_hi:[0,0]
	v_mul_f32_e32 v74, v47, v63
	v_mov_b32_e32 v60, v65
	v_mul_f32_e32 v76, v43, v61
	v_mul_f32_e32 v78, v43, v65
	v_pk_fma_f32 v[66:67], v[44:45], v[62:63], v[68:69] op_sel_hi:[1,0,1] neg_lo:[0,0,1] neg_hi:[0,0,1]
	v_pk_fma_f32 v[44:45], v[44:45], v[62:63], v[68:69] op_sel_hi:[1,0,1]
	v_pk_fma_f32 v[68:69], v[46:47], v[58:59], v[70:71] op_sel_hi:[1,1,0] neg_lo:[0,0,1] neg_hi:[0,0,1]
	v_mov_b32_e32 v62, v59
	v_pk_fma_f32 v[70:71], v[40:41], v[64:65], v[72:73] op_sel_hi:[1,0,1] neg_lo:[0,0,1] neg_hi:[0,0,1]
	v_pk_fma_f32 v[40:41], v[40:41], v[64:65], v[72:73] op_sel_hi:[1,0,1]
	v_mov_b32_e32 v64, v61
	v_pk_fma_f32 v[72:73], v[42:43], v[60:61], v[76:77] op_sel_hi:[1,1,0] neg_lo:[0,0,1] neg_hi:[0,0,1]
	v_pk_fma_f32 v[46:47], v[46:47], v[62:63], v[74:75] op_sel_hi:[1,1,0]
	v_mov_b32_e32 v67, v45
	v_pk_fma_f32 v[42:43], v[42:43], v[64:65], v[78:79] op_sel_hi:[1,1,0]
	v_mov_b32_e32 v71, v41
	v_mov_b32_e32 v69, v46
	v_mov_b32_e32 v73, v42
	v_mov_b64_e32 v[44:45], v[66:67]
	v_mov_b64_e32 v[40:41], v[70:71]
	v_mov_b64_e32 v[46:47], v[68:69]
	v_mov_b64_e32 v[42:43], v[72:73]
.LBB0_758:
	s_or_b64 exec, exec, s[10:11]
	s_waitcnt vmcnt(0)
	v_mov_b32_e32 v58, v52
	v_mov_b32_e32 v59, v48
	v_mov_b32_e32 v48, v53
	v_mov_b32_e32 v52, v54
	v_mov_b32_e32 v53, v50
	v_mov_b32_e32 v50, v55
	v_pk_add_f32 v[48:49], v[58:59], v[48:49]
	v_pk_add_f32 v[50:51], v[52:53], v[50:51]
	s_nop 0
	v_pk_add_f32 v[48:49], v[48:49], v[50:51]
	s_nop 0
	v_add_f32_e32 v48, v48, v49
	v_fmamk_f32 v48, v48, 0x3b2aaaab, v165
	v_mul_f32_e32 v49, 0x4f800000, v48
	v_cmp_gt_f32_e32 vcc, s55, v48
	s_nop 1
	v_cndmask_b32_e32 v48, v48, v49, vcc
	v_sqrt_f32_e32 v49, v48
	s_nop 0
	v_add_u32_e32 v50, -1, v49
	v_fma_f32 v51, -v50, v49, v48
	v_cmp_ge_f32_e64 s[10:11], 0, v51
	v_add_u32_e32 v51, 1, v49
	s_nop 0
	v_cndmask_b32_e64 v50, v49, v50, s[10:11]
	v_fma_f32 v49, -v51, v49, v48
	v_cmp_lt_f32_e64 s[10:11], 0, v49
	s_nop 1
	v_cndmask_b32_e64 v49, v50, v51, s[10:11]
	v_mul_f32_e32 v50, 0x37800000, v49
	v_cndmask_b32_e32 v49, v49, v50, vcc
	v_cmp_class_f32_e32 vcc, v48, v166
	s_nop 1
	v_cndmask_b32_e32 v48, v49, v48, vcc
	v_div_scale_f32 v49, s[10:11], v48, v48, 1.0
	v_rcp_f32_e32 v50, v49
	s_nop 0
	v_fma_f32 v51, -v49, v50, 1.0
	v_fmac_f32_e32 v50, v51, v50
	v_div_scale_f32 v51, vcc, 1.0, v48, 1.0
	v_mul_f32_e32 v52, v51, v50
	v_fma_f32 v53, -v49, v52, v51
	v_fmac_f32_e32 v52, v53, v50
	v_fma_f32 v49, -v49, v52, v51
	v_div_fmas_f32 v49, v49, v50, v52
	v_div_fixup_f32 v48, v49, v48, 1.0
	v_mul_f32_e32 v48, 0x3dd53b95, v48
	v_pk_mul_f32 v[44:45], v[48:49], v[44:45] op_sel_hi:[0,1]
	v_pk_mul_f32 v[40:41], v[48:49], v[40:41] op_sel_hi:[0,1]
	v_pk_mul_f32 v[46:47], v[48:49], v[46:47] op_sel_hi:[0,1]
	v_pk_mul_f32 v[50:51], v[48:49], v[42:43] op_sel_hi:[0,1]
	v_cvt_pk_bf16_f32 v42, v44, v45
	v_cvt_pk_bf16_f32 v43, v46, v47
	v_cvt_pk_bf16_f32 v44, v40, v41
	v_mov_b64_e32 v[40:41], s[36:37]
	v_mad_i64_i32 v[40:41], s[10:11], v56, s56, v[40:41]
	v_lshl_add_u64 v[40:41], v[156:157], 1, v[40:41]
	v_cvt_pk_bf16_f32 v45, v50, v51
	global_store_dwordx4 v[40:41], v[42:45], off sc1
	s_and_saveexec_b64 s[10:11], s[8:9]
	s_cbranch_execz .LBB0_760
	v_lshl_add_u64 v[42:43], s[18:19], 0, v[144:145]
	v_mov_b32_e32 v155, v145
	v_lshl_add_u64 v[46:47], v[42:43], 0, v[154:155]
	v_lshl_add_u64 v[42:43], s[34:35], 0, v[144:145]
	v_lshl_add_u64 v[42:43], v[42:43], 0, v[154:155]
	global_load_dwordx4 v[42:45], v[42:43], off
	s_nop 0
	global_load_dwordx4 v[50:53], v[46:47], off
	s_waitcnt vmcnt(1)
	v_pk_mul_f32 v[46:47], v[36:37], v[42:43] op_sel:[1,0] op_sel_hi:[0,0]
	v_pk_mul_f32 v[60:61], v[32:33], v[44:45] op_sel:[1,0] op_sel_hi:[0,0]
	s_waitcnt vmcnt(0)
	v_mov_b32_e32 v42, v51
	v_mul_f32_e32 v56, v39, v43
	v_mul_f32_e32 v62, v39, v51
	v_mov_b32_e32 v44, v53
	v_mul_f32_e32 v64, v35, v45
	v_mul_f32_e32 v66, v35, v53
	v_pk_fma_f32 v[54:55], v[36:37], v[50:51], v[46:47] op_sel_hi:[1,0,1] neg_lo:[0,0,1] neg_hi:[0,0,1]
	v_pk_fma_f32 v[36:37], v[36:37], v[50:51], v[46:47] op_sel_hi:[1,0,1]
	v_mov_b32_e32 v50, v43
	v_pk_fma_f32 v[58:59], v[32:33], v[52:53], v[60:61] op_sel_hi:[1,0,1] neg_lo:[0,0,1] neg_hi:[0,0,1]
	v_pk_fma_f32 v[32:33], v[32:33], v[52:53], v[60:61] op_sel_hi:[1,0,1]
	v_mov_b32_e32 v52, v45
	v_pk_fma_f32 v[56:57], v[38:39], v[42:43], v[56:57] op_sel_hi:[1,1,0] neg_lo:[0,0,1] neg_hi:[0,0,1]
	v_pk_fma_f32 v[60:61], v[34:35], v[44:45], v[64:65] op_sel_hi:[1,1,0] neg_lo:[0,0,1] neg_hi:[0,0,1]
	v_pk_fma_f32 v[38:39], v[38:39], v[50:51], v[62:63] op_sel_hi:[1,1,0]
	v_mov_b32_e32 v55, v37
	v_pk_fma_f32 v[34:35], v[34:35], v[52:53], v[66:67] op_sel_hi:[1,1,0]
	v_mov_b32_e32 v59, v33
	v_mov_b32_e32 v57, v38
	v_mov_b32_e32 v61, v34
	v_mov_b64_e32 v[36:37], v[54:55]
	v_mov_b64_e32 v[32:33], v[58:59]
	v_mov_b64_e32 v[38:39], v[56:57]
	v_mov_b64_e32 v[34:35], v[60:61]
.LBB0_760:
	s_or_b64 exec, exec, s[10:11]
	v_mov_b32_e32 v49, v48
	v_mov_b32_e32 v42, v48
	v_mov_b32_e32 v43, v48
	v_pk_mul_f32 v[38:39], v[42:43], v[38:39]
	v_pk_mul_f32 v[42:43], v[42:43], v[34:35]
	v_pk_mul_f32 v[34:35], v[48:49], v[32:33]
	v_pk_mul_f32 v[36:37], v[48:49], v[36:37]
	s_nop 0
	v_cvt_pk_bf16_f32 v32, v36, v37
	v_cvt_pk_bf16_f32 v33, v38, v39
	v_cvt_pk_bf16_f32 v34, v34, v35
	v_cvt_pk_bf16_f32 v35, v42, v43
	global_store_dwordx4 v[40:41], v[32:35], off offset:256 sc1
	v_add_u32_e32 v40, 0xa0, v158
	v_ashrrev_i32_e32 v41, 31, v40
	v_lshlrev_b64 v[32:33], 6, v[40:41]
	v_lshl_add_u64 v[36:37], s[38:39], 0, v[32:33]
	global_load_dwordx4 v[32:35], v[36:37], off offset:16
	s_nop 0
	global_load_dwordx4 v[36:39], v[36:37], off
	v_lshlrev_b32_e32 v41, 5, v40
	v_and_b32_e32 v41, 0x3fde0, v41
	v_lshlrev_b32_e32 v144, 2, v41
	s_and_saveexec_b64 s[10:11], s[6:7]
	s_cbranch_execz .LBB0_762
	v_lshl_add_u64 v[42:43], s[18:19], 0, v[144:145]
	v_mov_b32_e32 v155, v145
	v_lshl_add_u64 v[46:47], v[42:43], 0, v[154:155]
	v_lshl_add_u64 v[42:43], s[34:35], 0, v[144:145]
	v_lshl_add_u64 v[42:43], v[42:43], 0, v[154:155]
	global_load_dwordx4 v[42:45], v[42:43], off
	s_nop 0
	global_load_dwordx4 v[46:49], v[46:47], off
	s_waitcnt vmcnt(1)
	v_pk_mul_f32 v[52:53], v[28:29], v[42:43] op_sel:[1,0] op_sel_hi:[0,0]
	s_waitcnt vmcnt(0)
	v_mov_b32_e32 v42, v47
	v_mul_f32_e32 v54, v31, v43
	v_pk_mul_f32 v[56:57], v[24:25], v[44:45] op_sel:[1,0] op_sel_hi:[0,0]
	v_mul_f32_e32 v58, v31, v47
	v_mov_b32_e32 v44, v49
	v_mul_f32_e32 v60, v27, v45
	v_mul_f32_e32 v62, v27, v49
	v_pk_fma_f32 v[50:51], v[28:29], v[46:47], v[52:53] op_sel_hi:[1,0,1] neg_lo:[0,0,1] neg_hi:[0,0,1]
	v_pk_fma_f32 v[28:29], v[28:29], v[46:47], v[52:53] op_sel_hi:[1,0,1]
	v_pk_fma_f32 v[52:53], v[30:31], v[42:43], v[54:55] op_sel_hi:[1,1,0] neg_lo:[0,0,1] neg_hi:[0,0,1]
	v_mov_b32_e32 v46, v43
	v_pk_fma_f32 v[54:55], v[24:25], v[48:49], v[56:57] op_sel_hi:[1,0,1] neg_lo:[0,0,1] neg_hi:[0,0,1]
	v_pk_fma_f32 v[24:25], v[24:25], v[48:49], v[56:57] op_sel_hi:[1,0,1]
	v_mov_b32_e32 v48, v45
	v_pk_fma_f32 v[56:57], v[26:27], v[44:45], v[60:61] op_sel_hi:[1,1,0] neg_lo:[0,0,1] neg_hi:[0,0,1]
	v_pk_fma_f32 v[30:31], v[30:31], v[46:47], v[58:59] op_sel_hi:[1,1,0]
	v_mov_b32_e32 v51, v29
	v_pk_fma_f32 v[26:27], v[26:27], v[48:49], v[62:63] op_sel_hi:[1,1,0]
	v_mov_b32_e32 v55, v25
	v_mov_b32_e32 v53, v30
	v_mov_b32_e32 v57, v26
	v_mov_b64_e32 v[28:29], v[50:51]
	v_mov_b64_e32 v[24:25], v[54:55]
	v_mov_b64_e32 v[30:31], v[52:53]
	v_mov_b64_e32 v[26:27], v[56:57]
.LBB0_762:
	s_or_b64 exec, exec, s[10:11]
	s_waitcnt vmcnt(0)
	v_mov_b32_e32 v42, v36
	v_mov_b32_e32 v43, v32
	v_mov_b32_e32 v32, v37
	v_mov_b32_e32 v36, v38
	v_mov_b32_e32 v37, v34
	v_mov_b32_e32 v34, v39
	v_pk_add_f32 v[32:33], v[42:43], v[32:33]
	v_pk_add_f32 v[34:35], v[36:37], v[34:35]
	s_nop 0
	v_pk_add_f32 v[32:33], v[32:33], v[34:35]
	s_nop 0
	v_add_f32_e32 v32, v32, v33
	v_fmamk_f32 v32, v32, 0x3b2aaaab, v165
	v_mul_f32_e32 v33, 0x4f800000, v32
	v_cmp_gt_f32_e32 vcc, s55, v32
	s_nop 1
	v_cndmask_b32_e32 v32, v32, v33, vcc
	v_sqrt_f32_e32 v33, v32
	s_nop 0
	v_add_u32_e32 v34, -1, v33
	v_fma_f32 v35, -v34, v33, v32
	v_cmp_ge_f32_e64 s[10:11], 0, v35
	v_add_u32_e32 v35, 1, v33
	s_nop 0
	v_cndmask_b32_e64 v34, v33, v34, s[10:11]
	v_fma_f32 v33, -v35, v33, v32
	v_cmp_lt_f32_e64 s[10:11], 0, v33
	s_nop 1
	v_cndmask_b32_e64 v33, v34, v35, s[10:11]
	v_mul_f32_e32 v34, 0x37800000, v33
	v_cndmask_b32_e32 v33, v33, v34, vcc
	v_cmp_class_f32_e32 vcc, v32, v166
	s_nop 1
	v_cndmask_b32_e32 v32, v33, v32, vcc
	v_div_scale_f32 v33, s[10:11], v32, v32, 1.0
	v_rcp_f32_e32 v34, v33
	s_nop 0
	v_fma_f32 v35, -v33, v34, 1.0
	v_fmac_f32_e32 v34, v35, v34
	v_div_scale_f32 v35, vcc, 1.0, v32, 1.0
	v_mul_f32_e32 v36, v35, v34
	v_fma_f32 v37, -v33, v36, v35
	v_fmac_f32_e32 v36, v37, v34
	v_fma_f32 v33, -v33, v36, v35
	v_div_fmas_f32 v33, v33, v34, v36
	v_div_fixup_f32 v32, v33, v32, 1.0
	v_mul_f32_e32 v32, 0x3dd53b95, v32
	v_pk_mul_f32 v[28:29], v[32:33], v[28:29] op_sel_hi:[0,1]
	v_pk_mul_f32 v[24:25], v[32:33], v[24:25] op_sel_hi:[0,1]
	v_pk_mul_f32 v[30:31], v[32:33], v[30:31] op_sel_hi:[0,1]
	v_pk_mul_f32 v[34:35], v[32:33], v[26:27] op_sel_hi:[0,1]
	v_cvt_pk_bf16_f32 v26, v28, v29
	v_cvt_pk_bf16_f32 v27, v30, v31
	v_cvt_pk_bf16_f32 v28, v24, v25
	v_mov_b64_e32 v[24:25], s[36:37]
	v_mad_i64_i32 v[24:25], s[10:11], v40, s56, v[24:25]
	v_lshl_add_u64 v[24:25], v[156:157], 1, v[24:25]
	v_cvt_pk_bf16_f32 v29, v34, v35
	global_store_dwordx4 v[24:25], v[26:29], off sc1
	s_and_saveexec_b64 s[10:11], s[8:9]
	s_cbranch_execz .LBB0_764
	v_lshl_add_u64 v[26:27], s[18:19], 0, v[144:145]
	v_mov_b32_e32 v155, v145
	v_lshl_add_u64 v[30:31], v[26:27], 0, v[154:155]
	v_lshl_add_u64 v[26:27], s[34:35], 0, v[144:145]
	v_lshl_add_u64 v[26:27], v[26:27], 0, v[154:155]
	global_load_dwordx4 v[26:29], v[26:27], off
	s_nop 0
	global_load_dwordx4 v[34:37], v[30:31], off
	s_waitcnt vmcnt(1)
	v_pk_mul_f32 v[30:31], v[20:21], v[26:27] op_sel:[1,0] op_sel_hi:[0,0]
	v_pk_mul_f32 v[44:45], v[16:17], v[28:29] op_sel:[1,0] op_sel_hi:[0,0]
	s_waitcnt vmcnt(0)
	v_mov_b32_e32 v26, v35
	v_mul_f32_e32 v40, v23, v27
	v_mul_f32_e32 v46, v23, v35
	v_mov_b32_e32 v28, v37
	v_mul_f32_e32 v48, v19, v29
	v_mul_f32_e32 v50, v19, v37
	v_pk_fma_f32 v[38:39], v[20:21], v[34:35], v[30:31] op_sel_hi:[1,0,1] neg_lo:[0,0,1] neg_hi:[0,0,1]
	v_pk_fma_f32 v[20:21], v[20:21], v[34:35], v[30:31] op_sel_hi:[1,0,1]
	v_mov_b32_e32 v34, v27
	v_pk_fma_f32 v[42:43], v[16:17], v[36:37], v[44:45] op_sel_hi:[1,0,1] neg_lo:[0,0,1] neg_hi:[0,0,1]
	v_pk_fma_f32 v[16:17], v[16:17], v[36:37], v[44:45] op_sel_hi:[1,0,1]
	v_mov_b32_e32 v36, v29
	v_pk_fma_f32 v[40:41], v[22:23], v[26:27], v[40:41] op_sel_hi:[1,1,0] neg_lo:[0,0,1] neg_hi:[0,0,1]
	v_pk_fma_f32 v[44:45], v[18:19], v[28:29], v[48:49] op_sel_hi:[1,1,0] neg_lo:[0,0,1] neg_hi:[0,0,1]
	v_pk_fma_f32 v[22:23], v[22:23], v[34:35], v[46:47] op_sel_hi:[1,1,0]
	v_mov_b32_e32 v39, v21
	v_pk_fma_f32 v[18:19], v[18:19], v[36:37], v[50:51] op_sel_hi:[1,1,0]
	v_mov_b32_e32 v43, v17
	v_mov_b32_e32 v41, v22
	v_mov_b32_e32 v45, v18
	v_mov_b64_e32 v[20:21], v[38:39]
	v_mov_b64_e32 v[16:17], v[42:43]
	v_mov_b64_e32 v[22:23], v[40:41]
	v_mov_b64_e32 v[18:19], v[44:45]
.LBB0_764:
	s_or_b64 exec, exec, s[10:11]
	v_mov_b32_e32 v33, v32
	v_mov_b32_e32 v26, v32
	v_mov_b32_e32 v27, v32
	v_pk_mul_f32 v[22:23], v[26:27], v[22:23]
	v_pk_mul_f32 v[26:27], v[26:27], v[18:19]
	v_pk_mul_f32 v[18:19], v[32:33], v[16:17]
	v_pk_mul_f32 v[20:21], v[32:33], v[20:21]
	s_nop 0
	v_cvt_pk_bf16_f32 v16, v20, v21
	v_cvt_pk_bf16_f32 v17, v22, v23
	v_cvt_pk_bf16_f32 v18, v18, v19
	v_cvt_pk_bf16_f32 v19, v26, v27
	global_store_dwordx4 v[24:25], v[16:19], off offset:256 sc1
	v_add_u32_e32 v24, 0xb0, v158
	v_ashrrev_i32_e32 v25, 31, v24
	v_lshlrev_b64 v[16:17], 6, v[24:25]
	v_lshl_add_u64 v[20:21], s[38:39], 0, v[16:17]
	global_load_dwordx4 v[16:19], v[20:21], off offset:16
	s_nop 0
	global_load_dwordx4 v[20:23], v[20:21], off
	v_lshlrev_b32_e32 v25, 5, v24
	v_and_b32_e32 v25, 0x3ffe0, v25
	v_lshlrev_b32_e32 v144, 2, v25
	s_and_saveexec_b64 s[10:11], s[6:7]
	s_cbranch_execz .LBB0_766
	v_lshl_add_u64 v[26:27], s[18:19], 0, v[144:145]
	v_mov_b32_e32 v155, v145
	v_lshl_add_u64 v[30:31], v[26:27], 0, v[154:155]
	v_lshl_add_u64 v[26:27], s[34:35], 0, v[144:145]
	v_lshl_add_u64 v[26:27], v[26:27], 0, v[154:155]
	global_load_dwordx4 v[26:29], v[26:27], off
	s_nop 0
	global_load_dwordx4 v[30:33], v[30:31], off
	s_waitcnt vmcnt(1)
	v_pk_mul_f32 v[36:37], v[12:13], v[26:27] op_sel:[1,0] op_sel_hi:[0,0]
	s_waitcnt vmcnt(0)
	v_mov_b32_e32 v26, v31
	v_mul_f32_e32 v38, v15, v27
	v_pk_mul_f32 v[40:41], v[8:9], v[28:29] op_sel:[1,0] op_sel_hi:[0,0]
	v_mul_f32_e32 v42, v15, v31
	v_mov_b32_e32 v28, v33
	v_mul_f32_e32 v44, v11, v29
	v_mul_f32_e32 v46, v11, v33
	v_pk_fma_f32 v[34:35], v[12:13], v[30:31], v[36:37] op_sel_hi:[1,0,1] neg_lo:[0,0,1] neg_hi:[0,0,1]
	v_pk_fma_f32 v[12:13], v[12:13], v[30:31], v[36:37] op_sel_hi:[1,0,1]
	v_pk_fma_f32 v[36:37], v[14:15], v[26:27], v[38:39] op_sel_hi:[1,1,0] neg_lo:[0,0,1] neg_hi:[0,0,1]
	v_mov_b32_e32 v30, v27
	v_pk_fma_f32 v[38:39], v[8:9], v[32:33], v[40:41] op_sel_hi:[1,0,1] neg_lo:[0,0,1] neg_hi:[0,0,1]
	v_pk_fma_f32 v[8:9], v[8:9], v[32:33], v[40:41] op_sel_hi:[1,0,1]
	v_mov_b32_e32 v32, v29
	v_pk_fma_f32 v[40:41], v[10:11], v[28:29], v[44:45] op_sel_hi:[1,1,0] neg_lo:[0,0,1] neg_hi:[0,0,1]
	v_pk_fma_f32 v[14:15], v[14:15], v[30:31], v[42:43] op_sel_hi:[1,1,0]
	v_mov_b32_e32 v35, v13
	v_pk_fma_f32 v[10:11], v[10:11], v[32:33], v[46:47] op_sel_hi:[1,1,0]
	v_mov_b32_e32 v39, v9
	v_mov_b32_e32 v37, v14
	v_mov_b32_e32 v41, v10
	v_mov_b64_e32 v[12:13], v[34:35]
	v_mov_b64_e32 v[8:9], v[38:39]
	v_mov_b64_e32 v[14:15], v[36:37]
	v_mov_b64_e32 v[10:11], v[40:41]
.LBB0_766:
	s_or_b64 exec, exec, s[10:11]
	s_waitcnt vmcnt(0)
	v_mov_b32_e32 v26, v20
	v_mov_b32_e32 v27, v16
	v_mov_b32_e32 v16, v21
	v_mov_b32_e32 v20, v22
	v_mov_b32_e32 v21, v18
	v_mov_b32_e32 v18, v23
	v_pk_add_f32 v[16:17], v[26:27], v[16:17]
	v_pk_add_f32 v[18:19], v[20:21], v[18:19]
	s_nop 0
	v_pk_add_f32 v[16:17], v[16:17], v[18:19]
	s_nop 0
	v_add_f32_e32 v16, v16, v17
	v_fmamk_f32 v16, v16, 0x3b2aaaab, v165
	v_mul_f32_e32 v17, 0x4f800000, v16
	v_cmp_gt_f32_e32 vcc, s55, v16
	s_nop 1
	v_cndmask_b32_e32 v16, v16, v17, vcc
	v_sqrt_f32_e32 v17, v16
	s_nop 0
	v_add_u32_e32 v18, -1, v17
	v_fma_f32 v19, -v18, v17, v16
	v_cmp_ge_f32_e64 s[6:7], 0, v19
	v_add_u32_e32 v19, 1, v17
	s_nop 0
	v_cndmask_b32_e64 v18, v17, v18, s[6:7]
	v_fma_f32 v17, -v19, v17, v16
	v_cmp_lt_f32_e64 s[6:7], 0, v17
	s_nop 1
	v_cndmask_b32_e64 v17, v18, v19, s[6:7]
	v_mul_f32_e32 v18, 0x37800000, v17
	v_cndmask_b32_e32 v17, v17, v18, vcc
	v_cmp_class_f32_e32 vcc, v16, v166
	s_nop 1
	v_cndmask_b32_e32 v16, v17, v16, vcc
	v_div_scale_f32 v17, s[6:7], v16, v16, 1.0
	v_rcp_f32_e32 v18, v17
	s_nop 0
	v_fma_f32 v19, -v17, v18, 1.0
	v_fmac_f32_e32 v18, v19, v18
	v_div_scale_f32 v19, vcc, 1.0, v16, 1.0
	v_mul_f32_e32 v20, v19, v18
	v_fma_f32 v21, -v17, v20, v19
	v_fmac_f32_e32 v20, v21, v18
	v_fma_f32 v17, -v17, v20, v19
	v_div_fmas_f32 v17, v17, v18, v20
	v_div_fixup_f32 v16, v17, v16, 1.0
	v_mul_f32_e32 v16, 0x3dd53b95, v16
	v_pk_mul_f32 v[12:13], v[16:17], v[12:13] op_sel_hi:[0,1]
	v_pk_mul_f32 v[8:9], v[16:17], v[8:9] op_sel_hi:[0,1]
	v_pk_mul_f32 v[14:15], v[16:17], v[14:15] op_sel_hi:[0,1]
	v_pk_mul_f32 v[18:19], v[16:17], v[10:11] op_sel_hi:[0,1]
	v_cvt_pk_bf16_f32 v10, v12, v13
	v_cvt_pk_bf16_f32 v11, v14, v15
	v_cvt_pk_bf16_f32 v12, v8, v9
	v_mov_b64_e32 v[8:9], s[36:37]
	v_mad_i64_i32 v[8:9], s[6:7], v24, s56, v[8:9]
	v_lshl_add_u64 v[8:9], v[156:157], 1, v[8:9]
	v_cvt_pk_bf16_f32 v13, v18, v19
	global_store_dwordx4 v[8:9], v[10:13], off sc1
	s_and_saveexec_b64 s[6:7], s[8:9]
	s_cbranch_execz .LBB0_768
	v_lshl_add_u64 v[10:11], s[18:19], 0, v[144:145]
	v_mov_b32_e32 v155, v145
	v_lshl_add_u64 v[14:15], v[10:11], 0, v[154:155]
	v_lshl_add_u64 v[10:11], s[34:35], 0, v[144:145]
	v_lshl_add_u64 v[10:11], v[10:11], 0, v[154:155]
	global_load_dwordx4 v[10:13], v[10:11], off
	s_nop 0
	global_load_dwordx4 v[18:21], v[14:15], off
	s_waitcnt vmcnt(1)
	v_pk_mul_f32 v[14:15], v[4:5], v[10:11] op_sel:[1,0] op_sel_hi:[0,0]
	v_pk_mul_f32 v[28:29], v[0:1], v[12:13] op_sel:[1,0] op_sel_hi:[0,0]
	s_waitcnt vmcnt(0)
	v_mov_b32_e32 v10, v19
	v_mul_f32_e32 v24, v7, v11
	v_mul_f32_e32 v30, v7, v19
	v_mov_b32_e32 v12, v21
	v_mul_f32_e32 v32, v3, v13
	v_mul_f32_e32 v34, v3, v21
	v_pk_fma_f32 v[22:23], v[4:5], v[18:19], v[14:15] op_sel_hi:[1,0,1] neg_lo:[0,0,1] neg_hi:[0,0,1]
	v_pk_fma_f32 v[4:5], v[4:5], v[18:19], v[14:15] op_sel_hi:[1,0,1]
	v_mov_b32_e32 v18, v11
	v_pk_fma_f32 v[26:27], v[0:1], v[20:21], v[28:29] op_sel_hi:[1,0,1] neg_lo:[0,0,1] neg_hi:[0,0,1]
	v_pk_fma_f32 v[0:1], v[0:1], v[20:21], v[28:29] op_sel_hi:[1,0,1]
	v_mov_b32_e32 v20, v13
	v_pk_fma_f32 v[24:25], v[6:7], v[10:11], v[24:25] op_sel_hi:[1,1,0] neg_lo:[0,0,1] neg_hi:[0,0,1]
	v_pk_fma_f32 v[28:29], v[2:3], v[12:13], v[32:33] op_sel_hi:[1,1,0] neg_lo:[0,0,1] neg_hi:[0,0,1]
	v_pk_fma_f32 v[6:7], v[6:7], v[18:19], v[30:31] op_sel_hi:[1,1,0]
	v_mov_b32_e32 v23, v5
	v_pk_fma_f32 v[2:3], v[2:3], v[20:21], v[34:35] op_sel_hi:[1,1,0]
	v_mov_b32_e32 v27, v1
	v_mov_b32_e32 v25, v6
	v_mov_b32_e32 v29, v2
	v_mov_b64_e32 v[4:5], v[22:23]
	v_mov_b64_e32 v[0:1], v[26:27]
	v_mov_b64_e32 v[6:7], v[24:25]
	v_mov_b64_e32 v[2:3], v[28:29]
.LBB0_768:
	s_or_b64 exec, exec, s[6:7]
	v_mov_b32_e32 v17, v16
	v_mov_b32_e32 v10, v16
	v_mov_b32_e32 v11, v16
	v_pk_mul_f32 v[6:7], v[10:11], v[6:7]
	v_pk_mul_f32 v[10:11], v[10:11], v[2:3]
	v_pk_mul_f32 v[2:3], v[16:17], v[0:1]
	v_pk_mul_f32 v[4:5], v[16:17], v[4:5]
	s_and_b64 vcc, exec, s[4:5]
	v_cvt_pk_bf16_f32 v0, v4, v5
	v_cvt_pk_bf16_f32 v1, v6, v7
	v_cvt_pk_bf16_f32 v2, v2, v3
	v_cvt_pk_bf16_f32 v3, v10, v11
	global_store_dwordx4 v[8:9], v[0:3], off offset:256 sc1
	s_mov_b64 s[4:5], -1
	s_cbranch_vccnz .LBB0_723
	s_andn2_b64 vcc, exec, s[16:17]
	s_cbranch_vccnz .LBB0_722
	s_barrier
	s_branch .LBB0_722

.LBB0_798:
	s_lshl_b32 s6, s55, 8
	v_mov_b32_e32 v155, v148
	s_add_i32 s6, s6, s30
	s_nop 0
	v_and_or_b32 v146, v155, 15, s6
	v_ashrrev_i32_e32 v147, 31, v146
	v_lshlrev_b64 v[144:145], 6, v[146:147]
	v_lshl_add_u64 v[144:145], s[18:19], 0, v[144:145]
	global_load_dwordx4 v[156:159], v[144:145], off offset:32
	global_load_dwordx4 v[160:163], v[144:145], off offset:48
	v_lshlrev_b64 v[166:167], 12, v[146:147]
	v_ashrrev_i32_e32 v144, 1, v155
	s_lshl_b32 s6, s56, 8
	s_or_b32 s6, s6, s31
	v_and_b32_e32 v144, -8, v144
	v_add_u32_e32 v144, s6, v144
	v_ashrrev_i32_e32 v145, 31, v144
	v_or_b32_e32 v164, 16, v146
	v_lshl_add_u64 v[166:167], s[16:17], 0, v[166:167]
	v_lshlrev_b64 v[144:145], 1, v[144:145]
	v_ashrrev_i32_e32 v165, 31, v164
	s_waitcnt vmcnt(0)
	v_mov_b32_e32 v168, v156
	v_mov_b32_e32 v169, v160
	v_mov_b32_e32 v160, v157
	v_mov_b32_e32 v156, v158
	v_mov_b32_e32 v157, v162
	v_mov_b32_e32 v162, v159
	v_pk_add_f32 v[158:159], v[168:169], v[160:161]
	v_pk_add_f32 v[156:157], v[156:157], v[162:163]
	s_nop 0
	v_pk_add_f32 v[156:157], v[158:159], v[156:157]
	s_nop 0
	v_add_f32_e32 v147, v156, v157
	v_fmamk_f32 v147, v147, 0x3b800000, v153
	v_mul_f32_e32 v155, 0x4f800000, v147
	v_cmp_gt_f32_e32 vcc, s52, v147
	v_lshlrev_b64 v[156:157], 6, v[164:165]
	v_lshl_add_u64 v[156:157], s[18:19], 0, v[156:157]
	v_cndmask_b32_e32 v147, v147, v155, vcc
	v_sqrt_f32_e32 v155, v147
	s_nop 0
	v_add_u32_e32 v158, -1, v155
	v_add_u32_e32 v159, 1, v155
	v_fma_f32 v160, -v158, v155, v147
	v_fma_f32 v161, -v159, v155, v147
	v_cmp_ge_f32_e64 s[6:7], 0, v160
	s_nop 1
	v_cndmask_b32_e64 v155, v155, v158, s[6:7]
	v_cmp_lt_f32_e64 s[6:7], 0, v161
	s_nop 1
	v_cndmask_b32_e64 v155, v155, v159, s[6:7]
	v_mul_f32_e32 v158, 0x37800000, v155
	v_cndmask_b32_e32 v155, v155, v158, vcc
	v_cmp_class_f32_e32 vcc, v147, v154
	v_lshl_add_u64 v[158:159], v[166:167], 0, v[144:145]
	s_nop 0
	v_cndmask_b32_e32 v147, v155, v147, vcc
	v_div_scale_f32 v155, s[6:7], v147, v147, 1.0
	v_rcp_f32_e32 v160, v155
	v_div_scale_f32 v161, vcc, 1.0, v147, 1.0
	v_fma_f32 v162, -v155, v160, 1.0
	v_fmac_f32_e32 v160, v162, v160
	v_mul_f32_e32 v162, v161, v160
	v_fma_f32 v163, -v155, v162, v161
	v_fmac_f32_e32 v162, v163, v160
	v_fma_f32 v155, -v155, v162, v161
	v_div_fmas_f32 v155, v155, v160, v162
	v_div_fixup_f32 v160, v155, v147, 1.0
	v_pk_mul_f32 v[122:123], v[122:123], v[160:161] op_sel_hi:[1,0]
	v_pk_mul_f32 v[120:121], v[120:121], v[160:161] op_sel_hi:[1,0]
	v_pk_mul_f32 v[126:127], v[126:127], v[160:161] op_sel_hi:[1,0]
	v_pk_mul_f32 v[124:125], v[124:125], v[160:161] op_sel_hi:[1,0]
	v_pk_mul_f32 v[118:119], v[118:119], v[160:161] op_sel_hi:[1,0]
	v_pk_mul_f32 v[116:117], v[116:117], v[160:161] op_sel_hi:[1,0]
	v_pk_mul_f32 v[162:163], v[114:115], v[160:161] op_sel_hi:[1,0]
	v_pk_mul_f32 v[160:161], v[112:113], v[160:161] op_sel_hi:[1,0]
	v_cvt_pk_bf16_f32 v112, v120, v121
	v_cvt_pk_bf16_f32 v113, v122, v123
	v_cvt_pk_bf16_f32 v114, v124, v125
	v_cvt_pk_bf16_f32 v115, v126, v127
	global_store_dwordx4 v[158:159], v[112:115], off sc1
	v_lshlrev_b64 v[122:123], 12, v[164:165]
	v_or_b32_e32 v120, 32, v146
	v_cvt_pk_bf16_f32 v112, v116, v117
	v_cvt_pk_bf16_f32 v113, v118, v119
	v_cvt_pk_bf16_f32 v114, v160, v161
	v_cvt_pk_bf16_f32 v115, v162, v163
	global_store_dwordx4 v[158:159], v[112:115], off offset:256 sc1
	global_load_dwordx4 v[112:115], v[156:157], off offset:32
	global_load_dwordx4 v[116:119], v[156:157], off offset:48
	v_ashrrev_i32_e32 v121, 31, v120
	s_waitcnt vmcnt(1)
	v_mov_b32_e32 v124, v112
	s_waitcnt vmcnt(0)
	v_mov_b32_e32 v125, v116
	v_mov_b32_e32 v116, v113
	v_mov_b32_e32 v112, v114
	v_mov_b32_e32 v113, v118
	v_mov_b32_e32 v118, v115
	v_pk_add_f32 v[114:115], v[124:125], v[116:117]
	v_pk_add_f32 v[112:113], v[112:113], v[118:119]
	s_nop 0
	v_pk_add_f32 v[112:113], v[114:115], v[112:113]
	v_lshl_add_u64 v[114:115], s[16:17], 0, v[122:123]
	v_add_f32_e32 v112, v112, v113
	v_fmamk_f32 v112, v112, 0x3b800000, v153
	v_mul_f32_e32 v113, 0x4f800000, v112
	v_cmp_gt_f32_e32 vcc, s52, v112
	v_lshl_add_u64 v[114:115], v[114:115], 0, v[144:145]
	s_nop 0
	v_cndmask_b32_e32 v116, v112, v113, vcc
	v_sqrt_f32_e32 v117, v116
	v_lshlrev_b64 v[112:113], 6, v[120:121]
	v_lshl_add_u64 v[112:113], s[18:19], 0, v[112:113]
	v_add_u32_e32 v118, -1, v117
	v_add_u32_e32 v119, 1, v117
	v_fma_f32 v122, -v118, v117, v116
	v_fma_f32 v123, -v119, v117, v116
	v_cmp_ge_f32_e64 s[6:7], 0, v122
	s_nop 1
	v_cndmask_b32_e64 v117, v117, v118, s[6:7]
	v_cmp_lt_f32_e64 s[6:7], 0, v123
	s_nop 1
	v_cndmask_b32_e64 v117, v117, v119, s[6:7]
	v_mul_f32_e32 v118, 0x37800000, v117
	v_cndmask_b32_e32 v117, v117, v118, vcc
	v_cmp_class_f32_e32 vcc, v116, v154
	s_nop 1
	v_cndmask_b32_e32 v116, v117, v116, vcc
	v_div_scale_f32 v117, s[6:7], v116, v116, 1.0
	v_rcp_f32_e32 v118, v117
	v_div_scale_f32 v119, vcc, 1.0, v116, 1.0
	v_fma_f32 v122, -v117, v118, 1.0
	v_fmac_f32_e32 v118, v122, v118
	v_mul_f32_e32 v122, v119, v118
	v_fma_f32 v123, -v117, v122, v119
	v_fmac_f32_e32 v122, v123, v118
	v_fma_f32 v117, -v117, v122, v119
	v_div_fmas_f32 v117, v117, v118, v122
	v_div_fixup_f32 v116, v117, v116, 1.0
	v_pk_mul_f32 v[110:111], v[110:111], v[116:117] op_sel_hi:[1,0]
	v_pk_mul_f32 v[108:109], v[108:109], v[116:117] op_sel_hi:[1,0]
	v_pk_mul_f32 v[106:107], v[106:107], v[116:117] op_sel_hi:[1,0]
	v_pk_mul_f32 v[104:105], v[104:105], v[116:117] op_sel_hi:[1,0]
	v_pk_mul_f32 v[102:103], v[102:103], v[116:117] op_sel_hi:[1,0]
	v_pk_mul_f32 v[100:101], v[100:101], v[116:117] op_sel_hi:[1,0]
	v_pk_mul_f32 v[118:119], v[98:99], v[116:117] op_sel_hi:[1,0]
	v_pk_mul_f32 v[116:117], v[96:97], v[116:117] op_sel_hi:[1,0]
	v_cvt_pk_bf16_f32 v96, v108, v109
	v_cvt_pk_bf16_f32 v97, v110, v111
	v_cvt_pk_bf16_f32 v98, v104, v105
	v_cvt_pk_bf16_f32 v99, v106, v107
	global_store_dwordx4 v[114:115], v[96:99], off sc1
	v_lshlrev_b64 v[106:107], 12, v[120:121]
	v_or_b32_e32 v104, 48, v146
	v_cvt_pk_bf16_f32 v96, v100, v101
	v_cvt_pk_bf16_f32 v97, v102, v103
	v_cvt_pk_bf16_f32 v98, v116, v117
	v_cvt_pk_bf16_f32 v99, v118, v119
	global_store_dwordx4 v[114:115], v[96:99], off offset:256 sc1
	global_load_dwordx4 v[96:99], v[112:113], off offset:32
	global_load_dwordx4 v[100:103], v[112:113], off offset:48
	v_ashrrev_i32_e32 v105, 31, v104
	s_waitcnt vmcnt(1)
	v_mov_b32_e32 v108, v96
	s_waitcnt vmcnt(0)
	v_mov_b32_e32 v109, v100
	v_mov_b32_e32 v100, v97
	v_mov_b32_e32 v96, v98
	v_mov_b32_e32 v97, v102
	v_mov_b32_e32 v102, v99
	v_pk_add_f32 v[98:99], v[108:109], v[100:101]
	v_pk_add_f32 v[96:97], v[96:97], v[102:103]
	s_nop 0
	v_pk_add_f32 v[96:97], v[98:99], v[96:97]
	v_lshl_add_u64 v[98:99], s[16:17], 0, v[106:107]
	v_add_f32_e32 v96, v96, v97
	v_fmamk_f32 v96, v96, 0x3b800000, v153
	v_mul_f32_e32 v97, 0x4f800000, v96
	v_cmp_gt_f32_e32 vcc, s52, v96
	v_lshl_add_u64 v[98:99], v[98:99], 0, v[144:145]
	s_nop 0
	v_cndmask_b32_e32 v100, v96, v97, vcc
	v_sqrt_f32_e32 v101, v100
	v_lshlrev_b64 v[96:97], 6, v[104:105]
	v_lshl_add_u64 v[96:97], s[18:19], 0, v[96:97]
	v_add_u32_e32 v102, -1, v101
	v_add_u32_e32 v103, 1, v101
	v_fma_f32 v106, -v102, v101, v100
	v_fma_f32 v107, -v103, v101, v100
	v_cmp_ge_f32_e64 s[6:7], 0, v106
	s_nop 1
	v_cndmask_b32_e64 v101, v101, v102, s[6:7]
	v_cmp_lt_f32_e64 s[6:7], 0, v107
	s_nop 1
	v_cndmask_b32_e64 v101, v101, v103, s[6:7]
	v_mul_f32_e32 v102, 0x37800000, v101
	v_cndmask_b32_e32 v101, v101, v102, vcc
	v_cmp_class_f32_e32 vcc, v100, v154
	s_nop 1
	v_cndmask_b32_e32 v100, v101, v100, vcc
	v_div_scale_f32 v101, s[6:7], v100, v100, 1.0
	v_rcp_f32_e32 v102, v101
	v_div_scale_f32 v103, vcc, 1.0, v100, 1.0
	v_fma_f32 v106, -v101, v102, 1.0
	v_fmac_f32_e32 v102, v106, v102
	v_mul_f32_e32 v106, v103, v102
	v_fma_f32 v107, -v101, v106, v103
	v_fmac_f32_e32 v106, v107, v102
	v_fma_f32 v101, -v101, v106, v103
	v_div_fmas_f32 v101, v101, v102, v106
	v_div_fixup_f32 v100, v101, v100, 1.0
	v_pk_mul_f32 v[94:95], v[94:95], v[100:101] op_sel_hi:[1,0]
	v_pk_mul_f32 v[92:93], v[92:93], v[100:101] op_sel_hi:[1,0]
	v_pk_mul_f32 v[90:91], v[90:91], v[100:101] op_sel_hi:[1,0]
	v_pk_mul_f32 v[88:89], v[88:89], v[100:101] op_sel_hi:[1,0]
	v_pk_mul_f32 v[86:87], v[86:87], v[100:101] op_sel_hi:[1,0]
	v_pk_mul_f32 v[84:85], v[84:85], v[100:101] op_sel_hi:[1,0]
	v_pk_mul_f32 v[102:103], v[82:83], v[100:101] op_sel_hi:[1,0]
	v_pk_mul_f32 v[100:101], v[80:81], v[100:101] op_sel_hi:[1,0]
	v_cvt_pk_bf16_f32 v80, v92, v93
	v_cvt_pk_bf16_f32 v81, v94, v95
	v_cvt_pk_bf16_f32 v82, v88, v89
	v_cvt_pk_bf16_f32 v83, v90, v91
	global_store_dwordx4 v[98:99], v[80:83], off sc1
	v_lshlrev_b64 v[90:91], 12, v[104:105]
	v_add_u32_e32 v88, 0x80, v146
	v_cvt_pk_bf16_f32 v80, v84, v85
	v_cvt_pk_bf16_f32 v81, v86, v87
	v_cvt_pk_bf16_f32 v82, v100, v101
	v_cvt_pk_bf16_f32 v83, v102, v103
	global_store_dwordx4 v[98:99], v[80:83], off offset:256 sc1
	global_load_dwordx4 v[80:83], v[96:97], off offset:32
	global_load_dwordx4 v[84:87], v[96:97], off offset:48
	v_ashrrev_i32_e32 v89, 31, v88
	s_waitcnt vmcnt(1)
	v_mov_b32_e32 v92, v80
	s_waitcnt vmcnt(0)
	v_mov_b32_e32 v93, v84
	v_mov_b32_e32 v84, v81
	v_mov_b32_e32 v80, v82
	v_mov_b32_e32 v81, v86
	v_mov_b32_e32 v86, v83
	v_pk_add_f32 v[82:83], v[92:93], v[84:85]
	v_pk_add_f32 v[80:81], v[80:81], v[86:87]
	s_nop 0
	v_pk_add_f32 v[80:81], v[82:83], v[80:81]
	v_lshl_add_u64 v[82:83], s[16:17], 0, v[90:91]
	v_add_f32_e32 v80, v80, v81
	v_fmamk_f32 v80, v80, 0x3b800000, v153
	v_mul_f32_e32 v81, 0x4f800000, v80
	v_cmp_gt_f32_e32 vcc, s52, v80
	v_lshl_add_u64 v[82:83], v[82:83], 0, v[144:145]
	s_nop 0
	v_cndmask_b32_e32 v84, v80, v81, vcc
	v_sqrt_f32_e32 v85, v84
	v_lshlrev_b64 v[80:81], 6, v[88:89]
	v_lshl_add_u64 v[80:81], s[18:19], 0, v[80:81]
	v_add_u32_e32 v86, -1, v85
	v_add_u32_e32 v87, 1, v85
	v_fma_f32 v90, -v86, v85, v84
	v_fma_f32 v91, -v87, v85, v84
	v_cmp_ge_f32_e64 s[6:7], 0, v90
	s_nop 1
	v_cndmask_b32_e64 v85, v85, v86, s[6:7]
	v_cmp_lt_f32_e64 s[6:7], 0, v91
	s_nop 1
	v_cndmask_b32_e64 v85, v85, v87, s[6:7]
	v_mul_f32_e32 v86, 0x37800000, v85
	v_cndmask_b32_e32 v85, v85, v86, vcc
	v_cmp_class_f32_e32 vcc, v84, v154
	s_nop 1
	v_cndmask_b32_e32 v84, v85, v84, vcc
	v_div_scale_f32 v85, s[6:7], v84, v84, 1.0
	v_rcp_f32_e32 v86, v85
	v_div_scale_f32 v87, vcc, 1.0, v84, 1.0
	v_fma_f32 v90, -v85, v86, 1.0
	v_fmac_f32_e32 v86, v90, v86
	v_mul_f32_e32 v90, v87, v86
	v_fma_f32 v91, -v85, v90, v87
	v_fmac_f32_e32 v90, v91, v86
	v_fma_f32 v85, -v85, v90, v87
	v_div_fmas_f32 v85, v85, v86, v90
	v_div_fixup_f32 v84, v85, v84, 1.0
	v_pk_mul_f32 v[78:79], v[78:79], v[84:85] op_sel_hi:[1,0]
	v_pk_mul_f32 v[76:77], v[76:77], v[84:85] op_sel_hi:[1,0]
	v_pk_mul_f32 v[74:75], v[74:75], v[84:85] op_sel_hi:[1,0]
	v_pk_mul_f32 v[72:73], v[72:73], v[84:85] op_sel_hi:[1,0]
	v_pk_mul_f32 v[70:71], v[70:71], v[84:85] op_sel_hi:[1,0]
	v_pk_mul_f32 v[68:69], v[68:69], v[84:85] op_sel_hi:[1,0]
	v_pk_mul_f32 v[86:87], v[66:67], v[84:85] op_sel_hi:[1,0]
	v_pk_mul_f32 v[84:85], v[64:65], v[84:85] op_sel_hi:[1,0]
	v_cvt_pk_bf16_f32 v64, v76, v77
	v_cvt_pk_bf16_f32 v65, v78, v79
	v_cvt_pk_bf16_f32 v66, v72, v73
	v_cvt_pk_bf16_f32 v67, v74, v75
	global_store_dwordx4 v[82:83], v[64:67], off sc1
	v_lshlrev_b64 v[74:75], 12, v[88:89]
	v_add_u32_e32 v72, 0x90, v146
	v_cvt_pk_bf16_f32 v64, v68, v69
	v_cvt_pk_bf16_f32 v65, v70, v71
	v_cvt_pk_bf16_f32 v66, v84, v85
	v_cvt_pk_bf16_f32 v67, v86, v87
	global_store_dwordx4 v[82:83], v[64:67], off offset:256 sc1
	global_load_dwordx4 v[64:67], v[80:81], off offset:32
	global_load_dwordx4 v[68:71], v[80:81], off offset:48
	v_ashrrev_i32_e32 v73, 31, v72
	s_waitcnt vmcnt(1)
	v_mov_b32_e32 v76, v64
	s_waitcnt vmcnt(0)
	v_mov_b32_e32 v77, v68
	v_mov_b32_e32 v68, v65
	v_mov_b32_e32 v64, v66
	v_mov_b32_e32 v65, v70
	v_mov_b32_e32 v70, v67
	v_pk_add_f32 v[66:67], v[76:77], v[68:69]
	v_pk_add_f32 v[64:65], v[64:65], v[70:71]
	s_nop 0
	v_pk_add_f32 v[64:65], v[66:67], v[64:65]
	v_lshl_add_u64 v[66:67], s[16:17], 0, v[74:75]
	v_add_f32_e32 v64, v64, v65
	v_fmamk_f32 v64, v64, 0x3b800000, v153
	v_mul_f32_e32 v65, 0x4f800000, v64
	v_cmp_gt_f32_e32 vcc, s52, v64
	v_lshl_add_u64 v[66:67], v[66:67], 0, v[144:145]
	s_nop 0
	v_cndmask_b32_e32 v68, v64, v65, vcc
	v_sqrt_f32_e32 v69, v68
	v_lshlrev_b64 v[64:65], 6, v[72:73]
	v_lshl_add_u64 v[64:65], s[18:19], 0, v[64:65]
	v_add_u32_e32 v70, -1, v69
	v_add_u32_e32 v71, 1, v69
	v_fma_f32 v74, -v70, v69, v68
	v_fma_f32 v75, -v71, v69, v68
	v_cmp_ge_f32_e64 s[6:7], 0, v74
	s_nop 1
	v_cndmask_b32_e64 v69, v69, v70, s[6:7]
	v_cmp_lt_f32_e64 s[6:7], 0, v75
	s_nop 1
	v_cndmask_b32_e64 v69, v69, v71, s[6:7]
	v_mul_f32_e32 v70, 0x37800000, v69
	v_cndmask_b32_e32 v69, v69, v70, vcc
	v_cmp_class_f32_e32 vcc, v68, v154
	s_nop 1
	v_cndmask_b32_e32 v68, v69, v68, vcc
	v_div_scale_f32 v69, s[6:7], v68, v68, 1.0
	v_rcp_f32_e32 v70, v69
	v_div_scale_f32 v71, vcc, 1.0, v68, 1.0
	v_fma_f32 v74, -v69, v70, 1.0
	v_fmac_f32_e32 v70, v74, v70
	v_mul_f32_e32 v74, v71, v70
	v_fma_f32 v75, -v69, v74, v71
	v_fmac_f32_e32 v74, v75, v70
	v_fma_f32 v69, -v69, v74, v71
	v_div_fmas_f32 v69, v69, v70, v74
	v_div_fixup_f32 v68, v69, v68, 1.0
	v_pk_mul_f32 v[62:63], v[62:63], v[68:69] op_sel_hi:[1,0]
	v_pk_mul_f32 v[60:61], v[60:61], v[68:69] op_sel_hi:[1,0]
	v_pk_mul_f32 v[58:59], v[58:59], v[68:69] op_sel_hi:[1,0]
	v_pk_mul_f32 v[56:57], v[56:57], v[68:69] op_sel_hi:[1,0]
	v_pk_mul_f32 v[54:55], v[54:55], v[68:69] op_sel_hi:[1,0]
	v_pk_mul_f32 v[52:53], v[52:53], v[68:69] op_sel_hi:[1,0]
	v_pk_mul_f32 v[70:71], v[50:51], v[68:69] op_sel_hi:[1,0]
	v_pk_mul_f32 v[68:69], v[48:49], v[68:69] op_sel_hi:[1,0]
	v_cvt_pk_bf16_f32 v48, v60, v61
	v_cvt_pk_bf16_f32 v49, v62, v63
	v_cvt_pk_bf16_f32 v50, v56, v57
	v_cvt_pk_bf16_f32 v51, v58, v59
	global_store_dwordx4 v[66:67], v[48:51], off sc1
	v_lshlrev_b64 v[58:59], 12, v[72:73]
	v_add_u32_e32 v56, 0xa0, v146
	v_cvt_pk_bf16_f32 v48, v52, v53
	v_cvt_pk_bf16_f32 v49, v54, v55
	v_cvt_pk_bf16_f32 v50, v68, v69
	v_cvt_pk_bf16_f32 v51, v70, v71
	global_store_dwordx4 v[66:67], v[48:51], off offset:256 sc1
	global_load_dwordx4 v[48:51], v[64:65], off offset:32
	global_load_dwordx4 v[52:55], v[64:65], off offset:48
	v_ashrrev_i32_e32 v57, 31, v56
	s_waitcnt vmcnt(1)
	v_mov_b32_e32 v60, v48
	s_waitcnt vmcnt(0)
	v_mov_b32_e32 v61, v52
	v_mov_b32_e32 v52, v49
	v_mov_b32_e32 v48, v50
	v_mov_b32_e32 v49, v54
	v_mov_b32_e32 v54, v51
	v_pk_add_f32 v[50:51], v[60:61], v[52:53]
	v_pk_add_f32 v[48:49], v[48:49], v[54:55]
	s_nop 0
	v_pk_add_f32 v[48:49], v[50:51], v[48:49]
	v_lshl_add_u64 v[50:51], s[16:17], 0, v[58:59]
	v_add_f32_e32 v48, v48, v49
	v_fmamk_f32 v48, v48, 0x3b800000, v153
	v_mul_f32_e32 v49, 0x4f800000, v48
	v_cmp_gt_f32_e32 vcc, s52, v48
	v_lshl_add_u64 v[50:51], v[50:51], 0, v[144:145]
	s_nop 0
	v_cndmask_b32_e32 v52, v48, v49, vcc
	v_sqrt_f32_e32 v53, v52
	v_lshlrev_b64 v[48:49], 6, v[56:57]
	v_lshl_add_u64 v[48:49], s[18:19], 0, v[48:49]
	v_add_u32_e32 v54, -1, v53
	v_add_u32_e32 v55, 1, v53
	v_fma_f32 v58, -v54, v53, v52
	v_fma_f32 v59, -v55, v53, v52
	v_cmp_ge_f32_e64 s[6:7], 0, v58
	s_nop 1
	v_cndmask_b32_e64 v53, v53, v54, s[6:7]
	v_cmp_lt_f32_e64 s[6:7], 0, v59
	s_nop 1
	v_cndmask_b32_e64 v53, v53, v55, s[6:7]
	v_mul_f32_e32 v54, 0x37800000, v53
	v_cndmask_b32_e32 v53, v53, v54, vcc
	v_cmp_class_f32_e32 vcc, v52, v154
	s_nop 1
	v_cndmask_b32_e32 v52, v53, v52, vcc
	v_div_scale_f32 v53, s[6:7], v52, v52, 1.0
	v_rcp_f32_e32 v54, v53
	v_div_scale_f32 v55, vcc, 1.0, v52, 1.0
	v_fma_f32 v58, -v53, v54, 1.0
	v_fmac_f32_e32 v54, v58, v54
	v_mul_f32_e32 v58, v55, v54
	v_fma_f32 v59, -v53, v58, v55
	v_fmac_f32_e32 v58, v59, v54
	v_fma_f32 v53, -v53, v58, v55
	v_div_fmas_f32 v53, v53, v54, v58
	v_div_fixup_f32 v52, v53, v52, 1.0
	v_pk_mul_f32 v[46:47], v[46:47], v[52:53] op_sel_hi:[1,0]
	v_pk_mul_f32 v[44:45], v[44:45], v[52:53] op_sel_hi:[1,0]
	v_pk_mul_f32 v[42:43], v[42:43], v[52:53] op_sel_hi:[1,0]
	v_pk_mul_f32 v[40:41], v[40:41], v[52:53] op_sel_hi:[1,0]
	v_pk_mul_f32 v[38:39], v[38:39], v[52:53] op_sel_hi:[1,0]
	v_pk_mul_f32 v[36:37], v[36:37], v[52:53] op_sel_hi:[1,0]
	v_pk_mul_f32 v[54:55], v[34:35], v[52:53] op_sel_hi:[1,0]
	v_pk_mul_f32 v[52:53], v[32:33], v[52:53] op_sel_hi:[1,0]
	v_cvt_pk_bf16_f32 v32, v44, v45
	v_cvt_pk_bf16_f32 v33, v46, v47
	v_cvt_pk_bf16_f32 v34, v40, v41
	v_cvt_pk_bf16_f32 v35, v42, v43
	global_store_dwordx4 v[50:51], v[32:35], off sc1
	v_lshlrev_b64 v[42:43], 12, v[56:57]
	v_add_u32_e32 v40, 0xb0, v146
	v_cvt_pk_bf16_f32 v32, v36, v37
	v_cvt_pk_bf16_f32 v33, v38, v39
	v_cvt_pk_bf16_f32 v34, v52, v53
	v_cvt_pk_bf16_f32 v35, v54, v55
	global_store_dwordx4 v[50:51], v[32:35], off offset:256 sc1
	global_load_dwordx4 v[32:35], v[48:49], off offset:32
	global_load_dwordx4 v[36:39], v[48:49], off offset:48
	v_ashrrev_i32_e32 v41, 31, v40
	s_waitcnt vmcnt(1)
	v_mov_b32_e32 v44, v32
	s_waitcnt vmcnt(0)
	v_mov_b32_e32 v45, v36
	v_mov_b32_e32 v36, v33
	v_mov_b32_e32 v32, v34
	v_mov_b32_e32 v33, v38
	v_mov_b32_e32 v38, v35
	v_pk_add_f32 v[34:35], v[44:45], v[36:37]
	v_pk_add_f32 v[32:33], v[32:33], v[38:39]
	s_nop 0
	v_pk_add_f32 v[32:33], v[34:35], v[32:33]
	v_lshl_add_u64 v[34:35], s[16:17], 0, v[42:43]
	v_add_f32_e32 v32, v32, v33
	v_fmamk_f32 v32, v32, 0x3b800000, v153
	v_mul_f32_e32 v33, 0x4f800000, v32
	v_cmp_gt_f32_e32 vcc, s52, v32
	v_lshl_add_u64 v[34:35], v[34:35], 0, v[144:145]
	s_nop 0
	v_cndmask_b32_e32 v36, v32, v33, vcc
	v_sqrt_f32_e32 v37, v36
	v_lshlrev_b64 v[32:33], 6, v[40:41]
	v_lshl_add_u64 v[32:33], s[18:19], 0, v[32:33]
	v_add_u32_e32 v38, -1, v37
	v_add_u32_e32 v39, 1, v37
	v_fma_f32 v42, -v38, v37, v36
	v_fma_f32 v43, -v39, v37, v36
	v_cmp_ge_f32_e64 s[6:7], 0, v42
	s_nop 1
	v_cndmask_b32_e64 v37, v37, v38, s[6:7]
	v_cmp_lt_f32_e64 s[6:7], 0, v43
	s_nop 1
	v_cndmask_b32_e64 v37, v37, v39, s[6:7]
	v_mul_f32_e32 v38, 0x37800000, v37
	v_cndmask_b32_e32 v37, v37, v38, vcc
	v_cmp_class_f32_e32 vcc, v36, v154
	s_nop 1
	v_cndmask_b32_e32 v36, v37, v36, vcc
	v_div_scale_f32 v37, s[6:7], v36, v36, 1.0
	v_rcp_f32_e32 v38, v37
	v_div_scale_f32 v39, vcc, 1.0, v36, 1.0
	v_fma_f32 v42, -v37, v38, 1.0
	v_fmac_f32_e32 v38, v42, v38
	v_mul_f32_e32 v42, v39, v38
	v_fma_f32 v43, -v37, v42, v39
	v_fmac_f32_e32 v42, v43, v38
	v_fma_f32 v37, -v37, v42, v39
	v_div_fmas_f32 v37, v37, v38, v42
	v_div_fixup_f32 v36, v37, v36, 1.0
	v_pk_mul_f32 v[30:31], v[30:31], v[36:37] op_sel_hi:[1,0]
	v_pk_mul_f32 v[28:29], v[28:29], v[36:37] op_sel_hi:[1,0]
	v_pk_mul_f32 v[26:27], v[26:27], v[36:37] op_sel_hi:[1,0]
	v_pk_mul_f32 v[24:25], v[24:25], v[36:37] op_sel_hi:[1,0]
	v_pk_mul_f32 v[22:23], v[22:23], v[36:37] op_sel_hi:[1,0]
	v_pk_mul_f32 v[20:21], v[20:21], v[36:37] op_sel_hi:[1,0]
	v_pk_mul_f32 v[38:39], v[18:19], v[36:37] op_sel_hi:[1,0]
	v_pk_mul_f32 v[36:37], v[16:17], v[36:37] op_sel_hi:[1,0]
	v_cvt_pk_bf16_f32 v16, v28, v29
	v_cvt_pk_bf16_f32 v17, v30, v31
	v_cvt_pk_bf16_f32 v18, v24, v25
	v_cvt_pk_bf16_f32 v19, v26, v27
	global_store_dwordx4 v[34:35], v[16:19], off sc1
	s_nop 1
	v_cvt_pk_bf16_f32 v16, v20, v21
	v_cvt_pk_bf16_f32 v17, v22, v23
	v_cvt_pk_bf16_f32 v18, v36, v37
	v_cvt_pk_bf16_f32 v19, v38, v39
	global_store_dwordx4 v[34:35], v[16:19], off offset:256 sc1
	global_load_dwordx4 v[16:19], v[32:33], off offset:32
	global_load_dwordx4 v[20:23], v[32:33], off offset:48
	s_waitcnt vmcnt(1)
	v_mov_b32_e32 v24, v16
	s_waitcnt vmcnt(0)
	v_mov_b32_e32 v25, v20
	v_mov_b32_e32 v20, v17
	v_mov_b32_e32 v16, v18
	v_mov_b32_e32 v17, v22
	v_mov_b32_e32 v22, v19
	v_pk_add_f32 v[18:19], v[24:25], v[20:21]
	v_pk_add_f32 v[16:17], v[16:17], v[22:23]
	s_nop 0
	v_pk_add_f32 v[16:17], v[18:19], v[16:17]
	s_nop 0
	v_add_f32_e32 v16, v16, v17
	v_fmamk_f32 v16, v16, 0x3b800000, v153
	v_mul_f32_e32 v17, 0x4f800000, v16
	v_cmp_gt_f32_e32 vcc, s52, v16
	s_nop 1
	v_cndmask_b32_e32 v18, v16, v17, vcc
	v_sqrt_f32_e32 v19, v18
	v_lshlrev_b64 v[16:17], 12, v[40:41]
	v_lshl_add_u64 v[16:17], s[16:17], 0, v[16:17]
	v_lshl_add_u64 v[16:17], v[16:17], 0, v[144:145]
	v_add_u32_e32 v20, -1, v19
	v_add_u32_e32 v21, 1, v19
	v_fma_f32 v22, -v20, v19, v18
	v_fma_f32 v23, -v21, v19, v18
	v_cmp_ge_f32_e64 s[6:7], 0, v22
	s_nop 1
	v_cndmask_b32_e64 v19, v19, v20, s[6:7]
	v_cmp_lt_f32_e64 s[6:7], 0, v23
	s_nop 1
	v_cndmask_b32_e64 v19, v19, v21, s[6:7]
	v_mul_f32_e32 v20, 0x37800000, v19
	v_cndmask_b32_e32 v19, v19, v20, vcc
	v_cmp_class_f32_e32 vcc, v18, v154
	s_nop 1
	v_cndmask_b32_e32 v18, v19, v18, vcc
	v_div_scale_f32 v19, s[6:7], v18, v18, 1.0
	v_rcp_f32_e32 v20, v19
	v_div_scale_f32 v21, vcc, 1.0, v18, 1.0
	v_fma_f32 v22, -v19, v20, 1.0
	v_fmac_f32_e32 v20, v22, v20
	v_mul_f32_e32 v22, v21, v20
	v_fma_f32 v23, -v19, v22, v21
	v_fmac_f32_e32 v22, v23, v20
	v_fma_f32 v19, -v19, v22, v21
	v_div_fmas_f32 v19, v19, v20, v22
	v_div_fixup_f32 v18, v19, v18, 1.0
	v_pk_mul_f32 v[14:15], v[14:15], v[18:19] op_sel_hi:[1,0]
	v_pk_mul_f32 v[12:13], v[12:13], v[18:19] op_sel_hi:[1,0]
	v_pk_mul_f32 v[10:11], v[10:11], v[18:19] op_sel_hi:[1,0]
	v_pk_mul_f32 v[8:9], v[8:9], v[18:19] op_sel_hi:[1,0]
	v_pk_mul_f32 v[6:7], v[6:7], v[18:19] op_sel_hi:[1,0]
	v_pk_mul_f32 v[4:5], v[4:5], v[18:19] op_sel_hi:[1,0]
	v_pk_mul_f32 v[20:21], v[2:3], v[18:19] op_sel_hi:[1,0]
	v_pk_mul_f32 v[18:19], v[0:1], v[18:19] op_sel_hi:[1,0]
	v_cvt_pk_bf16_f32 v0, v12, v13
	v_cvt_pk_bf16_f32 v1, v14, v15
	v_cvt_pk_bf16_f32 v2, v8, v9
	v_cvt_pk_bf16_f32 v3, v10, v11
	global_store_dwordx4 v[16:17], v[0:3], off sc1
	s_and_b64 vcc, exec, s[4:5]
	s_mov_b64 s[4:5], -1
	v_cvt_pk_bf16_f32 v0, v4, v5
	v_cvt_pk_bf16_f32 v1, v6, v7
	v_cvt_pk_bf16_f32 v2, v18, v19
	v_cvt_pk_bf16_f32 v3, v20, v21
	global_store_dwordx4 v[16:17], v[0:3], off offset:256 sc1
	s_cbranch_vccnz .LBB0_782
	s_andn2_b64 vcc, exec, s[14:15]
	s_cbranch_vccnz .LBB0_781
	s_barrier
	s_branch .LBB0_781

.LBB0_1015:
	s_or_b64 exec, exec, s[6:7]
	s_waitcnt lgkmcnt(0)
	s_barrier
	v_lshl_add_u64 v[140:141], s[16:17], 0, v[132:133]
	v_lshl_add_u64 v[144:145], s[18:19], 0, v[132:133]
	global_load_dwordx4 v[128:131], v[140:141], off
	global_load_dwordx4 v[132:135], v[144:145], off
	v_or_b32_e32 v153, s0, v138
	v_lshl_add_u32 v152, v153, 3, 0
	ds_read_b64 v[156:157], v152 offset:8192
	v_add_u32_e32 v148, s3, v153
	v_ashrrev_i32_e32 v149, 31, v148
	v_lshlrev_b64 v[142:143], 10, v[148:149]
	v_mov_b32_e32 v154, 0x7fc00000
	s_waitcnt lgkmcnt(0)
	v_sub_f32_e32 v117, v117, v156
	v_sub_f32_e32 v116, v116, v156
	v_sub_f32_e32 v119, v119, v156
	v_sub_f32_e32 v118, v118, v156
	v_pk_mul_f32 v[118:119], v[156:157], v[118:119] op_sel:[1,0]
	v_pk_mul_f32 v[116:117], v[156:157], v[116:117] op_sel:[1,0]
	s_cmp_lg_u64 s[14:15], 0
	v_lshl_add_u64 v[138:139], v[142:143], 0, v[136:137]
	v_cmp_eq_u32_e64 s[4:5], 0, v150
	s_cselect_b64 s[8:9], -1, 0
	v_lshl_add_u64 v[146:147], v[138:139], 2, s[12:13]
	s_cmp_eq_u64 s[14:15], 0
	s_waitcnt vmcnt(0)
	v_pk_fma_f32 v[116:117], v[128:129], v[116:117], v[132:133]
	v_pk_fma_f32 v[118:119], v[130:131], v[118:119], v[134:135]
	v_cndmask_b32_e64 v117, v154, v117, s[4:5]
	v_cndmask_b32_e64 v119, v154, v119, s[4:5]
	v_cndmask_b32_e64 v118, v154, v118, s[4:5]
	v_cndmask_b32_e64 v116, v154, v116, s[4:5]
	global_store_dwordx4 v[146:147], v[116:119], off sc1
	s_cbranch_scc1 .LBB0_1017
	s_nop 0
	v_cvt_pk_bf16_f32 v116, v116, v117
	v_cvt_pk_bf16_f32 v117, v118, v119
	v_lshl_add_u64 v[118:119], v[138:139], 1, s[34:35]
	global_store_dwordx2 v[118:119], v[116:117], off sc1
.LBB0_1017:
	ds_read_b64 v[116:117], v152 offset:8320
	v_add3_u32 v118, s3, v153, 16
	v_ashrrev_i32_e32 v119, 31, v118
	v_lshlrev_b64 v[138:139], 10, v[118:119]
	v_lshl_add_u64 v[150:151], v[138:139], 0, v[136:137]
	s_waitcnt lgkmcnt(0)
	v_sub_f32_e32 v119, v125, v116
	v_sub_f32_e32 v118, v124, v116
	v_sub_f32_e32 v125, v127, v116
	v_sub_f32_e32 v124, v126, v116
	v_pk_mul_f32 v[124:125], v[116:117], v[124:125] op_sel:[1,0]
	v_pk_mul_f32 v[116:117], v[116:117], v[118:119] op_sel:[1,0]
	v_pk_fma_f32 v[118:119], v[130:131], v[124:125], v[134:135]
	v_pk_fma_f32 v[116:117], v[128:129], v[116:117], v[132:133]
	v_cndmask_b32_e64 v124, 0, 1, s[8:9]
	v_cndmask_b32_e64 v119, v154, v119, s[4:5]
	v_cndmask_b32_e64 v118, v154, v118, s[4:5]
	v_cndmask_b32_e64 v117, v154, v117, s[4:5]
	v_cndmask_b32_e64 v116, v154, v116, s[4:5]
	v_lshl_add_u64 v[126:127], v[150:151], 2, s[12:13]
	v_cmp_ne_u32_e64 s[6:7], 1, v124
	s_andn2_b64 vcc, exec, s[8:9]
	global_store_dwordx4 v[126:127], v[116:119], off sc1
	s_cbranch_vccnz .LBB0_1019
	s_nop 0
	v_cvt_pk_bf16_f32 v116, v116, v117
	v_cvt_pk_bf16_f32 v117, v118, v119
	v_lshl_add_u64 v[118:119], v[150:151], 1, s[34:35]
	global_store_dwordx2 v[118:119], v[116:117], off sc1
.LBB0_1019:
	ds_read_b64 v[116:117], v152 offset:8448
	v_add3_u32 v118, s3, v153, 32
	v_ashrrev_i32_e32 v119, 31, v118
	v_lshlrev_b64 v[124:125], 10, v[118:119]
	v_lshl_add_u64 v[150:151], v[124:125], 0, v[136:137]
	s_waitcnt lgkmcnt(0)
	v_sub_f32_e32 v119, v121, v116
	v_sub_f32_e32 v118, v120, v116
	v_sub_f32_e32 v121, v123, v116
	v_sub_f32_e32 v120, v122, v116
	v_pk_mul_f32 v[120:121], v[116:117], v[120:121] op_sel:[1,0]
	v_pk_mul_f32 v[116:117], v[116:117], v[118:119] op_sel:[1,0]
	v_pk_fma_f32 v[118:119], v[130:131], v[120:121], v[134:135]
	v_pk_fma_f32 v[116:117], v[128:129], v[116:117], v[132:133]
	v_mov_b32_e32 v149, 0x7fc00000
	v_cndmask_b32_e64 v119, v149, v119, s[4:5]
	v_cndmask_b32_e64 v118, v149, v118, s[4:5]
	v_cndmask_b32_e64 v117, v149, v117, s[4:5]
	v_cndmask_b32_e64 v116, v149, v116, s[4:5]
	v_lshl_add_u64 v[120:121], v[150:151], 2, s[12:13]
	s_and_b64 vcc, exec, s[6:7]
	global_store_dwordx4 v[120:121], v[116:119], off sc1
	s_cbranch_vccnz .LBB0_1021
	s_nop 0
	v_cvt_pk_bf16_f32 v116, v116, v117
	v_cvt_pk_bf16_f32 v117, v118, v119
	v_lshl_add_u64 v[118:119], v[150:151], 1, s[34:35]
	global_store_dwordx2 v[118:119], v[116:117], off sc1
.LBB0_1021:
	ds_read_b64 v[118:119], v152 offset:8576
	v_add3_u32 v116, s3, v153, 48
	v_ashrrev_i32_e32 v117, 31, v116
	v_lshlrev_b64 v[116:117], 10, v[116:117]
	v_lshl_add_u64 v[122:123], v[116:117], 0, v[136:137]
	s_waitcnt lgkmcnt(0)
	v_sub_f32_e32 v113, v113, v118
	v_sub_f32_e32 v112, v112, v118
	v_sub_f32_e32 v115, v115, v118
	v_sub_f32_e32 v114, v114, v118
	v_pk_mul_f32 v[114:115], v[118:119], v[114:115] op_sel:[1,0]
	v_pk_mul_f32 v[112:113], v[118:119], v[112:113] op_sel:[1,0]
	v_pk_fma_f32 v[114:115], v[130:131], v[114:115], v[134:135]
	v_pk_fma_f32 v[112:113], v[128:129], v[112:113], v[132:133]
	v_cndmask_b32_e64 v115, v149, v115, s[4:5]
	v_cndmask_b32_e64 v114, v149, v114, s[4:5]
	v_cndmask_b32_e64 v113, v149, v113, s[4:5]
	v_cndmask_b32_e64 v112, v149, v112, s[4:5]
	v_lshl_add_u64 v[118:119], v[122:123], 2, s[12:13]
	s_and_b64 vcc, exec, s[6:7]
	global_store_dwordx4 v[118:119], v[112:115], off sc1
	s_cbranch_vccnz .LBB0_1023
	s_nop 0
	v_cvt_pk_bf16_f32 v112, v112, v113
	v_cvt_pk_bf16_f32 v113, v114, v115
	v_lshl_add_u64 v[114:115], v[122:123], 1, s[34:35]
	global_store_dwordx2 v[114:115], v[112:113], off sc1
.LBB0_1023:
	ds_read_b64 v[114:115], v152 offset:9216
	v_add_u32_e32 v112, 0x80, v148
	v_ashrrev_i32_e32 v113, 31, v112
	v_lshlrev_b64 v[112:113], 10, v[112:113]
	v_lshl_add_u64 v[122:123], v[112:113], 0, v[136:137]
	s_waitcnt lgkmcnt(0)
	v_sub_f32_e32 v109, v109, v114
	v_sub_f32_e32 v108, v108, v114
	v_sub_f32_e32 v111, v111, v114
	v_sub_f32_e32 v110, v110, v114
	v_pk_mul_f32 v[110:111], v[114:115], v[110:111] op_sel:[1,0]
	v_pk_mul_f32 v[108:109], v[114:115], v[108:109] op_sel:[1,0]
	v_pk_fma_f32 v[110:111], v[130:131], v[110:111], v[134:135]
	v_pk_fma_f32 v[108:109], v[128:129], v[108:109], v[132:133]
	v_mov_b32_e32 v149, 0x7fc00000
	v_cndmask_b32_e64 v111, v149, v111, s[4:5]
	v_cndmask_b32_e64 v110, v149, v110, s[4:5]
	v_cndmask_b32_e64 v109, v149, v109, s[4:5]
	v_cndmask_b32_e64 v108, v149, v108, s[4:5]
	v_lshl_add_u64 v[114:115], v[122:123], 2, s[12:13]
	s_and_b64 vcc, exec, s[6:7]
	global_store_dwordx4 v[114:115], v[108:111], off sc1
	s_cbranch_vccnz .LBB0_1025
	s_nop 0
	v_cvt_pk_bf16_f32 v108, v108, v109
	v_cvt_pk_bf16_f32 v109, v110, v111
	v_lshl_add_u64 v[110:111], v[122:123], 1, s[34:35]
	global_store_dwordx2 v[110:111], v[108:109], off sc1
.LBB0_1025:
	ds_read_b64 v[110:111], v152 offset:9344
	v_add_u32_e32 v108, 0x90, v148
	v_ashrrev_i32_e32 v109, 31, v108
	v_lshlrev_b64 v[108:109], 10, v[108:109]
	v_lshl_add_u64 v[122:123], v[108:109], 0, v[136:137]
	s_waitcnt lgkmcnt(0)
	v_sub_f32_e32 v93, v93, v110
	v_sub_f32_e32 v92, v92, v110
	v_sub_f32_e32 v95, v95, v110
	v_sub_f32_e32 v94, v94, v110
	v_pk_mul_f32 v[94:95], v[110:111], v[94:95] op_sel:[1,0]
	v_pk_mul_f32 v[92:93], v[110:111], v[92:93] op_sel:[1,0]
	v_pk_fma_f32 v[94:95], v[130:131], v[94:95], v[134:135]
	v_pk_fma_f32 v[92:93], v[128:129], v[92:93], v[132:133]
	v_cndmask_b32_e64 v95, v149, v95, s[4:5]
	v_cndmask_b32_e64 v94, v149, v94, s[4:5]
	v_cndmask_b32_e64 v93, v149, v93, s[4:5]
	v_cndmask_b32_e64 v92, v149, v92, s[4:5]
	v_lshl_add_u64 v[110:111], v[122:123], 2, s[12:13]
	s_and_b64 vcc, exec, s[6:7]
	global_store_dwordx4 v[110:111], v[92:95], off sc1
	s_cbranch_vccnz .LBB0_1027
	s_nop 0
	v_cvt_pk_bf16_f32 v92, v92, v93
	v_cvt_pk_bf16_f32 v93, v94, v95
	v_lshl_add_u64 v[94:95], v[122:123], 1, s[34:35]
	global_store_dwordx2 v[94:95], v[92:93], off sc1
.LBB0_1027:
	ds_read_b64 v[122:123], v152 offset:9472
	v_add_u32_e32 v92, 0xa0, v148
	v_ashrrev_i32_e32 v93, 31, v92
	v_lshlrev_b64 v[92:93], 10, v[92:93]
	v_lshl_add_u64 v[94:95], v[92:93], 0, v[136:137]
	s_waitcnt lgkmcnt(0)
	v_sub_f32_e32 v77, v77, v122
	v_sub_f32_e32 v76, v76, v122
	v_sub_f32_e32 v79, v79, v122
	v_sub_f32_e32 v78, v78, v122
	v_pk_mul_f32 v[78:79], v[122:123], v[78:79] op_sel:[1,0]
	v_pk_mul_f32 v[76:77], v[122:123], v[76:77] op_sel:[1,0]
	v_pk_fma_f32 v[78:79], v[130:131], v[78:79], v[134:135]
	v_pk_fma_f32 v[76:77], v[128:129], v[76:77], v[132:133]
	v_mov_b32_e32 v149, 0x7fc00000
	v_cndmask_b32_e64 v79, v149, v79, s[4:5]
	v_cndmask_b32_e64 v78, v149, v78, s[4:5]
	v_cndmask_b32_e64 v77, v149, v77, s[4:5]
	v_cndmask_b32_e64 v76, v149, v76, s[4:5]
	v_lshl_add_u64 v[122:123], v[94:95], 2, s[12:13]
	s_and_b64 vcc, exec, s[6:7]
	global_store_dwordx4 v[122:123], v[76:79], off sc1
	s_cbranch_vccnz .LBB0_1029
	s_nop 0
	v_cvt_pk_bf16_f32 v76, v76, v77
	v_cvt_pk_bf16_f32 v77, v78, v79
	v_lshl_add_u64 v[78:79], v[94:95], 1, s[34:35]
	global_store_dwordx2 v[78:79], v[76:77], off sc1
.LBB0_1029:
	ds_read_b64 v[78:79], v152 offset:9600
	v_add_u32_e32 v76, 0xb0, v148
	v_ashrrev_i32_e32 v77, 31, v76
	v_lshlrev_b64 v[94:95], 10, v[76:77]
	v_lshl_add_u64 v[76:77], v[94:95], 0, v[136:137]
	s_waitcnt lgkmcnt(0)
	v_sub_f32_e32 v53, v53, v78
	v_sub_f32_e32 v52, v52, v78
	v_sub_f32_e32 v55, v55, v78
	v_sub_f32_e32 v54, v54, v78
	v_pk_mul_f32 v[54:55], v[78:79], v[54:55] op_sel:[1,0]
	v_pk_mul_f32 v[52:53], v[78:79], v[52:53] op_sel:[1,0]
	v_pk_fma_f32 v[54:55], v[130:131], v[54:55], v[134:135]
	v_pk_fma_f32 v[52:53], v[128:129], v[52:53], v[132:133]
	v_cndmask_b32_e64 v55, v149, v55, s[4:5]
	v_cndmask_b32_e64 v54, v149, v54, s[4:5]
	v_cndmask_b32_e64 v53, v149, v53, s[4:5]
	v_cndmask_b32_e64 v52, v149, v52, s[4:5]
	v_lshl_add_u64 v[128:129], v[76:77], 2, s[12:13]
	s_and_b64 vcc, exec, s[6:7]
	global_store_dwordx4 v[128:129], v[52:55], off sc1
	s_cbranch_vccnz .LBB0_1031
	s_nop 0
	v_cvt_pk_bf16_f32 v52, v52, v53
	v_cvt_pk_bf16_f32 v53, v54, v55
	v_lshl_add_u64 v[54:55], v[76:77], 1, s[34:35]
	global_store_dwordx2 v[54:55], v[52:53], off sc1
.LBB0_1031:
	global_load_dwordx4 v[52:55], v[140:141], off offset:64
	global_load_dwordx4 v[76:79], v[144:145], off offset:64
	ds_read_b64 v[134:135], v152 offset:8192
	v_mov_b32_e32 v132, 0x7fc00000
	v_lshl_add_u64 v[130:131], v[136:137], 0, 16
	s_and_b64 vcc, exec, s[6:7]
	s_waitcnt lgkmcnt(0)
	v_sub_f32_e32 v81, v81, v134
	v_sub_f32_e32 v80, v80, v134
	v_sub_f32_e32 v83, v83, v134
	v_sub_f32_e32 v82, v82, v134
	v_pk_mul_f32 v[82:83], v[134:135], v[82:83] op_sel:[1,0]
	v_pk_mul_f32 v[80:81], v[134:135], v[80:81] op_sel:[1,0]
	s_waitcnt vmcnt(0)
	v_pk_fma_f32 v[82:83], v[54:55], v[82:83], v[78:79]
	v_pk_fma_f32 v[80:81], v[52:53], v[80:81], v[76:77]
	v_cndmask_b32_e64 v83, v132, v83, s[4:5]
	v_cndmask_b32_e64 v82, v132, v82, s[4:5]
	v_cndmask_b32_e64 v81, v132, v81, s[4:5]
	v_cndmask_b32_e64 v80, v132, v80, s[4:5]
	global_store_dwordx4 v[146:147], v[80:83], off offset:64 sc1
	s_cbranch_vccnz .LBB0_1033
	v_lshl_add_u64 v[134:135], v[142:143], 0, v[130:131]
	v_cvt_pk_bf16_f32 v80, v80, v81
	v_cvt_pk_bf16_f32 v81, v82, v83
	v_lshl_add_u64 v[82:83], v[134:135], 1, s[34:35]
	global_store_dwordx2 v[82:83], v[80:81], off sc1
.LBB0_1033:
	ds_read_b64 v[80:81], v152 offset:8320
	s_and_b64 vcc, exec, s[6:7]
	s_waitcnt lgkmcnt(0)
	v_sub_f32_e32 v83, v85, v80
	v_sub_f32_e32 v82, v84, v80
	v_sub_f32_e32 v85, v87, v80
	v_sub_f32_e32 v84, v86, v80
	v_pk_mul_f32 v[84:85], v[80:81], v[84:85] op_sel:[1,0]
	v_pk_mul_f32 v[80:81], v[80:81], v[82:83] op_sel:[1,0]
	v_pk_fma_f32 v[82:83], v[54:55], v[84:85], v[78:79]
	v_pk_fma_f32 v[80:81], v[52:53], v[80:81], v[76:77]
	v_cndmask_b32_e64 v83, v132, v83, s[4:5]
	v_cndmask_b32_e64 v82, v132, v82, s[4:5]
	v_cndmask_b32_e64 v81, v132, v81, s[4:5]
	v_cndmask_b32_e64 v80, v132, v80, s[4:5]
	global_store_dwordx4 v[126:127], v[80:83], off offset:64 sc1
	s_cbranch_vccnz .LBB0_1035
	v_lshl_add_u64 v[84:85], v[138:139], 0, v[130:131]
	v_cvt_pk_bf16_f32 v80, v80, v81
	v_cvt_pk_bf16_f32 v81, v82, v83
	v_lshl_add_u64 v[82:83], v[84:85], 1, s[34:35]
	global_store_dwordx2 v[82:83], v[80:81], off sc1
.LBB0_1035:
	ds_read_b64 v[80:81], v152 offset:8448
	s_and_b64 vcc, exec, s[6:7]
	s_waitcnt lgkmcnt(0)
	v_sub_f32_e32 v83, v97, v80
	v_sub_f32_e32 v82, v96, v80
	v_sub_f32_e32 v85, v99, v80
	v_sub_f32_e32 v84, v98, v80
	v_pk_mul_f32 v[84:85], v[80:81], v[84:85] op_sel:[1,0]
	v_pk_mul_f32 v[80:81], v[80:81], v[82:83] op_sel:[1,0]
	v_pk_fma_f32 v[82:83], v[54:55], v[84:85], v[78:79]
	v_pk_fma_f32 v[80:81], v[52:53], v[80:81], v[76:77]
	v_mov_b32_e32 v84, 0x7fc00000
	v_cndmask_b32_e64 v83, v84, v83, s[4:5]
	v_cndmask_b32_e64 v82, v84, v82, s[4:5]
	v_cndmask_b32_e64 v81, v84, v81, s[4:5]
	v_cndmask_b32_e64 v80, v84, v80, s[4:5]
	global_store_dwordx4 v[120:121], v[80:83], off offset:64 sc1
	s_cbranch_vccnz .LBB0_1037
	v_lshl_add_u64 v[86:87], v[124:125], 0, v[130:131]
	v_cvt_pk_bf16_f32 v80, v80, v81
	v_cvt_pk_bf16_f32 v81, v82, v83
	v_lshl_add_u64 v[82:83], v[86:87], 1, s[34:35]
	global_store_dwordx2 v[82:83], v[80:81], off sc1
.LBB0_1037:
	ds_read_b64 v[80:81], v152 offset:8576
	s_and_b64 vcc, exec, s[6:7]
	s_waitcnt lgkmcnt(0)
	v_sub_f32_e32 v83, v101, v80
	v_sub_f32_e32 v82, v100, v80
	v_sub_f32_e32 v87, v103, v80
	v_sub_f32_e32 v86, v102, v80
	v_pk_mul_f32 v[86:87], v[80:81], v[86:87] op_sel:[1,0]
	v_pk_mul_f32 v[80:81], v[80:81], v[82:83] op_sel:[1,0]
	v_pk_fma_f32 v[82:83], v[54:55], v[86:87], v[78:79]
	v_pk_fma_f32 v[80:81], v[52:53], v[80:81], v[76:77]
	v_cndmask_b32_e64 v83, v84, v83, s[4:5]
	v_cndmask_b32_e64 v82, v84, v82, s[4:5]
	v_cndmask_b32_e64 v81, v84, v81, s[4:5]
	v_cndmask_b32_e64 v80, v84, v80, s[4:5]
	global_store_dwordx4 v[118:119], v[80:83], off offset:64 sc1
	s_cbranch_vccnz .LBB0_1039
	v_lshl_add_u64 v[84:85], v[116:117], 0, v[130:131]
	v_cvt_pk_bf16_f32 v80, v80, v81
	v_cvt_pk_bf16_f32 v81, v82, v83
	v_lshl_add_u64 v[82:83], v[84:85], 1, s[34:35]
	global_store_dwordx2 v[82:83], v[80:81], off sc1
.LBB0_1039:
	ds_read_b64 v[80:81], v152 offset:9216
	s_and_b64 vcc, exec, s[6:7]
	s_waitcnt lgkmcnt(0)
	v_sub_f32_e32 v83, v105, v80
	v_sub_f32_e32 v82, v104, v80
	v_sub_f32_e32 v85, v107, v80
	v_sub_f32_e32 v84, v106, v80
	v_pk_mul_f32 v[84:85], v[80:81], v[84:85] op_sel:[1,0]
	v_pk_mul_f32 v[80:81], v[80:81], v[82:83] op_sel:[1,0]
	v_pk_fma_f32 v[82:83], v[54:55], v[84:85], v[78:79]
	v_pk_fma_f32 v[80:81], v[52:53], v[80:81], v[76:77]
	v_mov_b32_e32 v84, 0x7fc00000
	v_cndmask_b32_e64 v83, v84, v83, s[4:5]
	v_cndmask_b32_e64 v82, v84, v82, s[4:5]
	v_cndmask_b32_e64 v81, v84, v81, s[4:5]
	v_cndmask_b32_e64 v80, v84, v80, s[4:5]
	global_store_dwordx4 v[114:115], v[80:83], off offset:64 sc1
	s_cbranch_vccnz .LBB0_1041
	v_lshl_add_u64 v[86:87], v[112:113], 0, v[130:131]
	v_cvt_pk_bf16_f32 v80, v80, v81
	v_cvt_pk_bf16_f32 v81, v82, v83
	v_lshl_add_u64 v[82:83], v[86:87], 1, s[34:35]
	global_store_dwordx2 v[82:83], v[80:81], off sc1
.LBB0_1041:
	ds_read_b64 v[80:81], v152 offset:9344
	s_and_b64 vcc, exec, s[6:7]
	s_waitcnt lgkmcnt(0)
	v_sub_f32_e32 v83, v89, v80
	v_sub_f32_e32 v82, v88, v80
	v_sub_f32_e32 v87, v91, v80
	v_sub_f32_e32 v86, v90, v80
	v_pk_mul_f32 v[86:87], v[80:81], v[86:87] op_sel:[1,0]
	v_pk_mul_f32 v[80:81], v[80:81], v[82:83] op_sel:[1,0]
	v_pk_fma_f32 v[82:83], v[54:55], v[86:87], v[78:79]
	v_pk_fma_f32 v[80:81], v[52:53], v[80:81], v[76:77]
	v_cndmask_b32_e64 v83, v84, v83, s[4:5]
	v_cndmask_b32_e64 v82, v84, v82, s[4:5]
	v_cndmask_b32_e64 v81, v84, v81, s[4:5]
	v_cndmask_b32_e64 v80, v84, v80, s[4:5]
	global_store_dwordx4 v[110:111], v[80:83], off offset:64 sc1
	s_cbranch_vccnz .LBB0_1043
	v_lshl_add_u64 v[84:85], v[108:109], 0, v[130:131]
	v_cvt_pk_bf16_f32 v80, v80, v81
	v_cvt_pk_bf16_f32 v81, v82, v83
	v_lshl_add_u64 v[82:83], v[84:85], 1, s[34:35]
	global_store_dwordx2 v[82:83], v[80:81], off sc1
.LBB0_1043:
	ds_read_b64 v[80:81], v152 offset:9472
	s_and_b64 vcc, exec, s[6:7]
	s_waitcnt lgkmcnt(0)
	v_sub_f32_e32 v73, v73, v80
	v_sub_f32_e32 v72, v72, v80
	v_sub_f32_e32 v75, v75, v80
	v_sub_f32_e32 v74, v74, v80
	v_pk_mul_f32 v[74:75], v[80:81], v[74:75] op_sel:[1,0]
	v_pk_mul_f32 v[72:73], v[80:81], v[72:73] op_sel:[1,0]
	v_pk_fma_f32 v[74:75], v[54:55], v[74:75], v[78:79]
	v_pk_fma_f32 v[72:73], v[52:53], v[72:73], v[76:77]
	v_mov_b32_e32 v80, 0x7fc00000
	v_cndmask_b32_e64 v75, v80, v75, s[4:5]
	v_cndmask_b32_e64 v74, v80, v74, s[4:5]
	v_cndmask_b32_e64 v73, v80, v73, s[4:5]
	v_cndmask_b32_e64 v72, v80, v72, s[4:5]
	global_store_dwordx4 v[122:123], v[72:75], off offset:64 sc1
	s_cbranch_vccnz .LBB0_1045
	v_lshl_add_u64 v[82:83], v[92:93], 0, v[130:131]
	v_cvt_pk_bf16_f32 v72, v72, v73
	v_cvt_pk_bf16_f32 v73, v74, v75
	v_lshl_add_u64 v[74:75], v[82:83], 1, s[34:35]
	global_store_dwordx2 v[74:75], v[72:73], off sc1
.LBB0_1045:
	ds_read_b64 v[72:73], v152 offset:9600
	s_and_b64 vcc, exec, s[6:7]
	s_waitcnt lgkmcnt(0)
	v_sub_f32_e32 v49, v49, v72
	v_sub_f32_e32 v48, v48, v72
	v_sub_f32_e32 v51, v51, v72
	v_sub_f32_e32 v50, v50, v72
	v_pk_mul_f32 v[50:51], v[72:73], v[50:51] op_sel:[1,0]
	v_pk_mul_f32 v[48:49], v[72:73], v[48:49] op_sel:[1,0]
	v_pk_fma_f32 v[50:51], v[54:55], v[50:51], v[78:79]
	v_pk_fma_f32 v[48:49], v[52:53], v[48:49], v[76:77]
	v_cndmask_b32_e64 v51, v80, v51, s[4:5]
	v_cndmask_b32_e64 v50, v80, v50, s[4:5]
	v_cndmask_b32_e64 v49, v80, v49, s[4:5]
	v_cndmask_b32_e64 v48, v80, v48, s[4:5]
	global_store_dwordx4 v[128:129], v[48:51], off offset:64 sc1
	s_cbranch_vccnz .LBB0_1047
	v_lshl_add_u64 v[52:53], v[94:95], 0, v[130:131]
	v_cvt_pk_bf16_f32 v48, v48, v49
	v_cvt_pk_bf16_f32 v49, v50, v51
	v_lshl_add_u64 v[50:51], v[52:53], 1, s[34:35]
	global_store_dwordx2 v[50:51], v[48:49], off sc1
.LBB0_1047:
	global_load_dwordx4 v[48:51], v[140:141], off offset:512
	global_load_dwordx4 v[52:55], v[144:145], off offset:512
	ds_read_b64 v[76:77], v152 offset:8192
	s_mov_b64 s[0:1], 0x80
	v_mov_b32_e32 v74, 0x7fc00000
	v_lshl_add_u64 v[72:73], v[136:137], 0, s[0:1]
	s_and_b64 vcc, exec, s[6:7]
	s_waitcnt lgkmcnt(0)
	v_sub_f32_e32 v29, v29, v76
	v_sub_f32_e32 v28, v28, v76
	v_sub_f32_e32 v31, v31, v76
	v_sub_f32_e32 v30, v30, v76
	v_pk_mul_f32 v[30:31], v[76:77], v[30:31] op_sel:[1,0]
	v_pk_mul_f32 v[28:29], v[76:77], v[28:29] op_sel:[1,0]
	s_waitcnt vmcnt(0)
	v_pk_fma_f32 v[30:31], v[50:51], v[30:31], v[54:55]
	v_pk_fma_f32 v[28:29], v[48:49], v[28:29], v[52:53]
	v_cndmask_b32_e64 v31, v74, v31, s[4:5]
	v_cndmask_b32_e64 v30, v74, v30, s[4:5]
	v_cndmask_b32_e64 v29, v74, v29, s[4:5]
	v_cndmask_b32_e64 v28, v74, v28, s[4:5]
	global_store_dwordx4 v[146:147], v[28:31], off offset:512 sc1
	s_cbranch_vccnz .LBB0_1049
	v_lshl_add_u64 v[76:77], v[142:143], 0, v[72:73]
	v_cvt_pk_bf16_f32 v28, v28, v29
	v_cvt_pk_bf16_f32 v29, v30, v31
	v_lshl_add_u64 v[30:31], v[76:77], 1, s[34:35]
	global_store_dwordx2 v[30:31], v[28:29], off sc1
.LBB0_1049:
	ds_read_b64 v[28:29], v152 offset:8320
	s_and_b64 vcc, exec, s[6:7]
	s_waitcnt lgkmcnt(0)
	v_sub_f32_e32 v31, v41, v28
	v_sub_f32_e32 v30, v40, v28
	v_sub_f32_e32 v41, v43, v28
	v_sub_f32_e32 v40, v42, v28
	v_pk_mul_f32 v[40:41], v[28:29], v[40:41] op_sel:[1,0]
	v_pk_mul_f32 v[28:29], v[28:29], v[30:31] op_sel:[1,0]
	v_pk_fma_f32 v[30:31], v[50:51], v[40:41], v[54:55]
	v_pk_fma_f32 v[28:29], v[48:49], v[28:29], v[52:53]
	v_cndmask_b32_e64 v31, v74, v31, s[4:5]
	v_cndmask_b32_e64 v30, v74, v30, s[4:5]
	v_cndmask_b32_e64 v29, v74, v29, s[4:5]
	v_cndmask_b32_e64 v28, v74, v28, s[4:5]
	global_store_dwordx4 v[126:127], v[28:31], off offset:512 sc1
	s_cbranch_vccnz .LBB0_1051
	v_lshl_add_u64 v[40:41], v[138:139], 0, v[72:73]
	v_cvt_pk_bf16_f32 v28, v28, v29
	v_cvt_pk_bf16_f32 v29, v30, v31
	v_lshl_add_u64 v[30:31], v[40:41], 1, s[34:35]
	global_store_dwordx2 v[30:31], v[28:29], off sc1
.LBB0_1051:
	ds_read_b64 v[28:29], v152 offset:8448
	s_and_b64 vcc, exec, s[6:7]
	s_waitcnt lgkmcnt(0)
	v_sub_f32_e32 v31, v45, v28
	v_sub_f32_e32 v30, v44, v28
	v_sub_f32_e32 v41, v47, v28
	v_sub_f32_e32 v40, v46, v28
	v_pk_mul_f32 v[40:41], v[28:29], v[40:41] op_sel:[1,0]
	v_pk_mul_f32 v[28:29], v[28:29], v[30:31] op_sel:[1,0]
	v_pk_fma_f32 v[30:31], v[50:51], v[40:41], v[54:55]
	v_pk_fma_f32 v[28:29], v[48:49], v[28:29], v[52:53]
	v_mov_b32_e32 v40, 0x7fc00000
	v_cndmask_b32_e64 v31, v40, v31, s[4:5]
	v_cndmask_b32_e64 v30, v40, v30, s[4:5]
	v_cndmask_b32_e64 v29, v40, v29, s[4:5]
	v_cndmask_b32_e64 v28, v40, v28, s[4:5]
	global_store_dwordx4 v[120:121], v[28:31], off offset:512 sc1
	s_cbranch_vccnz .LBB0_1053
	v_lshl_add_u64 v[42:43], v[124:125], 0, v[72:73]
	v_cvt_pk_bf16_f32 v28, v28, v29
	v_cvt_pk_bf16_f32 v29, v30, v31
	v_lshl_add_u64 v[30:31], v[42:43], 1, s[34:35]
	global_store_dwordx2 v[30:31], v[28:29], off sc1
.LBB0_1053:
	ds_read_b64 v[28:29], v152 offset:8576
	s_and_b64 vcc, exec, s[6:7]
	s_waitcnt lgkmcnt(0)
	v_sub_f32_e32 v31, v57, v28
	v_sub_f32_e32 v30, v56, v28
	v_sub_f32_e32 v43, v59, v28
	v_sub_f32_e32 v42, v58, v28
	v_pk_mul_f32 v[42:43], v[28:29], v[42:43] op_sel:[1,0]
	v_pk_mul_f32 v[28:29], v[28:29], v[30:31] op_sel:[1,0]
	v_pk_fma_f32 v[30:31], v[50:51], v[42:43], v[54:55]
	v_pk_fma_f32 v[28:29], v[48:49], v[28:29], v[52:53]
	v_cndmask_b32_e64 v31, v40, v31, s[4:5]
	v_cndmask_b32_e64 v30, v40, v30, s[4:5]
	v_cndmask_b32_e64 v29, v40, v29, s[4:5]
	v_cndmask_b32_e64 v28, v40, v28, s[4:5]
	global_store_dwordx4 v[118:119], v[28:31], off offset:512 sc1
	s_cbranch_vccnz .LBB0_1055
	v_lshl_add_u64 v[40:41], v[116:117], 0, v[72:73]
	v_cvt_pk_bf16_f32 v28, v28, v29
	v_cvt_pk_bf16_f32 v29, v30, v31
	v_lshl_add_u64 v[30:31], v[40:41], 1, s[34:35]
	global_store_dwordx2 v[30:31], v[28:29], off sc1
.LBB0_1055:
	ds_read_b64 v[28:29], v152 offset:9216
	s_and_b64 vcc, exec, s[6:7]
	s_waitcnt lgkmcnt(0)
	v_sub_f32_e32 v31, v61, v28
	v_sub_f32_e32 v30, v60, v28
	v_sub_f32_e32 v41, v63, v28
	v_sub_f32_e32 v40, v62, v28
	v_pk_mul_f32 v[40:41], v[28:29], v[40:41] op_sel:[1,0]
	v_pk_mul_f32 v[28:29], v[28:29], v[30:31] op_sel:[1,0]
	v_pk_fma_f32 v[30:31], v[50:51], v[40:41], v[54:55]
	v_pk_fma_f32 v[28:29], v[48:49], v[28:29], v[52:53]
	v_mov_b32_e32 v40, 0x7fc00000
	v_cndmask_b32_e64 v31, v40, v31, s[4:5]
	v_cndmask_b32_e64 v30, v40, v30, s[4:5]
	v_cndmask_b32_e64 v29, v40, v29, s[4:5]
	v_cndmask_b32_e64 v28, v40, v28, s[4:5]
	global_store_dwordx4 v[114:115], v[28:31], off offset:512 sc1
	s_cbranch_vccnz .LBB0_1057
	v_lshl_add_u64 v[42:43], v[112:113], 0, v[72:73]
	v_cvt_pk_bf16_f32 v28, v28, v29
	v_cvt_pk_bf16_f32 v29, v30, v31
	v_lshl_add_u64 v[30:31], v[42:43], 1, s[34:35]
	global_store_dwordx2 v[30:31], v[28:29], off sc1
.LBB0_1057:
	ds_read_b64 v[28:29], v152 offset:9344
	s_and_b64 vcc, exec, s[6:7]
	s_waitcnt lgkmcnt(0)
	v_sub_f32_e32 v31, v69, v28
	v_sub_f32_e32 v30, v68, v28
	v_sub_f32_e32 v43, v71, v28
	v_sub_f32_e32 v42, v70, v28
	v_pk_mul_f32 v[42:43], v[28:29], v[42:43] op_sel:[1,0]
	v_pk_mul_f32 v[28:29], v[28:29], v[30:31] op_sel:[1,0]
	v_pk_fma_f32 v[30:31], v[50:51], v[42:43], v[54:55]
	v_pk_fma_f32 v[28:29], v[48:49], v[28:29], v[52:53]
	v_cndmask_b32_e64 v31, v40, v31, s[4:5]
	v_cndmask_b32_e64 v30, v40, v30, s[4:5]
	v_cndmask_b32_e64 v29, v40, v29, s[4:5]
	v_cndmask_b32_e64 v28, v40, v28, s[4:5]
	global_store_dwordx4 v[110:111], v[28:31], off offset:512 sc1
	s_cbranch_vccnz .LBB0_1059
	v_lshl_add_u64 v[40:41], v[108:109], 0, v[72:73]
	v_cvt_pk_bf16_f32 v28, v28, v29
	v_cvt_pk_bf16_f32 v29, v30, v31
	v_lshl_add_u64 v[30:31], v[40:41], 1, s[34:35]
	global_store_dwordx2 v[30:31], v[28:29], off sc1
.LBB0_1059:
	ds_read_b64 v[28:29], v152 offset:9472
	s_and_b64 vcc, exec, s[6:7]
	s_waitcnt lgkmcnt(0)
	v_sub_f32_e32 v31, v65, v28
	v_sub_f32_e32 v30, v64, v28
	v_sub_f32_e32 v41, v67, v28
	v_sub_f32_e32 v40, v66, v28
	v_pk_mul_f32 v[40:41], v[28:29], v[40:41] op_sel:[1,0]
	v_pk_mul_f32 v[28:29], v[28:29], v[30:31] op_sel:[1,0]
	v_pk_fma_f32 v[30:31], v[50:51], v[40:41], v[54:55]
	v_pk_fma_f32 v[28:29], v[48:49], v[28:29], v[52:53]
	v_mov_b32_e32 v40, 0x7fc00000
	v_cndmask_b32_e64 v31, v40, v31, s[4:5]
	v_cndmask_b32_e64 v30, v40, v30, s[4:5]
	v_cndmask_b32_e64 v29, v40, v29, s[4:5]
	v_cndmask_b32_e64 v28, v40, v28, s[4:5]
	global_store_dwordx4 v[122:123], v[28:31], off offset:512 sc1
	s_cbranch_vccnz .LBB0_1061
	v_lshl_add_u64 v[42:43], v[92:93], 0, v[72:73]
	v_cvt_pk_bf16_f32 v28, v28, v29
	v_cvt_pk_bf16_f32 v29, v30, v31
	v_lshl_add_u64 v[30:31], v[42:43], 1, s[34:35]
	global_store_dwordx2 v[30:31], v[28:29], off sc1
.LBB0_1061:
	ds_read_b64 v[28:29], v152 offset:9600
	s_and_b64 vcc, exec, s[6:7]
	s_waitcnt lgkmcnt(0)
	v_sub_f32_e32 v31, v37, v28
	v_sub_f32_e32 v30, v36, v28
	v_sub_f32_e32 v37, v39, v28
	v_sub_f32_e32 v36, v38, v28
	v_pk_mul_f32 v[36:37], v[28:29], v[36:37] op_sel:[1,0]
	v_pk_mul_f32 v[28:29], v[28:29], v[30:31] op_sel:[1,0]
	v_pk_fma_f32 v[30:31], v[50:51], v[36:37], v[54:55]
	v_pk_fma_f32 v[28:29], v[48:49], v[28:29], v[52:53]
	v_cndmask_b32_e64 v31, v40, v31, s[4:5]
	v_cndmask_b32_e64 v30, v40, v30, s[4:5]
	v_cndmask_b32_e64 v29, v40, v29, s[4:5]
	v_cndmask_b32_e64 v28, v40, v28, s[4:5]
	global_store_dwordx4 v[128:129], v[28:31], off offset:512 sc1
	s_cbranch_vccnz .LBB0_1063
	v_lshl_add_u64 v[36:37], v[94:95], 0, v[72:73]
	v_cvt_pk_bf16_f32 v28, v28, v29
	v_cvt_pk_bf16_f32 v29, v30, v31
	v_lshl_add_u64 v[30:31], v[36:37], 1, s[34:35]
	global_store_dwordx2 v[30:31], v[28:29], off sc1
.LBB0_1063:
	global_load_dwordx4 v[28:31], v[140:141], off offset:576
	global_load_dwordx4 v[36:39], v[144:145], off offset:576
	ds_read_b64 v[44:45], v152 offset:8192
	s_mov_b64 s[0:1], 0x90
	v_mov_b32_e32 v42, 0x7fc00000
	v_lshl_add_u64 v[40:41], v[136:137], 0, s[0:1]
	s_and_b64 vcc, exec, s[6:7]
	s_waitcnt lgkmcnt(0)
	v_sub_f32_e32 v1, v1, v44
	v_sub_f32_e32 v0, v0, v44
	v_sub_f32_e32 v3, v3, v44
	v_sub_f32_e32 v2, v2, v44
	v_pk_mul_f32 v[2:3], v[44:45], v[2:3] op_sel:[1,0]
	v_pk_mul_f32 v[0:1], v[44:45], v[0:1] op_sel:[1,0]
	s_waitcnt vmcnt(0)
	v_pk_fma_f32 v[2:3], v[30:31], v[2:3], v[38:39]
	v_pk_fma_f32 v[0:1], v[28:29], v[0:1], v[36:37]
	v_cndmask_b32_e64 v3, v42, v3, s[4:5]
	v_cndmask_b32_e64 v2, v42, v2, s[4:5]
	v_cndmask_b32_e64 v1, v42, v1, s[4:5]
	v_cndmask_b32_e64 v0, v42, v0, s[4:5]
	global_store_dwordx4 v[146:147], v[0:3], off offset:576 sc1
	s_cbranch_vccnz .LBB0_1065
	v_lshl_add_u64 v[44:45], v[142:143], 0, v[40:41]
	v_cvt_pk_bf16_f32 v0, v0, v1
	v_cvt_pk_bf16_f32 v1, v2, v3
	v_lshl_add_u64 v[2:3], v[44:45], 1, s[34:35]
	global_store_dwordx2 v[2:3], v[0:1], off sc1
.LBB0_1065:
	ds_read_b64 v[0:1], v152 offset:8320
	s_and_b64 vcc, exec, s[6:7]
	s_waitcnt lgkmcnt(0)
	v_sub_f32_e32 v3, v5, v0
	v_sub_f32_e32 v2, v4, v0
	v_sub_f32_e32 v5, v7, v0
	v_sub_f32_e32 v4, v6, v0
	v_pk_mul_f32 v[4:5], v[0:1], v[4:5] op_sel:[1,0]
	v_pk_mul_f32 v[0:1], v[0:1], v[2:3] op_sel:[1,0]
	v_pk_fma_f32 v[2:3], v[30:31], v[4:5], v[38:39]
	v_pk_fma_f32 v[0:1], v[28:29], v[0:1], v[36:37]
	v_cndmask_b32_e64 v3, v42, v3, s[4:5]
	v_cndmask_b32_e64 v2, v42, v2, s[4:5]
	v_cndmask_b32_e64 v1, v42, v1, s[4:5]
	v_cndmask_b32_e64 v0, v42, v0, s[4:5]
	global_store_dwordx4 v[126:127], v[0:3], off offset:576 sc1
	s_cbranch_vccnz .LBB0_1067
	v_lshl_add_u64 v[4:5], v[138:139], 0, v[40:41]
	v_cvt_pk_bf16_f32 v0, v0, v1
	v_cvt_pk_bf16_f32 v1, v2, v3
	v_lshl_add_u64 v[2:3], v[4:5], 1, s[34:35]
	global_store_dwordx2 v[2:3], v[0:1], off sc1
.LBB0_1067:
	ds_read_b64 v[0:1], v152 offset:8448
	s_and_b64 vcc, exec, s[6:7]
	s_waitcnt lgkmcnt(0)
	v_sub_f32_e32 v3, v9, v0
	v_sub_f32_e32 v2, v8, v0
	v_sub_f32_e32 v5, v11, v0
	v_sub_f32_e32 v4, v10, v0
	v_pk_mul_f32 v[4:5], v[0:1], v[4:5] op_sel:[1,0]
	v_pk_mul_f32 v[0:1], v[0:1], v[2:3] op_sel:[1,0]
	v_pk_fma_f32 v[2:3], v[30:31], v[4:5], v[38:39]
	v_pk_fma_f32 v[0:1], v[28:29], v[0:1], v[36:37]
	v_mov_b32_e32 v4, 0x7fc00000
	v_cndmask_b32_e64 v3, v4, v3, s[4:5]
	v_cndmask_b32_e64 v2, v4, v2, s[4:5]
	v_cndmask_b32_e64 v1, v4, v1, s[4:5]
	v_cndmask_b32_e64 v0, v4, v0, s[4:5]
	global_store_dwordx4 v[120:121], v[0:3], off offset:576 sc1
	s_cbranch_vccnz .LBB0_1069
	v_lshl_add_u64 v[6:7], v[124:125], 0, v[40:41]
	v_cvt_pk_bf16_f32 v0, v0, v1
	v_cvt_pk_bf16_f32 v1, v2, v3
	v_lshl_add_u64 v[2:3], v[6:7], 1, s[34:35]
	global_store_dwordx2 v[2:3], v[0:1], off sc1
.LBB0_1069:
	ds_read_b64 v[0:1], v152 offset:8576
	s_and_b64 vcc, exec, s[6:7]
	s_waitcnt lgkmcnt(0)
	v_sub_f32_e32 v3, v13, v0
	v_sub_f32_e32 v2, v12, v0
	v_sub_f32_e32 v7, v15, v0
	v_sub_f32_e32 v6, v14, v0
	v_pk_mul_f32 v[6:7], v[0:1], v[6:7] op_sel:[1,0]
	v_pk_mul_f32 v[0:1], v[0:1], v[2:3] op_sel:[1,0]
	v_pk_fma_f32 v[2:3], v[30:31], v[6:7], v[38:39]
	v_pk_fma_f32 v[0:1], v[28:29], v[0:1], v[36:37]
	v_cndmask_b32_e64 v3, v4, v3, s[4:5]
	v_cndmask_b32_e64 v2, v4, v2, s[4:5]
	v_cndmask_b32_e64 v1, v4, v1, s[4:5]
	v_cndmask_b32_e64 v0, v4, v0, s[4:5]
	global_store_dwordx4 v[118:119], v[0:3], off offset:576 sc1
	s_cbranch_vccnz .LBB0_1071
	v_lshl_add_u64 v[4:5], v[116:117], 0, v[40:41]
	v_cvt_pk_bf16_f32 v0, v0, v1
	v_cvt_pk_bf16_f32 v1, v2, v3
	v_lshl_add_u64 v[2:3], v[4:5], 1, s[34:35]
	global_store_dwordx2 v[2:3], v[0:1], off sc1
.LBB0_1071:
	ds_read_b64 v[0:1], v152 offset:9216
	s_and_b64 vcc, exec, s[6:7]
	s_waitcnt lgkmcnt(0)
	v_sub_f32_e32 v3, v17, v0
	v_sub_f32_e32 v2, v16, v0
	v_sub_f32_e32 v5, v19, v0
	v_sub_f32_e32 v4, v18, v0
	v_pk_mul_f32 v[4:5], v[0:1], v[4:5] op_sel:[1,0]
	v_pk_mul_f32 v[0:1], v[0:1], v[2:3] op_sel:[1,0]
	v_pk_fma_f32 v[2:3], v[30:31], v[4:5], v[38:39]
	v_pk_fma_f32 v[0:1], v[28:29], v[0:1], v[36:37]
	v_mov_b32_e32 v4, 0x7fc00000
	v_cndmask_b32_e64 v3, v4, v3, s[4:5]
	v_cndmask_b32_e64 v2, v4, v2, s[4:5]
	v_cndmask_b32_e64 v1, v4, v1, s[4:5]
	v_cndmask_b32_e64 v0, v4, v0, s[4:5]
	global_store_dwordx4 v[114:115], v[0:3], off offset:576 sc1
	s_cbranch_vccnz .LBB0_1073
	v_lshl_add_u64 v[6:7], v[112:113], 0, v[40:41]
	v_cvt_pk_bf16_f32 v0, v0, v1
	v_cvt_pk_bf16_f32 v1, v2, v3
	v_lshl_add_u64 v[2:3], v[6:7], 1, s[34:35]
	global_store_dwordx2 v[2:3], v[0:1], off sc1
.LBB0_1073:
	ds_read_b64 v[0:1], v152 offset:9344
	s_and_b64 vcc, exec, s[6:7]
	s_waitcnt lgkmcnt(0)
	v_sub_f32_e32 v3, v21, v0
	v_sub_f32_e32 v2, v20, v0
	v_sub_f32_e32 v7, v23, v0
	v_sub_f32_e32 v6, v22, v0
	v_pk_mul_f32 v[6:7], v[0:1], v[6:7] op_sel:[1,0]
	v_pk_mul_f32 v[0:1], v[0:1], v[2:3] op_sel:[1,0]
	v_pk_fma_f32 v[2:3], v[30:31], v[6:7], v[38:39]
	v_pk_fma_f32 v[0:1], v[28:29], v[0:1], v[36:37]
	v_cndmask_b32_e64 v3, v4, v3, s[4:5]
	v_cndmask_b32_e64 v2, v4, v2, s[4:5]
	v_cndmask_b32_e64 v1, v4, v1, s[4:5]
	v_cndmask_b32_e64 v0, v4, v0, s[4:5]
	global_store_dwordx4 v[110:111], v[0:3], off offset:576 sc1
	s_cbranch_vccnz .LBB0_1075
	v_lshl_add_u64 v[4:5], v[108:109], 0, v[40:41]
	v_cvt_pk_bf16_f32 v0, v0, v1
	v_cvt_pk_bf16_f32 v1, v2, v3
	v_lshl_add_u64 v[2:3], v[4:5], 1, s[34:35]
	global_store_dwordx2 v[2:3], v[0:1], off sc1
.LBB0_1075:
	ds_read_b64 v[0:1], v152 offset:9472
	s_and_b64 vcc, exec, s[6:7]
	s_waitcnt lgkmcnt(0)
	v_sub_f32_e32 v3, v25, v0
	v_sub_f32_e32 v2, v24, v0
	v_sub_f32_e32 v5, v27, v0
	v_sub_f32_e32 v4, v26, v0
	v_pk_mul_f32 v[4:5], v[0:1], v[4:5] op_sel:[1,0]
	v_pk_mul_f32 v[0:1], v[0:1], v[2:3] op_sel:[1,0]
	v_pk_fma_f32 v[2:3], v[30:31], v[4:5], v[38:39]
	v_pk_fma_f32 v[0:1], v[28:29], v[0:1], v[36:37]
	v_mov_b32_e32 v4, 0x7fc00000
	v_cndmask_b32_e64 v3, v4, v3, s[4:5]
	v_cndmask_b32_e64 v2, v4, v2, s[4:5]
	v_cndmask_b32_e64 v1, v4, v1, s[4:5]
	v_cndmask_b32_e64 v0, v4, v0, s[4:5]
	global_store_dwordx4 v[122:123], v[0:3], off offset:576 sc1
	s_cbranch_vccnz .LBB0_1077
	v_lshl_add_u64 v[6:7], v[92:93], 0, v[40:41]
	v_cvt_pk_bf16_f32 v0, v0, v1
	v_cvt_pk_bf16_f32 v1, v2, v3
	v_lshl_add_u64 v[2:3], v[6:7], 1, s[34:35]
	global_store_dwordx2 v[2:3], v[0:1], off sc1
.LBB0_1077:
	ds_read_b64 v[0:1], v152 offset:9600
	s_and_b64 vcc, exec, s[6:7]
	s_waitcnt lgkmcnt(0)
	v_sub_f32_e32 v3, v33, v0
	v_sub_f32_e32 v2, v32, v0
	v_sub_f32_e32 v7, v35, v0
	v_sub_f32_e32 v6, v34, v0
	v_pk_mul_f32 v[6:7], v[0:1], v[6:7] op_sel:[1,0]
	v_pk_mul_f32 v[0:1], v[0:1], v[2:3] op_sel:[1,0]
	v_pk_fma_f32 v[2:3], v[30:31], v[6:7], v[38:39]
	v_pk_fma_f32 v[0:1], v[28:29], v[0:1], v[36:37]
	v_cndmask_b32_e64 v3, v4, v3, s[4:5]
	v_cndmask_b32_e64 v2, v4, v2, s[4:5]
	v_cndmask_b32_e64 v1, v4, v1, s[4:5]
	v_cndmask_b32_e64 v0, v4, v0, s[4:5]
	global_store_dwordx4 v[128:129], v[0:3], off offset:576 sc1
	s_cbranch_vccnz .LBB0_1079
	v_lshl_add_u64 v[4:5], v[94:95], 0, v[40:41]
	v_cvt_pk_bf16_f32 v0, v0, v1
	v_cvt_pk_bf16_f32 v1, v2, v3
	v_lshl_add_u64 v[2:3], v[4:5], 1, s[34:35]
	global_store_dwordx2 v[2:3], v[0:1], off sc1

.LBB0_1147:
	v_mul_f32_e32 v151, 0xbfb8aa3b, v124
	v_exp_f32_e32 v151, v151
	v_mul_f32_e32 v152, 0xbfb8aa3b, v125
	v_exp_f32_e32 v152, v152
	v_mov_b32_e32 v150, v144
	v_add_f32_e32 v151, 1.0, v151
	v_rcp_f32_e32 v153, v151
	v_add_f32_e32 v151, 1.0, v152
	v_rcp_f32_e32 v152, v151
	v_mul_f32_e32 v124, v124, v153
	v_mul_f32_e32 v116, v124, v116
	v_mul_f32_e32 v124, v125, v152
	v_mul_f32_e32 v125, 0xbfb8aa3b, v126
	v_exp_f32_e32 v125, v125
	v_mul_f32_e32 v152, 0xbfb8aa3b, v127
	v_exp_f32_e32 v152, v152
	v_mul_f32_e32 v117, v124, v117
	v_add_f32_e32 v124, 1.0, v125
	v_rcp_f32_e32 v124, v124
	v_add_f32_e32 v125, 1.0, v152
	v_rcp_f32_e32 v125, v125
	v_cvt_pk_bf16_f32 v116, v116, v117
	v_mul_f32_e32 v117, v126, v124
	v_mul_f32_e32 v124, 0xbfb8aa3b, v120
	v_exp_f32_e32 v124, v124
	v_mul_f32_e32 v117, v117, v118
	v_mul_f32_e32 v118, v127, v125
	v_mul_f32_e32 v125, 0xbfb8aa3b, v121
	v_exp_f32_e32 v125, v125
	v_mul_f32_e32 v118, v118, v119
	v_add_f32_e32 v119, 1.0, v124
	v_rcp_f32_e32 v119, v119
	v_add_f32_e32 v124, 1.0, v125
	v_rcp_f32_e32 v124, v124
	v_cvt_pk_bf16_f32 v117, v117, v118
	v_mul_f32_e32 v118, v120, v119
	v_mul_f32_e32 v119, 0xbfb8aa3b, v122
	v_exp_f32_e32 v119, v119
	v_mul_f32_e32 v120, 0xbfb8aa3b, v123
	v_exp_f32_e32 v120, v120
	v_mul_f32_e32 v112, v118, v112
	v_mul_f32_e32 v118, v121, v124
	v_mul_f32_e32 v113, v118, v113
	v_add_f32_e32 v118, 1.0, v119
	v_rcp_f32_e32 v119, v118
	v_add_f32_e32 v118, 1.0, v120
	v_rcp_f32_e32 v120, v118
	s_lshl_b32 s17, s38, 8
	s_add_i32 s17, s17, s27
	v_and_or_b32 v149, v150, 15, s17
	s_lshl_b32 s17, s49, 7
	v_ashrrev_i32_e32 v150, 1, v150
	s_or_b32 s17, s17, s28
	v_and_b32_e32 v150, -8, v150
	v_cvt_pk_bf16_f32 v118, v112, v113
	v_mul_f32_e32 v112, v122, v119
	v_mul_f32_e32 v113, v123, v120
	v_mul_f32_e32 v122, 0xbfb8aa3b, v108
	v_add_u32_e32 v150, s17, v150
	v_mul_f32_e32 v112, v112, v114
	v_mul_f32_e32 v113, v113, v115
	v_exp_f32_e32 v122, v122
	v_mul_f32_e32 v123, 0xbfb8aa3b, v109
	v_ashrrev_i32_e32 v151, 31, v150
	v_cvt_pk_bf16_f32 v119, v112, v113
	v_mov_b64_e32 v[112:113], s[10:11]
	v_exp_f32_e32 v123, v123
	v_mad_i64_i32 v[120:121], s[40:41], v149, s48, v[112:113]
	v_lshlrev_b64 v[114:115], 1, v[150:151]
	v_lshl_add_u64 v[120:121], v[120:121], 0, v[114:115]
	global_store_dwordx4 v[120:121], v[116:119], off sc1
	s_andn2_b64 vcc, exec, s[4:5]
	s_mov_b64 s[4:5], -1
	v_add_f32_e32 v116, 1.0, v122
	v_rcp_f32_e32 v116, v116
	v_add_f32_e32 v117, 1.0, v123
	v_rcp_f32_e32 v117, v117
	v_or_b32_e32 v118, 16, v149
	v_mul_f32_e32 v108, v108, v116
	v_mul_f32_e32 v100, v108, v100
	v_mul_f32_e32 v108, v109, v117
	v_mul_f32_e32 v109, 0xbfb8aa3b, v110
	v_exp_f32_e32 v109, v109
	v_mul_f32_e32 v116, 0xbfb8aa3b, v111
	v_exp_f32_e32 v116, v116
	v_mul_f32_e32 v101, v108, v101
	v_add_f32_e32 v108, 1.0, v109
	v_rcp_f32_e32 v108, v108
	v_add_f32_e32 v109, 1.0, v116
	v_rcp_f32_e32 v109, v109
	v_cvt_pk_bf16_f32 v100, v100, v101
	v_mul_f32_e32 v101, v110, v108
	v_mul_f32_e32 v108, 0xbfb8aa3b, v104
	v_exp_f32_e32 v108, v108
	v_mul_f32_e32 v101, v101, v102
	v_mul_f32_e32 v102, v111, v109
	v_mul_f32_e32 v109, 0xbfb8aa3b, v105
	v_exp_f32_e32 v109, v109
	v_mul_f32_e32 v102, v102, v103
	v_add_f32_e32 v103, 1.0, v108
	v_rcp_f32_e32 v103, v103
	v_add_f32_e32 v108, 1.0, v109
	v_rcp_f32_e32 v108, v108
	v_cvt_pk_bf16_f32 v101, v101, v102
	v_mul_f32_e32 v102, v104, v103
	v_mul_f32_e32 v103, 0xbfb8aa3b, v106
	v_exp_f32_e32 v103, v103
	v_mul_f32_e32 v104, 0xbfb8aa3b, v107
	v_exp_f32_e32 v104, v104
	v_mul_f32_e32 v96, v102, v96
	v_mul_f32_e32 v102, v105, v108
	v_mul_f32_e32 v97, v102, v97
	v_add_f32_e32 v102, 1.0, v103
	v_rcp_f32_e32 v103, v102
	v_add_f32_e32 v102, 1.0, v104
	v_rcp_f32_e32 v104, v102
	v_cvt_pk_bf16_f32 v102, v96, v97
	v_mul_f32_e32 v96, v106, v103
	v_mul_f32_e32 v96, v96, v98
	v_mul_f32_e32 v97, v107, v104
	v_mul_f32_e32 v98, 0xbfb8aa3b, v92
	v_mul_f32_e32 v97, v97, v99
	v_exp_f32_e32 v98, v98
	v_mul_f32_e32 v99, 0xbfb8aa3b, v93
	v_exp_f32_e32 v99, v99
	v_cvt_pk_bf16_f32 v103, v96, v97
	v_mad_i64_i32 v[96:97], s[40:41], v118, s48, v[112:113]
	v_lshl_add_u64 v[96:97], v[96:97], 0, v[114:115]
	global_store_dwordx4 v[96:97], v[100:103], off sc1
	v_add_f32_e32 v96, 1.0, v98
	v_rcp_f32_e32 v96, v96
	v_add_f32_e32 v97, 1.0, v99
	v_rcp_f32_e32 v97, v97
	v_or_b32_e32 v98, 32, v149
	v_mul_f32_e32 v92, v92, v96
	v_mul_f32_e32 v84, v92, v84
	v_mul_f32_e32 v92, v93, v97
	v_mul_f32_e32 v93, 0xbfb8aa3b, v94
	v_exp_f32_e32 v93, v93
	v_mul_f32_e32 v96, 0xbfb8aa3b, v95
	v_exp_f32_e32 v96, v96
	v_mul_f32_e32 v85, v92, v85
	v_add_f32_e32 v92, 1.0, v93
	v_rcp_f32_e32 v92, v92
	v_add_f32_e32 v93, 1.0, v96
	v_rcp_f32_e32 v93, v93
	v_cvt_pk_bf16_f32 v84, v84, v85
	v_mul_f32_e32 v85, v94, v92
	v_mul_f32_e32 v92, 0xbfb8aa3b, v88
	v_exp_f32_e32 v92, v92
	v_mul_f32_e32 v85, v85, v86
	v_mul_f32_e32 v86, v95, v93
	v_mul_f32_e32 v93, 0xbfb8aa3b, v89
	v_exp_f32_e32 v93, v93
	v_mul_f32_e32 v86, v86, v87
	v_add_f32_e32 v87, 1.0, v92
	v_rcp_f32_e32 v87, v87
	v_add_f32_e32 v92, 1.0, v93
	v_rcp_f32_e32 v92, v92
	v_cvt_pk_bf16_f32 v85, v85, v86
	v_mul_f32_e32 v86, v88, v87
	v_mul_f32_e32 v87, 0xbfb8aa3b, v90
	v_exp_f32_e32 v87, v87
	v_mul_f32_e32 v88, 0xbfb8aa3b, v91
	v_exp_f32_e32 v88, v88
	v_mul_f32_e32 v80, v86, v80
	v_mul_f32_e32 v86, v89, v92
	v_mul_f32_e32 v81, v86, v81
	v_add_f32_e32 v86, 1.0, v87
	v_rcp_f32_e32 v87, v86
	v_add_f32_e32 v86, 1.0, v88
	v_rcp_f32_e32 v88, v86
	v_cvt_pk_bf16_f32 v86, v80, v81
	v_mul_f32_e32 v80, v90, v87
	v_mul_f32_e32 v80, v80, v82
	v_mul_f32_e32 v81, v91, v88
	v_mul_f32_e32 v82, 0xbfb8aa3b, v76
	v_mul_f32_e32 v81, v81, v83
	v_exp_f32_e32 v82, v82
	v_mul_f32_e32 v83, 0xbfb8aa3b, v77
	v_exp_f32_e32 v83, v83
	v_cvt_pk_bf16_f32 v87, v80, v81
	v_mad_i64_i32 v[80:81], s[40:41], v98, s48, v[112:113]
	v_lshl_add_u64 v[80:81], v[80:81], 0, v[114:115]
	global_store_dwordx4 v[80:81], v[84:87], off sc1
	v_add_f32_e32 v80, 1.0, v82
	v_rcp_f32_e32 v80, v80
	v_add_f32_e32 v81, 1.0, v83
	v_rcp_f32_e32 v81, v81
	v_or_b32_e32 v82, 48, v149
	v_mul_f32_e32 v76, v76, v80
	v_mul_f32_e32 v68, v76, v68
	v_mul_f32_e32 v76, v77, v81
	v_mul_f32_e32 v77, 0xbfb8aa3b, v78
	v_exp_f32_e32 v77, v77
	v_mul_f32_e32 v80, 0xbfb8aa3b, v79
	v_exp_f32_e32 v80, v80
	v_mul_f32_e32 v69, v76, v69
	v_add_f32_e32 v76, 1.0, v77
	v_rcp_f32_e32 v76, v76
	v_add_f32_e32 v77, 1.0, v80
	v_rcp_f32_e32 v77, v77
	v_cvt_pk_bf16_f32 v68, v68, v69
	v_mul_f32_e32 v69, v78, v76
	v_mul_f32_e32 v76, 0xbfb8aa3b, v72
	v_exp_f32_e32 v76, v76
	v_mul_f32_e32 v69, v69, v70
	v_mul_f32_e32 v70, v79, v77
	v_mul_f32_e32 v77, 0xbfb8aa3b, v73
	v_exp_f32_e32 v77, v77
	v_mul_f32_e32 v70, v70, v71
	v_add_f32_e32 v71, 1.0, v76
	v_rcp_f32_e32 v71, v71
	v_add_f32_e32 v76, 1.0, v77
	v_rcp_f32_e32 v76, v76
	v_cvt_pk_bf16_f32 v69, v69, v70
	v_mul_f32_e32 v70, v72, v71
	v_mul_f32_e32 v71, 0xbfb8aa3b, v74
	v_exp_f32_e32 v71, v71
	v_mul_f32_e32 v72, 0xbfb8aa3b, v75
	v_exp_f32_e32 v72, v72
	v_mul_f32_e32 v64, v70, v64
	v_mul_f32_e32 v70, v73, v76
	v_mul_f32_e32 v65, v70, v65
	v_add_f32_e32 v70, 1.0, v71
	v_rcp_f32_e32 v71, v70
	v_add_f32_e32 v70, 1.0, v72
	v_rcp_f32_e32 v72, v70
	v_cvt_pk_bf16_f32 v70, v64, v65
	v_mul_f32_e32 v64, v74, v71
	v_mul_f32_e32 v64, v64, v66
	v_mul_f32_e32 v65, v75, v72
	v_mul_f32_e32 v66, 0xbfb8aa3b, v60
	v_mul_f32_e32 v65, v65, v67
	v_exp_f32_e32 v66, v66
	v_mul_f32_e32 v67, 0xbfb8aa3b, v61
	v_exp_f32_e32 v67, v67
	v_cvt_pk_bf16_f32 v71, v64, v65
	v_mad_i64_i32 v[64:65], s[40:41], v82, s48, v[112:113]
	v_lshl_add_u64 v[64:65], v[64:65], 0, v[114:115]
	global_store_dwordx4 v[64:65], v[68:71], off sc1
	v_add_f32_e32 v64, 1.0, v66
	v_rcp_f32_e32 v64, v64
	v_add_f32_e32 v65, 1.0, v67
	v_rcp_f32_e32 v65, v65
	v_add_u32_e32 v66, 0x80, v149
	v_mul_f32_e32 v60, v60, v64
	v_mul_f32_e32 v52, v60, v52
	v_mul_f32_e32 v60, v61, v65
	v_mul_f32_e32 v61, 0xbfb8aa3b, v62
	v_exp_f32_e32 v61, v61
	v_mul_f32_e32 v64, 0xbfb8aa3b, v63
	v_exp_f32_e32 v64, v64
	v_mul_f32_e32 v53, v60, v53
	v_add_f32_e32 v60, 1.0, v61
	v_rcp_f32_e32 v60, v60
	v_add_f32_e32 v61, 1.0, v64
	v_rcp_f32_e32 v61, v61
	v_cvt_pk_bf16_f32 v52, v52, v53
	v_mul_f32_e32 v53, v62, v60
	v_mul_f32_e32 v60, 0xbfb8aa3b, v56
	v_exp_f32_e32 v60, v60
	v_mul_f32_e32 v53, v53, v54
	v_mul_f32_e32 v54, v63, v61
	v_mul_f32_e32 v61, 0xbfb8aa3b, v57
	v_exp_f32_e32 v61, v61
	v_mul_f32_e32 v54, v54, v55
	v_add_f32_e32 v55, 1.0, v60
	v_rcp_f32_e32 v55, v55
	v_add_f32_e32 v60, 1.0, v61
	v_rcp_f32_e32 v60, v60
	v_cvt_pk_bf16_f32 v53, v53, v54
	v_mul_f32_e32 v54, v56, v55
	v_mul_f32_e32 v55, 0xbfb8aa3b, v58
	v_exp_f32_e32 v55, v55
	v_mul_f32_e32 v56, 0xbfb8aa3b, v59
	v_exp_f32_e32 v56, v56
	v_mul_f32_e32 v48, v54, v48
	v_mul_f32_e32 v54, v57, v60
	v_mul_f32_e32 v49, v54, v49
	v_add_f32_e32 v54, 1.0, v55
	v_rcp_f32_e32 v55, v54
	v_add_f32_e32 v54, 1.0, v56
	v_rcp_f32_e32 v56, v54
	v_cvt_pk_bf16_f32 v54, v48, v49
	v_mul_f32_e32 v48, v58, v55
	v_mul_f32_e32 v48, v48, v50
	v_mul_f32_e32 v49, v59, v56
	v_mul_f32_e32 v50, 0xbfb8aa3b, v44
	v_mul_f32_e32 v49, v49, v51
	v_exp_f32_e32 v50, v50
	v_mul_f32_e32 v51, 0xbfb8aa3b, v45
	v_exp_f32_e32 v51, v51
	v_cvt_pk_bf16_f32 v55, v48, v49
	v_mad_i64_i32 v[48:49], s[40:41], v66, s48, v[112:113]
	v_lshl_add_u64 v[48:49], v[48:49], 0, v[114:115]
	global_store_dwordx4 v[48:49], v[52:55], off sc1
	v_add_f32_e32 v48, 1.0, v50
	v_rcp_f32_e32 v48, v48
	v_add_f32_e32 v49, 1.0, v51
	v_rcp_f32_e32 v49, v49
	v_add_u32_e32 v50, 0x90, v149
	v_mul_f32_e32 v44, v44, v48
	v_mul_f32_e32 v36, v44, v36
	v_mul_f32_e32 v44, v45, v49
	v_mul_f32_e32 v45, 0xbfb8aa3b, v46
	v_exp_f32_e32 v45, v45
	v_mul_f32_e32 v48, 0xbfb8aa3b, v47
	v_exp_f32_e32 v48, v48
	v_mul_f32_e32 v37, v44, v37
	v_add_f32_e32 v44, 1.0, v45
	v_rcp_f32_e32 v44, v44
	v_add_f32_e32 v45, 1.0, v48
	v_rcp_f32_e32 v45, v45
	v_cvt_pk_bf16_f32 v36, v36, v37
	v_mul_f32_e32 v37, v46, v44
	v_mul_f32_e32 v44, 0xbfb8aa3b, v40
	v_exp_f32_e32 v44, v44
	v_mul_f32_e32 v37, v37, v38
	v_mul_f32_e32 v38, v47, v45
	v_mul_f32_e32 v45, 0xbfb8aa3b, v41
	v_exp_f32_e32 v45, v45
	v_mul_f32_e32 v38, v38, v39
	v_add_f32_e32 v39, 1.0, v44
	v_rcp_f32_e32 v39, v39
	v_add_f32_e32 v44, 1.0, v45
	v_rcp_f32_e32 v44, v44
	v_cvt_pk_bf16_f32 v37, v37, v38
	v_mul_f32_e32 v38, v40, v39
	v_mul_f32_e32 v39, 0xbfb8aa3b, v42
	v_exp_f32_e32 v39, v39
	v_mul_f32_e32 v40, 0xbfb8aa3b, v43
	v_exp_f32_e32 v40, v40
	v_mul_f32_e32 v32, v38, v32
	v_mul_f32_e32 v38, v41, v44
	v_mul_f32_e32 v33, v38, v33
	v_add_f32_e32 v38, 1.0, v39
	v_rcp_f32_e32 v39, v38
	v_add_f32_e32 v38, 1.0, v40
	v_rcp_f32_e32 v40, v38
	v_cvt_pk_bf16_f32 v38, v32, v33
	v_mul_f32_e32 v32, v42, v39
	v_mul_f32_e32 v32, v32, v34
	v_mul_f32_e32 v33, v43, v40
	v_mul_f32_e32 v34, 0xbfb8aa3b, v28
	v_mul_f32_e32 v33, v33, v35
	v_exp_f32_e32 v34, v34
	v_mul_f32_e32 v35, 0xbfb8aa3b, v29
	v_exp_f32_e32 v35, v35
	v_cvt_pk_bf16_f32 v39, v32, v33
	v_mad_i64_i32 v[32:33], s[40:41], v50, s48, v[112:113]
	v_lshl_add_u64 v[32:33], v[32:33], 0, v[114:115]
	global_store_dwordx4 v[32:33], v[36:39], off sc1
	v_add_f32_e32 v32, 1.0, v34
	v_rcp_f32_e32 v32, v32
	v_add_f32_e32 v33, 1.0, v35
	v_rcp_f32_e32 v33, v33
	v_add_u32_e32 v34, 0xa0, v149
	v_mul_f32_e32 v28, v28, v32
	v_mul_f32_e32 v20, v28, v20
	v_mul_f32_e32 v28, v29, v33
	v_mul_f32_e32 v29, 0xbfb8aa3b, v30
	v_exp_f32_e32 v29, v29
	v_mul_f32_e32 v32, 0xbfb8aa3b, v31
	v_exp_f32_e32 v32, v32
	v_mul_f32_e32 v21, v28, v21
	v_add_f32_e32 v28, 1.0, v29
	v_rcp_f32_e32 v28, v28
	v_add_f32_e32 v29, 1.0, v32
	v_rcp_f32_e32 v29, v29
	v_cvt_pk_bf16_f32 v20, v20, v21
	v_mul_f32_e32 v21, v30, v28
	v_mul_f32_e32 v28, 0xbfb8aa3b, v24
	v_exp_f32_e32 v28, v28
	v_mul_f32_e32 v21, v21, v22
	v_mul_f32_e32 v22, v31, v29
	v_mul_f32_e32 v29, 0xbfb8aa3b, v25
	v_exp_f32_e32 v29, v29
	v_mul_f32_e32 v22, v22, v23
	v_add_f32_e32 v23, 1.0, v28
	v_rcp_f32_e32 v23, v23
	v_add_f32_e32 v28, 1.0, v29
	v_rcp_f32_e32 v28, v28
	v_cvt_pk_bf16_f32 v21, v21, v22
	v_mul_f32_e32 v22, v24, v23
	v_mul_f32_e32 v23, 0xbfb8aa3b, v26
	v_exp_f32_e32 v23, v23
	v_mul_f32_e32 v24, 0xbfb8aa3b, v27
	v_exp_f32_e32 v24, v24
	v_mul_f32_e32 v16, v22, v16
	v_mul_f32_e32 v22, v25, v28
	v_mul_f32_e32 v17, v22, v17
	v_add_f32_e32 v22, 1.0, v23
	v_rcp_f32_e32 v23, v22
	v_add_f32_e32 v22, 1.0, v24
	v_rcp_f32_e32 v24, v22
	v_cvt_pk_bf16_f32 v22, v16, v17
	v_mul_f32_e32 v16, v26, v23
	v_mul_f32_e32 v16, v16, v18
	v_mul_f32_e32 v17, v27, v24
	v_mul_f32_e32 v18, 0xbfb8aa3b, v12
	v_mul_f32_e32 v17, v17, v19
	v_exp_f32_e32 v18, v18
	v_mul_f32_e32 v19, 0xbfb8aa3b, v13
	v_exp_f32_e32 v19, v19
	v_cvt_pk_bf16_f32 v23, v16, v17
	v_mad_i64_i32 v[16:17], s[40:41], v34, s48, v[112:113]
	v_lshl_add_u64 v[16:17], v[16:17], 0, v[114:115]
	global_store_dwordx4 v[16:17], v[20:23], off sc1
	v_add_f32_e32 v16, 1.0, v18
	v_rcp_f32_e32 v16, v16
	v_add_f32_e32 v17, 1.0, v19
	v_rcp_f32_e32 v17, v17
	v_add_u32_e32 v18, 0xb0, v149
	v_mul_f32_e32 v12, v12, v16
	v_mul_f32_e32 v4, v12, v4
	v_mul_f32_e32 v12, v13, v17
	v_mul_f32_e32 v13, 0xbfb8aa3b, v14
	v_exp_f32_e32 v13, v13
	v_mul_f32_e32 v16, 0xbfb8aa3b, v15
	v_exp_f32_e32 v16, v16
	v_mul_f32_e32 v5, v12, v5
	v_add_f32_e32 v12, 1.0, v13
	v_rcp_f32_e32 v12, v12
	v_add_f32_e32 v13, 1.0, v16
	v_rcp_f32_e32 v13, v13
	v_cvt_pk_bf16_f32 v4, v4, v5
	v_mul_f32_e32 v5, v14, v12
	v_mul_f32_e32 v12, 0xbfb8aa3b, v8
	v_exp_f32_e32 v12, v12
	v_mul_f32_e32 v5, v5, v6
	v_mul_f32_e32 v6, v15, v13
	v_mul_f32_e32 v13, 0xbfb8aa3b, v9
	v_exp_f32_e32 v13, v13
	v_mul_f32_e32 v6, v6, v7
	v_add_f32_e32 v7, 1.0, v12
	v_rcp_f32_e32 v7, v7
	v_add_f32_e32 v12, 1.0, v13
	v_rcp_f32_e32 v12, v12
	v_cvt_pk_bf16_f32 v5, v5, v6
	v_mul_f32_e32 v6, v8, v7
	v_mul_f32_e32 v7, 0xbfb8aa3b, v10
	v_exp_f32_e32 v7, v7
	v_mul_f32_e32 v8, 0xbfb8aa3b, v11
	v_exp_f32_e32 v8, v8
	v_mul_f32_e32 v0, v6, v0
	v_mul_f32_e32 v6, v9, v12
	v_mul_f32_e32 v1, v6, v1
	v_add_f32_e32 v6, 1.0, v7
	v_rcp_f32_e32 v7, v6
	v_add_f32_e32 v6, 1.0, v8
	v_rcp_f32_e32 v8, v6
	v_cvt_pk_bf16_f32 v6, v0, v1
	v_mul_f32_e32 v0, v10, v7
	v_mul_f32_e32 v0, v0, v2
	v_mul_f32_e32 v1, v11, v8
	v_mul_f32_e32 v1, v1, v3
	v_cvt_pk_bf16_f32 v7, v0, v1
	v_mad_i64_i32 v[0:1], s[40:41], v18, s48, v[112:113]
	v_lshl_add_u64 v[0:1], v[0:1], 0, v[114:115]
	global_store_dwordx4 v[0:1], v[4:7], off sc1
	s_cbranch_vccnz .LBB0_1140
	s_andn2_b64 vcc, exec, s[8:9]
	s_cbranch_vccnz .LBB0_1139
	s_barrier
	s_branch .LBB0_1139

.LBB0_1272:
	s_or_b64 exec, exec, s[6:7]
	s_waitcnt lgkmcnt(0)
	s_barrier
	v_lshl_add_u64 v[154:155], s[12:13], 0, v[132:133]
	v_lshl_add_u64 v[156:157], s[14:15], 0, v[132:133]
	global_load_dwordx4 v[128:131], v[154:155], off
	global_load_dwordx4 v[132:135], v[156:157], off
	v_or_b32_e32 v158, s0, v158
	v_lshl_add_u32 v167, v158, 3, 0
	ds_read_b64 v[160:161], v167 offset:8192
	v_mov_b32_e32 v166, 0x7fc00000
	s_waitcnt lgkmcnt(1)
	v_cmp_eq_u32_e32 vcc, 0, v159
	v_add_u32_e32 v164, s20, v158
	v_ashrrev_i32_e32 v165, 31, v164
	s_waitcnt lgkmcnt(0)
	v_sub_f32_e32 v113, v113, v160
	v_sub_f32_e32 v112, v112, v160
	v_sub_f32_e32 v115, v115, v160
	v_sub_f32_e32 v114, v114, v160
	v_pk_mul_f32 v[114:115], v[160:161], v[114:115] op_sel:[1,0]
	v_pk_mul_f32 v[112:113], v[160:161], v[112:113] op_sel:[1,0]
	s_add_u32 s4, s18, 0x7200000
	v_add_u32_e32 v168, 16, v164
	v_lshlrev_b64 v[162:163], 10, v[164:165]
	s_addc_u32 s5, s19, 0
	v_ashrrev_i32_e32 v169, 31, v168
	v_lshl_add_u64 v[176:177], v[162:163], 0, v[136:137]
	v_lshlrev_b64 v[160:161], 10, v[168:169]
	v_lshl_add_u64 v[168:169], v[176:177], 1, s[4:5]
	v_add_u32_e32 v170, 32, v164
	v_ashrrev_i32_e32 v171, 31, v170
	v_lshlrev_b64 v[158:159], 10, v[170:171]
	v_add_u32_e32 v172, 48, v164
	v_add_u32_e32 v174, 0x80, v164
	v_ashrrev_i32_e32 v173, 31, v172
	v_ashrrev_i32_e32 v175, 31, v174
	s_mov_b64 s[0:1], 0x80
	s_waitcnt vmcnt(0)
	v_pk_fma_f32 v[112:113], v[128:129], v[112:113], v[132:133]
	v_pk_fma_f32 v[114:115], v[130:131], v[114:115], v[134:135]
	v_cndmask_b32_e32 v113, v166, v113, vcc
	v_cndmask_b32_e32 v115, v166, v115, vcc
	v_cndmask_b32_e32 v114, v166, v114, vcc
	v_cndmask_b32_e32 v112, v166, v112, vcc
	global_store_dwordx4 v[138:139], v[112:115], off sc1
	s_nop 1
	v_cvt_pk_bf16_f32 v112, v112, v113
	v_cvt_pk_bf16_f32 v113, v114, v115
	ds_read_b64 v[114:115], v167 offset:8320
	global_store_dwordx2 v[168:169], v[112:113], off sc1
	s_waitcnt lgkmcnt(0)
	v_sub_f32_e32 v113, v121, v114
	v_sub_f32_e32 v112, v120, v114
	v_sub_f32_e32 v121, v123, v114
	v_sub_f32_e32 v120, v122, v114
	v_pk_mul_f32 v[120:121], v[114:115], v[120:121] op_sel:[1,0]
	v_pk_mul_f32 v[112:113], v[114:115], v[112:113] op_sel:[1,0]
	v_pk_fma_f32 v[114:115], v[130:131], v[120:121], v[134:135]
	v_pk_fma_f32 v[112:113], v[128:129], v[112:113], v[132:133]
	v_cndmask_b32_e32 v115, v166, v115, vcc
	v_cndmask_b32_e32 v114, v166, v114, vcc
	v_cndmask_b32_e32 v113, v166, v113, vcc
	v_cndmask_b32_e32 v112, v166, v112, vcc
	global_store_dwordx4 v[140:141], v[112:115], off sc1
	v_lshl_add_u64 v[122:123], v[160:161], 0, v[136:137]
	v_lshl_add_u64 v[122:123], v[122:123], 1, s[4:5]
	v_cvt_pk_bf16_f32 v112, v112, v113
	v_cvt_pk_bf16_f32 v113, v114, v115
	ds_read_b64 v[120:121], v167 offset:8448
	global_store_dwordx2 v[122:123], v[112:113], off sc1
	v_lshlrev_b64 v[114:115], 10, v[172:173]
	s_waitcnt lgkmcnt(0)
	v_sub_f32_e32 v113, v125, v120
	v_sub_f32_e32 v112, v124, v120
	v_sub_f32_e32 v123, v127, v120
	v_sub_f32_e32 v122, v126, v120
	v_pk_mul_f32 v[122:123], v[120:121], v[122:123] op_sel:[1,0]
	v_pk_mul_f32 v[112:113], v[120:121], v[112:113] op_sel:[1,0]
	v_pk_fma_f32 v[120:121], v[130:131], v[122:123], v[134:135]
	v_pk_fma_f32 v[112:113], v[128:129], v[112:113], v[132:133]
	v_cndmask_b32_e32 v123, v166, v121, vcc
	v_cndmask_b32_e32 v122, v166, v120, vcc
	v_cndmask_b32_e32 v121, v166, v113, vcc
	v_cndmask_b32_e32 v120, v166, v112, vcc
	global_store_dwordx4 v[142:143], v[120:123], off sc1
	v_lshl_add_u64 v[124:125], v[158:159], 0, v[136:137]
	v_lshl_add_u64 v[124:125], v[124:125], 1, s[4:5]
	v_cvt_pk_bf16_f32 v120, v120, v121
	v_cvt_pk_bf16_f32 v121, v122, v123
	ds_read_b64 v[122:123], v167 offset:8576
	global_store_dwordx2 v[124:125], v[120:121], off sc1
	v_lshlrev_b64 v[112:113], 10, v[174:175]
	v_lshl_add_u64 v[120:121], v[114:115], 0, v[136:137]
	v_lshl_add_u64 v[120:121], v[120:121], 1, s[4:5]
	s_waitcnt lgkmcnt(0)
	v_sub_f32_e32 v117, v117, v122
	v_sub_f32_e32 v116, v116, v122
	v_sub_f32_e32 v119, v119, v122
	v_sub_f32_e32 v118, v118, v122
	v_pk_mul_f32 v[118:119], v[122:123], v[118:119] op_sel:[1,0]
	v_pk_mul_f32 v[116:117], v[122:123], v[116:117] op_sel:[1,0]
	v_pk_fma_f32 v[118:119], v[130:131], v[118:119], v[134:135]
	v_pk_fma_f32 v[116:117], v[128:129], v[116:117], v[132:133]
	v_cndmask_b32_e32 v119, v166, v119, vcc
	v_cndmask_b32_e32 v118, v166, v118, vcc
	v_cndmask_b32_e32 v117, v166, v117, vcc
	v_cndmask_b32_e32 v116, v166, v116, vcc
	global_store_dwordx4 v[144:145], v[116:119], off sc1
	v_lshl_add_u64 v[122:123], v[112:113], 0, v[136:137]
	s_nop 0
	v_cvt_pk_bf16_f32 v116, v116, v117
	v_cvt_pk_bf16_f32 v117, v118, v119
	ds_read_b64 v[118:119], v167 offset:9216
	global_store_dwordx2 v[120:121], v[116:117], off sc1
	s_waitcnt lgkmcnt(0)
	v_sub_f32_e32 v105, v105, v118
	v_sub_f32_e32 v104, v104, v118
	v_sub_f32_e32 v107, v107, v118
	v_sub_f32_e32 v106, v106, v118
	v_pk_mul_f32 v[106:107], v[118:119], v[106:107] op_sel:[1,0]
	v_pk_mul_f32 v[104:105], v[118:119], v[104:105] op_sel:[1,0]
	v_pk_fma_f32 v[106:107], v[130:131], v[106:107], v[134:135]
	v_pk_fma_f32 v[104:105], v[128:129], v[104:105], v[132:133]
	v_cndmask_b32_e32 v107, v166, v107, vcc
	v_cndmask_b32_e32 v106, v166, v106, vcc
	v_cndmask_b32_e32 v105, v166, v105, vcc
	v_cndmask_b32_e32 v104, v166, v104, vcc
	global_store_dwordx4 v[146:147], v[104:107], off sc1
	s_nop 1
	v_cvt_pk_bf16_f32 v104, v104, v105
	v_cvt_pk_bf16_f32 v105, v106, v107
	v_lshl_add_u64 v[106:107], v[122:123], 1, s[4:5]
	global_store_dwordx2 v[106:107], v[104:105], off sc1
	ds_read_b64 v[106:107], v167 offset:9344
	v_add_u32_e32 v104, 0x90, v164
	v_ashrrev_i32_e32 v105, 31, v104
	v_lshlrev_b64 v[104:105], 10, v[104:105]
	v_lshl_add_u64 v[116:117], v[104:105], 0, v[136:137]
	s_waitcnt lgkmcnt(0)
	v_sub_f32_e32 v89, v89, v106
	v_sub_f32_e32 v88, v88, v106
	v_sub_f32_e32 v91, v91, v106
	v_sub_f32_e32 v90, v90, v106
	v_pk_mul_f32 v[90:91], v[106:107], v[90:91] op_sel:[1,0]
	v_pk_mul_f32 v[88:89], v[106:107], v[88:89] op_sel:[1,0]
	v_pk_fma_f32 v[90:91], v[130:131], v[90:91], v[134:135]
	v_pk_fma_f32 v[88:89], v[128:129], v[88:89], v[132:133]
	v_cndmask_b32_e32 v91, v166, v91, vcc
	v_cndmask_b32_e32 v90, v166, v90, vcc
	v_cndmask_b32_e32 v89, v166, v89, vcc
	v_cndmask_b32_e32 v88, v166, v88, vcc
	global_store_dwordx4 v[148:149], v[88:91], off sc1
	s_nop 1
	v_cvt_pk_bf16_f32 v88, v88, v89
	v_cvt_pk_bf16_f32 v89, v90, v91
	v_lshl_add_u64 v[90:91], v[116:117], 1, s[4:5]
	global_store_dwordx2 v[90:91], v[88:89], off sc1
	ds_read_b64 v[90:91], v167 offset:9472
	v_add_u32_e32 v88, 0xa0, v164
	v_ashrrev_i32_e32 v89, 31, v88
	v_lshlrev_b64 v[88:89], 10, v[88:89]
	v_lshl_add_u64 v[106:107], v[88:89], 0, v[136:137]
	s_waitcnt lgkmcnt(0)
	v_sub_f32_e32 v65, v65, v90
	v_sub_f32_e32 v64, v64, v90
	v_sub_f32_e32 v67, v67, v90
	v_sub_f32_e32 v66, v66, v90
	v_pk_mul_f32 v[66:67], v[90:91], v[66:67] op_sel:[1,0]
	v_pk_mul_f32 v[64:65], v[90:91], v[64:65] op_sel:[1,0]
	v_pk_fma_f32 v[66:67], v[130:131], v[66:67], v[134:135]
	v_pk_fma_f32 v[64:65], v[128:129], v[64:65], v[132:133]
	v_cndmask_b32_e32 v67, v166, v67, vcc
	v_cndmask_b32_e32 v66, v166, v66, vcc
	v_cndmask_b32_e32 v65, v166, v65, vcc
	v_cndmask_b32_e32 v64, v166, v64, vcc
	global_store_dwordx4 v[150:151], v[64:67], off sc1
	s_nop 1
	v_cvt_pk_bf16_f32 v64, v64, v65
	v_cvt_pk_bf16_f32 v65, v66, v67
	v_lshl_add_u64 v[66:67], v[106:107], 1, s[4:5]
	global_store_dwordx2 v[66:67], v[64:65], off sc1
	ds_read_b64 v[66:67], v167 offset:9600
	v_add_u32_e32 v64, 0xb0, v164
	v_ashrrev_i32_e32 v65, 31, v64
	v_lshlrev_b64 v[64:65], 10, v[64:65]
	v_lshl_add_u64 v[90:91], v[64:65], 0, v[136:137]
	s_waitcnt lgkmcnt(0)
	v_sub_f32_e32 v37, v37, v66
	v_sub_f32_e32 v36, v36, v66
	v_sub_f32_e32 v39, v39, v66
	v_sub_f32_e32 v38, v38, v66
	v_pk_mul_f32 v[38:39], v[66:67], v[38:39] op_sel:[1,0]
	v_pk_mul_f32 v[36:37], v[66:67], v[36:37] op_sel:[1,0]
	v_pk_fma_f32 v[38:39], v[130:131], v[38:39], v[134:135]
	v_pk_fma_f32 v[36:37], v[128:129], v[36:37], v[132:133]
	v_cndmask_b32_e32 v39, v166, v39, vcc
	v_cndmask_b32_e32 v38, v166, v38, vcc
	v_cndmask_b32_e32 v37, v166, v37, vcc
	v_cndmask_b32_e32 v36, v166, v36, vcc
	global_store_dwordx4 v[152:153], v[36:39], off sc1
	s_nop 1
	v_cvt_pk_bf16_f32 v36, v36, v37
	v_cvt_pk_bf16_f32 v37, v38, v39
	v_lshl_add_u64 v[38:39], v[90:91], 1, s[4:5]
	global_store_dwordx2 v[38:39], v[36:37], off sc1
	global_load_dwordx4 v[36:39], v[154:155], off offset:64
	global_load_dwordx4 v[116:119], v[156:157], off offset:64
	ds_read_b64 v[66:67], v167 offset:8192
	v_lshl_add_u64 v[90:91], v[136:137], 0, 16
	s_waitcnt lgkmcnt(0)
	v_sub_f32_e32 v85, v85, v66
	v_sub_f32_e32 v84, v84, v66
	v_sub_f32_e32 v87, v87, v66
	v_sub_f32_e32 v86, v86, v66
	v_pk_mul_f32 v[86:87], v[66:67], v[86:87] op_sel:[1,0]
	v_pk_mul_f32 v[66:67], v[66:67], v[84:85] op_sel:[1,0]
	s_waitcnt vmcnt(0)
	v_pk_fma_f32 v[84:85], v[38:39], v[86:87], v[118:119]
	v_pk_fma_f32 v[66:67], v[36:37], v[66:67], v[116:117]
	v_cndmask_b32_e32 v87, v166, v85, vcc
	v_cndmask_b32_e32 v86, v166, v84, vcc
	v_cndmask_b32_e32 v85, v166, v67, vcc
	v_cndmask_b32_e32 v84, v166, v66, vcc
	global_store_dwordx4 v[138:139], v[84:87], off offset:64 sc1
	v_cvt_pk_bf16_f32 v66, v84, v85
	v_cvt_pk_bf16_f32 v67, v86, v87
	ds_read_b64 v[84:85], v167 offset:8320
	s_nop 0
	v_lshl_add_u64 v[86:87], v[162:163], 0, v[90:91]
	v_lshl_add_u64 v[86:87], v[86:87], 1, s[4:5]
	global_store_dwordx2 v[86:87], v[66:67], off sc1
	s_waitcnt lgkmcnt(0)
	v_sub_f32_e32 v67, v93, v84
	v_sub_f32_e32 v66, v92, v84
	v_sub_f32_e32 v87, v95, v84
	v_sub_f32_e32 v86, v94, v84
	v_pk_mul_f32 v[86:87], v[84:85], v[86:87] op_sel:[1,0]
	v_pk_mul_f32 v[66:67], v[84:85], v[66:67] op_sel:[1,0]
	v_pk_fma_f32 v[84:85], v[38:39], v[86:87], v[118:119]
	v_pk_fma_f32 v[66:67], v[36:37], v[66:67], v[116:117]
	v_cndmask_b32_e32 v87, v166, v85, vcc
	v_cndmask_b32_e32 v86, v166, v84, vcc
	v_cndmask_b32_e32 v85, v166, v67, vcc
	v_cndmask_b32_e32 v84, v166, v66, vcc
	global_store_dwordx4 v[140:141], v[84:87], off offset:64 sc1
	v_cvt_pk_bf16_f32 v66, v84, v85
	v_cvt_pk_bf16_f32 v67, v86, v87
	ds_read_b64 v[84:85], v167 offset:8448
	s_nop 0
	v_lshl_add_u64 v[86:87], v[160:161], 0, v[90:91]
	v_lshl_add_u64 v[86:87], v[86:87], 1, s[4:5]
	global_store_dwordx2 v[86:87], v[66:67], off sc1
	s_waitcnt lgkmcnt(0)
	v_sub_f32_e32 v67, v97, v84
	v_sub_f32_e32 v66, v96, v84
	v_sub_f32_e32 v87, v99, v84
	v_sub_f32_e32 v86, v98, v84
	v_pk_mul_f32 v[86:87], v[84:85], v[86:87] op_sel:[1,0]
	v_pk_mul_f32 v[66:67], v[84:85], v[66:67] op_sel:[1,0]
	v_pk_fma_f32 v[84:85], v[38:39], v[86:87], v[118:119]
	v_pk_fma_f32 v[66:67], v[36:37], v[66:67], v[116:117]
	v_cndmask_b32_e32 v87, v166, v85, vcc
	v_cndmask_b32_e32 v86, v166, v84, vcc
	v_cndmask_b32_e32 v85, v166, v67, vcc
	v_cndmask_b32_e32 v84, v166, v66, vcc
	global_store_dwordx4 v[142:143], v[84:87], off offset:64 sc1
	v_cvt_pk_bf16_f32 v66, v84, v85
	v_cvt_pk_bf16_f32 v67, v86, v87
	ds_read_b64 v[84:85], v167 offset:8576
	s_nop 0
	v_lshl_add_u64 v[86:87], v[158:159], 0, v[90:91]
	v_lshl_add_u64 v[86:87], v[86:87], 1, s[4:5]
	global_store_dwordx2 v[86:87], v[66:67], off sc1
	s_waitcnt lgkmcnt(0)
	v_sub_f32_e32 v67, v109, v84
	v_sub_f32_e32 v66, v108, v84
	v_sub_f32_e32 v87, v111, v84
	v_sub_f32_e32 v86, v110, v84
	v_pk_mul_f32 v[86:87], v[84:85], v[86:87] op_sel:[1,0]
	v_pk_mul_f32 v[66:67], v[84:85], v[66:67] op_sel:[1,0]
	v_pk_fma_f32 v[84:85], v[38:39], v[86:87], v[118:119]
	v_pk_fma_f32 v[66:67], v[36:37], v[66:67], v[116:117]
	v_cndmask_b32_e32 v87, v166, v85, vcc
	v_cndmask_b32_e32 v86, v166, v84, vcc
	v_cndmask_b32_e32 v85, v166, v67, vcc
	v_cndmask_b32_e32 v84, v166, v66, vcc
	global_store_dwordx4 v[144:145], v[84:87], off offset:64 sc1
	v_cvt_pk_bf16_f32 v66, v84, v85
	v_cvt_pk_bf16_f32 v67, v86, v87
	ds_read_b64 v[84:85], v167 offset:9216
	s_nop 0
	v_lshl_add_u64 v[86:87], v[114:115], 0, v[90:91]
	v_lshl_add_u64 v[86:87], v[86:87], 1, s[4:5]
	global_store_dwordx2 v[86:87], v[66:67], off sc1
	s_waitcnt lgkmcnt(0)
	v_sub_f32_e32 v67, v101, v84
	v_sub_f32_e32 v66, v100, v84
	v_sub_f32_e32 v87, v103, v84
	v_sub_f32_e32 v86, v102, v84
	v_pk_mul_f32 v[86:87], v[84:85], v[86:87] op_sel:[1,0]
	v_pk_mul_f32 v[66:67], v[84:85], v[66:67] op_sel:[1,0]
	v_pk_fma_f32 v[84:85], v[38:39], v[86:87], v[118:119]
	v_pk_fma_f32 v[66:67], v[36:37], v[66:67], v[116:117]
	v_cndmask_b32_e32 v87, v166, v85, vcc
	v_cndmask_b32_e32 v86, v166, v84, vcc
	v_cndmask_b32_e32 v85, v166, v67, vcc
	v_cndmask_b32_e32 v84, v166, v66, vcc
	global_store_dwordx4 v[146:147], v[84:87], off offset:64 sc1
	v_cvt_pk_bf16_f32 v66, v84, v85
	v_cvt_pk_bf16_f32 v67, v86, v87
	ds_read_b64 v[84:85], v167 offset:9344
	s_nop 0
	v_lshl_add_u64 v[86:87], v[112:113], 0, v[90:91]
	v_lshl_add_u64 v[86:87], v[86:87], 1, s[4:5]
	global_store_dwordx2 v[86:87], v[66:67], off sc1
	s_waitcnt lgkmcnt(0)
	v_sub_f32_e32 v67, v81, v84
	v_sub_f32_e32 v66, v80, v84
	v_sub_f32_e32 v81, v83, v84
	v_sub_f32_e32 v80, v82, v84
	v_pk_mul_f32 v[80:81], v[84:85], v[80:81] op_sel:[1,0]
	v_pk_mul_f32 v[66:67], v[84:85], v[66:67] op_sel:[1,0]
	v_pk_fma_f32 v[80:81], v[38:39], v[80:81], v[118:119]
	v_pk_fma_f32 v[66:67], v[36:37], v[66:67], v[116:117]
	v_cndmask_b32_e32 v83, v166, v81, vcc
	v_cndmask_b32_e32 v82, v166, v80, vcc
	v_cndmask_b32_e32 v81, v166, v67, vcc
	v_cndmask_b32_e32 v80, v166, v66, vcc
	global_store_dwordx4 v[148:149], v[80:83], off offset:64 sc1
	v_cvt_pk_bf16_f32 v66, v80, v81
	v_cvt_pk_bf16_f32 v67, v82, v83
	ds_read_b64 v[80:81], v167 offset:9472
	s_waitcnt lgkmcnt(0)
	v_sub_f32_e32 v61, v61, v80
	v_sub_f32_e32 v60, v60, v80
	v_sub_f32_e32 v63, v63, v80
	v_sub_f32_e32 v62, v62, v80
	v_pk_mul_f32 v[62:63], v[80:81], v[62:63] op_sel:[1,0]
	v_pk_mul_f32 v[60:61], v[80:81], v[60:61] op_sel:[1,0]
	v_lshl_add_u64 v[82:83], v[104:105], 0, v[90:91]
	v_pk_fma_f32 v[60:61], v[36:37], v[60:61], v[116:117]
	v_pk_fma_f32 v[62:63], v[38:39], v[62:63], v[118:119]
	v_lshl_add_u64 v[82:83], v[82:83], 1, s[4:5]
	v_cndmask_b32_e32 v63, v166, v63, vcc
	v_cndmask_b32_e32 v62, v166, v62, vcc
	v_cndmask_b32_e32 v61, v166, v61, vcc
	v_cndmask_b32_e32 v60, v166, v60, vcc
	global_store_dwordx2 v[82:83], v[66:67], off sc1
	global_store_dwordx4 v[150:151], v[60:63], off offset:64 sc1
	v_lshl_add_u64 v[66:67], v[88:89], 0, v[90:91]
	v_lshl_add_u64 v[66:67], v[66:67], 1, s[4:5]
	v_cvt_pk_bf16_f32 v60, v60, v61
	v_cvt_pk_bf16_f32 v61, v62, v63
	ds_read_b64 v[62:63], v167 offset:9600
	global_store_dwordx2 v[66:67], v[60:61], off sc1
	v_lshl_add_u64 v[60:61], v[64:65], 0, v[90:91]
	s_waitcnt lgkmcnt(0)
	v_sub_f32_e32 v33, v33, v62
	v_sub_f32_e32 v32, v32, v62
	v_sub_f32_e32 v35, v35, v62
	v_sub_f32_e32 v34, v34, v62
	v_pk_mul_f32 v[34:35], v[62:63], v[34:35] op_sel:[1,0]
	v_pk_mul_f32 v[32:33], v[62:63], v[32:33] op_sel:[1,0]
	v_pk_fma_f32 v[34:35], v[38:39], v[34:35], v[118:119]
	v_pk_fma_f32 v[32:33], v[36:37], v[32:33], v[116:117]
	v_cndmask_b32_e32 v35, v166, v35, vcc
	v_cndmask_b32_e32 v34, v166, v34, vcc
	v_cndmask_b32_e32 v33, v166, v33, vcc
	v_cndmask_b32_e32 v32, v166, v32, vcc
	global_store_dwordx4 v[152:153], v[32:35], off offset:64 sc1
	s_nop 1
	v_cvt_pk_bf16_f32 v32, v32, v33
	v_cvt_pk_bf16_f32 v33, v34, v35
	v_lshl_add_u64 v[34:35], v[60:61], 1, s[4:5]
	global_store_dwordx2 v[34:35], v[32:33], off sc1
	global_load_dwordx4 v[32:35], v[154:155], off offset:512
	global_load_dwordx4 v[36:39], v[156:157], off offset:512
	ds_read_b64 v[60:61], v167 offset:8192
	s_waitcnt lgkmcnt(0)
	v_sub_f32_e32 v41, v41, v60
	v_sub_f32_e32 v40, v40, v60
	v_sub_f32_e32 v43, v43, v60
	v_sub_f32_e32 v42, v42, v60
	v_pk_mul_f32 v[42:43], v[60:61], v[42:43] op_sel:[1,0]
	v_pk_mul_f32 v[40:41], v[60:61], v[40:41] op_sel:[1,0]
	v_lshl_add_u64 v[60:61], v[136:137], 0, s[0:1]
	v_lshl_add_u64 v[62:63], v[162:163], 0, v[60:61]
	v_lshl_add_u64 v[62:63], v[62:63], 1, s[4:5]
	s_mov_b64 s[0:1], 0x90
	s_waitcnt vmcnt(0)
	v_pk_fma_f32 v[40:41], v[32:33], v[40:41], v[36:37]
	v_pk_fma_f32 v[42:43], v[34:35], v[42:43], v[38:39]
	v_cndmask_b32_e32 v41, v166, v41, vcc
	v_cndmask_b32_e32 v43, v166, v43, vcc
	v_cndmask_b32_e32 v42, v166, v42, vcc
	v_cndmask_b32_e32 v40, v166, v40, vcc
	global_store_dwordx4 v[138:139], v[40:43], off offset:512 sc1
	s_nop 1
	v_cvt_pk_bf16_f32 v40, v40, v41
	v_cvt_pk_bf16_f32 v41, v42, v43
	ds_read_b64 v[42:43], v167 offset:8320
	global_store_dwordx2 v[62:63], v[40:41], off sc1
	s_waitcnt lgkmcnt(0)
	v_sub_f32_e32 v41, v53, v42
	v_sub_f32_e32 v40, v52, v42
	v_sub_f32_e32 v53, v55, v42
	v_sub_f32_e32 v52, v54, v42
	v_pk_mul_f32 v[52:53], v[42:43], v[52:53] op_sel:[1,0]
	v_pk_mul_f32 v[40:41], v[42:43], v[40:41] op_sel:[1,0]
	v_pk_fma_f32 v[42:43], v[34:35], v[52:53], v[38:39]
	v_pk_fma_f32 v[40:41], v[32:33], v[40:41], v[36:37]
	v_cndmask_b32_e32 v43, v166, v43, vcc
	v_cndmask_b32_e32 v42, v166, v42, vcc
	v_cndmask_b32_e32 v41, v166, v41, vcc
	v_cndmask_b32_e32 v40, v166, v40, vcc
	global_store_dwordx4 v[140:141], v[40:43], off offset:512 sc1
	v_lshl_add_u64 v[52:53], v[160:161], 0, v[60:61]
	v_lshl_add_u64 v[52:53], v[52:53], 1, s[4:5]
	v_cvt_pk_bf16_f32 v40, v40, v41
	v_cvt_pk_bf16_f32 v41, v42, v43
	ds_read_b64 v[42:43], v167 offset:8448
	global_store_dwordx2 v[52:53], v[40:41], off sc1
	s_waitcnt lgkmcnt(0)
	v_sub_f32_e32 v41, v57, v42
	v_sub_f32_e32 v40, v56, v42
	v_sub_f32_e32 v53, v59, v42
	v_sub_f32_e32 v52, v58, v42
	v_pk_mul_f32 v[52:53], v[42:43], v[52:53] op_sel:[1,0]
	v_pk_mul_f32 v[40:41], v[42:43], v[40:41] op_sel:[1,0]
	v_pk_fma_f32 v[42:43], v[34:35], v[52:53], v[38:39]
	v_pk_fma_f32 v[40:41], v[32:33], v[40:41], v[36:37]
	v_cndmask_b32_e32 v43, v166, v43, vcc
	v_cndmask_b32_e32 v42, v166, v42, vcc
	v_cndmask_b32_e32 v41, v166, v41, vcc
	v_cndmask_b32_e32 v40, v166, v40, vcc
	global_store_dwordx4 v[142:143], v[40:43], off offset:512 sc1
	v_lshl_add_u64 v[52:53], v[158:159], 0, v[60:61]
	v_lshl_add_u64 v[52:53], v[52:53], 1, s[4:5]
	v_cvt_pk_bf16_f32 v40, v40, v41
	v_cvt_pk_bf16_f32 v41, v42, v43
	ds_read_b64 v[42:43], v167 offset:8576
	global_store_dwordx2 v[52:53], v[40:41], off sc1
	s_waitcnt lgkmcnt(0)
	v_sub_f32_e32 v41, v69, v42
	v_sub_f32_e32 v40, v68, v42
	v_sub_f32_e32 v53, v71, v42
	v_sub_f32_e32 v52, v70, v42
	v_pk_mul_f32 v[52:53], v[42:43], v[52:53] op_sel:[1,0]
	v_pk_mul_f32 v[40:41], v[42:43], v[40:41] op_sel:[1,0]
	v_pk_fma_f32 v[42:43], v[34:35], v[52:53], v[38:39]
	v_pk_fma_f32 v[40:41], v[32:33], v[40:41], v[36:37]
	v_cndmask_b32_e32 v43, v166, v43, vcc
	v_cndmask_b32_e32 v42, v166, v42, vcc
	v_cndmask_b32_e32 v41, v166, v41, vcc
	v_cndmask_b32_e32 v40, v166, v40, vcc
	global_store_dwordx4 v[144:145], v[40:43], off offset:512 sc1
	v_lshl_add_u64 v[52:53], v[114:115], 0, v[60:61]
	v_lshl_add_u64 v[52:53], v[52:53], 1, s[4:5]
	v_cvt_pk_bf16_f32 v40, v40, v41
	v_cvt_pk_bf16_f32 v41, v42, v43
	ds_read_b64 v[42:43], v167 offset:9216
	global_store_dwordx2 v[52:53], v[40:41], off sc1
	s_waitcnt lgkmcnt(0)
	v_sub_f32_e32 v41, v73, v42
	v_sub_f32_e32 v40, v72, v42
	v_sub_f32_e32 v53, v75, v42
	v_sub_f32_e32 v52, v74, v42
	v_pk_mul_f32 v[52:53], v[42:43], v[52:53] op_sel:[1,0]
	v_pk_mul_f32 v[40:41], v[42:43], v[40:41] op_sel:[1,0]
	v_pk_fma_f32 v[42:43], v[34:35], v[52:53], v[38:39]
	v_pk_fma_f32 v[40:41], v[32:33], v[40:41], v[36:37]
	v_cndmask_b32_e32 v43, v166, v43, vcc
	v_cndmask_b32_e32 v42, v166, v42, vcc
	v_cndmask_b32_e32 v41, v166, v41, vcc
	v_cndmask_b32_e32 v40, v166, v40, vcc
	global_store_dwordx4 v[146:147], v[40:43], off offset:512 sc1
	v_lshl_add_u64 v[52:53], v[112:113], 0, v[60:61]
	v_lshl_add_u64 v[52:53], v[52:53], 1, s[4:5]
	v_cvt_pk_bf16_f32 v40, v40, v41
	v_cvt_pk_bf16_f32 v41, v42, v43
	ds_read_b64 v[42:43], v167 offset:9344
	global_store_dwordx2 v[52:53], v[40:41], off sc1
	s_waitcnt lgkmcnt(0)
	v_sub_f32_e32 v41, v77, v42
	v_sub_f32_e32 v40, v76, v42
	v_sub_f32_e32 v53, v79, v42
	v_sub_f32_e32 v52, v78, v42
	v_pk_mul_f32 v[52:53], v[42:43], v[52:53] op_sel:[1,0]
	v_pk_mul_f32 v[40:41], v[42:43], v[40:41] op_sel:[1,0]
	v_pk_fma_f32 v[42:43], v[34:35], v[52:53], v[38:39]
	v_pk_fma_f32 v[40:41], v[32:33], v[40:41], v[36:37]
	v_cndmask_b32_e32 v43, v166, v43, vcc
	v_cndmask_b32_e32 v42, v166, v42, vcc
	v_cndmask_b32_e32 v41, v166, v41, vcc
	v_cndmask_b32_e32 v40, v166, v40, vcc
	global_store_dwordx4 v[148:149], v[40:43], off offset:512 sc1
	v_lshl_add_u64 v[52:53], v[104:105], 0, v[60:61]
	v_lshl_add_u64 v[52:53], v[52:53], 1, s[4:5]
	v_cvt_pk_bf16_f32 v40, v40, v41
	v_cvt_pk_bf16_f32 v41, v42, v43
	ds_read_b64 v[42:43], v167 offset:9472
	global_store_dwordx2 v[52:53], v[40:41], off sc1
	s_waitcnt lgkmcnt(0)
	v_sub_f32_e32 v41, v49, v42
	v_sub_f32_e32 v40, v48, v42
	v_sub_f32_e32 v49, v51, v42
	v_sub_f32_e32 v48, v50, v42
	v_pk_mul_f32 v[48:49], v[42:43], v[48:49] op_sel:[1,0]
	v_pk_mul_f32 v[40:41], v[42:43], v[40:41] op_sel:[1,0]
	v_pk_fma_f32 v[42:43], v[34:35], v[48:49], v[38:39]
	v_pk_fma_f32 v[40:41], v[32:33], v[40:41], v[36:37]
	v_cndmask_b32_e32 v43, v166, v43, vcc
	v_cndmask_b32_e32 v42, v166, v42, vcc
	v_cndmask_b32_e32 v41, v166, v41, vcc
	v_cndmask_b32_e32 v40, v166, v40, vcc
	global_store_dwordx4 v[150:151], v[40:43], off offset:512 sc1
	v_lshl_add_u64 v[48:49], v[88:89], 0, v[60:61]
	v_lshl_add_u64 v[48:49], v[48:49], 1, s[4:5]
	v_cvt_pk_bf16_f32 v40, v40, v41
	v_cvt_pk_bf16_f32 v41, v42, v43
	ds_read_b64 v[42:43], v167 offset:9600
	global_store_dwordx2 v[48:49], v[40:41], off sc1
	v_lshl_add_u64 v[40:41], v[64:65], 0, v[60:61]
	s_waitcnt lgkmcnt(0)
	v_sub_f32_e32 v21, v21, v42
	v_sub_f32_e32 v20, v20, v42
	v_sub_f32_e32 v23, v23, v42
	v_sub_f32_e32 v22, v22, v42
	v_pk_mul_f32 v[22:23], v[42:43], v[22:23] op_sel:[1,0]
	v_pk_mul_f32 v[20:21], v[42:43], v[20:21] op_sel:[1,0]
	v_pk_fma_f32 v[22:23], v[34:35], v[22:23], v[38:39]
	v_pk_fma_f32 v[20:21], v[32:33], v[20:21], v[36:37]
	v_cndmask_b32_e32 v23, v166, v23, vcc
	v_cndmask_b32_e32 v22, v166, v22, vcc
	v_cndmask_b32_e32 v21, v166, v21, vcc
	v_cndmask_b32_e32 v20, v166, v20, vcc
	global_store_dwordx4 v[152:153], v[20:23], off offset:512 sc1
	s_nop 1
	v_cvt_pk_bf16_f32 v20, v20, v21
	v_cvt_pk_bf16_f32 v21, v22, v23
	v_lshl_add_u64 v[22:23], v[40:41], 1, s[4:5]
	global_store_dwordx2 v[22:23], v[20:21], off sc1
	global_load_dwordx4 v[20:23], v[154:155], off offset:576
	global_load_dwordx4 v[32:35], v[156:157], off offset:576
	ds_read_b64 v[36:37], v167 offset:8192
	s_waitcnt lgkmcnt(0)
	v_sub_f32_e32 v1, v1, v36
	v_sub_f32_e32 v0, v0, v36
	v_sub_f32_e32 v3, v3, v36
	v_sub_f32_e32 v2, v2, v36
	v_pk_mul_f32 v[2:3], v[36:37], v[2:3] op_sel:[1,0]
	v_pk_mul_f32 v[0:1], v[36:37], v[0:1] op_sel:[1,0]
	v_lshl_add_u64 v[36:37], v[136:137], 0, s[0:1]
	v_lshl_add_u64 v[38:39], v[162:163], 0, v[36:37]
	v_lshl_add_u64 v[38:39], v[38:39], 1, s[4:5]
	s_waitcnt vmcnt(0)
	v_pk_fma_f32 v[0:1], v[20:21], v[0:1], v[32:33]
	v_pk_fma_f32 v[2:3], v[22:23], v[2:3], v[34:35]
	v_cndmask_b32_e32 v1, v166, v1, vcc
	v_cndmask_b32_e32 v3, v166, v3, vcc
	v_cndmask_b32_e32 v2, v166, v2, vcc
	v_cndmask_b32_e32 v0, v166, v0, vcc
	global_store_dwordx4 v[138:139], v[0:3], off offset:576 sc1
	s_nop 1
	v_cvt_pk_bf16_f32 v0, v0, v1
	v_cvt_pk_bf16_f32 v1, v2, v3
	ds_read_b64 v[2:3], v167 offset:8320
	global_store_dwordx2 v[38:39], v[0:1], off sc1
	s_waitcnt lgkmcnt(0)
	v_sub_f32_e32 v1, v5, v2
	v_sub_f32_e32 v0, v4, v2
	v_sub_f32_e32 v5, v7, v2
	v_sub_f32_e32 v4, v6, v2
	v_pk_mul_f32 v[4:5], v[2:3], v[4:5] op_sel:[1,0]
	v_pk_mul_f32 v[0:1], v[2:3], v[0:1] op_sel:[1,0]
	v_pk_fma_f32 v[2:3], v[22:23], v[4:5], v[34:35]
	v_pk_fma_f32 v[0:1], v[20:21], v[0:1], v[32:33]
	v_cndmask_b32_e32 v3, v166, v3, vcc
	v_cndmask_b32_e32 v2, v166, v2, vcc
	v_cndmask_b32_e32 v1, v166, v1, vcc
	v_cndmask_b32_e32 v0, v166, v0, vcc
	global_store_dwordx4 v[140:141], v[0:3], off offset:576 sc1
	v_lshl_add_u64 v[4:5], v[160:161], 0, v[36:37]
	v_lshl_add_u64 v[4:5], v[4:5], 1, s[4:5]
	v_cvt_pk_bf16_f32 v0, v0, v1
	v_cvt_pk_bf16_f32 v1, v2, v3
	ds_read_b64 v[2:3], v167 offset:8448
	global_store_dwordx2 v[4:5], v[0:1], off sc1
	s_waitcnt lgkmcnt(0)
	v_sub_f32_e32 v1, v9, v2
	v_sub_f32_e32 v0, v8, v2
	v_sub_f32_e32 v5, v11, v2
	v_sub_f32_e32 v4, v10, v2
	v_pk_mul_f32 v[4:5], v[2:3], v[4:5] op_sel:[1,0]
	v_pk_mul_f32 v[0:1], v[2:3], v[0:1] op_sel:[1,0]
	v_pk_fma_f32 v[2:3], v[22:23], v[4:5], v[34:35]
	v_pk_fma_f32 v[0:1], v[20:21], v[0:1], v[32:33]
	v_cndmask_b32_e32 v3, v166, v3, vcc
	v_cndmask_b32_e32 v2, v166, v2, vcc
	v_cndmask_b32_e32 v1, v166, v1, vcc
	v_cndmask_b32_e32 v0, v166, v0, vcc
	global_store_dwordx4 v[142:143], v[0:3], off offset:576 sc1
	v_lshl_add_u64 v[4:5], v[158:159], 0, v[36:37]
	v_lshl_add_u64 v[4:5], v[4:5], 1, s[4:5]
	v_cvt_pk_bf16_f32 v0, v0, v1
	v_cvt_pk_bf16_f32 v1, v2, v3
	ds_read_b64 v[2:3], v167 offset:8576
	global_store_dwordx2 v[4:5], v[0:1], off sc1
	s_waitcnt lgkmcnt(0)
	v_sub_f32_e32 v1, v13, v2
	v_sub_f32_e32 v0, v12, v2
	v_sub_f32_e32 v5, v15, v2
	v_sub_f32_e32 v4, v14, v2
	v_pk_mul_f32 v[4:5], v[2:3], v[4:5] op_sel:[1,0]
	v_pk_mul_f32 v[0:1], v[2:3], v[0:1] op_sel:[1,0]
	v_pk_fma_f32 v[2:3], v[22:23], v[4:5], v[34:35]
	v_pk_fma_f32 v[0:1], v[20:21], v[0:1], v[32:33]
	v_cndmask_b32_e32 v3, v166, v3, vcc
	v_cndmask_b32_e32 v2, v166, v2, vcc
	v_cndmask_b32_e32 v1, v166, v1, vcc
	v_cndmask_b32_e32 v0, v166, v0, vcc
	global_store_dwordx4 v[144:145], v[0:3], off offset:576 sc1
	v_lshl_add_u64 v[4:5], v[114:115], 0, v[36:37]
	v_lshl_add_u64 v[4:5], v[4:5], 1, s[4:5]
	v_cvt_pk_bf16_f32 v0, v0, v1
	v_cvt_pk_bf16_f32 v1, v2, v3
	ds_read_b64 v[2:3], v167 offset:9216
	global_store_dwordx2 v[4:5], v[0:1], off sc1
	s_waitcnt lgkmcnt(0)
	v_sub_f32_e32 v1, v25, v2
	v_sub_f32_e32 v0, v24, v2
	v_sub_f32_e32 v5, v27, v2
	v_sub_f32_e32 v4, v26, v2
	v_pk_mul_f32 v[4:5], v[2:3], v[4:5] op_sel:[1,0]
	v_pk_mul_f32 v[0:1], v[2:3], v[0:1] op_sel:[1,0]
	v_pk_fma_f32 v[2:3], v[22:23], v[4:5], v[34:35]
	v_pk_fma_f32 v[0:1], v[20:21], v[0:1], v[32:33]
	v_cndmask_b32_e32 v3, v166, v3, vcc
	v_cndmask_b32_e32 v2, v166, v2, vcc
	v_cndmask_b32_e32 v1, v166, v1, vcc
	v_cndmask_b32_e32 v0, v166, v0, vcc
	global_store_dwordx4 v[146:147], v[0:3], off offset:576 sc1
	v_lshl_add_u64 v[4:5], v[112:113], 0, v[36:37]
	v_lshl_add_u64 v[4:5], v[4:5], 1, s[4:5]
	v_cvt_pk_bf16_f32 v0, v0, v1
	v_cvt_pk_bf16_f32 v1, v2, v3
	ds_read_b64 v[2:3], v167 offset:9344
	global_store_dwordx2 v[4:5], v[0:1], off sc1
	s_waitcnt lgkmcnt(0)
	v_sub_f32_e32 v1, v29, v2
	v_sub_f32_e32 v0, v28, v2
	v_sub_f32_e32 v5, v31, v2
	v_sub_f32_e32 v4, v30, v2
	v_pk_mul_f32 v[4:5], v[2:3], v[4:5] op_sel:[1,0]
	v_pk_mul_f32 v[0:1], v[2:3], v[0:1] op_sel:[1,0]
	v_pk_fma_f32 v[2:3], v[22:23], v[4:5], v[34:35]
	v_pk_fma_f32 v[0:1], v[20:21], v[0:1], v[32:33]
	v_cndmask_b32_e32 v3, v166, v3, vcc
	v_cndmask_b32_e32 v2, v166, v2, vcc
	v_cndmask_b32_e32 v1, v166, v1, vcc
	v_cndmask_b32_e32 v0, v166, v0, vcc
	global_store_dwordx4 v[148:149], v[0:3], off offset:576 sc1
	v_lshl_add_u64 v[4:5], v[104:105], 0, v[36:37]
	v_lshl_add_u64 v[4:5], v[4:5], 1, s[4:5]
	v_cvt_pk_bf16_f32 v0, v0, v1
	v_cvt_pk_bf16_f32 v1, v2, v3
	ds_read_b64 v[2:3], v167 offset:9472
	global_store_dwordx2 v[4:5], v[0:1], off sc1
	s_waitcnt lgkmcnt(0)
	v_sub_f32_e32 v1, v45, v2
	v_sub_f32_e32 v0, v44, v2
	v_sub_f32_e32 v5, v47, v2
	v_sub_f32_e32 v4, v46, v2
	v_pk_mul_f32 v[4:5], v[2:3], v[4:5] op_sel:[1,0]
	v_pk_mul_f32 v[0:1], v[2:3], v[0:1] op_sel:[1,0]
	v_pk_fma_f32 v[2:3], v[22:23], v[4:5], v[34:35]
	v_pk_fma_f32 v[0:1], v[20:21], v[0:1], v[32:33]
	v_cndmask_b32_e32 v3, v166, v3, vcc
	v_cndmask_b32_e32 v2, v166, v2, vcc
	v_cndmask_b32_e32 v1, v166, v1, vcc
	v_cndmask_b32_e32 v0, v166, v0, vcc
	global_store_dwordx4 v[150:151], v[0:3], off offset:576 sc1
	v_lshl_add_u64 v[4:5], v[88:89], 0, v[36:37]
	v_lshl_add_u64 v[4:5], v[4:5], 1, s[4:5]
	v_cvt_pk_bf16_f32 v0, v0, v1
	v_cvt_pk_bf16_f32 v1, v2, v3
	ds_read_b64 v[2:3], v167 offset:9600
	global_store_dwordx2 v[4:5], v[0:1], off sc1
	v_lshl_add_u64 v[4:5], v[64:65], 0, v[36:37]
	s_waitcnt lgkmcnt(0)
	v_sub_f32_e32 v1, v17, v2
	v_sub_f32_e32 v0, v16, v2
	v_sub_f32_e32 v7, v19, v2
	v_sub_f32_e32 v6, v18, v2
	v_pk_mul_f32 v[6:7], v[2:3], v[6:7] op_sel:[1,0]
	v_pk_mul_f32 v[0:1], v[2:3], v[0:1] op_sel:[1,0]
	v_pk_fma_f32 v[2:3], v[22:23], v[6:7], v[34:35]
	v_pk_fma_f32 v[0:1], v[20:21], v[0:1], v[32:33]
	v_cndmask_b32_e32 v3, v166, v3, vcc
	v_cndmask_b32_e32 v2, v166, v2, vcc
	v_cndmask_b32_e32 v1, v166, v1, vcc
	v_cndmask_b32_e32 v0, v166, v0, vcc
	global_store_dwordx4 v[152:153], v[0:3], off offset:576 sc1
	s_nop 1
	v_cvt_pk_bf16_f32 v0, v0, v1
	v_cvt_pk_bf16_f32 v1, v2, v3
	v_lshl_add_u64 v[2:3], v[4:5], 1, s[4:5]
	global_store_dwordx2 v[2:3], v[0:1], off sc1

.LBB0_1340:
	s_ashr_i32 s17, s49, 31
	s_lshr_b32 s17, s17, 30
	s_add_i32 s17, s49, s17
	s_ashr_i32 s38, s17, 2
	s_ashr_i32 s39, s38, 31
	s_lshl_b32 s15, s49, 8
	s_lshl_b64 s[40:41], s[38:39], 11
	s_add_u32 s40, s27, s40
	s_addc_u32 s41, s28, s41
	s_add_i32 s17, s49, 3
	s_cmp_lt_u32 s17, 7
	s_cselect_b64 vcc, -1, 0
	s_lshl_b32 s17, s36, 8
	v_mov_b32_e32 v146, v145
	s_add_i32 s17, s17, s29
	s_or_b32 s15, s15, s30
	v_ashrrev_i32_e32 v147, 1, v146
	v_and_or_b32 v153, v146, 15, s17
	s_lshl_b32 s17, s38, 10
	v_and_b32_e32 v147, -8, v147
	s_sub_i32 s15, s15, s17
	v_add_u32_e32 v146, s15, v147
	v_ashrrev_i32_e32 v147, 31, v146
	v_cndmask_b32_e32 v144, 1.0, v152, vcc
	v_lshl_add_u64 v[146:147], v[146:147], 1, s[40:41]
	v_pk_add_f32 v[126:127], v[126:127], 0 op_sel_hi:[1,0]
	v_pk_add_f32 v[124:125], v[124:125], 0 op_sel_hi:[1,0]
	v_pk_add_f32 v[122:123], v[122:123], 0 op_sel_hi:[1,0]
	v_pk_add_f32 v[120:121], v[120:121], 0 op_sel_hi:[1,0]
	v_mad_i64_i32 v[154:155], s[38:39], v153, s48, v[146:147]
	v_pk_mul_f32 v[126:127], v[144:145], v[126:127] op_sel_hi:[0,1]
	v_pk_mul_f32 v[124:125], v[144:145], v[124:125] op_sel_hi:[0,1]
	v_pk_mul_f32 v[156:157], v[144:145], v[122:123] op_sel_hi:[0,1]
	v_pk_mul_f32 v[122:123], v[144:145], v[120:121] op_sel_hi:[0,1]
	v_cvt_pk_bf16_f32 v120, v124, v125
	v_cvt_pk_bf16_f32 v121, v126, v127
	v_pk_add_f32 v[110:111], v[110:111], 0 op_sel_hi:[1,0]
	v_pk_add_f32 v[108:109], v[108:109], 0 op_sel_hi:[1,0]
	v_cvt_pk_bf16_f32 v122, v122, v123
	v_cvt_pk_bf16_f32 v123, v156, v157
	global_store_dwordx4 v[154:155], v[120:123], off sc1
	v_pk_add_f32 v[118:119], v[118:119], 0 op_sel_hi:[1,0]
	v_pk_add_f32 v[116:117], v[116:117], 0 op_sel_hi:[1,0]
	v_pk_mul_f32 v[120:121], v[144:145], v[110:111] op_sel_hi:[0,1]
	v_pk_mul_f32 v[110:111], v[144:145], v[108:109] op_sel_hi:[0,1]
	v_pk_mul_f32 v[118:119], v[144:145], v[118:119] op_sel_hi:[0,1]
	v_pk_mul_f32 v[116:117], v[144:145], v[116:117] op_sel_hi:[0,1]
	v_cvt_pk_bf16_f32 v108, v116, v117
	v_cvt_pk_bf16_f32 v109, v118, v119
	v_cvt_pk_bf16_f32 v110, v110, v111
	v_cvt_pk_bf16_f32 v111, v120, v121
	global_store_dwordx4 v[154:155], v[108:111], off offset:256 sc1
	v_pk_add_f32 v[112:113], v[112:113], 0 op_sel_hi:[1,0]
	v_pk_add_f32 v[106:107], v[106:107], 0 op_sel_hi:[1,0]
	v_or_b32_e32 v108, 16, v153
	v_pk_add_f32 v[110:111], v[114:115], 0 op_sel_hi:[1,0]
	v_pk_add_f32 v[104:105], v[104:105], 0 op_sel_hi:[1,0]
	v_mad_i64_i32 v[108:109], s[38:39], v108, s48, v[146:147]
	v_pk_mul_f32 v[110:111], v[144:145], v[110:111] op_sel_hi:[0,1]
	v_pk_mul_f32 v[112:113], v[144:145], v[112:113] op_sel_hi:[0,1]
	v_pk_mul_f32 v[114:115], v[144:145], v[106:107] op_sel_hi:[0,1]
	v_pk_mul_f32 v[106:107], v[144:145], v[104:105] op_sel_hi:[0,1]
	v_cvt_pk_bf16_f32 v104, v112, v113
	v_cvt_pk_bf16_f32 v105, v110, v111
	v_pk_add_f32 v[94:95], v[94:95], 0 op_sel_hi:[1,0]
	v_pk_add_f32 v[92:93], v[92:93], 0 op_sel_hi:[1,0]
	v_cvt_pk_bf16_f32 v106, v106, v107
	v_cvt_pk_bf16_f32 v107, v114, v115
	global_store_dwordx4 v[108:109], v[104:107], off sc1
	v_pk_add_f32 v[102:103], v[102:103], 0 op_sel_hi:[1,0]
	v_pk_add_f32 v[100:101], v[100:101], 0 op_sel_hi:[1,0]
	v_pk_mul_f32 v[104:105], v[144:145], v[94:95] op_sel_hi:[0,1]
	v_pk_mul_f32 v[94:95], v[144:145], v[92:93] op_sel_hi:[0,1]
	v_pk_mul_f32 v[102:103], v[144:145], v[102:103] op_sel_hi:[0,1]
	v_pk_mul_f32 v[100:101], v[144:145], v[100:101] op_sel_hi:[0,1]
	v_cvt_pk_bf16_f32 v92, v100, v101
	v_cvt_pk_bf16_f32 v93, v102, v103
	v_cvt_pk_bf16_f32 v94, v94, v95
	v_cvt_pk_bf16_f32 v95, v104, v105
	global_store_dwordx4 v[108:109], v[92:95], off offset:256 sc1
	v_pk_add_f32 v[96:97], v[96:97], 0 op_sel_hi:[1,0]
	v_pk_add_f32 v[90:91], v[90:91], 0 op_sel_hi:[1,0]
	v_or_b32_e32 v92, 32, v153
	v_pk_add_f32 v[94:95], v[98:99], 0 op_sel_hi:[1,0]
	v_pk_add_f32 v[88:89], v[88:89], 0 op_sel_hi:[1,0]
	v_mad_i64_i32 v[92:93], s[38:39], v92, s48, v[146:147]
	v_pk_mul_f32 v[94:95], v[144:145], v[94:95] op_sel_hi:[0,1]
	v_pk_mul_f32 v[96:97], v[144:145], v[96:97] op_sel_hi:[0,1]
	v_pk_mul_f32 v[98:99], v[144:145], v[90:91] op_sel_hi:[0,1]
	v_pk_mul_f32 v[90:91], v[144:145], v[88:89] op_sel_hi:[0,1]
	v_cvt_pk_bf16_f32 v88, v96, v97
	v_cvt_pk_bf16_f32 v89, v94, v95
	v_pk_add_f32 v[78:79], v[78:79], 0 op_sel_hi:[1,0]
	v_pk_add_f32 v[76:77], v[76:77], 0 op_sel_hi:[1,0]
	v_cvt_pk_bf16_f32 v90, v90, v91
	v_cvt_pk_bf16_f32 v91, v98, v99
	global_store_dwordx4 v[92:93], v[88:91], off sc1
	v_pk_add_f32 v[86:87], v[86:87], 0 op_sel_hi:[1,0]
	v_pk_add_f32 v[84:85], v[84:85], 0 op_sel_hi:[1,0]
	v_pk_mul_f32 v[88:89], v[144:145], v[78:79] op_sel_hi:[0,1]
	v_pk_mul_f32 v[78:79], v[144:145], v[76:77] op_sel_hi:[0,1]
	v_pk_mul_f32 v[86:87], v[144:145], v[86:87] op_sel_hi:[0,1]
	v_pk_mul_f32 v[84:85], v[144:145], v[84:85] op_sel_hi:[0,1]
	v_cvt_pk_bf16_f32 v76, v84, v85
	v_cvt_pk_bf16_f32 v77, v86, v87
	v_cvt_pk_bf16_f32 v78, v78, v79
	v_cvt_pk_bf16_f32 v79, v88, v89
	global_store_dwordx4 v[92:93], v[76:79], off offset:256 sc1
	v_pk_add_f32 v[80:81], v[80:81], 0 op_sel_hi:[1,0]
	v_pk_add_f32 v[74:75], v[74:75], 0 op_sel_hi:[1,0]
	v_or_b32_e32 v76, 48, v153
	v_pk_add_f32 v[78:79], v[82:83], 0 op_sel_hi:[1,0]
	v_pk_add_f32 v[72:73], v[72:73], 0 op_sel_hi:[1,0]
	v_mad_i64_i32 v[76:77], s[38:39], v76, s48, v[146:147]
	v_pk_mul_f32 v[78:79], v[144:145], v[78:79] op_sel_hi:[0,1]
	v_pk_mul_f32 v[80:81], v[144:145], v[80:81] op_sel_hi:[0,1]
	v_pk_mul_f32 v[82:83], v[144:145], v[74:75] op_sel_hi:[0,1]
	v_pk_mul_f32 v[74:75], v[144:145], v[72:73] op_sel_hi:[0,1]
	v_cvt_pk_bf16_f32 v72, v80, v81
	v_cvt_pk_bf16_f32 v73, v78, v79
	v_pk_add_f32 v[68:69], v[68:69], 0 op_sel_hi:[1,0]
	v_pk_add_f32 v[66:67], v[66:67], 0 op_sel_hi:[1,0]
	v_pk_add_f32 v[64:65], v[64:65], 0 op_sel_hi:[1,0]
	v_cvt_pk_bf16_f32 v74, v74, v75
	v_cvt_pk_bf16_f32 v75, v82, v83
	global_store_dwordx4 v[76:77], v[72:75], off sc1
	v_pk_add_f32 v[70:71], v[70:71], 0 op_sel_hi:[1,0]
	v_pk_mul_f32 v[68:69], v[144:145], v[68:69] op_sel_hi:[0,1]
	v_pk_mul_f32 v[72:73], v[144:145], v[66:67] op_sel_hi:[0,1]
	v_pk_mul_f32 v[66:67], v[144:145], v[64:65] op_sel_hi:[0,1]
	v_cvt_pk_bf16_f32 v64, v68, v69
	v_pk_mul_f32 v[70:71], v[144:145], v[70:71] op_sel_hi:[0,1]
	v_cvt_pk_bf16_f32 v65, v70, v71
	v_cvt_pk_bf16_f32 v66, v66, v67
	v_cvt_pk_bf16_f32 v67, v72, v73
	global_store_dwordx4 v[76:77], v[64:67], off offset:256 sc1
	v_pk_add_f32 v[62:63], v[62:63], 0 op_sel_hi:[1,0]
	v_pk_add_f32 v[60:61], v[60:61], 0 op_sel_hi:[1,0]
	v_add_u32_e32 v64, 0x80, v153
	v_pk_add_f32 v[58:59], v[58:59], 0 op_sel_hi:[1,0]
	v_pk_add_f32 v[56:57], v[56:57], 0 op_sel_hi:[1,0]
	v_mad_i64_i32 v[64:65], s[38:39], v64, s48, v[146:147]
	v_pk_mul_f32 v[62:63], v[144:145], v[62:63] op_sel_hi:[0,1]
	v_pk_mul_f32 v[60:61], v[144:145], v[60:61] op_sel_hi:[0,1]
	v_pk_mul_f32 v[66:67], v[144:145], v[58:59] op_sel_hi:[0,1]
	v_pk_mul_f32 v[58:59], v[144:145], v[56:57] op_sel_hi:[0,1]
	v_cvt_pk_bf16_f32 v56, v60, v61
	v_cvt_pk_bf16_f32 v57, v62, v63
	v_pk_add_f32 v[46:47], v[46:47], 0 op_sel_hi:[1,0]
	v_pk_add_f32 v[44:45], v[44:45], 0 op_sel_hi:[1,0]
	v_cvt_pk_bf16_f32 v58, v58, v59
	v_cvt_pk_bf16_f32 v59, v66, v67
	global_store_dwordx4 v[64:65], v[56:59], off sc1
	v_pk_add_f32 v[54:55], v[54:55], 0 op_sel_hi:[1,0]
	v_pk_add_f32 v[52:53], v[52:53], 0 op_sel_hi:[1,0]
	v_pk_mul_f32 v[56:57], v[144:145], v[46:47] op_sel_hi:[0,1]
	v_pk_mul_f32 v[46:47], v[144:145], v[44:45] op_sel_hi:[0,1]
	v_pk_mul_f32 v[54:55], v[144:145], v[54:55] op_sel_hi:[0,1]
	v_pk_mul_f32 v[52:53], v[144:145], v[52:53] op_sel_hi:[0,1]
	v_cvt_pk_bf16_f32 v44, v52, v53
	v_cvt_pk_bf16_f32 v45, v54, v55
	v_cvt_pk_bf16_f32 v46, v46, v47
	v_cvt_pk_bf16_f32 v47, v56, v57
	global_store_dwordx4 v[64:65], v[44:47], off offset:256 sc1
	v_pk_add_f32 v[48:49], v[48:49], 0 op_sel_hi:[1,0]
	v_pk_add_f32 v[42:43], v[42:43], 0 op_sel_hi:[1,0]
	v_add_u32_e32 v44, 0x90, v153
	v_pk_add_f32 v[46:47], v[50:51], 0 op_sel_hi:[1,0]
	v_pk_add_f32 v[40:41], v[40:41], 0 op_sel_hi:[1,0]
	v_mad_i64_i32 v[44:45], s[38:39], v44, s48, v[146:147]
	v_pk_mul_f32 v[46:47], v[144:145], v[46:47] op_sel_hi:[0,1]
	v_pk_mul_f32 v[48:49], v[144:145], v[48:49] op_sel_hi:[0,1]
	v_pk_mul_f32 v[50:51], v[144:145], v[42:43] op_sel_hi:[0,1]
	v_pk_mul_f32 v[42:43], v[144:145], v[40:41] op_sel_hi:[0,1]
	v_cvt_pk_bf16_f32 v40, v48, v49
	v_cvt_pk_bf16_f32 v41, v46, v47
	v_pk_add_f32 v[30:31], v[30:31], 0 op_sel_hi:[1,0]
	v_pk_add_f32 v[28:29], v[28:29], 0 op_sel_hi:[1,0]
	v_cvt_pk_bf16_f32 v42, v42, v43
	v_cvt_pk_bf16_f32 v43, v50, v51
	global_store_dwordx4 v[44:45], v[40:43], off sc1
	v_pk_add_f32 v[38:39], v[38:39], 0 op_sel_hi:[1,0]
	v_pk_add_f32 v[36:37], v[36:37], 0 op_sel_hi:[1,0]
	v_pk_mul_f32 v[40:41], v[144:145], v[30:31] op_sel_hi:[0,1]
	v_pk_mul_f32 v[30:31], v[144:145], v[28:29] op_sel_hi:[0,1]
	v_pk_mul_f32 v[38:39], v[144:145], v[38:39] op_sel_hi:[0,1]
	v_pk_mul_f32 v[36:37], v[144:145], v[36:37] op_sel_hi:[0,1]
	v_cvt_pk_bf16_f32 v28, v36, v37
	v_cvt_pk_bf16_f32 v29, v38, v39
	v_cvt_pk_bf16_f32 v30, v30, v31
	v_cvt_pk_bf16_f32 v31, v40, v41
	global_store_dwordx4 v[44:45], v[28:31], off offset:256 sc1
	v_pk_add_f32 v[32:33], v[32:33], 0 op_sel_hi:[1,0]
	v_pk_add_f32 v[26:27], v[26:27], 0 op_sel_hi:[1,0]
	v_add_u32_e32 v28, 0xa0, v153
	v_pk_add_f32 v[30:31], v[34:35], 0 op_sel_hi:[1,0]
	v_pk_add_f32 v[24:25], v[24:25], 0 op_sel_hi:[1,0]
	v_mad_i64_i32 v[28:29], s[38:39], v28, s48, v[146:147]
	v_pk_mul_f32 v[30:31], v[144:145], v[30:31] op_sel_hi:[0,1]
	v_pk_mul_f32 v[32:33], v[144:145], v[32:33] op_sel_hi:[0,1]
	v_pk_mul_f32 v[34:35], v[144:145], v[26:27] op_sel_hi:[0,1]
	v_pk_mul_f32 v[26:27], v[144:145], v[24:25] op_sel_hi:[0,1]
	v_cvt_pk_bf16_f32 v24, v32, v33
	v_cvt_pk_bf16_f32 v25, v30, v31
	v_pk_add_f32 v[14:15], v[14:15], 0 op_sel_hi:[1,0]
	v_pk_add_f32 v[12:13], v[12:13], 0 op_sel_hi:[1,0]
	v_cvt_pk_bf16_f32 v26, v26, v27
	v_cvt_pk_bf16_f32 v27, v34, v35
	global_store_dwordx4 v[28:29], v[24:27], off sc1
	v_pk_add_f32 v[22:23], v[22:23], 0 op_sel_hi:[1,0]
	v_pk_add_f32 v[20:21], v[20:21], 0 op_sel_hi:[1,0]
	v_pk_mul_f32 v[24:25], v[144:145], v[14:15] op_sel_hi:[0,1]
	v_pk_mul_f32 v[14:15], v[144:145], v[12:13] op_sel_hi:[0,1]
	v_pk_mul_f32 v[22:23], v[144:145], v[22:23] op_sel_hi:[0,1]
	v_pk_mul_f32 v[20:21], v[144:145], v[20:21] op_sel_hi:[0,1]
	v_cvt_pk_bf16_f32 v12, v20, v21
	v_cvt_pk_bf16_f32 v13, v22, v23
	v_cvt_pk_bf16_f32 v14, v14, v15
	v_cvt_pk_bf16_f32 v15, v24, v25
	global_store_dwordx4 v[28:29], v[12:15], off offset:256 sc1
	v_pk_add_f32 v[16:17], v[16:17], 0 op_sel_hi:[1,0]
	v_pk_add_f32 v[10:11], v[10:11], 0 op_sel_hi:[1,0]
	v_add_u32_e32 v12, 0xb0, v153
	v_pk_add_f32 v[14:15], v[18:19], 0 op_sel_hi:[1,0]
	v_pk_add_f32 v[8:9], v[8:9], 0 op_sel_hi:[1,0]
	v_mad_i64_i32 v[12:13], s[38:39], v12, s48, v[146:147]
	v_pk_mul_f32 v[14:15], v[144:145], v[14:15] op_sel_hi:[0,1]
	v_pk_mul_f32 v[16:17], v[144:145], v[16:17] op_sel_hi:[0,1]
	v_pk_mul_f32 v[18:19], v[144:145], v[10:11] op_sel_hi:[0,1]
	v_pk_mul_f32 v[10:11], v[144:145], v[8:9] op_sel_hi:[0,1]
	v_cvt_pk_bf16_f32 v8, v16, v17
	v_cvt_pk_bf16_f32 v9, v14, v15
	v_pk_add_f32 v[2:3], v[2:3], 0 op_sel_hi:[1,0]
	v_pk_add_f32 v[0:1], v[0:1], 0 op_sel_hi:[1,0]
	v_cvt_pk_bf16_f32 v10, v10, v11
	v_cvt_pk_bf16_f32 v11, v18, v19
	global_store_dwordx4 v[12:13], v[8:11], off sc1
	v_pk_add_f32 v[6:7], v[6:7], 0 op_sel_hi:[1,0]
	v_pk_add_f32 v[4:5], v[4:5], 0 op_sel_hi:[1,0]
	v_pk_mul_f32 v[8:9], v[144:145], v[2:3] op_sel_hi:[0,1]
	v_pk_mul_f32 v[2:3], v[144:145], v[0:1] op_sel_hi:[0,1]
	s_andn2_b64 vcc, exec, s[4:5]
	s_mov_b64 s[4:5], -1
	v_pk_mul_f32 v[6:7], v[144:145], v[6:7] op_sel_hi:[0,1]
	v_pk_mul_f32 v[4:5], v[144:145], v[4:5] op_sel_hi:[0,1]
	v_cvt_pk_bf16_f32 v0, v4, v5
	v_cvt_pk_bf16_f32 v1, v6, v7
	v_cvt_pk_bf16_f32 v2, v2, v3
	v_cvt_pk_bf16_f32 v3, v8, v9
	global_store_dwordx4 v[12:13], v[0:3], off offset:256 sc1
	s_cbranch_vccnz .LBB0_1333
	s_andn2_b64 vcc, exec, s[8:9]
	s_cbranch_vccnz .LBB0_1332
	s_barrier
	s_branch .LBB0_1332

.LBB0_1601:
	s_or_b64 exec, exec, s[6:7]
	v_lshl_add_u64 v[158:159], s[12:13], 0, v[132:133]
	v_add_co_u32_e32 v128, vcc, 0x1000, v158
	v_lshl_add_u64 v[160:161], s[14:15], 0, v[132:133]
	s_nop 0
	v_addc_co_u32_e32 v129, vcc, 0, v159, vcc
	v_add_co_u32_e32 v132, vcc, 0x1000, v160
	s_waitcnt lgkmcnt(0)
	s_barrier
	s_nop 0
	v_addc_co_u32_e32 v133, vcc, 0, v161, vcc
	global_load_dwordx4 v[128:131], v[128:129], off
	v_or_b32_e32 v165, s0, v155
	global_load_dwordx4 v[132:135], v[132:133], off
	v_lshl_add_u32 v164, v165, 3, 0
	ds_read_b64 v[168:169], v164 offset:8192
	v_add_u32_e32 v162, s3, v165
	v_mov_b32_e32 v166, 0x7fc00000
	s_cmp_lg_u64 s[10:11], 0
	v_ashrrev_i32_e32 v163, 31, v162
	s_waitcnt lgkmcnt(0)
	v_sub_f32_e32 v119, v119, v168
	v_sub_f32_e32 v118, v118, v168
	v_sub_f32_e32 v117, v117, v168
	v_sub_f32_e32 v116, v116, v168
	v_pk_mul_f32 v[116:117], v[168:169], v[116:117] op_sel:[1,0]
	v_pk_mul_f32 v[118:119], v[168:169], v[118:119] op_sel:[1,0]
	v_cmp_eq_u32_e64 s[4:5], 0, v154
	s_cselect_b64 s[8:9], -1, 0
	v_lshlrev_b64 v[156:157], 10, v[162:163]
	s_cmp_eq_u64 s[10:11], 0
	s_waitcnt vmcnt(0)
	v_pk_fma_f32 v[118:119], v[130:131], v[118:119], v[134:135]
	v_pk_fma_f32 v[116:117], v[128:129], v[116:117], v[132:133]
	v_cndmask_b32_e64 v119, v166, v119, s[4:5]
	v_cndmask_b32_e64 v118, v166, v118, s[4:5]
	v_cndmask_b32_e64 v117, v166, v117, s[4:5]
	v_cndmask_b32_e64 v116, v166, v116, s[4:5]
	global_store_dwordx4 v[136:137], v[116:119], off sc1
	s_cbranch_scc1 .LBB0_1603
	v_lshl_add_u64 v[154:155], v[156:157], 0, v[138:139]
	v_cvt_pk_bf16_f32 v116, v116, v117
	v_cvt_pk_bf16_f32 v117, v118, v119
	v_lshl_add_u64 v[118:119], v[154:155], 1, s[18:19]
	global_store_dwordx2 v[118:119], v[116:117], off sc1
.LBB0_1603:
	ds_read_b64 v[116:117], v164 offset:8320
	v_add3_u32 v118, s3, v165, 16
	v_ashrrev_i32_e32 v119, 31, v118
	v_lshlrev_b64 v[154:155], 10, v[118:119]
	s_andn2_b64 vcc, exec, s[8:9]
	s_waitcnt lgkmcnt(0)
	v_sub_f32_e32 v119, v125, v116
	v_sub_f32_e32 v118, v124, v116
	v_sub_f32_e32 v125, v127, v116
	v_sub_f32_e32 v124, v126, v116
	v_pk_mul_f32 v[124:125], v[116:117], v[124:125] op_sel:[1,0]
	v_pk_mul_f32 v[116:117], v[116:117], v[118:119] op_sel:[1,0]
	v_pk_fma_f32 v[118:119], v[130:131], v[124:125], v[134:135]
	v_pk_fma_f32 v[116:117], v[128:129], v[116:117], v[132:133]
	v_cndmask_b32_e64 v124, 0, 1, s[8:9]
	v_cndmask_b32_e64 v119, v166, v119, s[4:5]
	v_cndmask_b32_e64 v118, v166, v118, s[4:5]
	v_cndmask_b32_e64 v117, v166, v117, s[4:5]
	v_cndmask_b32_e64 v116, v166, v116, s[4:5]
	v_cmp_ne_u32_e64 s[6:7], 1, v124
	global_store_dwordx4 v[140:141], v[116:119], off sc1
	s_cbranch_vccnz .LBB0_1605
	v_lshl_add_u64 v[124:125], v[154:155], 0, v[138:139]
	v_cvt_pk_bf16_f32 v116, v116, v117
	v_cvt_pk_bf16_f32 v117, v118, v119
	v_lshl_add_u64 v[118:119], v[124:125], 1, s[18:19]
	global_store_dwordx2 v[118:119], v[116:117], off sc1
.LBB0_1605:
	ds_read_b64 v[116:117], v164 offset:8448
	v_add3_u32 v118, s3, v165, 32
	v_ashrrev_i32_e32 v119, 31, v118
	v_lshlrev_b64 v[124:125], 10, v[118:119]
	s_and_b64 vcc, exec, s[6:7]
	s_waitcnt lgkmcnt(0)
	v_sub_f32_e32 v119, v121, v116
	v_sub_f32_e32 v118, v120, v116
	v_sub_f32_e32 v121, v123, v116
	v_sub_f32_e32 v120, v122, v116
	v_pk_mul_f32 v[120:121], v[116:117], v[120:121] op_sel:[1,0]
	v_pk_mul_f32 v[116:117], v[116:117], v[118:119] op_sel:[1,0]
	v_pk_fma_f32 v[118:119], v[130:131], v[120:121], v[134:135]
	v_pk_fma_f32 v[116:117], v[128:129], v[116:117], v[132:133]
	v_mov_b32_e32 v120, 0x7fc00000
	v_cndmask_b32_e64 v119, v120, v119, s[4:5]
	v_cndmask_b32_e64 v118, v120, v118, s[4:5]
	v_cndmask_b32_e64 v117, v120, v117, s[4:5]
	v_cndmask_b32_e64 v116, v120, v116, s[4:5]
	global_store_dwordx4 v[142:143], v[116:119], off sc1
	s_cbranch_vccnz .LBB0_1607
	v_lshl_add_u64 v[122:123], v[124:125], 0, v[138:139]
	v_cvt_pk_bf16_f32 v116, v116, v117
	v_cvt_pk_bf16_f32 v117, v118, v119
	v_lshl_add_u64 v[118:119], v[122:123], 1, s[18:19]
	global_store_dwordx2 v[118:119], v[116:117], off sc1
.LBB0_1607:
	ds_read_b64 v[118:119], v164 offset:8576
	v_add3_u32 v116, s3, v165, 48
	v_ashrrev_i32_e32 v117, 31, v116
	v_lshlrev_b64 v[116:117], 10, v[116:117]
	s_and_b64 vcc, exec, s[6:7]
	s_waitcnt lgkmcnt(0)
	v_sub_f32_e32 v113, v113, v118
	v_sub_f32_e32 v112, v112, v118
	v_sub_f32_e32 v115, v115, v118
	v_sub_f32_e32 v114, v114, v118
	v_pk_mul_f32 v[114:115], v[118:119], v[114:115] op_sel:[1,0]
	v_pk_mul_f32 v[112:113], v[118:119], v[112:113] op_sel:[1,0]
	v_pk_fma_f32 v[114:115], v[130:131], v[114:115], v[134:135]
	v_pk_fma_f32 v[112:113], v[128:129], v[112:113], v[132:133]
	v_cndmask_b32_e64 v115, v120, v115, s[4:5]
	v_cndmask_b32_e64 v114, v120, v114, s[4:5]
	v_cndmask_b32_e64 v113, v120, v113, s[4:5]
	v_cndmask_b32_e64 v112, v120, v112, s[4:5]
	global_store_dwordx4 v[144:145], v[112:115], off sc1
	s_cbranch_vccnz .LBB0_1609
	v_lshl_add_u64 v[118:119], v[116:117], 0, v[138:139]
	v_cvt_pk_bf16_f32 v112, v112, v113
	v_cvt_pk_bf16_f32 v113, v114, v115
	v_lshl_add_u64 v[114:115], v[118:119], 1, s[18:19]
	global_store_dwordx2 v[114:115], v[112:113], off sc1
.LBB0_1609:
	ds_read_b64 v[114:115], v164 offset:9216
	v_add_u32_e32 v112, 0x80, v162
	v_ashrrev_i32_e32 v113, 31, v112
	v_lshlrev_b64 v[112:113], 10, v[112:113]
	s_and_b64 vcc, exec, s[6:7]
	s_waitcnt lgkmcnt(0)
	v_sub_f32_e32 v109, v109, v114
	v_sub_f32_e32 v108, v108, v114
	v_sub_f32_e32 v111, v111, v114
	v_sub_f32_e32 v110, v110, v114
	v_pk_mul_f32 v[110:111], v[114:115], v[110:111] op_sel:[1,0]
	v_pk_mul_f32 v[108:109], v[114:115], v[108:109] op_sel:[1,0]
	v_pk_fma_f32 v[110:111], v[130:131], v[110:111], v[134:135]
	v_pk_fma_f32 v[108:109], v[128:129], v[108:109], v[132:133]
	v_mov_b32_e32 v114, 0x7fc00000
	v_cndmask_b32_e64 v111, v114, v111, s[4:5]
	v_cndmask_b32_e64 v110, v114, v110, s[4:5]
	v_cndmask_b32_e64 v109, v114, v109, s[4:5]
	v_cndmask_b32_e64 v108, v114, v108, s[4:5]
	global_store_dwordx4 v[146:147], v[108:111], off sc1
	s_cbranch_vccnz .LBB0_1611
	v_lshl_add_u64 v[118:119], v[112:113], 0, v[138:139]
	v_cvt_pk_bf16_f32 v108, v108, v109
	v_cvt_pk_bf16_f32 v109, v110, v111
	v_lshl_add_u64 v[110:111], v[118:119], 1, s[18:19]
	global_store_dwordx2 v[110:111], v[108:109], off sc1
.LBB0_1611:
	ds_read_b64 v[110:111], v164 offset:9344
	v_add_u32_e32 v108, 0x90, v162
	v_ashrrev_i32_e32 v109, 31, v108
	v_lshlrev_b64 v[108:109], 10, v[108:109]
	s_and_b64 vcc, exec, s[6:7]
	s_waitcnt lgkmcnt(0)
	v_sub_f32_e32 v93, v93, v110
	v_sub_f32_e32 v92, v92, v110
	v_sub_f32_e32 v95, v95, v110
	v_sub_f32_e32 v94, v94, v110
	v_pk_mul_f32 v[94:95], v[110:111], v[94:95] op_sel:[1,0]
	v_pk_mul_f32 v[92:93], v[110:111], v[92:93] op_sel:[1,0]
	v_pk_fma_f32 v[94:95], v[130:131], v[94:95], v[134:135]
	v_pk_fma_f32 v[92:93], v[128:129], v[92:93], v[132:133]
	v_cndmask_b32_e64 v95, v114, v95, s[4:5]
	v_cndmask_b32_e64 v94, v114, v94, s[4:5]
	v_cndmask_b32_e64 v93, v114, v93, s[4:5]
	v_cndmask_b32_e64 v92, v114, v92, s[4:5]
	global_store_dwordx4 v[148:149], v[92:95], off sc1
	s_cbranch_vccnz .LBB0_1613
	v_lshl_add_u64 v[110:111], v[108:109], 0, v[138:139]
	v_cvt_pk_bf16_f32 v92, v92, v93
	v_cvt_pk_bf16_f32 v93, v94, v95
	v_lshl_add_u64 v[94:95], v[110:111], 1, s[18:19]
	global_store_dwordx2 v[94:95], v[92:93], off sc1
.LBB0_1613:
	ds_read_b64 v[94:95], v164 offset:9472
	v_add_u32_e32 v92, 0xa0, v162
	v_ashrrev_i32_e32 v93, 31, v92
	v_mov_b32_e32 v118, 0x7fc00000
	s_mov_b64 s[8:9], 0x1000
	s_waitcnt lgkmcnt(0)
	v_sub_f32_e32 v77, v77, v94
	v_sub_f32_e32 v76, v76, v94
	v_sub_f32_e32 v79, v79, v94
	v_sub_f32_e32 v78, v78, v94
	v_pk_mul_f32 v[78:79], v[94:95], v[78:79] op_sel:[1,0]
	v_pk_mul_f32 v[76:77], v[94:95], v[76:77] op_sel:[1,0]
	v_pk_fma_f32 v[78:79], v[130:131], v[78:79], v[134:135]
	v_pk_fma_f32 v[76:77], v[128:129], v[76:77], v[132:133]
	v_lshlrev_b64 v[92:93], 10, v[92:93]
	v_cndmask_b32_e64 v79, v118, v79, s[4:5]
	v_cndmask_b32_e64 v78, v118, v78, s[4:5]
	v_cndmask_b32_e64 v77, v118, v77, s[4:5]
	v_cndmask_b32_e64 v76, v118, v76, s[4:5]
	s_and_b64 vcc, exec, s[6:7]
	global_store_dwordx4 v[150:151], v[76:79], off sc1
	s_cbranch_vccnz .LBB0_1615
	v_lshl_add_u64 v[94:95], v[92:93], 0, v[138:139]
	v_cvt_pk_bf16_f32 v76, v76, v77
	v_cvt_pk_bf16_f32 v77, v78, v79
	v_lshl_add_u64 v[78:79], v[94:95], 1, s[18:19]
	global_store_dwordx2 v[78:79], v[76:77], off sc1
.LBB0_1615:
	ds_read_b64 v[76:77], v164 offset:9600
	v_add_u32_e32 v78, 0xb0, v162
	v_ashrrev_i32_e32 v79, 31, v78
	v_lshl_add_u64 v[110:111], v[158:159], 0, s[8:9]
	v_lshl_add_u64 v[114:115], v[160:161], 0, s[8:9]
	s_waitcnt lgkmcnt(0)
	v_sub_f32_e32 v53, v53, v76
	v_sub_f32_e32 v52, v52, v76
	v_sub_f32_e32 v55, v55, v76
	v_sub_f32_e32 v54, v54, v76
	v_pk_mul_f32 v[54:55], v[76:77], v[54:55] op_sel:[1,0]
	v_pk_mul_f32 v[52:53], v[76:77], v[52:53] op_sel:[1,0]
	v_pk_fma_f32 v[54:55], v[130:131], v[54:55], v[134:135]
	v_pk_fma_f32 v[52:53], v[128:129], v[52:53], v[132:133]
	v_lshlrev_b64 v[94:95], 10, v[78:79]
	v_cndmask_b32_e64 v55, v118, v55, s[4:5]
	v_cndmask_b32_e64 v54, v118, v54, s[4:5]
	v_cndmask_b32_e64 v53, v118, v53, s[4:5]
	v_cndmask_b32_e64 v52, v118, v52, s[4:5]
	s_and_b64 vcc, exec, s[6:7]
	global_store_dwordx4 v[152:153], v[52:55], off sc1
	s_cbranch_vccnz .LBB0_1617
	v_lshl_add_u64 v[76:77], v[94:95], 0, v[138:139]
	v_cvt_pk_bf16_f32 v52, v52, v53
	v_cvt_pk_bf16_f32 v53, v54, v55
	v_lshl_add_u64 v[54:55], v[76:77], 1, s[18:19]
	global_store_dwordx2 v[54:55], v[52:53], off sc1
.LBB0_1617:
	global_load_dwordx4 v[52:55], v[110:111], off offset:64
	global_load_dwordx4 v[76:79], v[114:115], off offset:64
	ds_read_b64 v[122:123], v164 offset:8192
	v_mov_b32_e32 v120, 0x7fc00000
	v_lshl_add_u64 v[118:119], v[138:139], 0, 16
	s_and_b64 vcc, exec, s[6:7]
	s_waitcnt lgkmcnt(0)
	v_sub_f32_e32 v81, v81, v122
	v_sub_f32_e32 v80, v80, v122
	v_sub_f32_e32 v83, v83, v122
	v_sub_f32_e32 v82, v82, v122
	v_pk_mul_f32 v[82:83], v[122:123], v[82:83] op_sel:[1,0]
	v_pk_mul_f32 v[80:81], v[122:123], v[80:81] op_sel:[1,0]
	s_waitcnt vmcnt(0)
	v_pk_fma_f32 v[82:83], v[54:55], v[82:83], v[78:79]
	v_pk_fma_f32 v[80:81], v[52:53], v[80:81], v[76:77]
	v_cndmask_b32_e64 v83, v120, v83, s[4:5]
	v_cndmask_b32_e64 v82, v120, v82, s[4:5]
	v_cndmask_b32_e64 v81, v120, v81, s[4:5]
	v_cndmask_b32_e64 v80, v120, v80, s[4:5]
	global_store_dwordx4 v[136:137], v[80:83], off offset:64 sc1
	s_cbranch_vccnz .LBB0_1619
	v_lshl_add_u64 v[122:123], v[156:157], 0, v[118:119]
	v_cvt_pk_bf16_f32 v80, v80, v81
	v_cvt_pk_bf16_f32 v81, v82, v83
	v_lshl_add_u64 v[82:83], v[122:123], 1, s[18:19]
	global_store_dwordx2 v[82:83], v[80:81], off sc1
.LBB0_1619:
	ds_read_b64 v[80:81], v164 offset:8320
	s_and_b64 vcc, exec, s[6:7]
	s_waitcnt lgkmcnt(0)
	v_sub_f32_e32 v83, v85, v80
	v_sub_f32_e32 v82, v84, v80
	v_sub_f32_e32 v85, v87, v80
	v_sub_f32_e32 v84, v86, v80
	v_pk_mul_f32 v[84:85], v[80:81], v[84:85] op_sel:[1,0]
	v_pk_mul_f32 v[80:81], v[80:81], v[82:83] op_sel:[1,0]
	v_pk_fma_f32 v[82:83], v[54:55], v[84:85], v[78:79]
	v_pk_fma_f32 v[80:81], v[52:53], v[80:81], v[76:77]
	v_cndmask_b32_e64 v83, v120, v83, s[4:5]
	v_cndmask_b32_e64 v82, v120, v82, s[4:5]
	v_cndmask_b32_e64 v81, v120, v81, s[4:5]
	v_cndmask_b32_e64 v80, v120, v80, s[4:5]
	global_store_dwordx4 v[140:141], v[80:83], off offset:64 sc1
	s_cbranch_vccnz .LBB0_1621
	v_lshl_add_u64 v[84:85], v[154:155], 0, v[118:119]
	v_cvt_pk_bf16_f32 v80, v80, v81
	v_cvt_pk_bf16_f32 v81, v82, v83
	v_lshl_add_u64 v[82:83], v[84:85], 1, s[18:19]
	global_store_dwordx2 v[82:83], v[80:81], off sc1
.LBB0_1621:
	ds_read_b64 v[80:81], v164 offset:8448
	s_and_b64 vcc, exec, s[6:7]
	s_waitcnt lgkmcnt(0)
	v_sub_f32_e32 v83, v97, v80
	v_sub_f32_e32 v82, v96, v80
	v_sub_f32_e32 v85, v99, v80
	v_sub_f32_e32 v84, v98, v80
	v_pk_mul_f32 v[84:85], v[80:81], v[84:85] op_sel:[1,0]
	v_pk_mul_f32 v[80:81], v[80:81], v[82:83] op_sel:[1,0]
	v_pk_fma_f32 v[82:83], v[54:55], v[84:85], v[78:79]
	v_pk_fma_f32 v[80:81], v[52:53], v[80:81], v[76:77]
	v_mov_b32_e32 v84, 0x7fc00000
	v_cndmask_b32_e64 v83, v84, v83, s[4:5]
	v_cndmask_b32_e64 v82, v84, v82, s[4:5]
	v_cndmask_b32_e64 v81, v84, v81, s[4:5]
	v_cndmask_b32_e64 v80, v84, v80, s[4:5]
	global_store_dwordx4 v[142:143], v[80:83], off offset:64 sc1
	s_cbranch_vccnz .LBB0_1623
	v_lshl_add_u64 v[86:87], v[124:125], 0, v[118:119]
	v_cvt_pk_bf16_f32 v80, v80, v81
	v_cvt_pk_bf16_f32 v81, v82, v83
	v_lshl_add_u64 v[82:83], v[86:87], 1, s[18:19]
	global_store_dwordx2 v[82:83], v[80:81], off sc1
.LBB0_1623:
	ds_read_b64 v[80:81], v164 offset:8576
	s_and_b64 vcc, exec, s[6:7]
	s_waitcnt lgkmcnt(0)
	v_sub_f32_e32 v83, v101, v80
	v_sub_f32_e32 v82, v100, v80
	v_sub_f32_e32 v87, v103, v80
	v_sub_f32_e32 v86, v102, v80
	v_pk_mul_f32 v[86:87], v[80:81], v[86:87] op_sel:[1,0]
	v_pk_mul_f32 v[80:81], v[80:81], v[82:83] op_sel:[1,0]
	v_pk_fma_f32 v[82:83], v[54:55], v[86:87], v[78:79]
	v_pk_fma_f32 v[80:81], v[52:53], v[80:81], v[76:77]
	v_cndmask_b32_e64 v83, v84, v83, s[4:5]
	v_cndmask_b32_e64 v82, v84, v82, s[4:5]
	v_cndmask_b32_e64 v81, v84, v81, s[4:5]
	v_cndmask_b32_e64 v80, v84, v80, s[4:5]
	global_store_dwordx4 v[144:145], v[80:83], off offset:64 sc1
	s_cbranch_vccnz .LBB0_1625
	v_lshl_add_u64 v[84:85], v[116:117], 0, v[118:119]
	v_cvt_pk_bf16_f32 v80, v80, v81
	v_cvt_pk_bf16_f32 v81, v82, v83
	v_lshl_add_u64 v[82:83], v[84:85], 1, s[18:19]
	global_store_dwordx2 v[82:83], v[80:81], off sc1
.LBB0_1625:
	ds_read_b64 v[80:81], v164 offset:9216
	s_and_b64 vcc, exec, s[6:7]
	s_waitcnt lgkmcnt(0)
	v_sub_f32_e32 v83, v105, v80
	v_sub_f32_e32 v82, v104, v80
	v_sub_f32_e32 v85, v107, v80
	v_sub_f32_e32 v84, v106, v80
	v_pk_mul_f32 v[84:85], v[80:81], v[84:85] op_sel:[1,0]
	v_pk_mul_f32 v[80:81], v[80:81], v[82:83] op_sel:[1,0]
	v_pk_fma_f32 v[82:83], v[54:55], v[84:85], v[78:79]
	v_pk_fma_f32 v[80:81], v[52:53], v[80:81], v[76:77]
	v_mov_b32_e32 v84, 0x7fc00000
	v_cndmask_b32_e64 v83, v84, v83, s[4:5]
	v_cndmask_b32_e64 v82, v84, v82, s[4:5]
	v_cndmask_b32_e64 v81, v84, v81, s[4:5]
	v_cndmask_b32_e64 v80, v84, v80, s[4:5]
	global_store_dwordx4 v[146:147], v[80:83], off offset:64 sc1
	s_cbranch_vccnz .LBB0_1627
	v_lshl_add_u64 v[86:87], v[112:113], 0, v[118:119]
	v_cvt_pk_bf16_f32 v80, v80, v81
	v_cvt_pk_bf16_f32 v81, v82, v83
	v_lshl_add_u64 v[82:83], v[86:87], 1, s[18:19]
	global_store_dwordx2 v[82:83], v[80:81], off sc1
.LBB0_1627:
	ds_read_b64 v[80:81], v164 offset:9344
	s_and_b64 vcc, exec, s[6:7]
	s_waitcnt lgkmcnt(0)
	v_sub_f32_e32 v83, v89, v80
	v_sub_f32_e32 v82, v88, v80
	v_sub_f32_e32 v87, v91, v80
	v_sub_f32_e32 v86, v90, v80
	v_pk_mul_f32 v[86:87], v[80:81], v[86:87] op_sel:[1,0]
	v_pk_mul_f32 v[80:81], v[80:81], v[82:83] op_sel:[1,0]
	v_pk_fma_f32 v[82:83], v[54:55], v[86:87], v[78:79]
	v_pk_fma_f32 v[80:81], v[52:53], v[80:81], v[76:77]
	v_cndmask_b32_e64 v83, v84, v83, s[4:5]
	v_cndmask_b32_e64 v82, v84, v82, s[4:5]
	v_cndmask_b32_e64 v81, v84, v81, s[4:5]
	v_cndmask_b32_e64 v80, v84, v80, s[4:5]
	global_store_dwordx4 v[148:149], v[80:83], off offset:64 sc1
	s_cbranch_vccnz .LBB0_1629
	v_lshl_add_u64 v[84:85], v[108:109], 0, v[118:119]
	v_cvt_pk_bf16_f32 v80, v80, v81
	v_cvt_pk_bf16_f32 v81, v82, v83
	v_lshl_add_u64 v[82:83], v[84:85], 1, s[18:19]
	global_store_dwordx2 v[82:83], v[80:81], off sc1
.LBB0_1629:
	ds_read_b64 v[80:81], v164 offset:9472
	s_and_b64 vcc, exec, s[6:7]
	s_waitcnt lgkmcnt(0)
	v_sub_f32_e32 v73, v73, v80
	v_sub_f32_e32 v72, v72, v80
	v_sub_f32_e32 v75, v75, v80
	v_sub_f32_e32 v74, v74, v80
	v_pk_mul_f32 v[74:75], v[80:81], v[74:75] op_sel:[1,0]
	v_pk_mul_f32 v[72:73], v[80:81], v[72:73] op_sel:[1,0]
	v_pk_fma_f32 v[74:75], v[54:55], v[74:75], v[78:79]
	v_pk_fma_f32 v[72:73], v[52:53], v[72:73], v[76:77]
	v_mov_b32_e32 v80, 0x7fc00000
	v_cndmask_b32_e64 v75, v80, v75, s[4:5]
	v_cndmask_b32_e64 v74, v80, v74, s[4:5]
	v_cndmask_b32_e64 v73, v80, v73, s[4:5]
	v_cndmask_b32_e64 v72, v80, v72, s[4:5]
	global_store_dwordx4 v[150:151], v[72:75], off offset:64 sc1
	s_cbranch_vccnz .LBB0_1631
	v_lshl_add_u64 v[82:83], v[92:93], 0, v[118:119]
	v_cvt_pk_bf16_f32 v72, v72, v73
	v_cvt_pk_bf16_f32 v73, v74, v75
	v_lshl_add_u64 v[74:75], v[82:83], 1, s[18:19]
	global_store_dwordx2 v[74:75], v[72:73], off sc1
.LBB0_1631:
	ds_read_b64 v[72:73], v164 offset:9600
	s_and_b64 vcc, exec, s[6:7]
	s_waitcnt lgkmcnt(0)
	v_sub_f32_e32 v49, v49, v72
	v_sub_f32_e32 v48, v48, v72
	v_sub_f32_e32 v51, v51, v72
	v_sub_f32_e32 v50, v50, v72
	v_pk_mul_f32 v[50:51], v[72:73], v[50:51] op_sel:[1,0]
	v_pk_mul_f32 v[48:49], v[72:73], v[48:49] op_sel:[1,0]
	v_pk_fma_f32 v[50:51], v[54:55], v[50:51], v[78:79]
	v_pk_fma_f32 v[48:49], v[52:53], v[48:49], v[76:77]
	v_cndmask_b32_e64 v51, v80, v51, s[4:5]
	v_cndmask_b32_e64 v50, v80, v50, s[4:5]
	v_cndmask_b32_e64 v49, v80, v49, s[4:5]
	v_cndmask_b32_e64 v48, v80, v48, s[4:5]
	global_store_dwordx4 v[152:153], v[48:51], off offset:64 sc1
	s_cbranch_vccnz .LBB0_1633
	v_lshl_add_u64 v[52:53], v[94:95], 0, v[118:119]
	v_cvt_pk_bf16_f32 v48, v48, v49
	v_cvt_pk_bf16_f32 v49, v50, v51
	v_lshl_add_u64 v[50:51], v[52:53], 1, s[18:19]
	global_store_dwordx2 v[50:51], v[48:49], off sc1
.LBB0_1633:
	global_load_dwordx4 v[48:51], v[110:111], off offset:512
	global_load_dwordx4 v[52:55], v[114:115], off offset:512
	ds_read_b64 v[76:77], v164 offset:8192
	s_mov_b64 s[0:1], 0x80
	v_mov_b32_e32 v74, 0x7fc00000
	v_lshl_add_u64 v[72:73], v[138:139], 0, s[0:1]
	s_and_b64 vcc, exec, s[6:7]
	s_waitcnt lgkmcnt(0)
	v_sub_f32_e32 v29, v29, v76
	v_sub_f32_e32 v28, v28, v76
	v_sub_f32_e32 v31, v31, v76
	v_sub_f32_e32 v30, v30, v76
	v_pk_mul_f32 v[30:31], v[76:77], v[30:31] op_sel:[1,0]
	v_pk_mul_f32 v[28:29], v[76:77], v[28:29] op_sel:[1,0]
	s_waitcnt vmcnt(0)
	v_pk_fma_f32 v[30:31], v[50:51], v[30:31], v[54:55]
	v_pk_fma_f32 v[28:29], v[48:49], v[28:29], v[52:53]
	v_cndmask_b32_e64 v31, v74, v31, s[4:5]
	v_cndmask_b32_e64 v30, v74, v30, s[4:5]
	v_cndmask_b32_e64 v29, v74, v29, s[4:5]
	v_cndmask_b32_e64 v28, v74, v28, s[4:5]
	global_store_dwordx4 v[136:137], v[28:31], off offset:512 sc1
	s_cbranch_vccnz .LBB0_1635
	v_lshl_add_u64 v[76:77], v[156:157], 0, v[72:73]
	v_cvt_pk_bf16_f32 v28, v28, v29
	v_cvt_pk_bf16_f32 v29, v30, v31
	v_lshl_add_u64 v[30:31], v[76:77], 1, s[18:19]
	global_store_dwordx2 v[30:31], v[28:29], off sc1
.LBB0_1635:
	ds_read_b64 v[28:29], v164 offset:8320
	s_and_b64 vcc, exec, s[6:7]
	s_waitcnt lgkmcnt(0)
	v_sub_f32_e32 v31, v41, v28
	v_sub_f32_e32 v30, v40, v28
	v_sub_f32_e32 v41, v43, v28
	v_sub_f32_e32 v40, v42, v28
	v_pk_mul_f32 v[40:41], v[28:29], v[40:41] op_sel:[1,0]
	v_pk_mul_f32 v[28:29], v[28:29], v[30:31] op_sel:[1,0]
	v_pk_fma_f32 v[30:31], v[50:51], v[40:41], v[54:55]
	v_pk_fma_f32 v[28:29], v[48:49], v[28:29], v[52:53]
	v_cndmask_b32_e64 v31, v74, v31, s[4:5]
	v_cndmask_b32_e64 v30, v74, v30, s[4:5]
	v_cndmask_b32_e64 v29, v74, v29, s[4:5]
	v_cndmask_b32_e64 v28, v74, v28, s[4:5]
	global_store_dwordx4 v[140:141], v[28:31], off offset:512 sc1
	s_cbranch_vccnz .LBB0_1637
	v_lshl_add_u64 v[40:41], v[154:155], 0, v[72:73]
	v_cvt_pk_bf16_f32 v28, v28, v29
	v_cvt_pk_bf16_f32 v29, v30, v31
	v_lshl_add_u64 v[30:31], v[40:41], 1, s[18:19]
	global_store_dwordx2 v[30:31], v[28:29], off sc1
.LBB0_1637:
	ds_read_b64 v[28:29], v164 offset:8448
	s_and_b64 vcc, exec, s[6:7]
	s_waitcnt lgkmcnt(0)
	v_sub_f32_e32 v31, v45, v28
	v_sub_f32_e32 v30, v44, v28
	v_sub_f32_e32 v41, v47, v28
	v_sub_f32_e32 v40, v46, v28
	v_pk_mul_f32 v[40:41], v[28:29], v[40:41] op_sel:[1,0]
	v_pk_mul_f32 v[28:29], v[28:29], v[30:31] op_sel:[1,0]
	v_pk_fma_f32 v[30:31], v[50:51], v[40:41], v[54:55]
	v_pk_fma_f32 v[28:29], v[48:49], v[28:29], v[52:53]
	v_mov_b32_e32 v40, 0x7fc00000
	v_cndmask_b32_e64 v31, v40, v31, s[4:5]
	v_cndmask_b32_e64 v30, v40, v30, s[4:5]
	v_cndmask_b32_e64 v29, v40, v29, s[4:5]
	v_cndmask_b32_e64 v28, v40, v28, s[4:5]
	global_store_dwordx4 v[142:143], v[28:31], off offset:512 sc1
	s_cbranch_vccnz .LBB0_1639
	v_lshl_add_u64 v[42:43], v[124:125], 0, v[72:73]
	v_cvt_pk_bf16_f32 v28, v28, v29
	v_cvt_pk_bf16_f32 v29, v30, v31
	v_lshl_add_u64 v[30:31], v[42:43], 1, s[18:19]
	global_store_dwordx2 v[30:31], v[28:29], off sc1
.LBB0_1639:
	ds_read_b64 v[28:29], v164 offset:8576
	s_and_b64 vcc, exec, s[6:7]
	s_waitcnt lgkmcnt(0)
	v_sub_f32_e32 v31, v57, v28
	v_sub_f32_e32 v30, v56, v28
	v_sub_f32_e32 v43, v59, v28
	v_sub_f32_e32 v42, v58, v28
	v_pk_mul_f32 v[42:43], v[28:29], v[42:43] op_sel:[1,0]
	v_pk_mul_f32 v[28:29], v[28:29], v[30:31] op_sel:[1,0]
	v_pk_fma_f32 v[30:31], v[50:51], v[42:43], v[54:55]
	v_pk_fma_f32 v[28:29], v[48:49], v[28:29], v[52:53]
	v_cndmask_b32_e64 v31, v40, v31, s[4:5]
	v_cndmask_b32_e64 v30, v40, v30, s[4:5]
	v_cndmask_b32_e64 v29, v40, v29, s[4:5]
	v_cndmask_b32_e64 v28, v40, v28, s[4:5]
	global_store_dwordx4 v[144:145], v[28:31], off offset:512 sc1
	s_cbranch_vccnz .LBB0_1641
	v_lshl_add_u64 v[40:41], v[116:117], 0, v[72:73]
	v_cvt_pk_bf16_f32 v28, v28, v29
	v_cvt_pk_bf16_f32 v29, v30, v31
	v_lshl_add_u64 v[30:31], v[40:41], 1, s[18:19]
	global_store_dwordx2 v[30:31], v[28:29], off sc1
.LBB0_1641:
	ds_read_b64 v[28:29], v164 offset:9216
	s_and_b64 vcc, exec, s[6:7]
	s_waitcnt lgkmcnt(0)
	v_sub_f32_e32 v31, v61, v28
	v_sub_f32_e32 v30, v60, v28
	v_sub_f32_e32 v41, v63, v28
	v_sub_f32_e32 v40, v62, v28
	v_pk_mul_f32 v[40:41], v[28:29], v[40:41] op_sel:[1,0]
	v_pk_mul_f32 v[28:29], v[28:29], v[30:31] op_sel:[1,0]
	v_pk_fma_f32 v[30:31], v[50:51], v[40:41], v[54:55]
	v_pk_fma_f32 v[28:29], v[48:49], v[28:29], v[52:53]
	v_mov_b32_e32 v40, 0x7fc00000
	v_cndmask_b32_e64 v31, v40, v31, s[4:5]
	v_cndmask_b32_e64 v30, v40, v30, s[4:5]
	v_cndmask_b32_e64 v29, v40, v29, s[4:5]
	v_cndmask_b32_e64 v28, v40, v28, s[4:5]
	global_store_dwordx4 v[146:147], v[28:31], off offset:512 sc1
	s_cbranch_vccnz .LBB0_1643
	v_lshl_add_u64 v[42:43], v[112:113], 0, v[72:73]
	v_cvt_pk_bf16_f32 v28, v28, v29
	v_cvt_pk_bf16_f32 v29, v30, v31
	v_lshl_add_u64 v[30:31], v[42:43], 1, s[18:19]
	global_store_dwordx2 v[30:31], v[28:29], off sc1
.LBB0_1643:
	ds_read_b64 v[28:29], v164 offset:9344
	s_and_b64 vcc, exec, s[6:7]
	s_waitcnt lgkmcnt(0)
	v_sub_f32_e32 v31, v69, v28
	v_sub_f32_e32 v30, v68, v28
	v_sub_f32_e32 v43, v71, v28
	v_sub_f32_e32 v42, v70, v28
	v_pk_mul_f32 v[42:43], v[28:29], v[42:43] op_sel:[1,0]
	v_pk_mul_f32 v[28:29], v[28:29], v[30:31] op_sel:[1,0]
	v_pk_fma_f32 v[30:31], v[50:51], v[42:43], v[54:55]
	v_pk_fma_f32 v[28:29], v[48:49], v[28:29], v[52:53]
	v_cndmask_b32_e64 v31, v40, v31, s[4:5]
	v_cndmask_b32_e64 v30, v40, v30, s[4:5]
	v_cndmask_b32_e64 v29, v40, v29, s[4:5]
	v_cndmask_b32_e64 v28, v40, v28, s[4:5]
	global_store_dwordx4 v[148:149], v[28:31], off offset:512 sc1
	s_cbranch_vccnz .LBB0_1645
	v_lshl_add_u64 v[40:41], v[108:109], 0, v[72:73]
	v_cvt_pk_bf16_f32 v28, v28, v29
	v_cvt_pk_bf16_f32 v29, v30, v31
	v_lshl_add_u64 v[30:31], v[40:41], 1, s[18:19]
	global_store_dwordx2 v[30:31], v[28:29], off sc1
.LBB0_1645:
	ds_read_b64 v[28:29], v164 offset:9472
	s_and_b64 vcc, exec, s[6:7]
	s_waitcnt lgkmcnt(0)
	v_sub_f32_e32 v31, v65, v28
	v_sub_f32_e32 v30, v64, v28
	v_sub_f32_e32 v41, v67, v28
	v_sub_f32_e32 v40, v66, v28
	v_pk_mul_f32 v[40:41], v[28:29], v[40:41] op_sel:[1,0]
	v_pk_mul_f32 v[28:29], v[28:29], v[30:31] op_sel:[1,0]
	v_pk_fma_f32 v[30:31], v[50:51], v[40:41], v[54:55]
	v_pk_fma_f32 v[28:29], v[48:49], v[28:29], v[52:53]
	v_mov_b32_e32 v40, 0x7fc00000
	v_cndmask_b32_e64 v31, v40, v31, s[4:5]
	v_cndmask_b32_e64 v30, v40, v30, s[4:5]
	v_cndmask_b32_e64 v29, v40, v29, s[4:5]
	v_cndmask_b32_e64 v28, v40, v28, s[4:5]
	global_store_dwordx4 v[150:151], v[28:31], off offset:512 sc1
	s_cbranch_vccnz .LBB0_1647
	v_lshl_add_u64 v[42:43], v[92:93], 0, v[72:73]
	v_cvt_pk_bf16_f32 v28, v28, v29
	v_cvt_pk_bf16_f32 v29, v30, v31
	v_lshl_add_u64 v[30:31], v[42:43], 1, s[18:19]
	global_store_dwordx2 v[30:31], v[28:29], off sc1
.LBB0_1647:
	ds_read_b64 v[28:29], v164 offset:9600
	s_and_b64 vcc, exec, s[6:7]
	s_waitcnt lgkmcnt(0)
	v_sub_f32_e32 v31, v37, v28
	v_sub_f32_e32 v30, v36, v28
	v_sub_f32_e32 v37, v39, v28
	v_sub_f32_e32 v36, v38, v28
	v_pk_mul_f32 v[36:37], v[28:29], v[36:37] op_sel:[1,0]
	v_pk_mul_f32 v[28:29], v[28:29], v[30:31] op_sel:[1,0]
	v_pk_fma_f32 v[30:31], v[50:51], v[36:37], v[54:55]
	v_pk_fma_f32 v[28:29], v[48:49], v[28:29], v[52:53]
	v_cndmask_b32_e64 v31, v40, v31, s[4:5]
	v_cndmask_b32_e64 v30, v40, v30, s[4:5]
	v_cndmask_b32_e64 v29, v40, v29, s[4:5]
	v_cndmask_b32_e64 v28, v40, v28, s[4:5]
	global_store_dwordx4 v[152:153], v[28:31], off offset:512 sc1
	s_cbranch_vccnz .LBB0_1649
	v_lshl_add_u64 v[36:37], v[94:95], 0, v[72:73]
	v_cvt_pk_bf16_f32 v28, v28, v29
	v_cvt_pk_bf16_f32 v29, v30, v31
	v_lshl_add_u64 v[30:31], v[36:37], 1, s[18:19]
	global_store_dwordx2 v[30:31], v[28:29], off sc1
.LBB0_1649:
	global_load_dwordx4 v[28:31], v[110:111], off offset:576
	global_load_dwordx4 v[36:39], v[114:115], off offset:576
	ds_read_b64 v[44:45], v164 offset:8192
	s_mov_b64 s[0:1], 0x90
	v_mov_b32_e32 v42, 0x7fc00000
	v_lshl_add_u64 v[40:41], v[138:139], 0, s[0:1]
	s_and_b64 vcc, exec, s[6:7]
	s_waitcnt lgkmcnt(0)
	v_sub_f32_e32 v1, v1, v44
	v_sub_f32_e32 v0, v0, v44
	v_sub_f32_e32 v3, v3, v44
	v_sub_f32_e32 v2, v2, v44
	v_pk_mul_f32 v[2:3], v[44:45], v[2:3] op_sel:[1,0]
	v_pk_mul_f32 v[0:1], v[44:45], v[0:1] op_sel:[1,0]
	s_waitcnt vmcnt(0)
	v_pk_fma_f32 v[2:3], v[30:31], v[2:3], v[38:39]
	v_pk_fma_f32 v[0:1], v[28:29], v[0:1], v[36:37]
	v_cndmask_b32_e64 v3, v42, v3, s[4:5]
	v_cndmask_b32_e64 v2, v42, v2, s[4:5]
	v_cndmask_b32_e64 v1, v42, v1, s[4:5]
	v_cndmask_b32_e64 v0, v42, v0, s[4:5]
	global_store_dwordx4 v[136:137], v[0:3], off offset:576 sc1
	s_cbranch_vccnz .LBB0_1651
	v_lshl_add_u64 v[44:45], v[156:157], 0, v[40:41]
	v_cvt_pk_bf16_f32 v0, v0, v1
	v_cvt_pk_bf16_f32 v1, v2, v3
	v_lshl_add_u64 v[2:3], v[44:45], 1, s[18:19]
	global_store_dwordx2 v[2:3], v[0:1], off sc1
.LBB0_1651:
	ds_read_b64 v[0:1], v164 offset:8320
	s_and_b64 vcc, exec, s[6:7]
	s_waitcnt lgkmcnt(0)
	v_sub_f32_e32 v3, v5, v0
	v_sub_f32_e32 v2, v4, v0
	v_sub_f32_e32 v5, v7, v0
	v_sub_f32_e32 v4, v6, v0
	v_pk_mul_f32 v[4:5], v[0:1], v[4:5] op_sel:[1,0]
	v_pk_mul_f32 v[0:1], v[0:1], v[2:3] op_sel:[1,0]
	v_pk_fma_f32 v[2:3], v[30:31], v[4:5], v[38:39]
	v_pk_fma_f32 v[0:1], v[28:29], v[0:1], v[36:37]
	v_cndmask_b32_e64 v3, v42, v3, s[4:5]
	v_cndmask_b32_e64 v2, v42, v2, s[4:5]
	v_cndmask_b32_e64 v1, v42, v1, s[4:5]
	v_cndmask_b32_e64 v0, v42, v0, s[4:5]
	global_store_dwordx4 v[140:141], v[0:3], off offset:576 sc1
	s_cbranch_vccnz .LBB0_1653
	v_lshl_add_u64 v[4:5], v[154:155], 0, v[40:41]
	v_cvt_pk_bf16_f32 v0, v0, v1
	v_cvt_pk_bf16_f32 v1, v2, v3
	v_lshl_add_u64 v[2:3], v[4:5], 1, s[18:19]
	global_store_dwordx2 v[2:3], v[0:1], off sc1
.LBB0_1653:
	ds_read_b64 v[0:1], v164 offset:8448
	s_and_b64 vcc, exec, s[6:7]
	s_waitcnt lgkmcnt(0)
	v_sub_f32_e32 v3, v9, v0
	v_sub_f32_e32 v2, v8, v0
	v_sub_f32_e32 v5, v11, v0
	v_sub_f32_e32 v4, v10, v0
	v_pk_mul_f32 v[4:5], v[0:1], v[4:5] op_sel:[1,0]
	v_pk_mul_f32 v[0:1], v[0:1], v[2:3] op_sel:[1,0]
	v_pk_fma_f32 v[2:3], v[30:31], v[4:5], v[38:39]
	v_pk_fma_f32 v[0:1], v[28:29], v[0:1], v[36:37]
	v_mov_b32_e32 v4, 0x7fc00000
	v_cndmask_b32_e64 v3, v4, v3, s[4:5]
	v_cndmask_b32_e64 v2, v4, v2, s[4:5]
	v_cndmask_b32_e64 v1, v4, v1, s[4:5]
	v_cndmask_b32_e64 v0, v4, v0, s[4:5]
	global_store_dwordx4 v[142:143], v[0:3], off offset:576 sc1
	s_cbranch_vccnz .LBB0_1655
	v_lshl_add_u64 v[6:7], v[124:125], 0, v[40:41]
	v_cvt_pk_bf16_f32 v0, v0, v1
	v_cvt_pk_bf16_f32 v1, v2, v3
	v_lshl_add_u64 v[2:3], v[6:7], 1, s[18:19]
	global_store_dwordx2 v[2:3], v[0:1], off sc1
.LBB0_1655:
	ds_read_b64 v[0:1], v164 offset:8576
	s_and_b64 vcc, exec, s[6:7]
	s_waitcnt lgkmcnt(0)
	v_sub_f32_e32 v3, v13, v0
	v_sub_f32_e32 v2, v12, v0
	v_sub_f32_e32 v7, v15, v0
	v_sub_f32_e32 v6, v14, v0
	v_pk_mul_f32 v[6:7], v[0:1], v[6:7] op_sel:[1,0]
	v_pk_mul_f32 v[0:1], v[0:1], v[2:3] op_sel:[1,0]
	v_pk_fma_f32 v[2:3], v[30:31], v[6:7], v[38:39]
	v_pk_fma_f32 v[0:1], v[28:29], v[0:1], v[36:37]
	v_cndmask_b32_e64 v3, v4, v3, s[4:5]
	v_cndmask_b32_e64 v2, v4, v2, s[4:5]
	v_cndmask_b32_e64 v1, v4, v1, s[4:5]
	v_cndmask_b32_e64 v0, v4, v0, s[4:5]
	global_store_dwordx4 v[144:145], v[0:3], off offset:576 sc1
	s_cbranch_vccnz .LBB0_1657
	v_lshl_add_u64 v[4:5], v[116:117], 0, v[40:41]
	v_cvt_pk_bf16_f32 v0, v0, v1
	v_cvt_pk_bf16_f32 v1, v2, v3
	v_lshl_add_u64 v[2:3], v[4:5], 1, s[18:19]
	global_store_dwordx2 v[2:3], v[0:1], off sc1
.LBB0_1657:
	ds_read_b64 v[0:1], v164 offset:9216
	s_and_b64 vcc, exec, s[6:7]
	s_waitcnt lgkmcnt(0)
	v_sub_f32_e32 v3, v17, v0
	v_sub_f32_e32 v2, v16, v0
	v_sub_f32_e32 v5, v19, v0
	v_sub_f32_e32 v4, v18, v0
	v_pk_mul_f32 v[4:5], v[0:1], v[4:5] op_sel:[1,0]
	v_pk_mul_f32 v[0:1], v[0:1], v[2:3] op_sel:[1,0]
	v_pk_fma_f32 v[2:3], v[30:31], v[4:5], v[38:39]
	v_pk_fma_f32 v[0:1], v[28:29], v[0:1], v[36:37]
	v_mov_b32_e32 v4, 0x7fc00000
	v_cndmask_b32_e64 v3, v4, v3, s[4:5]
	v_cndmask_b32_e64 v2, v4, v2, s[4:5]
	v_cndmask_b32_e64 v1, v4, v1, s[4:5]
	v_cndmask_b32_e64 v0, v4, v0, s[4:5]
	global_store_dwordx4 v[146:147], v[0:3], off offset:576 sc1
	s_cbranch_vccnz .LBB0_1659
	v_lshl_add_u64 v[6:7], v[112:113], 0, v[40:41]
	v_cvt_pk_bf16_f32 v0, v0, v1
	v_cvt_pk_bf16_f32 v1, v2, v3
	v_lshl_add_u64 v[2:3], v[6:7], 1, s[18:19]
	global_store_dwordx2 v[2:3], v[0:1], off sc1
.LBB0_1659:
	ds_read_b64 v[0:1], v164 offset:9344
	s_and_b64 vcc, exec, s[6:7]
	s_waitcnt lgkmcnt(0)
	v_sub_f32_e32 v3, v21, v0
	v_sub_f32_e32 v2, v20, v0
	v_sub_f32_e32 v7, v23, v0
	v_sub_f32_e32 v6, v22, v0
	v_pk_mul_f32 v[6:7], v[0:1], v[6:7] op_sel:[1,0]
	v_pk_mul_f32 v[0:1], v[0:1], v[2:3] op_sel:[1,0]
	v_pk_fma_f32 v[2:3], v[30:31], v[6:7], v[38:39]
	v_pk_fma_f32 v[0:1], v[28:29], v[0:1], v[36:37]
	v_cndmask_b32_e64 v3, v4, v3, s[4:5]
	v_cndmask_b32_e64 v2, v4, v2, s[4:5]
	v_cndmask_b32_e64 v1, v4, v1, s[4:5]
	v_cndmask_b32_e64 v0, v4, v0, s[4:5]
	global_store_dwordx4 v[148:149], v[0:3], off offset:576 sc1
	s_cbranch_vccnz .LBB0_1661
	v_lshl_add_u64 v[4:5], v[108:109], 0, v[40:41]
	v_cvt_pk_bf16_f32 v0, v0, v1
	v_cvt_pk_bf16_f32 v1, v2, v3
	v_lshl_add_u64 v[2:3], v[4:5], 1, s[18:19]
	global_store_dwordx2 v[2:3], v[0:1], off sc1
.LBB0_1661:
	ds_read_b64 v[0:1], v164 offset:9472
	s_and_b64 vcc, exec, s[6:7]
	s_waitcnt lgkmcnt(0)
	v_sub_f32_e32 v3, v25, v0
	v_sub_f32_e32 v2, v24, v0
	v_sub_f32_e32 v5, v27, v0
	v_sub_f32_e32 v4, v26, v0
	v_pk_mul_f32 v[4:5], v[0:1], v[4:5] op_sel:[1,0]
	v_pk_mul_f32 v[0:1], v[0:1], v[2:3] op_sel:[1,0]
	v_pk_fma_f32 v[2:3], v[30:31], v[4:5], v[38:39]
	v_pk_fma_f32 v[0:1], v[28:29], v[0:1], v[36:37]
	v_mov_b32_e32 v4, 0x7fc00000
	v_cndmask_b32_e64 v3, v4, v3, s[4:5]
	v_cndmask_b32_e64 v2, v4, v2, s[4:5]
	v_cndmask_b32_e64 v1, v4, v1, s[4:5]
	v_cndmask_b32_e64 v0, v4, v0, s[4:5]
	global_store_dwordx4 v[150:151], v[0:3], off offset:576 sc1
	s_cbranch_vccnz .LBB0_1663
	v_lshl_add_u64 v[6:7], v[92:93], 0, v[40:41]
	v_cvt_pk_bf16_f32 v0, v0, v1
	v_cvt_pk_bf16_f32 v1, v2, v3
	v_lshl_add_u64 v[2:3], v[6:7], 1, s[18:19]
	global_store_dwordx2 v[2:3], v[0:1], off sc1
.LBB0_1663:
	ds_read_b64 v[0:1], v164 offset:9600
	s_and_b64 vcc, exec, s[6:7]
	s_waitcnt lgkmcnt(0)
	v_sub_f32_e32 v3, v33, v0
	v_sub_f32_e32 v2, v32, v0
	v_sub_f32_e32 v7, v35, v0
	v_sub_f32_e32 v6, v34, v0
	v_pk_mul_f32 v[6:7], v[0:1], v[6:7] op_sel:[1,0]
	v_pk_mul_f32 v[0:1], v[0:1], v[2:3] op_sel:[1,0]
	v_pk_fma_f32 v[2:3], v[30:31], v[6:7], v[38:39]
	v_pk_fma_f32 v[0:1], v[28:29], v[0:1], v[36:37]
	v_cndmask_b32_e64 v3, v4, v3, s[4:5]
	v_cndmask_b32_e64 v2, v4, v2, s[4:5]
	v_cndmask_b32_e64 v1, v4, v1, s[4:5]
	v_cndmask_b32_e64 v0, v4, v0, s[4:5]
	global_store_dwordx4 v[152:153], v[0:3], off offset:576 sc1
	s_cbranch_vccnz .LBB0_1665
	v_lshl_add_u64 v[4:5], v[94:95], 0, v[40:41]
	v_cvt_pk_bf16_f32 v0, v0, v1
	v_cvt_pk_bf16_f32 v1, v2, v3
	v_lshl_add_u64 v[2:3], v[4:5], 1, s[18:19]
	global_store_dwordx2 v[2:3], v[0:1], off sc1

.LBB0_1858:
	s_or_b64 exec, exec, s[2:3]
	v_lshl_add_u64 v[140:141], s[8:9], 0, v[136:137]
	v_add_co_u32_e32 v128, vcc, 0x1000, v140
	v_lshl_add_u64 v[142:143], s[10:11], 0, v[136:137]
	s_nop 0
	v_addc_co_u32_e32 v129, vcc, 0, v141, vcc
	v_add_co_u32_e32 v132, vcc, 0x1000, v142
	s_waitcnt lgkmcnt(0)
	s_barrier
	s_nop 0
	v_addc_co_u32_e32 v133, vcc, 0, v143, vcc
	global_load_dwordx4 v[128:131], v[128:129], off
	v_or_b32_e32 v144, s20, v138
	global_load_dwordx4 v[132:135], v[132:133], off
	s_mov_b64 s[0:1], 0x1000
	v_lshl_add_u64 v[138:139], v[140:141], 0, s[0:1]
	v_lshl_add_u64 v[140:141], v[142:143], 0, s[0:1]
	v_lshl_add_u32 v142, v144, 3, 0
	v_add_u32_e32 v149, 0x2000, v142
	ds_read2_b64 v[152:155], v149 offset1:16
	ds_read2_b64 v[156:159], v149 offset0:32 offset1:48
	v_add_u32_e32 v160, s22, v144
	v_add_u32_e32 v142, 16, v160
	v_add_u32_e32 v144, 32, v160
	v_ashrrev_i32_e32 v143, 31, v142
	v_ashrrev_i32_e32 v145, 31, v144
	v_ashrrev_i32_e32 v161, 31, v160
	v_lshlrev_b64 v[142:143], 12, v[142:143]
	v_lshlrev_b64 v[144:145], 12, v[144:145]
	s_waitcnt lgkmcnt(1)
	v_sub_f32_e32 v115, v115, v152
	v_sub_f32_e32 v114, v114, v152
	v_sub_f32_e32 v113, v113, v152
	v_sub_f32_e32 v112, v112, v152
	v_lshlrev_b64 v[146:147], 12, v[160:161]
	v_lshl_add_u64 v[142:143], s[12:13], 0, v[142:143]
	v_lshl_add_u64 v[164:165], s[12:13], 0, v[144:145]
	v_sub_f32_e32 v123, v123, v154
	v_sub_f32_e32 v122, v122, v154
	v_sub_f32_e32 v121, v121, v154
	v_sub_f32_e32 v120, v120, v154
	s_waitcnt lgkmcnt(0)
	v_sub_f32_e32 v127, v127, v156
	v_sub_f32_e32 v126, v126, v156
	v_sub_f32_e32 v125, v125, v156
	v_sub_f32_e32 v124, v124, v156
	v_pk_mul_f32 v[112:113], v[152:153], v[112:113] op_sel:[1,0]
	v_pk_mul_f32 v[114:115], v[152:153], v[114:115] op_sel:[1,0]
	v_mov_b32_e32 v148, 0x7fc00000
	v_lshl_add_u64 v[146:147], s[12:13], 0, v[146:147]
	v_lshl_add_u64 v[144:145], v[142:143], 0, v[136:137]
	v_lshl_add_u64 v[142:143], v[164:165], 0, v[136:137]
	v_sub_f32_e32 v165, v119, v158
	v_sub_f32_e32 v164, v118, v158
	v_pk_mul_f32 v[118:119], v[154:155], v[120:121] op_sel:[1,0]
	v_pk_mul_f32 v[120:121], v[154:155], v[122:123] op_sel:[1,0]
	v_pk_mul_f32 v[122:123], v[156:157], v[124:125] op_sel:[1,0]
	v_pk_mul_f32 v[124:125], v[156:157], v[126:127] op_sel:[1,0]
	v_cmp_eq_u32_e32 vcc, 0, v150
	v_lshl_add_u64 v[146:147], v[146:147], 0, v[136:137]
	v_sub_f32_e32 v117, v117, v158
	v_sub_f32_e32 v116, v116, v158
	v_add_u32_e32 v162, 48, v160
	v_ashrrev_i32_e32 v163, 31, v162
	s_waitcnt vmcnt(0)
	v_pk_fma_f32 v[114:115], v[130:131], v[114:115], v[134:135]
	v_pk_fma_f32 v[112:113], v[128:129], v[112:113], v[132:133]
	v_pk_fma_f32 v[120:121], v[130:131], v[120:121], v[134:135]
	v_pk_fma_f32 v[118:119], v[128:129], v[118:119], v[132:133]
	v_pk_fma_f32 v[124:125], v[130:131], v[124:125], v[134:135]
	v_pk_fma_f32 v[122:123], v[128:129], v[122:123], v[132:133]
	v_cndmask_b32_e32 v115, v148, v115, vcc
	v_cndmask_b32_e32 v114, v148, v114, vcc
	v_cndmask_b32_e32 v113, v148, v113, vcc
	v_cndmask_b32_e32 v112, v148, v112, vcc
	v_cndmask_b32_e32 v121, v148, v121, vcc
	v_cndmask_b32_e32 v120, v148, v120, vcc
	v_cndmask_b32_e32 v119, v148, v119, vcc
	v_cndmask_b32_e32 v118, v148, v118, vcc
	v_cndmask_b32_e32 v125, v148, v125, vcc
	v_cndmask_b32_e32 v124, v148, v124, vcc
	v_cndmask_b32_e32 v123, v148, v123, vcc
	v_cndmask_b32_e32 v122, v148, v122, vcc
	global_store_dwordx4 v[146:147], v[112:115], off sc1
	global_store_dwordx4 v[144:145], v[118:121], off sc1
	global_store_dwordx4 v[142:143], v[122:125], off sc1
	ds_read2_b64 v[118:121], v149 offset0:128 offset1:144
	v_pk_mul_f32 v[112:113], v[158:159], v[116:117] op_sel:[1,0]
	v_pk_mul_f32 v[114:115], v[158:159], v[164:165] op_sel:[1,0]
	v_pk_fma_f32 v[112:113], v[128:129], v[112:113], v[132:133]
	v_pk_fma_f32 v[114:115], v[130:131], v[114:115], v[134:135]
	s_waitcnt lgkmcnt(0)
	v_sub_f32_e32 v99, v99, v118
	v_cndmask_b32_e32 v117, v148, v115, vcc
	v_cndmask_b32_e32 v116, v148, v114, vcc
	v_cndmask_b32_e32 v115, v148, v113, vcc
	v_cndmask_b32_e32 v114, v148, v112, vcc
	v_lshlrev_b64 v[112:113], 12, v[162:163]
	v_sub_f32_e32 v98, v98, v118
	v_sub_f32_e32 v97, v97, v118
	v_sub_f32_e32 v96, v96, v118
	v_sub_f32_e32 v83, v83, v120
	v_sub_f32_e32 v82, v82, v120
	v_sub_f32_e32 v81, v81, v120
	v_sub_f32_e32 v80, v80, v120
	v_lshl_add_u64 v[112:113], s[12:13], 0, v[112:113]
	v_add_u32_e32 v122, 0x80, v160
	v_pk_mul_f32 v[96:97], v[118:119], v[96:97] op_sel:[1,0]
	v_pk_mul_f32 v[98:99], v[118:119], v[98:99] op_sel:[1,0]
	v_pk_mul_f32 v[80:81], v[120:121], v[80:81] op_sel:[1,0]
	v_pk_mul_f32 v[82:83], v[120:121], v[82:83] op_sel:[1,0]
	ds_read2_b64 v[118:121], v149 offset0:160 offset1:176
	v_lshl_add_u64 v[112:113], v[112:113], 0, v[136:137]
	v_ashrrev_i32_e32 v123, 31, v122
	v_pk_fma_f32 v[96:97], v[128:129], v[96:97], v[132:133]
	global_store_dwordx4 v[112:113], v[114:117], off sc1
	v_pk_fma_f32 v[98:99], v[130:131], v[98:99], v[134:135]
	v_pk_fma_f32 v[80:81], v[128:129], v[80:81], v[132:133]
	v_cndmask_b32_e32 v115, v148, v97, vcc
	v_cndmask_b32_e32 v114, v148, v96, vcc
	v_lshlrev_b64 v[96:97], 12, v[122:123]
	v_cndmask_b32_e32 v116, v148, v98, vcc
	v_lshl_add_u64 v[96:97], s[12:13], 0, v[96:97]
	v_add_u32_e32 v98, 0x90, v160
	v_cndmask_b32_e32 v117, v148, v99, vcc
	v_lshl_add_u64 v[96:97], v[96:97], 0, v[136:137]
	v_ashrrev_i32_e32 v99, 31, v98
	global_store_dwordx4 v[96:97], v[114:117], off sc1
	v_pk_fma_f32 v[82:83], v[130:131], v[82:83], v[134:135]
	s_waitcnt lgkmcnt(0)
	v_sub_f32_e32 v45, v45, v118
	v_cndmask_b32_e32 v115, v148, v81, vcc
	v_cndmask_b32_e32 v114, v148, v80, vcc
	v_lshlrev_b64 v[80:81], 12, v[98:99]
	v_sub_f32_e32 v44, v44, v118
	v_cndmask_b32_e32 v116, v148, v82, vcc
	v_lshl_add_u64 v[80:81], s[12:13], 0, v[80:81]
	v_add_u32_e32 v82, 0xa0, v160
	v_sub_f32_e32 v47, v47, v118
	v_sub_f32_e32 v46, v46, v118
	v_pk_mul_f32 v[44:45], v[118:119], v[44:45] op_sel:[1,0]
	v_cndmask_b32_e32 v117, v148, v83, vcc
	v_lshl_add_u64 v[80:81], v[80:81], 0, v[136:137]
	v_ashrrev_i32_e32 v83, 31, v82
	v_pk_mul_f32 v[46:47], v[118:119], v[46:47] op_sel:[1,0]
	v_pk_fma_f32 v[44:45], v[128:129], v[44:45], v[132:133]
	global_store_dwordx4 v[80:81], v[114:117], off sc1
	v_pk_fma_f32 v[46:47], v[130:131], v[46:47], v[134:135]
	v_sub_f32_e32 v17, v17, v120
	v_cndmask_b32_e32 v115, v148, v45, vcc
	v_cndmask_b32_e32 v114, v148, v44, vcc
	v_lshlrev_b64 v[44:45], 12, v[82:83]
	v_sub_f32_e32 v16, v16, v120
	v_cndmask_b32_e32 v116, v148, v46, vcc
	v_lshl_add_u64 v[44:45], s[12:13], 0, v[44:45]
	v_add_u32_e32 v46, 0xb0, v160
	v_pk_mul_f32 v[16:17], v[120:121], v[16:17] op_sel:[1,0]
	v_cndmask_b32_e32 v117, v148, v47, vcc
	v_lshl_add_u64 v[44:45], v[44:45], 0, v[136:137]
	v_ashrrev_i32_e32 v47, 31, v46
	v_sub_f32_e32 v19, v19, v120
	v_sub_f32_e32 v18, v18, v120
	v_pk_fma_f32 v[16:17], v[128:129], v[16:17], v[132:133]
	global_store_dwordx4 v[44:45], v[114:117], off sc1
	v_pk_mul_f32 v[18:19], v[120:121], v[18:19] op_sel:[1,0]
	s_nop 0
	v_cndmask_b32_e32 v115, v148, v17, vcc
	v_cndmask_b32_e32 v114, v148, v16, vcc
	v_lshlrev_b64 v[16:17], 12, v[46:47]
	v_pk_fma_f32 v[18:19], v[130:131], v[18:19], v[134:135]
	v_lshl_add_u64 v[16:17], s[12:13], 0, v[16:17]
	v_cndmask_b32_e32 v117, v148, v19, vcc
	v_cndmask_b32_e32 v116, v148, v18, vcc
	v_lshl_add_u64 v[16:17], v[16:17], 0, v[136:137]
	global_store_dwordx4 v[16:17], v[114:117], off sc1
	global_load_dwordx4 v[114:117], v[138:139], off offset:64
	global_load_dwordx4 v[118:121], v[140:141], off offset:64
	ds_read2_b64 v[122:125], v149 offset1:16
	s_waitcnt lgkmcnt(0)
	v_sub_f32_e32 v19, v89, v122
	v_sub_f32_e32 v18, v88, v122
	v_pk_mul_f32 v[18:19], v[122:123], v[18:19] op_sel:[1,0]
	v_sub_f32_e32 v47, v91, v122
	v_sub_f32_e32 v46, v90, v122
	v_pk_mul_f32 v[46:47], v[122:123], v[46:47] op_sel:[1,0]
	s_waitcnt vmcnt(0)
	v_pk_fma_f32 v[18:19], v[114:115], v[18:19], v[118:119]
	s_nop 0
	v_cndmask_b32_e32 v89, v148, v19, vcc
	v_cndmask_b32_e32 v88, v148, v18, vcc
	v_sub_f32_e32 v19, v101, v124
	v_sub_f32_e32 v18, v100, v124
	ds_read2_b64 v[98:101], v149 offset0:32 offset1:48
	v_pk_fma_f32 v[46:47], v[116:117], v[46:47], v[120:121]
	v_pk_mul_f32 v[18:19], v[124:125], v[18:19] op_sel:[1,0]
	v_cndmask_b32_e32 v91, v148, v47, vcc
	v_cndmask_b32_e32 v90, v148, v46, vcc
	v_sub_f32_e32 v47, v103, v124
	v_sub_f32_e32 v46, v102, v124
	v_pk_mul_f32 v[46:47], v[124:125], v[46:47] op_sel:[1,0]
	v_pk_fma_f32 v[18:19], v[114:115], v[18:19], v[118:119]
	v_pk_fma_f32 v[46:47], v[116:117], v[46:47], v[120:121]
	global_store_dwordx4 v[146:147], v[88:91], off offset:64 sc1
	s_nop 1
	v_cndmask_b32_e32 v91, v148, v47, vcc
	v_cndmask_b32_e32 v90, v148, v46, vcc
	v_cndmask_b32_e32 v89, v148, v19, vcc
	v_cndmask_b32_e32 v88, v148, v18, vcc
	s_waitcnt lgkmcnt(0)
	v_sub_f32_e32 v19, v105, v98
	v_sub_f32_e32 v18, v104, v98
	v_sub_f32_e32 v47, v107, v98
	v_sub_f32_e32 v46, v106, v98
	v_pk_mul_f32 v[46:47], v[98:99], v[46:47] op_sel:[1,0]
	v_pk_mul_f32 v[18:19], v[98:99], v[18:19] op_sel:[1,0]
	v_pk_fma_f32 v[46:47], v[116:117], v[46:47], v[120:121]
	v_pk_fma_f32 v[18:19], v[114:115], v[18:19], v[118:119]
	global_store_dwordx4 v[144:145], v[88:91], off offset:64 sc1
	s_nop 1
	v_cndmask_b32_e32 v91, v148, v47, vcc
	v_cndmask_b32_e32 v90, v148, v46, vcc
	v_cndmask_b32_e32 v89, v148, v19, vcc
	v_cndmask_b32_e32 v88, v148, v18, vcc
	v_sub_f32_e32 v19, v109, v100
	v_sub_f32_e32 v18, v108, v100
	v_sub_f32_e32 v47, v111, v100
	v_sub_f32_e32 v46, v110, v100
	v_pk_mul_f32 v[46:47], v[100:101], v[46:47] op_sel:[1,0]
	v_pk_mul_f32 v[18:19], v[100:101], v[18:19] op_sel:[1,0]
	ds_read2_b64 v[98:101], v149 offset0:128 offset1:144
	v_pk_fma_f32 v[18:19], v[114:115], v[18:19], v[118:119]
	v_pk_fma_f32 v[46:47], v[116:117], v[46:47], v[120:121]
	global_store_dwordx4 v[142:143], v[88:91], off offset:64 sc1
	s_nop 1
	v_cndmask_b32_e32 v91, v148, v47, vcc
	v_cndmask_b32_e32 v90, v148, v46, vcc
	v_cndmask_b32_e32 v89, v148, v19, vcc
	v_cndmask_b32_e32 v88, v148, v18, vcc
	s_waitcnt lgkmcnt(0)
	v_sub_f32_e32 v19, v93, v98
	v_sub_f32_e32 v18, v92, v98
	v_sub_f32_e32 v47, v95, v98
	v_sub_f32_e32 v46, v94, v98
	v_pk_mul_f32 v[46:47], v[98:99], v[46:47] op_sel:[1,0]
	v_pk_mul_f32 v[18:19], v[98:99], v[18:19] op_sel:[1,0]
	v_pk_fma_f32 v[46:47], v[116:117], v[46:47], v[120:121]
	v_pk_fma_f32 v[18:19], v[114:115], v[18:19], v[118:119]
	global_store_dwordx4 v[112:113], v[88:91], off offset:64 sc1
	s_nop 1
	v_cndmask_b32_e32 v91, v148, v47, vcc
	v_cndmask_b32_e32 v90, v148, v46, vcc
	v_cndmask_b32_e32 v89, v148, v19, vcc
	v_cndmask_b32_e32 v88, v148, v18, vcc
	global_store_dwordx4 v[96:97], v[88:91], off offset:64 sc1
	ds_read2_b64 v[88:91], v149 offset0:160 offset1:176
	v_sub_f32_e32 v19, v73, v100
	v_sub_f32_e32 v18, v72, v100
	v_pk_mul_f32 v[18:19], v[100:101], v[18:19] op_sel:[1,0]
	v_sub_f32_e32 v47, v75, v100
	v_pk_fma_f32 v[18:19], v[114:115], v[18:19], v[118:119]
	v_sub_f32_e32 v46, v74, v100
	v_cndmask_b32_e32 v73, v148, v19, vcc
	v_cndmask_b32_e32 v72, v148, v18, vcc
	s_waitcnt lgkmcnt(0)
	v_sub_f32_e32 v19, v41, v88
	v_sub_f32_e32 v18, v40, v88
	v_sub_f32_e32 v41, v43, v88
	v_sub_f32_e32 v40, v42, v88
	v_sub_f32_e32 v13, v13, v90
	v_sub_f32_e32 v12, v12, v90
	v_sub_f32_e32 v15, v15, v90
	v_sub_f32_e32 v14, v14, v90
	v_pk_mul_f32 v[46:47], v[100:101], v[46:47] op_sel:[1,0]
	v_pk_mul_f32 v[40:41], v[88:89], v[40:41] op_sel:[1,0]
	v_pk_mul_f32 v[18:19], v[88:89], v[18:19] op_sel:[1,0]
	v_pk_mul_f32 v[14:15], v[90:91], v[14:15] op_sel:[1,0]
	v_pk_mul_f32 v[12:13], v[90:91], v[12:13] op_sel:[1,0]
	v_pk_fma_f32 v[46:47], v[116:117], v[46:47], v[120:121]
	v_pk_fma_f32 v[18:19], v[114:115], v[18:19], v[118:119]
	v_pk_fma_f32 v[40:41], v[116:117], v[40:41], v[120:121]
	v_pk_fma_f32 v[12:13], v[114:115], v[12:13], v[118:119]
	v_pk_fma_f32 v[14:15], v[116:117], v[14:15], v[120:121]
	v_cndmask_b32_e32 v75, v148, v47, vcc
	v_cndmask_b32_e32 v74, v148, v46, vcc
	v_cndmask_b32_e32 v43, v148, v41, vcc
	v_cndmask_b32_e32 v42, v148, v40, vcc
	v_cndmask_b32_e32 v41, v148, v19, vcc
	v_cndmask_b32_e32 v40, v148, v18, vcc
	v_cndmask_b32_e32 v15, v148, v15, vcc
	v_cndmask_b32_e32 v14, v148, v14, vcc
	v_cndmask_b32_e32 v13, v148, v13, vcc
	v_cndmask_b32_e32 v12, v148, v12, vcc
	global_store_dwordx4 v[80:81], v[72:75], off offset:64 sc1
	global_store_dwordx4 v[44:45], v[40:43], off offset:64 sc1
	global_store_dwordx4 v[16:17], v[12:15], off offset:64 sc1
	global_load_dwordx4 v[12:15], v[138:139], off offset:512
	global_load_dwordx4 v[40:43], v[140:141], off offset:512
	ds_read2_b64 v[72:75], v149 offset1:16
	s_waitcnt lgkmcnt(0)
	v_sub_f32_e32 v19, v53, v72
	v_sub_f32_e32 v18, v52, v72
	v_sub_f32_e32 v47, v55, v72
	v_sub_f32_e32 v46, v54, v72
	v_pk_mul_f32 v[46:47], v[72:73], v[46:47] op_sel:[1,0]
	v_pk_mul_f32 v[18:19], v[72:73], v[18:19] op_sel:[1,0]
	s_waitcnt vmcnt(0)
	v_pk_fma_f32 v[46:47], v[14:15], v[46:47], v[42:43]
	v_pk_fma_f32 v[18:19], v[12:13], v[18:19], v[40:41]
	v_cndmask_b32_e32 v55, v148, v47, vcc
	v_cndmask_b32_e32 v54, v148, v46, vcc
	v_cndmask_b32_e32 v53, v148, v19, vcc
	v_cndmask_b32_e32 v52, v148, v18, vcc
	v_sub_f32_e32 v19, v61, v74
	v_sub_f32_e32 v18, v60, v74
	v_sub_f32_e32 v47, v63, v74
	v_sub_f32_e32 v46, v62, v74
	ds_read2_b64 v[60:63], v149 offset0:32 offset1:48
	v_pk_mul_f32 v[46:47], v[74:75], v[46:47] op_sel:[1,0]
	v_pk_mul_f32 v[18:19], v[74:75], v[18:19] op_sel:[1,0]
	v_pk_fma_f32 v[46:47], v[14:15], v[46:47], v[42:43]
	v_pk_fma_f32 v[18:19], v[12:13], v[18:19], v[40:41]
	global_store_dwordx4 v[146:147], v[52:55], off offset:512 sc1
	s_nop 1
	v_cndmask_b32_e32 v55, v148, v47, vcc
	v_cndmask_b32_e32 v54, v148, v46, vcc
	v_cndmask_b32_e32 v53, v148, v19, vcc
	v_cndmask_b32_e32 v52, v148, v18, vcc
	s_waitcnt lgkmcnt(0)
	v_sub_f32_e32 v19, v69, v60
	v_sub_f32_e32 v18, v68, v60
	v_sub_f32_e32 v47, v71, v60
	v_sub_f32_e32 v46, v70, v60
	v_pk_mul_f32 v[46:47], v[60:61], v[46:47] op_sel:[1,0]
	v_pk_mul_f32 v[18:19], v[60:61], v[18:19] op_sel:[1,0]
	v_pk_fma_f32 v[46:47], v[14:15], v[46:47], v[42:43]
	v_pk_fma_f32 v[18:19], v[12:13], v[18:19], v[40:41]
	global_store_dwordx4 v[144:145], v[52:55], off offset:512 sc1
	s_nop 1
	v_cndmask_b32_e32 v55, v148, v47, vcc
	v_cndmask_b32_e32 v54, v148, v46, vcc
	v_cndmask_b32_e32 v53, v148, v19, vcc
	v_cndmask_b32_e32 v52, v148, v18, vcc
	v_sub_f32_e32 v19, v77, v62
	v_sub_f32_e32 v18, v76, v62
	v_sub_f32_e32 v47, v79, v62
	v_sub_f32_e32 v46, v78, v62
	v_pk_mul_f32 v[46:47], v[62:63], v[46:47] op_sel:[1,0]
	v_pk_mul_f32 v[18:19], v[62:63], v[18:19] op_sel:[1,0]
	ds_read2_b64 v[60:63], v149 offset0:128 offset1:144
	v_pk_fma_f32 v[18:19], v[12:13], v[18:19], v[40:41]
	v_pk_fma_f32 v[46:47], v[14:15], v[46:47], v[42:43]
	global_store_dwordx4 v[142:143], v[52:55], off offset:512 sc1
	s_nop 1
	v_cndmask_b32_e32 v55, v148, v47, vcc
	v_cndmask_b32_e32 v54, v148, v46, vcc
	v_cndmask_b32_e32 v53, v148, v19, vcc
	v_cndmask_b32_e32 v52, v148, v18, vcc
	s_waitcnt lgkmcnt(0)
	v_sub_f32_e32 v19, v85, v60
	v_sub_f32_e32 v18, v84, v60
	v_sub_f32_e32 v47, v87, v60
	v_sub_f32_e32 v46, v86, v60
	v_pk_mul_f32 v[46:47], v[60:61], v[46:47] op_sel:[1,0]
	v_pk_mul_f32 v[18:19], v[60:61], v[18:19] op_sel:[1,0]
	v_pk_fma_f32 v[46:47], v[14:15], v[46:47], v[42:43]
	v_pk_fma_f32 v[18:19], v[12:13], v[18:19], v[40:41]
	global_store_dwordx4 v[112:113], v[52:55], off offset:512 sc1
	s_nop 1
	v_cndmask_b32_e32 v55, v148, v47, vcc
	v_cndmask_b32_e32 v54, v148, v46, vcc
	v_cndmask_b32_e32 v53, v148, v19, vcc
	v_cndmask_b32_e32 v52, v148, v18, vcc
	v_sub_f32_e32 v19, v65, v62
	v_sub_f32_e32 v18, v64, v62
	v_sub_f32_e32 v47, v67, v62
	v_sub_f32_e32 v46, v66, v62
	v_pk_mul_f32 v[46:47], v[62:63], v[46:47] op_sel:[1,0]
	v_pk_mul_f32 v[18:19], v[62:63], v[18:19] op_sel:[1,0]
	ds_read2_b64 v[60:63], v149 offset0:160 offset1:176
	v_pk_fma_f32 v[18:19], v[12:13], v[18:19], v[40:41]
	global_store_dwordx4 v[96:97], v[52:55], off offset:512 sc1
	v_pk_fma_f32 v[46:47], v[14:15], v[46:47], v[42:43]
	s_waitcnt lgkmcnt(0)
	v_sub_f32_e32 v5, v5, v62
	v_cndmask_b32_e32 v53, v148, v19, vcc
	v_cndmask_b32_e32 v52, v148, v18, vcc
	v_sub_f32_e32 v19, v33, v60
	v_sub_f32_e32 v18, v32, v60
	v_sub_f32_e32 v33, v35, v60
	v_sub_f32_e32 v32, v34, v60
	v_sub_f32_e32 v4, v4, v62
	v_sub_f32_e32 v7, v7, v62
	v_sub_f32_e32 v6, v6, v62
	v_pk_mul_f32 v[32:33], v[60:61], v[32:33] op_sel:[1,0]
	v_pk_mul_f32 v[18:19], v[60:61], v[18:19] op_sel:[1,0]
	v_pk_mul_f32 v[6:7], v[62:63], v[6:7] op_sel:[1,0]
	v_pk_mul_f32 v[4:5], v[62:63], v[4:5] op_sel:[1,0]
	v_pk_fma_f32 v[18:19], v[12:13], v[18:19], v[40:41]
	v_pk_fma_f32 v[32:33], v[14:15], v[32:33], v[42:43]
	v_pk_fma_f32 v[4:5], v[12:13], v[4:5], v[40:41]
	v_pk_fma_f32 v[6:7], v[14:15], v[6:7], v[42:43]
	v_cndmask_b32_e32 v55, v148, v47, vcc
	v_cndmask_b32_e32 v54, v148, v46, vcc
	v_cndmask_b32_e32 v35, v148, v33, vcc
	v_cndmask_b32_e32 v34, v148, v32, vcc
	v_cndmask_b32_e32 v33, v148, v19, vcc
	v_cndmask_b32_e32 v32, v148, v18, vcc
	v_cndmask_b32_e32 v7, v148, v7, vcc
	v_cndmask_b32_e32 v6, v148, v6, vcc
	v_cndmask_b32_e32 v5, v148, v5, vcc
	v_cndmask_b32_e32 v4, v148, v4, vcc
	global_store_dwordx4 v[80:81], v[52:55], off offset:512 sc1
	global_store_dwordx4 v[44:45], v[32:35], off offset:512 sc1
	global_store_dwordx4 v[16:17], v[4:7], off offset:512 sc1
	global_load_dwordx4 v[4:7], v[138:139], off offset:576
	global_load_dwordx4 v[12:15], v[140:141], off offset:576
	ds_read2_b64 v[32:35], v149 offset1:16
	s_waitcnt lgkmcnt(0)
	v_sub_f32_e32 v9, v9, v32
	v_sub_f32_e32 v8, v8, v32
	v_sub_f32_e32 v11, v11, v32
	v_sub_f32_e32 v10, v10, v32
	v_pk_mul_f32 v[10:11], v[32:33], v[10:11] op_sel:[1,0]
	v_pk_mul_f32 v[8:9], v[32:33], v[8:9] op_sel:[1,0]
	s_waitcnt vmcnt(0)
	v_pk_fma_f32 v[10:11], v[6:7], v[10:11], v[14:15]
	v_pk_fma_f32 v[8:9], v[4:5], v[8:9], v[12:13]
	v_cndmask_b32_e32 v11, v148, v11, vcc
	v_cndmask_b32_e32 v10, v148, v10, vcc
	v_cndmask_b32_e32 v9, v148, v9, vcc
	v_cndmask_b32_e32 v8, v148, v8, vcc
	global_store_dwordx4 v[146:147], v[8:11], off offset:576 sc1
	s_nop 1
	v_sub_f32_e32 v9, v21, v34
	v_sub_f32_e32 v8, v20, v34
	ds_read2_b64 v[18:21], v149 offset0:32 offset1:48
	v_sub_f32_e32 v11, v23, v34
	v_sub_f32_e32 v10, v22, v34
	v_pk_mul_f32 v[10:11], v[34:35], v[10:11] op_sel:[1,0]
	v_pk_mul_f32 v[8:9], v[34:35], v[8:9] op_sel:[1,0]
	v_pk_fma_f32 v[10:11], v[6:7], v[10:11], v[14:15]
	v_pk_fma_f32 v[8:9], v[4:5], v[8:9], v[12:13]
	v_cndmask_b32_e32 v11, v148, v11, vcc
	v_cndmask_b32_e32 v10, v148, v10, vcc
	v_cndmask_b32_e32 v9, v148, v9, vcc
	v_cndmask_b32_e32 v8, v148, v8, vcc
	global_store_dwordx4 v[144:145], v[8:11], off offset:576 sc1
	s_waitcnt lgkmcnt(0)
	s_nop 0
	v_sub_f32_e32 v9, v29, v18
	v_sub_f32_e32 v8, v28, v18
	v_sub_f32_e32 v11, v31, v18
	v_sub_f32_e32 v10, v30, v18
	v_pk_mul_f32 v[10:11], v[18:19], v[10:11] op_sel:[1,0]
	v_pk_mul_f32 v[8:9], v[18:19], v[8:9] op_sel:[1,0]
	v_pk_fma_f32 v[10:11], v[6:7], v[10:11], v[14:15]
	v_pk_fma_f32 v[8:9], v[4:5], v[8:9], v[12:13]
	v_cndmask_b32_e32 v11, v148, v11, vcc
	v_cndmask_b32_e32 v10, v148, v10, vcc
	v_cndmask_b32_e32 v9, v148, v9, vcc
	v_cndmask_b32_e32 v8, v148, v8, vcc
	global_store_dwordx4 v[142:143], v[8:11], off offset:576 sc1
	s_nop 1
	v_sub_f32_e32 v9, v37, v20
	v_sub_f32_e32 v8, v36, v20
	v_sub_f32_e32 v11, v39, v20
	v_sub_f32_e32 v10, v38, v20
	v_pk_mul_f32 v[10:11], v[20:21], v[10:11] op_sel:[1,0]
	v_pk_mul_f32 v[8:9], v[20:21], v[8:9] op_sel:[1,0]
	ds_read2_b64 v[18:21], v149 offset0:128 offset1:144
	v_pk_fma_f32 v[8:9], v[4:5], v[8:9], v[12:13]
	v_pk_fma_f32 v[10:11], v[6:7], v[10:11], v[14:15]
	v_cndmask_b32_e32 v9, v148, v9, vcc
	v_cndmask_b32_e32 v11, v148, v11, vcc
	v_cndmask_b32_e32 v10, v148, v10, vcc
	v_cndmask_b32_e32 v8, v148, v8, vcc
	global_store_dwordx4 v[112:113], v[8:11], off offset:576 sc1
	s_waitcnt lgkmcnt(0)
	s_nop 0
	v_sub_f32_e32 v9, v49, v18
	v_sub_f32_e32 v8, v48, v18
	v_sub_f32_e32 v11, v51, v18
	v_sub_f32_e32 v10, v50, v18
	v_pk_mul_f32 v[10:11], v[18:19], v[10:11] op_sel:[1,0]
	v_pk_mul_f32 v[8:9], v[18:19], v[8:9] op_sel:[1,0]
	v_pk_fma_f32 v[10:11], v[6:7], v[10:11], v[14:15]
	v_pk_fma_f32 v[8:9], v[4:5], v[8:9], v[12:13]
	v_cndmask_b32_e32 v11, v148, v11, vcc
	v_cndmask_b32_e32 v10, v148, v10, vcc
	v_cndmask_b32_e32 v9, v148, v9, vcc
	v_cndmask_b32_e32 v8, v148, v8, vcc
	global_store_dwordx4 v[96:97], v[8:11], off offset:576 sc1
	s_nop 1
	v_sub_f32_e32 v9, v57, v20
	v_sub_f32_e32 v8, v56, v20
	v_sub_f32_e32 v11, v59, v20
	v_sub_f32_e32 v10, v58, v20
	v_pk_mul_f32 v[10:11], v[20:21], v[10:11] op_sel:[1,0]
	v_pk_mul_f32 v[8:9], v[20:21], v[8:9] op_sel:[1,0]
	ds_read2_b64 v[18:21], v149 offset0:160 offset1:176
	v_pk_fma_f32 v[8:9], v[4:5], v[8:9], v[12:13]
	v_pk_fma_f32 v[10:11], v[6:7], v[10:11], v[14:15]
	v_cndmask_b32_e32 v9, v148, v9, vcc
	v_cndmask_b32_e32 v11, v148, v11, vcc
	v_cndmask_b32_e32 v10, v148, v10, vcc
	v_cndmask_b32_e32 v8, v148, v8, vcc
	global_store_dwordx4 v[80:81], v[8:11], off offset:576 sc1
	s_waitcnt lgkmcnt(0)
	v_sub_f32_e32 v1, v1, v20
	v_sub_f32_e32 v0, v0, v20
	v_sub_f32_e32 v9, v25, v18
	v_sub_f32_e32 v8, v24, v18
	v_sub_f32_e32 v11, v27, v18
	v_sub_f32_e32 v10, v26, v18
	v_sub_f32_e32 v3, v3, v20
	v_sub_f32_e32 v2, v2, v20
	v_pk_mul_f32 v[10:11], v[18:19], v[10:11] op_sel:[1,0]
	v_pk_mul_f32 v[8:9], v[18:19], v[8:9] op_sel:[1,0]
	v_pk_mul_f32 v[2:3], v[20:21], v[2:3] op_sel:[1,0]
	v_pk_mul_f32 v[0:1], v[20:21], v[0:1] op_sel:[1,0]
	v_pk_fma_f32 v[8:9], v[4:5], v[8:9], v[12:13]
	v_pk_fma_f32 v[10:11], v[6:7], v[10:11], v[14:15]
	v_pk_fma_f32 v[0:1], v[4:5], v[0:1], v[12:13]
	v_pk_fma_f32 v[2:3], v[6:7], v[2:3], v[14:15]
	v_cndmask_b32_e32 v11, v148, v11, vcc
	v_cndmask_b32_e32 v10, v148, v10, vcc
	v_cndmask_b32_e32 v9, v148, v9, vcc
	v_cndmask_b32_e32 v8, v148, v8, vcc
	v_cndmask_b32_e32 v3, v148, v3, vcc
	v_cndmask_b32_e32 v2, v148, v2, vcc
	v_cndmask_b32_e32 v1, v148, v1, vcc
	v_cndmask_b32_e32 v0, v148, v0, vcc
	global_store_dwordx4 v[44:45], v[8:11], off offset:576 sc1
	global_store_dwordx4 v[16:17], v[0:3], off offset:576 sc1
